# nt hint also on attention Q loads, rowpass x loads and pool_local x-row loads (all read once)
# speedup vs baseline: 1.0329x; 1.0114x over previous
.LBB0_110:
	s_add_u32 s27, s12, s20
	s_addc_u32 s2, s13, s21
	s_add_i32 s22, s27, 0xffffe000
	s_cmpk_lt_i32 s27, 0x2000
	s_cselect_b32 s3, s2, 0
	s_cselect_b32 s2, s27, s22
	s_cselect_b32 s22, s5, s7
	s_cselect_b32 s23, s4, s6
	s_lshl_b64 s[2:3], s[2:3], 12
	s_add_u32 s2, s23, s2
	s_addc_u32 s3, s22, s3
	global_load_dwordx4 v[44:47], v66, s[2:3] nt
	global_load_dwordx4 v[40:43], v66, s[2:3] offset:1024 nt
	global_load_dwordx4 v[36:39], v66, s[2:3] offset:2048 nt
	global_load_dwordx4 v[32:35], v66, s[2:3] offset:3072 nt
	s_add_i32 s24, s27, 1
	s_add_i32 s22, s27, 0xffffe001
	s_ashr_i32 s25, s24, 31
	s_cmpk_lt_i32 s24, 0x2000
	s_cselect_b32 s3, s25, 0
	s_cselect_b32 s2, s24, s22
	s_cselect_b32 s23, s5, s7
	s_cselect_b32 s22, s4, s6
	s_lshl_b64 s[2:3], s[2:3], 12
	s_add_u32 s22, s22, s2
	s_addc_u32 s23, s23, s3
	s_add_i32 s28, s27, 2
	s_lshl_b64 s[2:3], s[24:25], 11
	s_add_i32 s24, s27, 0xffffe002
	s_ashr_i32 s29, s28, 31
	v_add_co_u32_e32 v56, vcc, s34, v54
	s_cmpk_lt_i32 s28, 0x2000
	s_nop 0
	v_addc_co_u32_e32 v57, vcc, -1, v55, vcc
	v_lshl_add_u64 v[60:61], v[48:49], 0, s[2:3]
	v_lshl_add_u64 v[58:59], v[50:51], 0, s[2:3]
	s_cselect_b32 s3, s29, 0
	s_cselect_b32 s2, s28, s24
	s_cselect_b32 s25, s5, s7
	s_cselect_b32 s24, s4, s6
	s_lshl_b64 s[2:3], s[2:3], 12
	s_add_u32 s24, s24, s2
	s_addc_u32 s25, s25, s3
	s_add_i32 s26, s27, 3
	s_lshl_b64 s[2:3], s[28:29], 11
	s_add_i32 s28, s27, 0xffffe003
	s_ashr_i32 s27, s26, 31
	s_cmpk_lt_i32 s26, 0x2000
	v_lshl_add_u64 v[64:65], v[48:49], 0, s[2:3]
	v_lshl_add_u64 v[62:63], v[50:51], 0, s[2:3]
	s_cselect_b32 s3, s27, 0
	s_cselect_b32 s2, s26, s28
	s_cselect_b32 s29, s5, s7
	s_cselect_b32 s28, s4, s6
	s_lshl_b64 s[2:3], s[2:3], 12
	s_add_u32 s28, s28, s2
	s_addc_u32 s29, s29, s3
	s_waitcnt vmcnt(3)
	v_cvt_pk_bf16_f32 v72, v44, v45
	v_mul_f32_e32 v74, v45, v45
	v_mul_f32_e32 v75, v47, v47
	s_waitcnt vmcnt(2)
	v_mul_f32_e32 v76, v41, v41
	v_mul_f32_e32 v77, v43, v43
	v_cvt_pk_bf16_f32 v73, v46, v47
	s_waitcnt vmcnt(1)
	v_mul_f32_e32 v78, v37, v37
	v_mul_f32_e32 v79, v39, v39
	global_store_dwordx2 v[54:55], v[72:73], off offset:-1536
	v_cvt_pk_bf16_f32 v72, v40, v41
	v_fmac_f32_e32 v74, v44, v44
	v_fmac_f32_e32 v75, v46, v46
	v_fmac_f32_e32 v76, v40, v40
	v_fmac_f32_e32 v77, v42, v42
	s_waitcnt vmcnt(1)
	v_mul_f32_e32 v80, v33, v33
	v_mul_f32_e32 v81, v35, v35
	v_cvt_pk_bf16_f32 v73, v42, v43
	v_fmac_f32_e32 v78, v36, v36
	v_fmac_f32_e32 v79, v38, v38
	global_store_dwordx2 v[54:55], v[72:73], off offset:-1024
	v_cvt_pk_bf16_f32 v72, v36, v37
	v_add_f32_e32 v74, v74, v75
	v_add_f32_e32 v75, v76, v77
	v_fmac_f32_e32 v80, v32, v32
	v_fmac_f32_e32 v81, v34, v34
	v_cvt_pk_bf16_f32 v73, v38, v39
	v_add_f32_e32 v76, v78, v79
	global_store_dwordx2 v[54:55], v[72:73], off offset:-512
	v_cvt_pk_bf16_f32 v72, v32, v33
	v_add_f32_e32 v74, v74, v75
	v_add_f32_e32 v77, v80, v81
	v_cvt_pk_bf16_f32 v73, v34, v35
	global_store_dwordx2 v[54:55], v[72:73], off
	v_add_f32_e32 v72, v74, v76
	v_add_f32_e32 v72, v72, v77
	v_lshl_add_u64 v[54:55], v[54:55], 0, s[18:19]
	s_nop 0
	v_add_f32_dpp v72, v72, v72 row_ror:8 row_mask:0xf bank_mask:0xf bound_ctrl:1
	s_nop 1
	v_add_f32_dpp v72, v72, v72 row_ror:4 row_mask:0xf bank_mask:0xf bound_ctrl:1
	s_nop 1
	v_add_f32_dpp v72, v72, v72 row_ror:2 row_mask:0xf bank_mask:0xf bound_ctrl:1
	s_nop 1
	v_add_f32_dpp v72, v72, v72 row_ror:1 row_mask:0xf bank_mask:0xf bound_ctrl:1
	v_mov_b32_e32 v73, v72
	s_nop 1
	v_permlane16_swap_b32_e32 v72, v73
	v_add_f32_e32 v72, v72, v73
	v_mov_b32_e32 v73, v72
	s_nop 1
	v_permlane32_swap_b32_e32 v72, v73
	v_add_f32_e32 v72, v72, v73
	v_fmamk_f32 v72, v72, 0x3a800000, v70
	v_mul_f32_e32 v73, 0x4f800000, v72
	v_cmp_gt_f32_e32 vcc, s33, v72
	s_nop 1
	v_cndmask_b32_e32 v72, v72, v73, vcc
	v_sqrt_f32_e32 v73, v72
	s_nop 0
	v_add_u32_e32 v74, -1, v73
	v_add_u32_e32 v75, 1, v73
	v_fma_f32 v76, -v74, v73, v72
	v_fma_f32 v77, -v75, v73, v72
	v_cmp_ge_f32_e64 s[2:3], 0, v76
	s_nop 1
	v_cndmask_b32_e64 v73, v73, v74, s[2:3]
	v_cmp_lt_f32_e64 s[2:3], 0, v77
	s_nop 1
	v_cndmask_b32_e64 v73, v73, v75, s[2:3]
	v_mul_f32_e32 v74, 0x37800000, v73
	v_cndmask_b32_e32 v73, v73, v74, vcc
	v_cmp_class_f32_e32 vcc, v72, v71
	s_nop 1
	v_cndmask_b32_e32 v72, v73, v72, vcc
	v_div_scale_f32 v73, s[2:3], v72, v72, 1.0
	v_rcp_f32_e32 v75, v73
	v_div_scale_f32 v74, vcc, 1.0, v72, 1.0
	v_fma_f32 v76, -v73, v75, 1.0
	v_fmac_f32_e32 v75, v76, v75
	v_mul_f32_e32 v76, v74, v75
	v_fma_f32 v77, -v73, v76, v74
	v_fmac_f32_e32 v76, v77, v75
	v_fma_f32 v73, -v73, v76, v74
	v_div_fmas_f32 v73, v73, v75, v76
	v_div_fixup_f32 v72, v73, v72, 1.0
	v_pk_mul_f32 v[44:45], v[44:45], v[72:73] op_sel_hi:[1,0]
	v_pk_mul_f32 v[40:41], v[40:41], v[72:73] op_sel_hi:[1,0]
	v_pk_mul_f32 v[36:37], v[36:37], v[72:73] op_sel_hi:[1,0]
	v_pk_mul_f32 v[32:33], v[32:33], v[72:73] op_sel_hi:[1,0]
	v_pk_mul_f32 v[46:47], v[46:47], v[72:73] op_sel_hi:[1,0]
	v_pk_mul_f32 v[42:43], v[42:43], v[72:73] op_sel_hi:[1,0]
	v_pk_mul_f32 v[38:39], v[38:39], v[72:73] op_sel_hi:[1,0]
	v_pk_mul_f32 v[34:35], v[34:35], v[72:73] op_sel_hi:[1,0]
	v_pk_fma_f32 v[44:45], v[8:9], v[44:45], v[0:1]
	v_pk_fma_f32 v[40:41], v[12:13], v[40:41], v[4:5]
	v_pk_fma_f32 v[36:37], v[24:25], v[36:37], v[16:17]
	v_pk_fma_f32 v[32:33], v[28:29], v[32:33], v[20:21]
	v_pk_fma_f32 v[46:47], v[10:11], v[46:47], v[2:3]
	v_pk_fma_f32 v[42:43], v[14:15], v[42:43], v[6:7]
	v_pk_fma_f32 v[38:39], v[26:27], v[38:39], v[18:19]
	v_pk_fma_f32 v[34:35], v[30:31], v[34:35], v[22:23]
	v_cvt_pk_bf16_f32 v44, v44, v45
	v_cvt_pk_bf16_f32 v45, v46, v47
	global_store_dwordx2 v[56:57], v[44:45], off offset:-1536
	v_cvt_pk_bf16_f32 v40, v40, v41
	v_cvt_pk_bf16_f32 v41, v42, v43
	global_store_dwordx2 v[56:57], v[40:41], off offset:-1024
	v_cvt_pk_bf16_f32 v36, v36, v37
	v_cvt_pk_bf16_f32 v37, v38, v39
	global_store_dwordx2 v[56:57], v[36:37], off offset:-512
	v_cvt_pk_bf16_f32 v32, v32, v33
	v_cvt_pk_bf16_f32 v33, v34, v35
	global_store_dwordx2 v[56:57], v[32:33], off
	global_load_dwordx4 v[32:35], v66, s[22:23] nt
	s_nop 0
	global_load_dwordx4 v[36:39], v66, s[22:23] offset:1024 nt
	global_load_dwordx4 v[40:43], v66, s[22:23] offset:2048 nt
	global_load_dwordx4 v[44:47], v66, s[22:23] offset:3072 nt
	s_waitcnt vmcnt(3)
	v_cvt_pk_bf16_f32 v56, v32, v33
	v_mul_f32_e32 v72, v33, v33
	v_mul_f32_e32 v73, v35, v35
	s_waitcnt vmcnt(2)
	v_mul_f32_e32 v74, v37, v37
	v_mul_f32_e32 v75, v39, v39
	v_cvt_pk_bf16_f32 v57, v34, v35
	s_waitcnt vmcnt(1)
	v_mul_f32_e32 v76, v41, v41
	v_mul_f32_e32 v77, v43, v43
	global_store_dwordx2 v[60:61], v[56:57], off
	v_cvt_pk_bf16_f32 v56, v36, v37
	v_fmac_f32_e32 v72, v32, v32
	v_fmac_f32_e32 v73, v34, v34
	v_fmac_f32_e32 v74, v36, v36
	v_fmac_f32_e32 v75, v38, v38
	s_waitcnt vmcnt(1)
	v_mul_f32_e32 v78, v45, v45
	v_mul_f32_e32 v79, v47, v47
	v_cvt_pk_bf16_f32 v57, v38, v39
	v_fmac_f32_e32 v76, v40, v40
	v_fmac_f32_e32 v77, v42, v42
	global_store_dwordx2 v[60:61], v[56:57], off offset:512
	v_cvt_pk_bf16_f32 v56, v40, v41
	v_add_f32_e32 v72, v72, v73
	v_add_f32_e32 v73, v74, v75
	v_fmac_f32_e32 v78, v44, v44
	v_fmac_f32_e32 v79, v46, v46
	v_cvt_pk_bf16_f32 v57, v42, v43
	v_add_f32_e32 v74, v76, v77
	global_store_dwordx2 v[60:61], v[56:57], off offset:1024
	v_cvt_pk_bf16_f32 v56, v44, v45
	v_add_f32_e32 v72, v72, v73
	v_add_f32_e32 v75, v78, v79
	v_cvt_pk_bf16_f32 v57, v46, v47
	global_store_dwordx2 v[60:61], v[56:57], off offset:1536
	v_add_f32_e32 v56, v72, v74
	v_add_f32_e32 v56, v56, v75
	s_nop 1
	v_add_f32_dpp v56, v56, v56 row_ror:8 row_mask:0xf bank_mask:0xf bound_ctrl:1
	s_nop 1
	v_add_f32_dpp v56, v56, v56 row_ror:4 row_mask:0xf bank_mask:0xf bound_ctrl:1
	s_nop 1
	v_add_f32_dpp v56, v56, v56 row_ror:2 row_mask:0xf bank_mask:0xf bound_ctrl:1
	s_nop 1
	v_add_f32_dpp v56, v56, v56 row_ror:1 row_mask:0xf bank_mask:0xf bound_ctrl:1
	v_mov_b32_e32 v57, v56
	s_nop 1
	v_permlane16_swap_b32_e32 v56, v57
	v_add_f32_e32 v56, v56, v57
	v_mov_b32_e32 v57, v56
	s_nop 1
	v_permlane32_swap_b32_e32 v56, v57
	v_add_f32_e32 v56, v56, v57
	v_fmamk_f32 v56, v56, 0x3a800000, v70
	v_mul_f32_e32 v57, 0x4f800000, v56
	v_cmp_gt_f32_e32 vcc, s33, v56
	s_nop 1
	v_cndmask_b32_e32 v56, v56, v57, vcc
	v_sqrt_f32_e32 v57, v56
	s_nop 0
	v_add_u32_e32 v60, -1, v57
	v_add_u32_e32 v61, 1, v57
	v_fma_f32 v72, -v60, v57, v56
	v_fma_f32 v73, -v61, v57, v56
	v_cmp_ge_f32_e64 s[2:3], 0, v72
	s_nop 1
	v_cndmask_b32_e64 v57, v57, v60, s[2:3]
	v_cmp_lt_f32_e64 s[2:3], 0, v73
	s_nop 1
	v_cndmask_b32_e64 v57, v57, v61, s[2:3]
	v_mul_f32_e32 v60, 0x37800000, v57
	v_cndmask_b32_e32 v57, v57, v60, vcc
	v_cmp_class_f32_e32 vcc, v56, v71
	s_nop 1
	v_cndmask_b32_e32 v56, v57, v56, vcc
	v_div_scale_f32 v57, s[2:3], v56, v56, 1.0
	v_rcp_f32_e32 v61, v57
	v_div_scale_f32 v60, vcc, 1.0, v56, 1.0
	v_fma_f32 v72, -v57, v61, 1.0
	v_fmac_f32_e32 v61, v72, v61
	v_mul_f32_e32 v72, v60, v61
	v_fma_f32 v73, -v57, v72, v60
	v_fmac_f32_e32 v72, v73, v61
	v_fma_f32 v57, -v57, v72, v60
	v_div_fmas_f32 v57, v57, v61, v72
	v_div_fixup_f32 v56, v57, v56, 1.0
	v_pk_mul_f32 v[32:33], v[32:33], v[56:57] op_sel_hi:[1,0]
	v_pk_mul_f32 v[34:35], v[34:35], v[56:57] op_sel_hi:[1,0]
	v_pk_fma_f32 v[32:33], v[8:9], v[32:33], v[0:1]
	v_pk_mul_f32 v[36:37], v[36:37], v[56:57] op_sel_hi:[1,0]
	v_pk_mul_f32 v[38:39], v[38:39], v[56:57] op_sel_hi:[1,0]
	v_pk_fma_f32 v[34:35], v[10:11], v[34:35], v[2:3]
	v_cvt_pk_bf16_f32 v32, v32, v33
	v_pk_mul_f32 v[40:41], v[40:41], v[56:57] op_sel_hi:[1,0]
	v_cvt_pk_bf16_f32 v33, v34, v35
	v_pk_mul_f32 v[42:43], v[42:43], v[56:57] op_sel_hi:[1,0]
	v_pk_fma_f32 v[38:39], v[14:15], v[38:39], v[6:7]
	v_pk_fma_f32 v[36:37], v[12:13], v[36:37], v[4:5]
	global_store_dwordx2 v[58:59], v[32:33], off
	v_cvt_pk_bf16_f32 v32, v36, v37
	v_cvt_pk_bf16_f32 v33, v38, v39
	v_pk_mul_f32 v[44:45], v[44:45], v[56:57] op_sel_hi:[1,0]
	v_pk_mul_f32 v[46:47], v[46:47], v[56:57] op_sel_hi:[1,0]
	v_pk_fma_f32 v[42:43], v[26:27], v[42:43], v[18:19]
	v_pk_fma_f32 v[40:41], v[24:25], v[40:41], v[16:17]
	global_store_dwordx2 v[58:59], v[32:33], off offset:512
	v_cvt_pk_bf16_f32 v32, v40, v41
	v_cvt_pk_bf16_f32 v33, v42, v43
	v_pk_fma_f32 v[46:47], v[30:31], v[46:47], v[22:23]
	v_pk_fma_f32 v[44:45], v[28:29], v[44:45], v[20:21]
	global_store_dwordx2 v[58:59], v[32:33], off offset:1024
	v_cvt_pk_bf16_f32 v32, v44, v45
	v_cvt_pk_bf16_f32 v33, v46, v47
	global_store_dwordx2 v[58:59], v[32:33], off offset:1536
	global_load_dwordx4 v[32:35], v66, s[24:25] nt
	s_nop 0
	global_load_dwordx4 v[36:39], v66, s[24:25] offset:1024 nt
	global_load_dwordx4 v[40:43], v66, s[24:25] offset:2048 nt
	global_load_dwordx4 v[44:47], v66, s[24:25] offset:3072 nt
	s_waitcnt vmcnt(3)
	v_cvt_pk_bf16_f32 v56, v32, v33
	v_mul_f32_e32 v58, v33, v33
	v_mul_f32_e32 v59, v35, v35
	s_waitcnt vmcnt(2)
	v_mul_f32_e32 v60, v37, v37
	v_mul_f32_e32 v61, v39, v39
	v_cvt_pk_bf16_f32 v57, v34, v35
	s_waitcnt vmcnt(1)
	v_mul_f32_e32 v72, v41, v41
	v_mul_f32_e32 v73, v43, v43
	global_store_dwordx2 v[64:65], v[56:57], off
	v_cvt_pk_bf16_f32 v56, v36, v37
	v_fmac_f32_e32 v58, v32, v32
	v_fmac_f32_e32 v59, v34, v34
	v_fmac_f32_e32 v60, v36, v36
	v_fmac_f32_e32 v61, v38, v38
	s_waitcnt vmcnt(1)
	v_mul_f32_e32 v74, v45, v45
	v_mul_f32_e32 v75, v47, v47
	v_cvt_pk_bf16_f32 v57, v38, v39
	v_fmac_f32_e32 v72, v40, v40
	v_fmac_f32_e32 v73, v42, v42
	global_store_dwordx2 v[64:65], v[56:57], off offset:512
	v_cvt_pk_bf16_f32 v56, v40, v41
	v_add_f32_e32 v58, v58, v59
	v_add_f32_e32 v59, v60, v61
	v_fmac_f32_e32 v74, v44, v44
	v_fmac_f32_e32 v75, v46, v46
	v_cvt_pk_bf16_f32 v57, v42, v43
	v_add_f32_e32 v60, v72, v73
	global_store_dwordx2 v[64:65], v[56:57], off offset:1024
	v_cvt_pk_bf16_f32 v56, v44, v45
	v_add_f32_e32 v58, v58, v59
	v_add_f32_e32 v61, v74, v75
	v_cvt_pk_bf16_f32 v57, v46, v47
	global_store_dwordx2 v[64:65], v[56:57], off offset:1536
	v_add_f32_e32 v56, v58, v60
	v_add_f32_e32 v56, v56, v61
	s_nop 1
	v_add_f32_dpp v56, v56, v56 row_ror:8 row_mask:0xf bank_mask:0xf bound_ctrl:1
	s_nop 1
	v_add_f32_dpp v56, v56, v56 row_ror:4 row_mask:0xf bank_mask:0xf bound_ctrl:1
	s_nop 1
	v_add_f32_dpp v56, v56, v56 row_ror:2 row_mask:0xf bank_mask:0xf bound_ctrl:1
	s_nop 1
	v_add_f32_dpp v56, v56, v56 row_ror:1 row_mask:0xf bank_mask:0xf bound_ctrl:1
	v_mov_b32_e32 v57, v56
	s_nop 1
	v_permlane16_swap_b32_e32 v56, v57
	v_add_f32_e32 v56, v56, v57
	v_mov_b32_e32 v57, v56
	s_nop 1
	v_permlane32_swap_b32_e32 v56, v57
	v_add_f32_e32 v56, v56, v57
	v_fmamk_f32 v56, v56, 0x3a800000, v70
	v_mul_f32_e32 v57, 0x4f800000, v56
	v_cmp_gt_f32_e32 vcc, s33, v56
	s_nop 1
	v_cndmask_b32_e32 v56, v56, v57, vcc
	v_sqrt_f32_e32 v57, v56
	s_nop 0
	v_add_u32_e32 v58, -1, v57
	v_add_u32_e32 v59, 1, v57
	v_fma_f32 v60, -v58, v57, v56
	v_fma_f32 v61, -v59, v57, v56
	v_cmp_ge_f32_e64 s[2:3], 0, v60
	s_nop 1
	v_cndmask_b32_e64 v57, v57, v58, s[2:3]
	v_cmp_lt_f32_e64 s[2:3], 0, v61
	s_nop 1
	v_cndmask_b32_e64 v57, v57, v59, s[2:3]
	v_mul_f32_e32 v58, 0x37800000, v57
	v_cndmask_b32_e32 v57, v57, v58, vcc
	v_cmp_class_f32_e32 vcc, v56, v71
	s_nop 1
	v_cndmask_b32_e32 v56, v57, v56, vcc
	v_div_scale_f32 v57, s[2:3], v56, v56, 1.0
	v_rcp_f32_e32 v59, v57
	v_div_scale_f32 v58, vcc, 1.0, v56, 1.0
	s_lshl_b64 s[2:3], s[26:27], 11
	v_fma_f32 v60, -v57, v59, 1.0
	v_fmac_f32_e32 v59, v60, v59
	v_mul_f32_e32 v60, v58, v59
	v_fma_f32 v61, -v57, v60, v58
	v_fmac_f32_e32 v60, v61, v59
	v_fma_f32 v57, -v57, v60, v58
	v_div_fmas_f32 v57, v57, v59, v60
	v_div_fixup_f32 v56, v57, v56, 1.0
	v_pk_mul_f32 v[32:33], v[32:33], v[56:57] op_sel_hi:[1,0]
	v_pk_mul_f32 v[34:35], v[34:35], v[56:57] op_sel_hi:[1,0]
	v_pk_fma_f32 v[32:33], v[8:9], v[32:33], v[0:1]
	v_pk_mul_f32 v[36:37], v[36:37], v[56:57] op_sel_hi:[1,0]
	v_pk_mul_f32 v[38:39], v[38:39], v[56:57] op_sel_hi:[1,0]
	v_pk_fma_f32 v[34:35], v[10:11], v[34:35], v[2:3]
	v_cvt_pk_bf16_f32 v32, v32, v33
	v_pk_mul_f32 v[40:41], v[40:41], v[56:57] op_sel_hi:[1,0]
	v_cvt_pk_bf16_f32 v33, v34, v35
	v_pk_mul_f32 v[42:43], v[42:43], v[56:57] op_sel_hi:[1,0]
	v_pk_fma_f32 v[38:39], v[14:15], v[38:39], v[6:7]
	v_pk_fma_f32 v[36:37], v[12:13], v[36:37], v[4:5]
	global_store_dwordx2 v[62:63], v[32:33], off
	v_cvt_pk_bf16_f32 v32, v36, v37
	v_cvt_pk_bf16_f32 v33, v38, v39
	v_pk_mul_f32 v[44:45], v[44:45], v[56:57] op_sel_hi:[1,0]
	v_pk_mul_f32 v[46:47], v[46:47], v[56:57] op_sel_hi:[1,0]
	v_pk_fma_f32 v[42:43], v[26:27], v[42:43], v[18:19]
	v_pk_fma_f32 v[40:41], v[24:25], v[40:41], v[16:17]
	global_store_dwordx2 v[62:63], v[32:33], off offset:512
	v_cvt_pk_bf16_f32 v32, v40, v41
	v_cvt_pk_bf16_f32 v33, v42, v43
	v_pk_fma_f32 v[46:47], v[30:31], v[46:47], v[22:23]
	v_pk_fma_f32 v[44:45], v[28:29], v[44:45], v[20:21]
	global_store_dwordx2 v[62:63], v[32:33], off offset:1024
	v_cvt_pk_bf16_f32 v32, v44, v45
	v_cvt_pk_bf16_f32 v33, v46, v47
	global_store_dwordx2 v[62:63], v[32:33], off offset:1536
	global_load_dwordx4 v[32:35], v66, s[28:29] nt
	s_nop 0
	global_load_dwordx4 v[36:39], v66, s[28:29] offset:1024 nt
	global_load_dwordx4 v[40:43], v66, s[28:29] offset:2048 nt
	global_load_dwordx4 v[44:47], v66, s[28:29] offset:3072 nt
	v_lshl_add_u64 v[56:57], v[48:49], 0, s[2:3]
	s_waitcnt vmcnt(3)
	v_cvt_pk_bf16_f32 v60, v32, v33
	v_mul_f32_e32 v62, v33, v33
	v_mul_f32_e32 v63, v35, v35
	s_waitcnt vmcnt(2)
	v_mul_f32_e32 v64, v37, v37
	v_mul_f32_e32 v65, v39, v39
	v_cvt_pk_bf16_f32 v61, v34, v35
	s_waitcnt vmcnt(1)
	v_mul_f32_e32 v72, v41, v41
	v_mul_f32_e32 v73, v43, v43
	v_fmac_f32_e32 v62, v32, v32
	v_fmac_f32_e32 v63, v34, v34
	v_fmac_f32_e32 v64, v36, v36
	v_fmac_f32_e32 v65, v38, v38
	s_waitcnt vmcnt(0)
	v_mul_f32_e32 v74, v45, v45
	v_mul_f32_e32 v75, v47, v47
	global_store_dwordx2 v[56:57], v[60:61], off
	v_cvt_pk_bf16_f32 v60, v36, v37
	v_cvt_pk_bf16_f32 v61, v38, v39
	v_fmac_f32_e32 v72, v40, v40
	v_fmac_f32_e32 v73, v42, v42
	v_add_f32_e32 v62, v62, v63
	v_add_f32_e32 v63, v64, v65
	v_fmac_f32_e32 v74, v44, v44
	v_fmac_f32_e32 v75, v46, v46
	global_store_dwordx2 v[56:57], v[60:61], off offset:512
	v_cvt_pk_bf16_f32 v60, v40, v41
	v_cvt_pk_bf16_f32 v61, v42, v43
	v_add_f32_e32 v64, v72, v73
	v_add_f32_e32 v62, v62, v63
	v_add_f32_e32 v65, v74, v75
	global_store_dwordx2 v[56:57], v[60:61], off offset:1024
	v_cvt_pk_bf16_f32 v60, v44, v45
	v_cvt_pk_bf16_f32 v61, v46, v47
	global_store_dwordx2 v[56:57], v[60:61], off offset:1536
	v_add_f32_e32 v56, v62, v64
	v_add_f32_e32 v56, v56, v65
	v_lshl_add_u64 v[58:59], v[50:51], 0, s[2:3]
	s_add_u32 s20, s20, 4
	v_add_f32_dpp v56, v56, v56 row_ror:8 row_mask:0xf bank_mask:0xf bound_ctrl:1
	s_addc_u32 s21, s21, 0
	s_cmp_eq_u32 s20, 8
	v_add_f32_dpp v56, v56, v56 row_ror:4 row_mask:0xf bank_mask:0xf bound_ctrl:1
	s_nop 1
	v_add_f32_dpp v56, v56, v56 row_ror:2 row_mask:0xf bank_mask:0xf bound_ctrl:1
	s_nop 1
	v_add_f32_dpp v56, v56, v56 row_ror:1 row_mask:0xf bank_mask:0xf bound_ctrl:1
	v_mov_b32_e32 v57, v56
	s_nop 1
	v_permlane16_swap_b32_e32 v56, v57
	v_add_f32_e32 v56, v56, v57
	v_mov_b32_e32 v57, v56
	s_nop 1
	v_permlane32_swap_b32_e32 v56, v57
	v_add_f32_e32 v56, v56, v57
	v_fmamk_f32 v56, v56, 0x3a800000, v70
	v_mul_f32_e32 v57, 0x4f800000, v56
	v_cmp_gt_f32_e32 vcc, s33, v56
	s_nop 1
	v_cndmask_b32_e32 v56, v56, v57, vcc
	v_sqrt_f32_e32 v57, v56
	s_nop 0
	v_add_u32_e32 v60, -1, v57
	v_add_u32_e32 v61, 1, v57
	v_fma_f32 v62, -v60, v57, v56
	v_fma_f32 v63, -v61, v57, v56
	v_cmp_ge_f32_e64 s[2:3], 0, v62
	s_nop 1
	v_cndmask_b32_e64 v57, v57, v60, s[2:3]
	v_cmp_lt_f32_e64 s[2:3], 0, v63
	s_nop 1
	v_cndmask_b32_e64 v57, v57, v61, s[2:3]
	v_mul_f32_e32 v60, 0x37800000, v57
	v_cndmask_b32_e32 v57, v57, v60, vcc
	v_cmp_class_f32_e32 vcc, v56, v71
	s_nop 1
	v_cndmask_b32_e32 v56, v57, v56, vcc
	v_div_scale_f32 v57, s[2:3], v56, v56, 1.0
	v_rcp_f32_e32 v61, v57
	v_div_scale_f32 v60, vcc, 1.0, v56, 1.0
	v_fma_f32 v62, -v57, v61, 1.0
	v_fmac_f32_e32 v61, v62, v61
	v_mul_f32_e32 v62, v60, v61
	v_fma_f32 v63, -v57, v62, v60
	v_fmac_f32_e32 v62, v63, v61
	v_fma_f32 v57, -v57, v62, v60
	v_div_fmas_f32 v57, v57, v61, v62
	v_div_fixup_f32 v56, v57, v56, 1.0
	v_pk_mul_f32 v[32:33], v[32:33], v[56:57] op_sel_hi:[1,0]
	v_pk_mul_f32 v[34:35], v[34:35], v[56:57] op_sel_hi:[1,0]
	v_pk_fma_f32 v[32:33], v[8:9], v[32:33], v[0:1]
	v_pk_mul_f32 v[36:37], v[36:37], v[56:57] op_sel_hi:[1,0]
	v_pk_mul_f32 v[38:39], v[38:39], v[56:57] op_sel_hi:[1,0]
	v_pk_fma_f32 v[34:35], v[10:11], v[34:35], v[2:3]
	v_cvt_pk_bf16_f32 v32, v32, v33
	v_pk_mul_f32 v[40:41], v[40:41], v[56:57] op_sel_hi:[1,0]
	v_cvt_pk_bf16_f32 v33, v34, v35
	v_pk_mul_f32 v[42:43], v[42:43], v[56:57] op_sel_hi:[1,0]
	v_pk_fma_f32 v[38:39], v[14:15], v[38:39], v[6:7]
	v_pk_fma_f32 v[36:37], v[12:13], v[36:37], v[4:5]
	global_store_dwordx2 v[58:59], v[32:33], off
	v_cvt_pk_bf16_f32 v32, v36, v37
	v_cvt_pk_bf16_f32 v33, v38, v39
	v_pk_mul_f32 v[44:45], v[44:45], v[56:57] op_sel_hi:[1,0]
	v_pk_mul_f32 v[46:47], v[46:47], v[56:57] op_sel_hi:[1,0]
	v_pk_fma_f32 v[42:43], v[26:27], v[42:43], v[18:19]
	v_pk_fma_f32 v[40:41], v[24:25], v[40:41], v[16:17]
	global_store_dwordx2 v[58:59], v[32:33], off offset:512
	v_cvt_pk_bf16_f32 v32, v40, v41
	v_cvt_pk_bf16_f32 v33, v42, v43
	v_pk_fma_f32 v[46:47], v[30:31], v[46:47], v[22:23]
	v_pk_fma_f32 v[44:45], v[28:29], v[44:45], v[20:21]
	global_store_dwordx2 v[58:59], v[32:33], off offset:1024
	v_cvt_pk_bf16_f32 v32, v44, v45
	v_cvt_pk_bf16_f32 v33, v46, v47
	global_store_dwordx2 v[58:59], v[32:33], off offset:1536
	s_cbranch_scc0 .LBB0_110
	s_add_u32 s12, s12, s14
	s_addc_u32 s13, s13, s15
	s_cmpk_gt_i32 s12, 0x3fff
	v_lshl_add_u64 v[52:53], v[52:53], 0, s[16:17]
	s_cbranch_scc0 .LBB0_109

.LBB0_294:
	s_add_i32 s5, s4, -1
	s_cmp_lt_u32 s5, s23
	s_cselect_b64 vcc, -1, 0
	v_lshl_add_u64 v[8:9], s[2:3], 0, v[96:97]
	s_and_b64 s[2:3], vcc, exec
	s_cselect_b32 s2, s5, s4
	s_ashr_i32 s3, s2, 31
	s_lshl_b64 s[16:17], s[2:3], 11
	v_lshl_add_u64 v[4:5], v[8:9], 0, s[16:17]
	global_load_dwordx2 v[4:5], v[4:5], off nt
	s_add_i32 s2, s2, s14
	s_ashr_i32 s3, s2, 31
	s_lshl_b64 s[2:3], s[2:3], 2
	s_add_u32 s2, s26, s2
	s_addc_u32 s3, s27, s3
	s_cmp_lt_u32 s4, s23
	s_waitcnt vmcnt(0)
	v_cndmask_b32_e32 v102, 0, v4, vcc
	v_cndmask_b32_e32 v5, 0, v5, vcc
	s_cselect_b64 vcc, -1, 0
	s_ashr_i32 s5, s4, 31
	global_load_dword v4, v97, s[2:3]
	s_lshl_b64 s[2:3], s[4:5], 11
	v_lshl_add_u64 v[6:7], v[8:9], 0, s[2:3]
	global_load_dwordx2 v[6:7], v[6:7], off nt
	s_ashr_i32 s7, s6, 31
	s_lshl_b64 s[2:3], s[6:7], 2
	s_add_u32 s2, s26, s2
	s_addc_u32 s3, s27, s3
	s_or_b32 s86, s4, 1
	s_cmp_lt_u32 s86, s23
	global_load_dword v70, v97, s[2:3]
	s_cselect_b64 s[2:3], -1, 0
	s_and_b64 s[16:17], s[2:3], exec
	s_cselect_b32 s16, s86, s4
	s_ashr_i32 s17, s16, 31
	s_lshl_b64 s[18:19], s[16:17], 11
	s_add_i32 s16, s16, s14
	s_ashr_i32 s17, s16, 31
	s_lshl_b64 s[16:17], s[16:17], 2
	s_add_u32 s16, s26, s16
	s_addc_u32 s17, s27, s17
	s_or_b32 s85, s4, 2
	s_cmp_lt_u32 s85, s23
	v_lshlrev_b32_e32 v106, 16, v102
	v_and_b32_e32 v107, 0xffff0000, v102
	v_lshlrev_b32_e32 v108, 16, v5
	v_and_b32_e32 v109, 0xffff0000, v5
	global_load_dword v68, v97, s[16:17]
	s_waitcnt vmcnt(3)
	v_pk_mul_f32 v[110:111], v[4:5], v[108:109] op_sel_hi:[0,1]
	v_pk_mul_f32 v[112:113], v[4:5], v[106:107] op_sel_hi:[0,1]
	v_pk_fma_f32 v[106:107], v[4:5], v[106:107], 0 op_sel_hi:[0,1,0]
	s_waitcnt vmcnt(2)
	v_cndmask_b32_e32 v104, 0, v6, vcc
	v_cndmask_b32_e32 v103, 0, v7, vcc
	v_lshl_add_u64 v[6:7], v[8:9], 0, s[18:19]
	s_cselect_b64 vcc, -1, 0
	global_load_dwordx2 v[66:67], v[6:7], off nt
	s_and_b64 s[16:17], vcc, exec
	s_cselect_b32 s16, s85, s4
	s_ashr_i32 s17, s16, 31
	s_lshl_b64 s[18:19], s[16:17], 11
	v_lshl_add_u64 v[6:7], v[8:9], 0, s[18:19]
	global_load_dwordx2 v[6:7], v[6:7], off nt
	s_add_i32 s16, s16, s14
	s_ashr_i32 s17, s16, 31
	s_lshl_b64 s[16:17], s[16:17], 2
	s_add_u32 s16, s26, s16
	s_addc_u32 s17, s27, s17
	s_or_b32 s84, s4, 3
	s_cmp_lt_u32 s84, s23
	global_load_dword v64, v97, s[16:17]
	v_pk_fma_f32 v[4:5], v[4:5], v[108:109], 0 op_sel_hi:[0,1,0]
	v_lshlrev_b32_e32 v108, 16, v104
	v_and_b32_e32 v109, 0xffff0000, v104
	v_lshlrev_b32_e32 v102, 16, v103
	v_and_b32_e32 v103, 0xffff0000, v103
	s_waitcnt vmcnt(1)
	v_cndmask_b32_e32 v101, 0, v6, vcc
	v_cndmask_b32_e32 v65, 0, v7, vcc
	s_cselect_b64 vcc, -1, 0
	s_and_b64 s[16:17], vcc, exec
	s_cselect_b32 s16, s84, s4
	s_ashr_i32 s17, s16, 31
	s_lshl_b64 s[18:19], s[16:17], 11
	v_lshl_add_u64 v[6:7], v[8:9], 0, s[18:19]
	global_load_dwordx2 v[6:7], v[6:7], off nt
	s_add_i32 s16, s16, s14
	s_ashr_i32 s17, s16, 31
	s_lshl_b64 s[16:17], s[16:17], 2
	s_add_u32 s16, s26, s16
	s_addc_u32 s17, s27, s17
	s_or_b32 s83, s4, 4
	s_cmp_lt_u32 s83, s23
	global_load_dword v62, v97, s[16:17]
	s_waitcnt vmcnt(1)
	v_cndmask_b32_e32 v100, 0, v6, vcc
	v_cndmask_b32_e32 v99, 0, v7, vcc
	s_cselect_b64 vcc, -1, 0
	s_and_b64 s[16:17], vcc, exec
	s_cselect_b32 s16, s83, s4
	s_ashr_i32 s17, s16, 31
	s_lshl_b64 s[18:19], s[16:17], 11
	v_lshl_add_u64 v[6:7], v[8:9], 0, s[18:19]
	global_load_dwordx2 v[6:7], v[6:7], off nt
	s_add_i32 s16, s16, s14
	s_ashr_i32 s17, s16, 31
	s_lshl_b64 s[16:17], s[16:17], 2
	s_add_u32 s16, s26, s16
	s_addc_u32 s17, s27, s17
	s_or_b32 s82, s4, 5
	s_cmp_lt_u32 s82, s23
	global_load_dword v60, v97, s[16:17]
	s_waitcnt vmcnt(1)
	v_cndmask_b32_e32 v98, 0, v6, vcc
	v_cndmask_b32_e32 v95, 0, v7, vcc
	s_cselect_b64 vcc, -1, 0
	s_and_b64 s[16:17], vcc, exec
	s_cselect_b32 s16, s82, s4
	s_ashr_i32 s17, s16, 31
	s_lshl_b64 s[18:19], s[16:17], 11
	v_lshl_add_u64 v[6:7], v[8:9], 0, s[18:19]
	global_load_dwordx2 v[6:7], v[6:7], off nt
	s_add_i32 s16, s16, s14
	s_ashr_i32 s17, s16, 31
	s_lshl_b64 s[16:17], s[16:17], 2
	s_add_u32 s16, s26, s16
	s_addc_u32 s17, s27, s17
	s_or_b32 s81, s4, 6
	s_cmp_lt_u32 s81, s23
	global_load_dword v58, v97, s[16:17]
	s_waitcnt vmcnt(1)
	v_cndmask_b32_e32 v94, 0, v6, vcc
	v_cndmask_b32_e32 v93, 0, v7, vcc
	s_cselect_b64 vcc, -1, 0
	s_and_b64 s[16:17], vcc, exec
	s_cselect_b32 s16, s81, s4
	s_ashr_i32 s17, s16, 31
	s_lshl_b64 s[18:19], s[16:17], 11
	v_lshl_add_u64 v[6:7], v[8:9], 0, s[18:19]
	global_load_dwordx2 v[6:7], v[6:7], off nt
	s_add_i32 s16, s16, s14
	s_ashr_i32 s17, s16, 31
	s_lshl_b64 s[16:17], s[16:17], 2
	s_add_u32 s16, s26, s16
	s_addc_u32 s17, s27, s17
	s_or_b32 s80, s4, 7
	s_cmp_lt_u32 s80, s23
	global_load_dword v56, v97, s[16:17]
	s_waitcnt vmcnt(1)
	v_cndmask_b32_e32 v92, 0, v6, vcc
	v_cndmask_b32_e32 v57, 0, v7, vcc
	s_cselect_b64 vcc, -1, 0
	s_and_b64 s[16:17], vcc, exec
	s_cselect_b32 s16, s80, s4
	s_ashr_i32 s17, s16, 31
	s_lshl_b64 s[18:19], s[16:17], 11
	v_lshl_add_u64 v[6:7], v[8:9], 0, s[18:19]
	global_load_dwordx2 v[6:7], v[6:7], off nt
	s_add_i32 s16, s16, s14
	s_ashr_i32 s17, s16, 31
	s_lshl_b64 s[16:17], s[16:17], 2
	s_add_u32 s16, s26, s16
	s_addc_u32 s17, s27, s17
	s_or_b32 s79, s4, 8
	s_cmp_lt_u32 s79, s23
	global_load_dword v54, v97, s[16:17]
	s_waitcnt vmcnt(1)
	v_cndmask_b32_e32 v91, 0, v6, vcc
	v_cndmask_b32_e32 v90, 0, v7, vcc
	s_cselect_b64 vcc, -1, 0
	s_and_b64 s[16:17], vcc, exec
	s_cselect_b32 s16, s79, s4
	s_ashr_i32 s17, s16, 31
	s_lshl_b64 s[18:19], s[16:17], 11
	v_lshl_add_u64 v[6:7], v[8:9], 0, s[18:19]
	global_load_dwordx2 v[6:7], v[6:7], off nt
	s_add_i32 s16, s16, s14
	s_ashr_i32 s17, s16, 31
	s_lshl_b64 s[16:17], s[16:17], 2
	s_add_u32 s16, s26, s16
	s_addc_u32 s17, s27, s17
	s_or_b32 s78, s4, 9
	s_cmp_lt_u32 s78, s23
	global_load_dword v52, v97, s[16:17]
	s_waitcnt vmcnt(1)
	v_cndmask_b32_e32 v89, 0, v6, vcc
	v_cndmask_b32_e32 v88, 0, v7, vcc
	s_cselect_b64 vcc, -1, 0
	s_and_b64 s[16:17], vcc, exec
	s_cselect_b32 s16, s78, s4
	s_ashr_i32 s17, s16, 31
	s_lshl_b64 s[18:19], s[16:17], 11
	v_lshl_add_u64 v[6:7], v[8:9], 0, s[18:19]
	global_load_dwordx2 v[6:7], v[6:7], off nt
	s_add_i32 s16, s16, s14
	s_ashr_i32 s17, s16, 31
	s_lshl_b64 s[16:17], s[16:17], 2
	s_add_u32 s16, s26, s16
	s_addc_u32 s17, s27, s17
	s_or_b32 s77, s4, 10
	s_cmp_lt_u32 s77, s23
	global_load_dword v50, v97, s[16:17]
	s_waitcnt vmcnt(1)
	v_cndmask_b32_e32 v87, 0, v6, vcc
	v_cndmask_b32_e32 v86, 0, v7, vcc
	s_cselect_b64 vcc, -1, 0
	s_and_b64 s[16:17], vcc, exec
	s_cselect_b32 s16, s77, s4
	s_ashr_i32 s17, s16, 31
	s_lshl_b64 s[18:19], s[16:17], 11
	v_lshl_add_u64 v[6:7], v[8:9], 0, s[18:19]
	global_load_dwordx2 v[6:7], v[6:7], off nt
	s_add_i32 s16, s16, s14
	s_ashr_i32 s17, s16, 31
	s_lshl_b64 s[16:17], s[16:17], 2
	s_add_u32 s16, s26, s16
	s_addc_u32 s17, s27, s17
	s_or_b32 s76, s4, 11
	s_cmp_lt_u32 s76, s23
	global_load_dword v48, v97, s[16:17]
	s_waitcnt vmcnt(1)
	v_cndmask_b32_e32 v85, 0, v6, vcc
	v_cndmask_b32_e32 v49, 0, v7, vcc
	s_cselect_b64 vcc, -1, 0
	s_and_b64 s[16:17], vcc, exec
	s_cselect_b32 s16, s76, s4
	s_ashr_i32 s17, s16, 31
	s_lshl_b64 s[18:19], s[16:17], 11
	v_lshl_add_u64 v[6:7], v[8:9], 0, s[18:19]
	global_load_dwordx2 v[6:7], v[6:7], off nt
	s_add_i32 s16, s16, s14
	s_ashr_i32 s17, s16, 31
	s_lshl_b64 s[16:17], s[16:17], 2
	s_add_u32 s16, s26, s16
	s_addc_u32 s17, s27, s17
	s_or_b32 s74, s4, 12
	s_cmp_lt_u32 s74, s23
	global_load_dword v44, v97, s[16:17]
	s_waitcnt vmcnt(1)
	v_cndmask_b32_e32 v84, 0, v6, vcc
	v_cndmask_b32_e32 v83, 0, v7, vcc
	s_cselect_b64 vcc, -1, 0
	s_and_b64 s[16:17], vcc, exec
	s_cselect_b32 s16, s74, s4
	s_ashr_i32 s17, s16, 31
	s_lshl_b64 s[18:19], s[16:17], 11
	v_lshl_add_u64 v[6:7], v[8:9], 0, s[18:19]
	global_load_dwordx2 v[6:7], v[6:7], off nt
	s_add_i32 s16, s16, s14
	s_ashr_i32 s17, s16, 31
	s_lshl_b64 s[16:17], s[16:17], 2
	s_add_u32 s16, s26, s16
	s_addc_u32 s17, s27, s17
	s_or_b32 s35, s4, 13
	s_cmp_lt_u32 s35, s23
	global_load_dword v38, v97, s[16:17]
	s_waitcnt vmcnt(1)
	v_cndmask_b32_e32 v80, 0, v6, vcc
	v_cndmask_b32_e32 v79, 0, v7, vcc
	s_cselect_b64 vcc, -1, 0
	s_and_b64 s[16:17], vcc, exec
	s_cselect_b32 s16, s35, s4
	s_ashr_i32 s17, s16, 31
	s_lshl_b64 s[18:19], s[16:17], 11
	v_lshl_add_u64 v[6:7], v[8:9], 0, s[18:19]
	global_load_dwordx2 v[6:7], v[6:7], off nt
	s_add_i32 s16, s16, s14
	s_ashr_i32 s17, s16, 31
	s_lshl_b64 s[16:17], s[16:17], 2
	s_add_u32 s16, s26, s16
	s_addc_u32 s17, s27, s17
	s_or_b32 s75, s4, 14
	s_cmp_lt_u32 s75, s23
	global_load_dword v46, v97, s[16:17]
	s_waitcnt vmcnt(1)
	v_cndmask_b32_e32 v76, 0, v6, vcc
	v_cndmask_b32_e32 v39, 0, v7, vcc
	s_cselect_b64 vcc, -1, 0
	s_and_b64 s[16:17], vcc, exec
	s_cselect_b32 s16, s75, s4
	s_ashr_i32 s17, s16, 31
	s_lshl_b64 s[18:19], s[16:17], 11
	v_lshl_add_u64 v[6:7], v[8:9], 0, s[18:19]
	global_load_dwordx2 v[6:7], v[6:7], off nt
	s_add_i32 s16, s16, s14
	s_ashr_i32 s17, s16, 31
	s_lshl_b64 s[16:17], s[16:17], 2
	s_add_u32 s16, s26, s16
	s_addc_u32 s17, s27, s17
	s_or_b32 s73, s4, 15
	s_cmp_lt_u32 s73, s23
	global_load_dword v42, v97, s[16:17]
	s_waitcnt vmcnt(1)
	v_cndmask_b32_e32 v82, 0, v6, vcc
	v_cndmask_b32_e32 v81, 0, v7, vcc
	s_cselect_b64 vcc, -1, 0
	s_and_b64 s[16:17], vcc, exec
	s_cselect_b32 s16, s73, s4
	s_ashr_i32 s17, s16, 31
	s_lshl_b64 s[18:19], s[16:17], 11
	v_lshl_add_u64 v[6:7], v[8:9], 0, s[18:19]
	global_load_dwordx2 v[6:7], v[6:7], off nt
	s_add_i32 s16, s16, s14
	s_ashr_i32 s17, s16, 31
	s_lshl_b64 s[16:17], s[16:17], 2
	s_add_u32 s16, s26, s16
	s_addc_u32 s17, s27, s17
	s_or_b32 s72, s4, 16
	s_cmp_lt_u32 s72, s23
	global_load_dword v40, v97, s[16:17]
	s_waitcnt vmcnt(1)
	v_cndmask_b32_e32 v78, 0, v6, vcc
	v_cndmask_b32_e32 v77, 0, v7, vcc
	s_cselect_b64 vcc, -1, 0
	s_and_b64 s[16:17], vcc, exec
	s_cselect_b32 s16, s72, s4
	s_ashr_i32 s17, s16, 31
	s_lshl_b64 s[18:19], s[16:17], 11
	v_lshl_add_u64 v[6:7], v[8:9], 0, s[18:19]
	global_load_dwordx2 v[6:7], v[6:7], off nt
	s_add_i32 s16, s16, s14
	s_ashr_i32 s17, s16, 31
	s_lshl_b64 s[16:17], s[16:17], 2
	s_add_u32 s16, s26, s16
	s_addc_u32 s17, s27, s17
	s_or_b32 s71, s4, 17
	s_cmp_lt_u32 s71, s23
	global_load_dword v36, v97, s[16:17]
	s_waitcnt vmcnt(1)
	v_cndmask_b32_e32 v75, 0, v6, vcc
	v_cndmask_b32_e32 v74, 0, v7, vcc
	s_cselect_b64 vcc, -1, 0
	s_and_b64 s[16:17], vcc, exec
	s_cselect_b32 s16, s71, s4
	s_ashr_i32 s17, s16, 31
	s_lshl_b64 s[18:19], s[16:17], 11
	v_lshl_add_u64 v[6:7], v[8:9], 0, s[18:19]
	global_load_dwordx2 v[6:7], v[6:7], off nt
	s_add_i32 s16, s16, s14
	s_ashr_i32 s17, s16, 31
	s_lshl_b64 s[16:17], s[16:17], 2
	s_add_u32 s16, s26, s16
	s_addc_u32 s17, s27, s17
	s_or_b32 s70, s4, 18
	s_cmp_lt_u32 s70, s23
	global_load_dword v34, v97, s[16:17]
	s_waitcnt vmcnt(1)
	v_cndmask_b32_e32 v73, 0, v6, vcc
	v_cndmask_b32_e32 v72, 0, v7, vcc
	s_cselect_b64 vcc, -1, 0
	s_and_b64 s[16:17], vcc, exec
	s_cselect_b32 s16, s70, s4
	s_ashr_i32 s17, s16, 31
	s_lshl_b64 s[18:19], s[16:17], 11
	v_lshl_add_u64 v[6:7], v[8:9], 0, s[18:19]
	global_load_dwordx2 v[6:7], v[6:7], off nt
	s_add_i32 s16, s16, s14
	s_ashr_i32 s17, s16, 31
	s_lshl_b64 s[16:17], s[16:17], 2
	s_add_u32 s16, s26, s16
	s_addc_u32 s17, s27, s17
	s_or_b32 s69, s4, 19
	s_cmp_lt_u32 s69, s23
	global_load_dword v32, v97, s[16:17]
	s_waitcnt vmcnt(1)
	v_cndmask_b32_e32 v71, 0, v6, vcc
	v_cndmask_b32_e32 v33, 0, v7, vcc
	s_cselect_b64 vcc, -1, 0
	s_and_b64 s[16:17], vcc, exec
	s_cselect_b32 s16, s69, s4
	s_ashr_i32 s17, s16, 31
	s_lshl_b64 s[18:19], s[16:17], 11
	v_lshl_add_u64 v[6:7], v[8:9], 0, s[18:19]
	global_load_dwordx2 v[6:7], v[6:7], off nt
	s_add_i32 s16, s16, s14
	s_ashr_i32 s17, s16, 31
	s_lshl_b64 s[16:17], s[16:17], 2
	s_add_u32 s16, s26, s16
	s_addc_u32 s17, s27, s17
	s_or_b32 s68, s4, 20
	s_cmp_lt_u32 s68, s23
	global_load_dword v30, v97, s[16:17]
	v_pk_mul_f32 v[104:105], v[70:71], v[102:103] op_sel_hi:[0,1]
	v_pk_mul_f32 v[114:115], v[70:71], v[108:109] op_sel_hi:[0,1]
	v_pk_fma_f32 v[102:103], v[70:71], v[102:103], v[4:5] op_sel_hi:[0,1,1]
	v_pk_fma_f32 v[106:107], v[70:71], v[108:109], v[106:107] op_sel_hi:[0,1,1]
	s_waitcnt vmcnt(1)
	v_cndmask_b32_e32 v69, 0, v6, vcc
	v_cndmask_b32_e32 v63, 0, v7, vcc
	s_cselect_b64 vcc, -1, 0
	s_and_b64 s[16:17], vcc, exec
	s_cselect_b32 s16, s68, s4
	s_ashr_i32 s17, s16, 31
	s_lshl_b64 s[18:19], s[16:17], 11
	v_lshl_add_u64 v[6:7], v[8:9], 0, s[18:19]
	global_load_dwordx2 v[6:7], v[6:7], off nt
	s_add_i32 s16, s16, s14
	s_ashr_i32 s17, s16, 31
	s_lshl_b64 s[16:17], s[16:17], 2
	s_add_u32 s16, s26, s16
	s_addc_u32 s17, s27, s17
	s_or_b32 s67, s4, 21
	s_cmp_lt_u32 s67, s23
	global_load_dword v28, v97, s[16:17]
	s_waitcnt vmcnt(1)
	v_cndmask_b32_e32 v61, 0, v6, vcc
	v_cndmask_b32_e32 v59, 0, v7, vcc
	s_cselect_b64 vcc, -1, 0
	s_and_b64 s[16:17], vcc, exec
	s_cselect_b32 s16, s67, s4
	s_ashr_i32 s17, s16, 31
	s_lshl_b64 s[18:19], s[16:17], 11
	v_lshl_add_u64 v[6:7], v[8:9], 0, s[18:19]
	global_load_dwordx2 v[6:7], v[6:7], off nt
	s_add_i32 s16, s16, s14
	s_ashr_i32 s17, s16, 31
	s_lshl_b64 s[16:17], s[16:17], 2
	s_add_u32 s16, s26, s16
	s_addc_u32 s17, s27, s17
	s_or_b32 s66, s4, 22
	s_cmp_lt_u32 s66, s23
	global_load_dword v26, v97, s[16:17]
	s_waitcnt vmcnt(1)
	v_cndmask_b32_e32 v55, 0, v6, vcc
	v_cndmask_b32_e32 v53, 0, v7, vcc
	s_cselect_b64 vcc, -1, 0
	s_and_b64 s[16:17], vcc, exec
	s_cselect_b32 s16, s66, s4
	s_ashr_i32 s17, s16, 31
	s_lshl_b64 s[18:19], s[16:17], 11
	v_lshl_add_u64 v[6:7], v[8:9], 0, s[18:19]
	global_load_dwordx2 v[6:7], v[6:7], off nt
	s_add_i32 s16, s16, s14
	s_ashr_i32 s17, s16, 31
	s_lshl_b64 s[16:17], s[16:17], 2
	s_add_u32 s16, s26, s16
	s_addc_u32 s17, s27, s17
	s_or_b32 s34, s4, 23
	s_cmp_lt_u32 s34, s23
	global_load_dword v20, v97, s[16:17]
	s_waitcnt vmcnt(1)
	v_cndmask_b32_e32 v51, 0, v6, vcc
	v_cndmask_b32_e32 v21, 0, v7, vcc
	s_cselect_b64 vcc, -1, 0
	s_and_b64 s[16:17], vcc, exec
	s_cselect_b32 s16, s34, s4
	s_ashr_i32 s17, s16, 31
	s_lshl_b64 s[18:19], s[16:17], 11
	v_lshl_add_u64 v[6:7], v[8:9], 0, s[18:19]
	global_load_dwordx2 v[6:7], v[6:7], off nt
	s_add_i32 s16, s16, s14
	s_ashr_i32 s17, s16, 31
	s_lshl_b64 s[16:17], s[16:17], 2
	s_add_u32 s16, s26, s16
	s_addc_u32 s17, s27, s17
	s_or_b32 s63, s4, 24
	s_cmp_lt_u32 s63, s23
	global_load_dword v24, v97, s[16:17]
	s_waitcnt vmcnt(1)
	v_cndmask_b32_e32 v37, 0, v6, vcc
	v_cndmask_b32_e32 v35, 0, v7, vcc
	s_cselect_b64 vcc, -1, 0
	s_and_b64 s[16:17], vcc, exec
	s_cselect_b32 s16, s63, s4
	s_ashr_i32 s17, s16, 31
	s_lshl_b64 s[18:19], s[16:17], 11
	v_lshl_add_u64 v[6:7], v[8:9], 0, s[18:19]
	global_load_dwordx2 v[6:7], v[6:7], off nt
	s_add_i32 s16, s16, s14
	s_ashr_i32 s17, s16, 31
	s_lshl_b64 s[16:17], s[16:17], 2
	s_add_u32 s16, s26, s16
	s_addc_u32 s17, s27, s17
	s_or_b32 s62, s4, 25
	s_cmp_lt_u32 s62, s23
	global_load_dword v22, v97, s[16:17]
	s_waitcnt vmcnt(1)
	v_cndmask_b32_e32 v47, 0, v6, vcc
	v_cndmask_b32_e32 v45, 0, v7, vcc
	s_cselect_b64 vcc, -1, 0
	s_and_b64 s[16:17], vcc, exec
	s_cselect_b32 s16, s62, s4
	s_ashr_i32 s17, s16, 31
	s_lshl_b64 s[18:19], s[16:17], 11
	v_lshl_add_u64 v[6:7], v[8:9], 0, s[18:19]
	global_load_dwordx2 v[6:7], v[6:7], off nt
	s_add_i32 s16, s16, s14
	s_ashr_i32 s17, s16, 31
	s_lshl_b64 s[16:17], s[16:17], 2
	s_add_u32 s16, s26, s16
	s_addc_u32 s17, s27, s17
	s_or_b32 s21, s4, 26
	s_cmp_lt_u32 s21, s23
	global_load_dword v18, v97, s[16:17]
	s_waitcnt vmcnt(1)
	v_cndmask_b32_e32 v43, 0, v6, vcc
	v_cndmask_b32_e32 v41, 0, v7, vcc
	s_cselect_b64 vcc, -1, 0
	s_and_b64 s[16:17], vcc, exec
	s_cselect_b32 s16, s21, s4
	s_ashr_i32 s17, s16, 31
	s_lshl_b64 s[18:19], s[16:17], 11
	v_lshl_add_u64 v[6:7], v[8:9], 0, s[18:19]
	global_load_dwordx2 v[6:7], v[6:7], off nt
	s_add_i32 s16, s16, s14
	s_ashr_i32 s17, s16, 31
	s_lshl_b64 s[16:17], s[16:17], 2
	s_add_u32 s16, s26, s16
	s_addc_u32 s17, s27, s17
	s_or_b32 s20, s4, 27
	s_cmp_lt_u32 s20, s23
	global_load_dword v16, v97, s[16:17]
	s_waitcnt vmcnt(1)
	v_cndmask_b32_e32 v31, 0, v6, vcc
	v_cndmask_b32_e32 v17, 0, v7, vcc
	s_cselect_b64 vcc, -1, 0
	s_and_b64 s[16:17], vcc, exec
	s_cselect_b32 s16, s20, s4
	s_ashr_i32 s17, s16, 31
	s_lshl_b64 s[18:19], s[16:17], 11
	v_lshl_add_u64 v[6:7], v[8:9], 0, s[18:19]
	global_load_dwordx2 v[6:7], v[6:7], off nt
	s_add_i32 s16, s16, s14
	s_ashr_i32 s17, s16, 31
	s_lshl_b64 s[16:17], s[16:17], 2
	s_add_u32 s16, s26, s16
	s_addc_u32 s17, s27, s17
	s_or_b32 s19, s4, 28
	s_cmp_lt_u32 s19, s23
	global_load_dword v14, v97, s[16:17]
	s_waitcnt vmcnt(1)
	v_cndmask_b32_e32 v29, 0, v6, vcc
	v_cndmask_b32_e32 v27, 0, v7, vcc
	s_cselect_b64 vcc, -1, 0
	s_and_b64 s[16:17], vcc, exec
	s_cselect_b32 s16, s19, s4
	s_ashr_i32 s17, s16, 31
	s_lshl_b64 s[88:89], s[16:17], 11
	v_lshl_add_u64 v[6:7], v[8:9], 0, s[88:89]
	global_load_dwordx2 v[6:7], v[6:7], off nt
	s_add_i32 s16, s16, s14
	s_ashr_i32 s17, s16, 31
	s_lshl_b64 s[16:17], s[16:17], 2
	s_add_u32 s16, s26, s16
	s_addc_u32 s17, s27, s17
	s_or_b32 s18, s4, 29
	s_cmp_lt_u32 s18, s23
	global_load_dword v12, v97, s[16:17]
	s_waitcnt vmcnt(1)
	v_cndmask_b32_e32 v25, 0, v6, vcc
	v_cndmask_b32_e32 v23, 0, v7, vcc
	s_cselect_b64 vcc, -1, 0
	s_and_b64 s[16:17], vcc, exec
	s_cselect_b32 s16, s18, s4
	s_ashr_i32 s17, s16, 31
	s_lshl_b64 s[88:89], s[16:17], 11
	v_lshl_add_u64 v[6:7], v[8:9], 0, s[88:89]
	global_load_dwordx2 v[6:7], v[6:7], off nt
	s_add_i32 s16, s16, s14
	s_ashr_i32 s17, s16, 31
	s_lshl_b64 s[16:17], s[16:17], 2
	s_add_u32 s16, s26, s16
	s_addc_u32 s17, s27, s17
	s_or_b32 s15, s4, 30
	s_cmp_lt_u32 s15, s23
	global_load_dword v10, v97, s[16:17]
	s_waitcnt vmcnt(1)
	v_cndmask_b32_e32 v15, 0, v6, vcc
	v_cndmask_b32_e32 v13, 0, v7, vcc
	s_cselect_b64 vcc, -1, 0
	s_and_b64 s[16:17], vcc, exec
	s_cselect_b32 s16, s15, s4
	s_ashr_i32 s17, s16, 31
	s_lshl_b64 s[88:89], s[16:17], 11
	v_lshl_add_u64 v[6:7], v[8:9], 0, s[88:89]
	global_load_dwordx2 v[6:7], v[6:7], off nt
	s_add_i32 s16, s16, s14
	s_ashr_i32 s17, s16, 31
	s_lshl_b64 s[16:17], s[16:17], 2
	s_add_u32 s16, s26, s16
	s_addc_u32 s17, s27, s17
	s_or_b32 s5, s4, 31
	s_cmp_lt_u32 s5, s23
	s_waitcnt vmcnt(0)
	v_cndmask_b32_e32 v11, 0, v6, vcc
	v_cndmask_b32_e32 v7, 0, v7, vcc
	s_cselect_b64 vcc, -1, 0
	global_load_dword v6, v97, s[16:17]
	s_and_b64 s[16:17], vcc, exec
	s_cselect_b32 s16, s5, s4
	s_ashr_i32 s17, s16, 31
	s_lshl_b64 s[88:89], s[16:17], 11
	v_lshl_add_u64 v[8:9], v[8:9], 0, s[88:89]
	global_load_dwordx2 v[8:9], v[8:9], off nt
	s_add_i32 s16, s16, s14
	s_ashr_i32 s17, s16, 31
	s_lshl_b64 s[16:17], s[16:17], 2
	s_add_u32 s16, s26, s16
	s_addc_u32 s17, s27, s17
	s_lshl_b64 s[6:7], s[6:7], 11
	s_add_u32 s6, s24, s6
	s_addc_u32 s7, s25, s7
	s_max_i32 s14, s4, 1
	v_lshl_add_u64 v[4:5], s[6:7], 0, v[96:97]
	s_waitcnt vmcnt(0)
	v_cndmask_b32_e32 v19, 0, v8, vcc
	global_load_dword v8, v97, s[16:17]
	s_min_i32 s16, s86, s23
	s_sub_i32 s14, s16, s14
	s_add_i32 s14, s14, 1
	v_cvt_f32_i32_e32 v70, s14
	v_cndmask_b32_e32 v9, 0, v9, vcc
	v_div_scale_f32 v108, s[16:17], v70, v70, 1.0
	v_rcp_f32_e32 v109, v108
	s_nop 0
	v_fma_f32 v116, -v108, v109, 1.0
	v_fmac_f32_e32 v109, v116, v109
	v_div_scale_f32 v116, vcc, 1.0, v70, 1.0
	v_mul_f32_e32 v117, v116, v109
	v_fma_f32 v118, -v108, v117, v116
	v_fmac_f32_e32 v117, v118, v109
	v_fma_f32 v108, -v108, v117, v116
	v_div_fmas_f32 v108, v108, v109, v117
	v_div_fixup_f32 v70, v108, v70, 1.0
	v_pk_fma_f32 v[108:109], v[70:71], v[106:107], v[114:115] op_sel_hi:[0,1,1] neg_lo:[0,0,1] neg_hi:[0,0,1]
	v_pk_fma_f32 v[116:117], v[70:71], v[102:103], v[104:105] op_sel_hi:[0,1,1] neg_lo:[0,0,1] neg_hi:[0,0,1]
	v_pk_mul_f32 v[108:109], v[0:1], v[108:109]
	v_cndmask_b32_e64 v70, 0, v67, s[2:3]
	v_cndmask_b32_e64 v67, 0, v66, s[2:3]
	s_max_i32 s2, s86, 1
	s_min_i32 s3, s85, s23
	v_pk_mul_f32 v[116:117], v[2:3], v[116:117]
	v_cvt_pk_bf16_f32 v108, v108, v109
	s_sub_i32 s2, s3, s2
	v_cvt_pk_bf16_f32 v109, v116, v117
	global_store_dwordx2 v96, v[108:109], s[6:7]
	v_lshlrev_b32_e32 v66, 16, v67
	v_and_b32_e32 v67, 0xffff0000, v67
	v_lshlrev_b32_e32 v108, 16, v70
	v_and_b32_e32 v109, 0xffff0000, v70
	s_add_i32 s2, s2, 1
	v_pk_mul_f32 v[116:117], v[68:69], v[108:109] op_sel_hi:[0,1]
	v_pk_mul_f32 v[118:119], v[68:69], v[66:67] op_sel_hi:[0,1]
	v_pk_fma_f32 v[66:67], v[68:69], v[66:67], v[112:113] op_sel_hi:[0,1,1] neg_lo:[0,0,1] neg_hi:[0,0,1]
	v_pk_fma_f32 v[108:109], v[68:69], v[108:109], v[110:111] op_sel_hi:[0,1,1] neg_lo:[0,0,1] neg_hi:[0,0,1]
	v_cvt_f32_i32_e32 v68, s2
	v_pk_add_f32 v[66:67], v[106:107], v[66:67]
	v_pk_add_f32 v[102:103], v[102:103], v[108:109]
	v_div_scale_f32 v70, s[2:3], v68, v68, 1.0
	v_rcp_f32_e32 v106, v70
	s_max_i32 s2, s85, 1
	s_min_i32 s3, s84, s23
	s_sub_i32 s2, s3, s2
	v_fma_f32 v107, -v70, v106, 1.0
	v_fmac_f32_e32 v106, v107, v106
	v_div_scale_f32 v107, vcc, 1.0, v68, 1.0
	v_mul_f32_e32 v108, v107, v106
	v_fma_f32 v109, -v70, v108, v107
	v_fmac_f32_e32 v108, v109, v106
	v_fma_f32 v70, -v70, v108, v107
	v_div_fmas_f32 v70, v70, v106, v108
	v_div_fixup_f32 v68, v70, v68, 1.0
	v_pk_fma_f32 v[106:107], v[68:69], v[66:67], v[118:119] op_sel_hi:[0,1,1] neg_lo:[0,0,1] neg_hi:[0,0,1]
	v_pk_fma_f32 v[108:109], v[68:69], v[102:103], v[116:117] op_sel_hi:[0,1,1] neg_lo:[0,0,1] neg_hi:[0,0,1]
	v_pk_mul_f32 v[106:107], v[0:1], v[106:107]
	v_pk_mul_f32 v[108:109], v[2:3], v[108:109]
	v_cvt_pk_bf16_f32 v106, v106, v107
	s_add_i32 s2, s2, 1
	v_cvt_pk_bf16_f32 v107, v108, v109
	global_store_dwordx2 v96, v[106:107], s[6:7] offset:2048
	v_lshlrev_b32_e32 v106, 16, v101
	v_and_b32_e32 v107, 0xffff0000, v101
	v_lshlrev_b32_e32 v108, 16, v65
	v_and_b32_e32 v109, 0xffff0000, v65
	v_pk_mul_f32 v[110:111], v[64:65], v[108:109] op_sel_hi:[0,1]
	v_pk_mul_f32 v[112:113], v[64:65], v[106:107] op_sel_hi:[0,1]
	v_pk_fma_f32 v[106:107], v[64:65], v[106:107], v[114:115] op_sel_hi:[0,1,1] neg_lo:[0,0,1] neg_hi:[0,0,1]
	v_pk_fma_f32 v[64:65], v[64:65], v[108:109], v[104:105] op_sel_hi:[0,1,1] neg_lo:[0,0,1] neg_hi:[0,0,1]
	v_pk_add_f32 v[102:103], v[102:103], v[64:65]
	v_cvt_f32_i32_e32 v64, s2
	v_pk_add_f32 v[66:67], v[66:67], v[106:107]
	v_div_scale_f32 v65, s[2:3], v64, v64, 1.0
	v_rcp_f32_e32 v68, v65
	s_max_i32 s2, s84, 1
	s_min_i32 s3, s83, s23
	s_sub_i32 s2, s3, s2
	v_fma_f32 v70, -v65, v68, 1.0
	v_fmac_f32_e32 v68, v70, v68
	v_div_scale_f32 v70, vcc, 1.0, v64, 1.0
	v_mul_f32_e32 v96, v70, v68
	v_fma_f32 v101, -v65, v96, v70
	v_fmac_f32_e32 v96, v101, v68
	v_fma_f32 v65, -v65, v96, v70
	v_div_fmas_f32 v65, v65, v68, v96
	v_div_fixup_f32 v64, v65, v64, 1.0
	v_pk_fma_f32 v[104:105], v[64:65], v[66:67], v[112:113] op_sel_hi:[0,1,1] neg_lo:[0,0,1] neg_hi:[0,0,1]
	v_pk_fma_f32 v[64:65], v[64:65], v[102:103], v[110:111] op_sel_hi:[0,1,1] neg_lo:[0,0,1] neg_hi:[0,0,1]
	v_add_co_u32_e32 v106, vcc, s92, v4
	v_pk_mul_f32 v[64:65], v[2:3], v[64:65]
	v_pk_mul_f32 v[104:105], v[0:1], v[104:105]
	v_addc_co_u32_e32 v107, vcc, 0, v5, vcc
	v_cvt_pk_bf16_f32 v104, v104, v105
	v_cvt_pk_bf16_f32 v105, v64, v65
	v_add_co_u32_e32 v64, vcc, s91, v4
	v_and_b32_e32 v101, 0xffff0000, v99
	s_nop 0
	v_addc_co_u32_e32 v65, vcc, 0, v5, vcc
	global_store_dwordx2 v[64:65], v[104:105], off offset:-4096
	v_lshlrev_b32_e32 v104, 16, v100
	v_and_b32_e32 v105, 0xffff0000, v100
	v_lshlrev_b32_e32 v100, 16, v99
	s_add_i32 s2, s2, 1
	v_pk_mul_f32 v[108:109], v[62:63], v[100:101] op_sel_hi:[0,1]
	v_pk_mul_f32 v[114:115], v[62:63], v[104:105] op_sel_hi:[0,1]
	v_pk_fma_f32 v[104:105], v[62:63], v[104:105], v[118:119] op_sel_hi:[0,1,1] neg_lo:[0,0,1] neg_hi:[0,0,1]
	v_pk_fma_f32 v[100:101], v[62:63], v[100:101], v[116:117] op_sel_hi:[0,1,1] neg_lo:[0,0,1] neg_hi:[0,0,1]
	v_cvt_f32_i32_e32 v62, s2
	v_pk_add_f32 v[100:101], v[102:103], v[100:101]
	v_pk_add_f32 v[66:67], v[66:67], v[104:105]
	v_div_scale_f32 v68, s[2:3], v62, v62, 1.0
	v_rcp_f32_e32 v70, v68
	s_max_i32 s2, s83, 1
	s_min_i32 s3, s82, s23
	s_sub_i32 s2, s3, s2
	v_fma_f32 v96, -v68, v70, 1.0
	v_fmac_f32_e32 v70, v96, v70
	v_div_scale_f32 v96, vcc, 1.0, v62, 1.0
	v_mul_f32_e32 v99, v96, v70
	v_fma_f32 v102, -v68, v99, v96
	v_fmac_f32_e32 v99, v102, v70
	v_fma_f32 v68, -v68, v99, v96
	v_div_fmas_f32 v68, v68, v70, v99
	v_div_fixup_f32 v62, v68, v62, 1.0
	v_pk_fma_f32 v[102:103], v[62:63], v[66:67], v[114:115] op_sel_hi:[0,1,1] neg_lo:[0,0,1] neg_hi:[0,0,1]
	v_pk_fma_f32 v[104:105], v[62:63], v[100:101], v[108:109] op_sel_hi:[0,1,1] neg_lo:[0,0,1] neg_hi:[0,0,1]
	v_pk_mul_f32 v[102:103], v[0:1], v[102:103]
	v_pk_mul_f32 v[104:105], v[2:3], v[104:105]
	v_cvt_pk_bf16_f32 v102, v102, v103
	v_and_b32_e32 v99, 0xffff0000, v95
	v_cvt_pk_bf16_f32 v103, v104, v105
	global_store_dwordx2 v[106:107], v[102:103], off offset:2048
	v_lshlrev_b32_e32 v102, 16, v98
	v_and_b32_e32 v103, 0xffff0000, v98
	v_lshlrev_b32_e32 v98, 16, v95
	s_add_i32 s2, s2, 1
	v_pk_mul_f32 v[104:105], v[60:61], v[98:99] op_sel_hi:[0,1]
	v_pk_mul_f32 v[106:107], v[60:61], v[102:103] op_sel_hi:[0,1]
	v_pk_fma_f32 v[102:103], v[60:61], v[102:103], v[112:113] op_sel_hi:[0,1,1] neg_lo:[0,0,1] neg_hi:[0,0,1]
	v_pk_fma_f32 v[98:99], v[60:61], v[98:99], v[110:111] op_sel_hi:[0,1,1] neg_lo:[0,0,1] neg_hi:[0,0,1]
	v_cvt_f32_i32_e32 v60, s2
	v_pk_add_f32 v[66:67], v[66:67], v[102:103]
	v_pk_add_f32 v[98:99], v[100:101], v[98:99]
	v_div_scale_f32 v62, s[2:3], v60, v60, 1.0
	v_rcp_f32_e32 v68, v62
	s_max_i32 s2, s82, 1
	s_min_i32 s3, s81, s23
	s_sub_i32 s2, s3, s2
	v_fma_f32 v70, -v62, v68, 1.0
	v_fmac_f32_e32 v68, v70, v68
	v_div_scale_f32 v70, vcc, 1.0, v60, 1.0
	v_mul_f32_e32 v95, v70, v68
	v_fma_f32 v96, -v62, v95, v70
	v_fmac_f32_e32 v95, v96, v68
	v_fma_f32 v62, -v62, v95, v70
	v_div_fmas_f32 v62, v62, v68, v95
	v_div_fixup_f32 v60, v62, v60, 1.0
	v_pk_fma_f32 v[100:101], v[60:61], v[66:67], v[106:107] op_sel_hi:[0,1,1] neg_lo:[0,0,1] neg_hi:[0,0,1]
	v_pk_fma_f32 v[102:103], v[60:61], v[98:99], v[104:105] op_sel_hi:[0,1,1] neg_lo:[0,0,1] neg_hi:[0,0,1]
	v_pk_mul_f32 v[100:101], v[0:1], v[100:101]
	v_pk_mul_f32 v[102:103], v[2:3], v[102:103]
	v_cvt_pk_bf16_f32 v100, v100, v101
	v_and_b32_e32 v95, 0xffff0000, v93
	v_cvt_pk_bf16_f32 v101, v102, v103
	global_store_dwordx2 v[64:65], v[100:101], off
	v_lshlrev_b32_e32 v100, 16, v94
	v_and_b32_e32 v101, 0xffff0000, v94
	v_lshlrev_b32_e32 v94, 16, v93
	s_add_i32 s2, s2, 1
	v_pk_mul_f32 v[102:103], v[58:59], v[94:95] op_sel_hi:[0,1]
	v_pk_mul_f32 v[110:111], v[58:59], v[100:101] op_sel_hi:[0,1]
	v_pk_fma_f32 v[100:101], v[58:59], v[100:101], v[114:115] op_sel_hi:[0,1,1] neg_lo:[0,0,1] neg_hi:[0,0,1]
	v_pk_fma_f32 v[94:95], v[58:59], v[94:95], v[108:109] op_sel_hi:[0,1,1] neg_lo:[0,0,1] neg_hi:[0,0,1]
	v_cvt_f32_i32_e32 v58, s2
	v_pk_add_f32 v[66:67], v[66:67], v[100:101]
	v_pk_add_f32 v[94:95], v[98:99], v[94:95]
	v_div_scale_f32 v60, s[2:3], v58, v58, 1.0
	v_rcp_f32_e32 v62, v60
	s_max_i32 s2, s81, 1
	s_min_i32 s3, s80, s23
	s_sub_i32 s2, s3, s2
	v_fma_f32 v68, -v60, v62, 1.0
	v_fmac_f32_e32 v62, v68, v62
	v_div_scale_f32 v68, vcc, 1.0, v58, 1.0
	v_mul_f32_e32 v70, v68, v62
	v_fma_f32 v93, -v60, v70, v68
	v_fmac_f32_e32 v70, v93, v62
	v_fma_f32 v60, -v60, v70, v68
	v_div_fmas_f32 v60, v60, v62, v70
	v_div_fixup_f32 v58, v60, v58, 1.0
	v_pk_fma_f32 v[98:99], v[58:59], v[66:67], v[110:111] op_sel_hi:[0,1,1] neg_lo:[0,0,1] neg_hi:[0,0,1]
	v_pk_fma_f32 v[100:101], v[58:59], v[94:95], v[102:103] op_sel_hi:[0,1,1] neg_lo:[0,0,1] neg_hi:[0,0,1]
	v_pk_mul_f32 v[98:99], v[0:1], v[98:99]
	v_pk_mul_f32 v[100:101], v[2:3], v[100:101]
	v_cvt_pk_bf16_f32 v98, v98, v99
	v_and_b32_e32 v93, 0xffff0000, v57
	v_cvt_pk_bf16_f32 v99, v100, v101
	global_store_dwordx2 v[64:65], v[98:99], off offset:2048
	v_lshlrev_b32_e32 v64, 16, v92
	v_and_b32_e32 v65, 0xffff0000, v92
	v_lshlrev_b32_e32 v92, 16, v57
	v_pk_mul_f32 v[98:99], v[56:57], v[92:93] op_sel_hi:[0,1]
	v_pk_mul_f32 v[100:101], v[56:57], v[64:65] op_sel_hi:[0,1]
	v_pk_fma_f32 v[64:65], v[56:57], v[64:65], v[106:107] op_sel_hi:[0,1,1] neg_lo:[0,0,1] neg_hi:[0,0,1]
	v_pk_fma_f32 v[56:57], v[56:57], v[92:93], v[104:105] op_sel_hi:[0,1,1] neg_lo:[0,0,1] neg_hi:[0,0,1]
	s_add_i32 s2, s2, 1
	v_pk_add_f32 v[92:93], v[94:95], v[56:57]
	v_cvt_f32_i32_e32 v56, s2
	v_pk_add_f32 v[64:65], v[66:67], v[64:65]
	v_lshlrev_b32_e32 v104, 16, v90
	v_and_b32_e32 v105, 0xffff0000, v90
	v_div_scale_f32 v57, s[2:3], v56, v56, 1.0
	v_rcp_f32_e32 v58, v57
	s_movk_i32 s2, 0x3000
	s_min_i32 s3, s79, s23
	v_pk_fma_f32 v[102:103], v[54:55], v[104:105], v[102:103] op_sel_hi:[0,1,1] neg_lo:[0,0,1] neg_hi:[0,0,1]
	v_fma_f32 v60, -v57, v58, 1.0
	v_fmac_f32_e32 v58, v60, v58
	v_div_scale_f32 v60, vcc, 1.0, v56, 1.0
	v_mul_f32_e32 v62, v60, v58
	v_fma_f32 v66, -v57, v62, v60
	v_fmac_f32_e32 v62, v66, v58
	v_fma_f32 v57, -v57, v62, v60
	v_div_fmas_f32 v57, v57, v58, v62
	v_div_fixup_f32 v56, v57, v56, 1.0
	v_pk_fma_f32 v[66:67], v[56:57], v[64:65], v[100:101] op_sel_hi:[0,1,1] neg_lo:[0,0,1] neg_hi:[0,0,1]
	v_pk_fma_f32 v[56:57], v[56:57], v[92:93], v[98:99] op_sel_hi:[0,1,1] neg_lo:[0,0,1] neg_hi:[0,0,1]
	v_add_co_u32_e32 v94, vcc, s2, v4
	v_pk_mul_f32 v[56:57], v[2:3], v[56:57]
	v_pk_mul_f32 v[66:67], v[0:1], v[66:67]
	v_addc_co_u32_e32 v95, vcc, 0, v5, vcc
	v_cvt_pk_bf16_f32 v66, v66, v67
	v_cvt_pk_bf16_f32 v67, v56, v57
	v_add_co_u32_e32 v56, vcc, s9, v4
	s_max_i32 s2, s80, 1
	s_nop 0
	v_addc_co_u32_e32 v57, vcc, 0, v5, vcc
	s_sub_i32 s2, s3, s2
	global_store_dwordx2 v[56:57], v[66:67], off offset:-4096
	v_lshlrev_b32_e32 v66, 16, v91
	v_and_b32_e32 v67, 0xffff0000, v91
	s_add_i32 s2, s2, 1
	v_pk_mul_f32 v[90:91], v[54:55], v[104:105] op_sel_hi:[0,1]
	v_pk_mul_f32 v[106:107], v[54:55], v[66:67] op_sel_hi:[0,1]
	v_pk_fma_f32 v[66:67], v[54:55], v[66:67], v[110:111] op_sel_hi:[0,1,1] neg_lo:[0,0,1] neg_hi:[0,0,1]
	v_cvt_f32_i32_e32 v54, s2
	v_pk_add_f32 v[64:65], v[64:65], v[66:67]
	v_pk_add_f32 v[92:93], v[92:93], v[102:103]
	v_div_scale_f32 v58, s[2:3], v54, v54, 1.0
	v_rcp_f32_e32 v60, v58
	s_max_i32 s2, s79, 1
	s_min_i32 s3, s78, s23
	s_sub_i32 s2, s3, s2
	v_fma_f32 v62, -v58, v60, 1.0
	v_fmac_f32_e32 v60, v62, v60
	v_div_scale_f32 v62, vcc, 1.0, v54, 1.0
	v_mul_f32_e32 v66, v62, v60
	v_fma_f32 v67, -v58, v66, v62
	v_fmac_f32_e32 v66, v67, v60
	v_fma_f32 v58, -v58, v66, v62
	v_div_fmas_f32 v58, v58, v60, v66
	v_div_fixup_f32 v54, v58, v54, 1.0
	v_pk_fma_f32 v[66:67], v[54:55], v[64:65], v[106:107] op_sel_hi:[0,1,1] neg_lo:[0,0,1] neg_hi:[0,0,1]
	v_pk_fma_f32 v[102:103], v[54:55], v[92:93], v[90:91] op_sel_hi:[0,1,1] neg_lo:[0,0,1] neg_hi:[0,0,1]
	v_pk_mul_f32 v[66:67], v[0:1], v[66:67]
	v_pk_mul_f32 v[102:103], v[2:3], v[102:103]
	v_cvt_pk_bf16_f32 v66, v66, v67
	s_add_i32 s2, s2, 1
	v_cvt_pk_bf16_f32 v67, v102, v103
	global_store_dwordx2 v[94:95], v[66:67], off offset:2048
	v_lshlrev_b32_e32 v66, 16, v89
	v_and_b32_e32 v67, 0xffff0000, v89
	v_lshlrev_b32_e32 v94, 16, v88
	v_and_b32_e32 v95, 0xffff0000, v88
	v_pk_mul_f32 v[88:89], v[52:53], v[94:95] op_sel_hi:[0,1]
	v_pk_mul_f32 v[102:103], v[52:53], v[66:67] op_sel_hi:[0,1]
	v_pk_fma_f32 v[66:67], v[52:53], v[66:67], v[100:101] op_sel_hi:[0,1,1] neg_lo:[0,0,1] neg_hi:[0,0,1]
	v_pk_fma_f32 v[94:95], v[52:53], v[94:95], v[98:99] op_sel_hi:[0,1,1] neg_lo:[0,0,1] neg_hi:[0,0,1]
	v_cvt_f32_i32_e32 v52, s2
	v_pk_add_f32 v[64:65], v[64:65], v[66:67]
	v_pk_add_f32 v[92:93], v[92:93], v[94:95]
	v_div_scale_f32 v54, s[2:3], v52, v52, 1.0
	v_rcp_f32_e32 v58, v54
	s_max_i32 s2, s78, 1
	s_min_i32 s3, s77, s23
	s_sub_i32 s2, s3, s2
	v_fma_f32 v60, -v54, v58, 1.0
	v_fmac_f32_e32 v58, v60, v58
	v_div_scale_f32 v60, vcc, 1.0, v52, 1.0
	v_mul_f32_e32 v62, v60, v58
	v_fma_f32 v66, -v54, v62, v60
	v_fmac_f32_e32 v62, v66, v58
	v_fma_f32 v54, -v54, v62, v60
	v_div_fmas_f32 v54, v54, v58, v62
	v_div_fixup_f32 v52, v54, v52, 1.0
	v_pk_fma_f32 v[66:67], v[52:53], v[64:65], v[102:103] op_sel_hi:[0,1,1] neg_lo:[0,0,1] neg_hi:[0,0,1]
	v_pk_fma_f32 v[94:95], v[52:53], v[92:93], v[88:89] op_sel_hi:[0,1,1] neg_lo:[0,0,1] neg_hi:[0,0,1]
	v_pk_mul_f32 v[66:67], v[0:1], v[66:67]
	v_pk_mul_f32 v[94:95], v[2:3], v[94:95]
	v_cvt_pk_bf16_f32 v66, v66, v67
	s_add_i32 s2, s2, 1
	v_cvt_pk_bf16_f32 v67, v94, v95
	global_store_dwordx2 v[56:57], v[66:67], off
	v_lshlrev_b32_e32 v66, 16, v87
	v_and_b32_e32 v67, 0xffff0000, v87
	v_lshlrev_b32_e32 v94, 16, v86
	v_and_b32_e32 v95, 0xffff0000, v86
	v_pk_mul_f32 v[86:87], v[50:51], v[94:95] op_sel_hi:[0,1]
	v_pk_mul_f32 v[98:99], v[50:51], v[66:67] op_sel_hi:[0,1]
	v_pk_fma_f32 v[66:67], v[50:51], v[66:67], v[106:107] op_sel_hi:[0,1,1] neg_lo:[0,0,1] neg_hi:[0,0,1]
	v_pk_fma_f32 v[90:91], v[50:51], v[94:95], v[90:91] op_sel_hi:[0,1,1] neg_lo:[0,0,1] neg_hi:[0,0,1]
	v_cvt_f32_i32_e32 v50, s2
	v_pk_add_f32 v[64:65], v[64:65], v[66:67]
	v_pk_add_f32 v[90:91], v[92:93], v[90:91]
	v_div_scale_f32 v52, s[2:3], v50, v50, 1.0
	v_rcp_f32_e32 v54, v52
	s_max_i32 s2, s77, 1
	s_min_i32 s3, s76, s23
	s_sub_i32 s2, s3, s2
	v_fma_f32 v58, -v52, v54, 1.0
	v_fmac_f32_e32 v54, v58, v54
	v_div_scale_f32 v58, vcc, 1.0, v50, 1.0
	v_mul_f32_e32 v60, v58, v54
	v_fma_f32 v62, -v52, v60, v58
	v_fmac_f32_e32 v60, v62, v54
	v_fma_f32 v52, -v52, v60, v58
	v_div_fmas_f32 v52, v52, v54, v60
	v_div_fixup_f32 v50, v52, v50, 1.0
	v_pk_fma_f32 v[66:67], v[50:51], v[64:65], v[98:99] op_sel_hi:[0,1,1] neg_lo:[0,0,1] neg_hi:[0,0,1]
	v_pk_fma_f32 v[92:93], v[50:51], v[90:91], v[86:87] op_sel_hi:[0,1,1] neg_lo:[0,0,1] neg_hi:[0,0,1]
	v_pk_mul_f32 v[66:67], v[0:1], v[66:67]
	v_pk_mul_f32 v[92:93], v[2:3], v[92:93]
	v_cvt_pk_bf16_f32 v66, v66, v67
	s_add_i32 s2, s2, 1
	v_cvt_pk_bf16_f32 v67, v92, v93
	global_store_dwordx2 v[56:57], v[66:67], off offset:2048
	v_lshlrev_b32_e32 v56, 16, v85
	v_and_b32_e32 v57, 0xffff0000, v85
	v_lshlrev_b32_e32 v66, 16, v49
	v_and_b32_e32 v67, 0xffff0000, v49
	v_pk_mul_f32 v[92:93], v[48:49], v[66:67] op_sel_hi:[0,1]
	v_pk_mul_f32 v[94:95], v[48:49], v[56:57] op_sel_hi:[0,1]
	v_pk_fma_f32 v[56:57], v[48:49], v[56:57], v[102:103] op_sel_hi:[0,1,1] neg_lo:[0,0,1] neg_hi:[0,0,1]
	v_pk_fma_f32 v[48:49], v[48:49], v[66:67], v[88:89] op_sel_hi:[0,1,1] neg_lo:[0,0,1] neg_hi:[0,0,1]
	v_pk_add_f32 v[66:67], v[90:91], v[48:49]
	v_cvt_f32_i32_e32 v48, s2
	v_pk_add_f32 v[56:57], v[64:65], v[56:57]
	v_and_b32_e32 v85, 0xffff0000, v83
	v_lshlrev_b32_e32 v62, 16, v63
	v_div_scale_f32 v49, s[2:3], v48, v48, 1.0
	v_rcp_f32_e32 v50, v49
	s_max_i32 s2, s76, 1
	s_min_i32 s3, s74, s23
	s_sub_i32 s2, s3, s2
	v_fma_f32 v52, -v49, v50, 1.0
	v_fmac_f32_e32 v50, v52, v50
	v_div_scale_f32 v52, vcc, 1.0, v48, 1.0
	v_mul_f32_e32 v54, v52, v50
	v_fma_f32 v58, -v49, v54, v52
	v_fmac_f32_e32 v54, v58, v50
	v_fma_f32 v49, -v49, v54, v52
	v_div_fmas_f32 v49, v49, v50, v54
	v_div_fixup_f32 v48, v49, v48, 1.0
	v_pk_fma_f32 v[64:65], v[48:49], v[56:57], v[94:95] op_sel_hi:[0,1,1] neg_lo:[0,0,1] neg_hi:[0,0,1]
	v_pk_fma_f32 v[48:49], v[48:49], v[66:67], v[92:93] op_sel_hi:[0,1,1] neg_lo:[0,0,1] neg_hi:[0,0,1]
	v_add_co_u32_e32 v88, vcc, s38, v4
	v_pk_mul_f32 v[48:49], v[2:3], v[48:49]
	v_pk_mul_f32 v[64:65], v[0:1], v[64:65]
	v_addc_co_u32_e32 v89, vcc, 0, v5, vcc
	v_cvt_pk_bf16_f32 v64, v64, v65
	v_cvt_pk_bf16_f32 v65, v48, v49
	v_add_co_u32_e32 v48, vcc, s39, v4
	s_add_i32 s2, s2, 1
	s_nop 0
	v_addc_co_u32_e32 v49, vcc, 0, v5, vcc
	global_store_dwordx2 v[48:49], v[64:65], off offset:-4096
	v_lshlrev_b32_e32 v64, 16, v84
	v_and_b32_e32 v65, 0xffff0000, v84
	v_lshlrev_b32_e32 v84, 16, v83
	v_pk_mul_f32 v[90:91], v[44:45], v[84:85] op_sel_hi:[0,1]
	v_pk_mul_f32 v[100:101], v[44:45], v[64:65] op_sel_hi:[0,1]
	v_pk_fma_f32 v[64:65], v[44:45], v[64:65], v[98:99] op_sel_hi:[0,1,1] neg_lo:[0,0,1] neg_hi:[0,0,1]
	v_pk_fma_f32 v[84:85], v[44:45], v[84:85], v[86:87] op_sel_hi:[0,1,1] neg_lo:[0,0,1] neg_hi:[0,0,1]
	v_cvt_f32_i32_e32 v44, s2
	v_pk_add_f32 v[56:57], v[56:57], v[64:65]
	v_pk_add_f32 v[66:67], v[66:67], v[84:85]
	v_and_b32_e32 v63, 0xffff0000, v63
	v_div_scale_f32 v50, s[2:3], v44, v44, 1.0
	v_rcp_f32_e32 v52, v50
	s_max_i32 s2, s74, 1
	s_min_i32 s3, s35, s23
	s_sub_i32 s2, s3, s2
	v_fma_f32 v54, -v50, v52, 1.0
	v_fmac_f32_e32 v52, v54, v52
	v_div_scale_f32 v54, vcc, 1.0, v44, 1.0
	v_mul_f32_e32 v58, v54, v52
	v_fma_f32 v60, -v50, v58, v54
	v_fmac_f32_e32 v58, v60, v52
	v_fma_f32 v50, -v50, v58, v54
	v_div_fmas_f32 v50, v50, v52, v58
	v_div_fixup_f32 v44, v50, v44, 1.0
	v_pk_fma_f32 v[64:65], v[44:45], v[56:57], v[100:101] op_sel_hi:[0,1,1] neg_lo:[0,0,1] neg_hi:[0,0,1]
	v_pk_fma_f32 v[84:85], v[44:45], v[66:67], v[90:91] op_sel_hi:[0,1,1] neg_lo:[0,0,1] neg_hi:[0,0,1]
	v_pk_mul_f32 v[64:65], v[0:1], v[64:65]
	v_pk_mul_f32 v[84:85], v[2:3], v[84:85]
	v_cvt_pk_bf16_f32 v64, v64, v65
	s_add_i32 s2, s2, 1
	v_cvt_pk_bf16_f32 v65, v84, v85
	global_store_dwordx2 v[88:89], v[64:65], off offset:2048
	v_lshlrev_b32_e32 v64, 16, v80
	v_and_b32_e32 v65, 0xffff0000, v80
	v_lshlrev_b32_e32 v84, 16, v79
	v_and_b32_e32 v85, 0xffff0000, v79
	v_pk_mul_f32 v[86:87], v[38:39], v[84:85] op_sel_hi:[0,1]
	v_pk_mul_f32 v[88:89], v[38:39], v[64:65] op_sel_hi:[0,1]
	v_pk_fma_f32 v[64:65], v[38:39], v[64:65], v[94:95] op_sel_hi:[0,1,1] neg_lo:[0,0,1] neg_hi:[0,0,1]
	v_pk_fma_f32 v[84:85], v[38:39], v[84:85], v[92:93] op_sel_hi:[0,1,1] neg_lo:[0,0,1] neg_hi:[0,0,1]
	v_cvt_f32_i32_e32 v38, s2
	v_pk_add_f32 v[56:57], v[56:57], v[64:65]
	v_pk_add_f32 v[66:67], v[66:67], v[84:85]
	v_div_scale_f32 v44, s[2:3], v38, v38, 1.0
	v_rcp_f32_e32 v50, v44
	s_max_i32 s2, s35, 1
	s_min_i32 s3, s75, s23
	s_sub_i32 s2, s3, s2
	v_fma_f32 v52, -v44, v50, 1.0
	v_fmac_f32_e32 v50, v52, v50
	v_div_scale_f32 v52, vcc, 1.0, v38, 1.0
	v_mul_f32_e32 v54, v52, v50
	v_fma_f32 v58, -v44, v54, v52
	v_fmac_f32_e32 v54, v58, v50
	v_fma_f32 v44, -v44, v54, v52
	v_div_fmas_f32 v44, v44, v50, v54
	v_div_fixup_f32 v38, v44, v38, 1.0
	s_add_i32 s2, s2, 1
	v_pk_fma_f32 v[64:65], v[38:39], v[56:57], v[88:89] op_sel_hi:[0,1,1] neg_lo:[0,0,1] neg_hi:[0,0,1]
	v_cvt_f32_i32_e32 v44, s2
	v_pk_fma_f32 v[84:85], v[38:39], v[66:67], v[86:87] op_sel_hi:[0,1,1] neg_lo:[0,0,1] neg_hi:[0,0,1]
	v_pk_mul_f32 v[64:65], v[0:1], v[64:65]
	v_pk_mul_f32 v[84:85], v[2:3], v[84:85]
	v_cvt_pk_bf16_f32 v64, v64, v65
	v_lshlrev_b32_e32 v38, 16, v39
	v_cvt_pk_bf16_f32 v65, v84, v85
	global_store_dwordx2 v[48:49], v[64:65], off
	v_lshlrev_b32_e32 v64, 16, v76
	v_and_b32_e32 v65, 0xffff0000, v76
	v_and_b32_e32 v39, 0xffff0000, v39
	v_pk_mul_f32 v[84:85], v[46:47], v[38:39] op_sel_hi:[0,1]
	v_pk_mul_f32 v[92:93], v[46:47], v[64:65] op_sel_hi:[0,1]
	v_pk_fma_f32 v[64:65], v[46:47], v[64:65], v[100:101] op_sel_hi:[0,1,1] neg_lo:[0,0,1] neg_hi:[0,0,1]
	v_pk_fma_f32 v[38:39], v[46:47], v[38:39], v[90:91] op_sel_hi:[0,1,1] neg_lo:[0,0,1] neg_hi:[0,0,1]
	v_div_scale_f32 v46, s[2:3], v44, v44, 1.0
	v_rcp_f32_e32 v50, v46
	v_pk_add_f32 v[56:57], v[56:57], v[64:65]
	v_pk_add_f32 v[38:39], v[66:67], v[38:39]
	s_max_i32 s2, s75, 1
	v_fma_f32 v52, -v46, v50, 1.0
	v_fmac_f32_e32 v50, v52, v50
	v_div_scale_f32 v52, vcc, 1.0, v44, 1.0
	v_mul_f32_e32 v54, v52, v50
	v_fma_f32 v58, -v46, v54, v52
	v_fmac_f32_e32 v54, v58, v50
	v_fma_f32 v46, -v46, v54, v52
	v_div_fmas_f32 v46, v46, v50, v54
	v_div_fixup_f32 v44, v46, v44, 1.0
	v_pk_fma_f32 v[64:65], v[44:45], v[56:57], v[92:93] op_sel_hi:[0,1,1] neg_lo:[0,0,1] neg_hi:[0,0,1]
	v_pk_fma_f32 v[66:67], v[44:45], v[38:39], v[84:85] op_sel_hi:[0,1,1] neg_lo:[0,0,1] neg_hi:[0,0,1]
	v_pk_mul_f32 v[64:65], v[0:1], v[64:65]
	v_pk_mul_f32 v[66:67], v[2:3], v[66:67]
	v_cvt_pk_bf16_f32 v64, v64, v65
	s_min_i32 s3, s73, s23
	v_cvt_pk_bf16_f32 v65, v66, v67
	global_store_dwordx2 v[48:49], v[64:65], off offset:2048
	v_lshlrev_b32_e32 v64, 16, v81
	v_and_b32_e32 v65, 0xffff0000, v81
	s_sub_i32 s2, s3, s2
	v_pk_mul_f32 v[66:67], v[42:43], v[64:65] op_sel_hi:[0,1]
	v_pk_fma_f32 v[64:65], v[42:43], v[64:65], v[86:87] op_sel_hi:[0,1,1] neg_lo:[0,0,1] neg_hi:[0,0,1]
	s_add_i32 s2, s2, 1
	v_pk_add_f32 v[64:65], v[38:39], v[64:65]
	v_cvt_f32_i32_e32 v38, s2
	v_lshlrev_b32_e32 v48, 16, v82
	v_and_b32_e32 v49, 0xffff0000, v82
	v_pk_mul_f32 v[80:81], v[42:43], v[48:49] op_sel_hi:[0,1]
	v_div_scale_f32 v39, s[2:3], v38, v38, 1.0
	v_pk_fma_f32 v[48:49], v[42:43], v[48:49], v[88:89] op_sel_hi:[0,1,1] neg_lo:[0,0,1] neg_hi:[0,0,1]
	v_rcp_f32_e32 v42, v39
	v_pk_add_f32 v[48:49], v[56:57], v[48:49]
	s_movk_i32 s2, 0x7000
	s_min_i32 s3, s72, s23
	v_fma_f32 v44, -v39, v42, 1.0
	v_fmac_f32_e32 v42, v44, v42
	v_div_scale_f32 v44, vcc, 1.0, v38, 1.0
	v_mul_f32_e32 v46, v44, v42
	v_fma_f32 v50, -v39, v46, v44
	v_fmac_f32_e32 v46, v50, v42
	v_fma_f32 v39, -v39, v46, v44
	v_div_fmas_f32 v39, v39, v42, v46
	v_div_fixup_f32 v38, v39, v38, 1.0
	v_pk_fma_f32 v[56:57], v[38:39], v[48:49], v[80:81] op_sel_hi:[0,1,1] neg_lo:[0,0,1] neg_hi:[0,0,1]
	v_pk_fma_f32 v[38:39], v[38:39], v[64:65], v[66:67] op_sel_hi:[0,1,1] neg_lo:[0,0,1] neg_hi:[0,0,1]
	v_add_co_u32_e32 v82, vcc, s2, v4
	v_pk_mul_f32 v[38:39], v[2:3], v[38:39]
	v_pk_mul_f32 v[56:57], v[0:1], v[56:57]
	v_addc_co_u32_e32 v83, vcc, 0, v5, vcc
	v_cvt_pk_bf16_f32 v56, v56, v57
	v_cvt_pk_bf16_f32 v57, v38, v39
	v_add_co_u32_e32 v38, vcc, s61, v4
	s_max_i32 s2, s73, 1
	s_nop 0
	v_addc_co_u32_e32 v39, vcc, 0, v5, vcc
	s_sub_i32 s2, s3, s2
	global_store_dwordx2 v[38:39], v[56:57], off offset:-4096
	v_lshlrev_b32_e32 v56, 16, v78
	v_and_b32_e32 v57, 0xffff0000, v78
	v_lshlrev_b32_e32 v76, 16, v77
	v_and_b32_e32 v77, 0xffff0000, v77
	s_add_i32 s2, s2, 1
	v_pk_mul_f32 v[78:79], v[40:41], v[76:77] op_sel_hi:[0,1]
	v_pk_mul_f32 v[86:87], v[40:41], v[56:57] op_sel_hi:[0,1]
	v_pk_fma_f32 v[56:57], v[40:41], v[56:57], v[92:93] op_sel_hi:[0,1,1] neg_lo:[0,0,1] neg_hi:[0,0,1]
	v_pk_fma_f32 v[76:77], v[40:41], v[76:77], v[84:85] op_sel_hi:[0,1,1] neg_lo:[0,0,1] neg_hi:[0,0,1]
	v_cvt_f32_i32_e32 v40, s2
	v_pk_add_f32 v[48:49], v[48:49], v[56:57]
	v_pk_add_f32 v[64:65], v[64:65], v[76:77]
	v_lshlrev_b32_e32 v58, 16, v59
	v_div_scale_f32 v42, s[2:3], v40, v40, 1.0
	v_rcp_f32_e32 v44, v42
	s_max_i32 s2, s72, 1
	s_min_i32 s3, s71, s23
	s_sub_i32 s2, s3, s2
	v_fma_f32 v46, -v42, v44, 1.0
	v_fmac_f32_e32 v44, v46, v44
	v_div_scale_f32 v46, vcc, 1.0, v40, 1.0
	v_mul_f32_e32 v50, v46, v44
	v_fma_f32 v52, -v42, v50, v46
	v_fmac_f32_e32 v50, v52, v44
	v_fma_f32 v42, -v42, v50, v46
	v_div_fmas_f32 v42, v42, v44, v50
	v_div_fixup_f32 v40, v42, v40, 1.0
	v_pk_fma_f32 v[56:57], v[40:41], v[48:49], v[86:87] op_sel_hi:[0,1,1] neg_lo:[0,0,1] neg_hi:[0,0,1]
	v_pk_fma_f32 v[76:77], v[40:41], v[64:65], v[78:79] op_sel_hi:[0,1,1] neg_lo:[0,0,1] neg_hi:[0,0,1]
	v_pk_mul_f32 v[56:57], v[0:1], v[56:57]
	v_pk_mul_f32 v[76:77], v[2:3], v[76:77]
	v_cvt_pk_bf16_f32 v56, v56, v57
	s_add_i32 s2, s2, 1
	v_cvt_pk_bf16_f32 v57, v76, v77
	global_store_dwordx2 v[82:83], v[56:57], off offset:2048
	v_lshlrev_b32_e32 v56, 16, v75
	v_and_b32_e32 v57, 0xffff0000, v75
	v_lshlrev_b32_e32 v76, 16, v74
	v_and_b32_e32 v77, 0xffff0000, v74
	v_pk_mul_f32 v[74:75], v[36:37], v[76:77] op_sel_hi:[0,1]
	v_pk_mul_f32 v[82:83], v[36:37], v[56:57] op_sel_hi:[0,1]
	v_pk_fma_f32 v[56:57], v[36:37], v[56:57], v[80:81] op_sel_hi:[0,1,1] neg_lo:[0,0,1] neg_hi:[0,0,1]
	v_pk_fma_f32 v[66:67], v[36:37], v[76:77], v[66:67] op_sel_hi:[0,1,1] neg_lo:[0,0,1] neg_hi:[0,0,1]
	v_cvt_f32_i32_e32 v36, s2
	v_pk_add_f32 v[48:49], v[48:49], v[56:57]
	v_pk_add_f32 v[64:65], v[64:65], v[66:67]
	v_and_b32_e32 v59, 0xffff0000, v59
	v_div_scale_f32 v40, s[2:3], v36, v36, 1.0
	v_rcp_f32_e32 v42, v40
	s_max_i32 s2, s71, 1
	s_min_i32 s3, s70, s23
	s_sub_i32 s2, s3, s2
	v_fma_f32 v44, -v40, v42, 1.0
	v_fmac_f32_e32 v42, v44, v42
	v_div_scale_f32 v44, vcc, 1.0, v36, 1.0
	v_mul_f32_e32 v46, v44, v42
	v_fma_f32 v50, -v40, v46, v44
	v_fmac_f32_e32 v46, v50, v42
	v_fma_f32 v40, -v40, v46, v44
	v_div_fmas_f32 v40, v40, v42, v46
	v_div_fixup_f32 v36, v40, v36, 1.0
	v_pk_fma_f32 v[56:57], v[36:37], v[48:49], v[82:83] op_sel_hi:[0,1,1] neg_lo:[0,0,1] neg_hi:[0,0,1]
	v_pk_fma_f32 v[66:67], v[36:37], v[64:65], v[74:75] op_sel_hi:[0,1,1] neg_lo:[0,0,1] neg_hi:[0,0,1]
	v_pk_mul_f32 v[56:57], v[0:1], v[56:57]
	v_pk_mul_f32 v[66:67], v[2:3], v[66:67]
	v_cvt_pk_bf16_f32 v56, v56, v57
	s_add_i32 s2, s2, 1
	v_cvt_pk_bf16_f32 v57, v66, v67
	global_store_dwordx2 v[38:39], v[56:57], off
	v_lshlrev_b32_e32 v56, 16, v73
	v_and_b32_e32 v57, 0xffff0000, v73
	v_lshlrev_b32_e32 v66, 16, v72
	v_and_b32_e32 v67, 0xffff0000, v72
	v_pk_mul_f32 v[72:73], v[34:35], v[66:67] op_sel_hi:[0,1]
	v_pk_mul_f32 v[76:77], v[34:35], v[56:57] op_sel_hi:[0,1]
	v_pk_fma_f32 v[56:57], v[34:35], v[56:57], v[86:87] op_sel_hi:[0,1,1] neg_lo:[0,0,1] neg_hi:[0,0,1]
	v_pk_fma_f32 v[66:67], v[34:35], v[66:67], v[78:79] op_sel_hi:[0,1,1] neg_lo:[0,0,1] neg_hi:[0,0,1]
	v_cvt_f32_i32_e32 v34, s2
	v_pk_add_f32 v[48:49], v[48:49], v[56:57]
	v_pk_add_f32 v[64:65], v[64:65], v[66:67]
	v_lshlrev_b32_e32 v52, 16, v53
	v_div_scale_f32 v36, s[2:3], v34, v34, 1.0
	v_rcp_f32_e32 v40, v36
	s_max_i32 s2, s70, 1
	s_min_i32 s3, s69, s23
	s_sub_i32 s2, s3, s2
	v_fma_f32 v42, -v36, v40, 1.0
	v_fmac_f32_e32 v40, v42, v40
	v_div_scale_f32 v42, vcc, 1.0, v34, 1.0
	v_mul_f32_e32 v44, v42, v40
	v_fma_f32 v46, -v36, v44, v42
	v_fmac_f32_e32 v44, v46, v40
	v_fma_f32 v36, -v36, v44, v42
	v_div_fmas_f32 v36, v36, v40, v44
	v_div_fixup_f32 v34, v36, v34, 1.0
	v_pk_fma_f32 v[56:57], v[34:35], v[48:49], v[76:77] op_sel_hi:[0,1,1] neg_lo:[0,0,1] neg_hi:[0,0,1]
	v_pk_fma_f32 v[66:67], v[34:35], v[64:65], v[72:73] op_sel_hi:[0,1,1] neg_lo:[0,0,1] neg_hi:[0,0,1]
	v_pk_mul_f32 v[56:57], v[0:1], v[56:57]
	v_pk_mul_f32 v[66:67], v[2:3], v[66:67]
	v_cvt_pk_bf16_f32 v56, v56, v57
	s_add_i32 s2, s2, 1
	v_cvt_pk_bf16_f32 v57, v66, v67
	global_store_dwordx2 v[38:39], v[56:57], off offset:2048
	v_lshlrev_b32_e32 v38, 16, v71
	v_and_b32_e32 v39, 0xffff0000, v71
	v_lshlrev_b32_e32 v56, 16, v33
	v_and_b32_e32 v57, 0xffff0000, v33
	v_pk_mul_f32 v[66:67], v[32:33], v[56:57] op_sel_hi:[0,1]
	v_pk_mul_f32 v[70:71], v[32:33], v[38:39] op_sel_hi:[0,1]
	v_pk_fma_f32 v[38:39], v[32:33], v[38:39], v[82:83] op_sel_hi:[0,1,1] neg_lo:[0,0,1] neg_hi:[0,0,1]
	v_pk_fma_f32 v[32:33], v[32:33], v[56:57], v[74:75] op_sel_hi:[0,1,1] neg_lo:[0,0,1] neg_hi:[0,0,1]
	v_pk_add_f32 v[56:57], v[64:65], v[32:33]
	v_cvt_f32_i32_e32 v32, s2
	v_pk_add_f32 v[38:39], v[48:49], v[38:39]
	v_and_b32_e32 v53, 0xffff0000, v53
	v_div_scale_f32 v33, s[2:3], v32, v32, 1.0
	v_rcp_f32_e32 v34, v33
	s_mov_b32 s2, 0xa000
	s_min_i32 s3, s68, s23
	v_fma_f32 v36, -v33, v34, 1.0
	v_fmac_f32_e32 v34, v36, v34
	v_div_scale_f32 v36, vcc, 1.0, v32, 1.0
	v_mul_f32_e32 v40, v36, v34
	v_fma_f32 v42, -v33, v40, v36
	v_fmac_f32_e32 v40, v42, v34
	v_fma_f32 v33, -v33, v40, v36
	v_div_fmas_f32 v33, v33, v34, v40
	v_div_fixup_f32 v32, v33, v32, 1.0
	v_pk_fma_f32 v[48:49], v[32:33], v[38:39], v[70:71] op_sel_hi:[0,1,1] neg_lo:[0,0,1] neg_hi:[0,0,1]
	v_pk_fma_f32 v[32:33], v[32:33], v[56:57], v[66:67] op_sel_hi:[0,1,1] neg_lo:[0,0,1] neg_hi:[0,0,1]
	v_add_co_u32_e32 v64, vcc, s94, v4
	v_pk_mul_f32 v[32:33], v[2:3], v[32:33]
	v_pk_mul_f32 v[48:49], v[0:1], v[48:49]
	v_addc_co_u32_e32 v65, vcc, 0, v5, vcc
	v_cvt_pk_bf16_f32 v48, v48, v49
	v_cvt_pk_bf16_f32 v49, v32, v33
	v_add_co_u32_e32 v32, vcc, s2, v4
	s_max_i32 s2, s69, 1
	s_nop 0
	v_addc_co_u32_e32 v33, vcc, 0, v5, vcc
	s_sub_i32 s2, s3, s2
	global_store_dwordx2 v[32:33], v[48:49], off offset:-4096
	v_lshlrev_b32_e32 v48, 16, v69
	v_and_b32_e32 v49, 0xffff0000, v69
	s_add_i32 s2, s2, 1
	v_pk_mul_f32 v[68:69], v[30:31], v[62:63] op_sel_hi:[0,1]
	v_pk_mul_f32 v[74:75], v[30:31], v[48:49] op_sel_hi:[0,1]
	v_pk_fma_f32 v[48:49], v[30:31], v[48:49], v[76:77] op_sel_hi:[0,1,1] neg_lo:[0,0,1] neg_hi:[0,0,1]
	v_pk_fma_f32 v[62:63], v[30:31], v[62:63], v[72:73] op_sel_hi:[0,1,1] neg_lo:[0,0,1] neg_hi:[0,0,1]
	v_cvt_f32_i32_e32 v30, s2
	v_pk_add_f32 v[38:39], v[38:39], v[48:49]
	v_pk_add_f32 v[56:57], v[56:57], v[62:63]
	v_div_scale_f32 v34, s[2:3], v30, v30, 1.0
	v_rcp_f32_e32 v36, v34
	s_max_i32 s2, s68, 1
	s_min_i32 s3, s67, s23
	s_sub_i32 s2, s3, s2
	v_fma_f32 v40, -v34, v36, 1.0
	v_fmac_f32_e32 v36, v40, v36
	v_div_scale_f32 v40, vcc, 1.0, v30, 1.0
	v_mul_f32_e32 v42, v40, v36
	v_fma_f32 v44, -v34, v42, v40
	v_fmac_f32_e32 v42, v44, v36
	v_fma_f32 v34, -v34, v42, v40
	v_div_fmas_f32 v34, v34, v36, v42
	v_div_fixup_f32 v30, v34, v30, 1.0
	v_pk_fma_f32 v[48:49], v[30:31], v[38:39], v[74:75] op_sel_hi:[0,1,1] neg_lo:[0,0,1] neg_hi:[0,0,1]
	v_pk_fma_f32 v[62:63], v[30:31], v[56:57], v[68:69] op_sel_hi:[0,1,1] neg_lo:[0,0,1] neg_hi:[0,0,1]
	v_pk_mul_f32 v[48:49], v[0:1], v[48:49]
	v_pk_mul_f32 v[62:63], v[2:3], v[62:63]
	v_cvt_pk_bf16_f32 v48, v48, v49
	s_add_i32 s2, s2, 1
	v_cvt_pk_bf16_f32 v49, v62, v63
	global_store_dwordx2 v[64:65], v[48:49], off offset:2048
	v_lshlrev_b32_e32 v48, 16, v61
	v_and_b32_e32 v49, 0xffff0000, v61
	v_pk_mul_f32 v[60:61], v[28:29], v[58:59] op_sel_hi:[0,1]
	v_pk_mul_f32 v[62:63], v[28:29], v[48:49] op_sel_hi:[0,1]
	v_pk_fma_f32 v[48:49], v[28:29], v[48:49], v[70:71] op_sel_hi:[0,1,1] neg_lo:[0,0,1] neg_hi:[0,0,1]
	v_pk_fma_f32 v[58:59], v[28:29], v[58:59], v[66:67] op_sel_hi:[0,1,1] neg_lo:[0,0,1] neg_hi:[0,0,1]
	v_cvt_f32_i32_e32 v28, s2
	v_pk_add_f32 v[38:39], v[38:39], v[48:49]
	v_pk_add_f32 v[56:57], v[56:57], v[58:59]
	v_lshlrev_b32_e32 v44, 16, v45
	v_div_scale_f32 v30, s[2:3], v28, v28, 1.0
	v_rcp_f32_e32 v34, v30
	s_max_i32 s2, s67, 1
	s_min_i32 s3, s66, s23
	s_sub_i32 s2, s3, s2
	v_fma_f32 v36, -v30, v34, 1.0
	v_fmac_f32_e32 v34, v36, v34
	v_div_scale_f32 v36, vcc, 1.0, v28, 1.0
	v_mul_f32_e32 v40, v36, v34
	v_fma_f32 v42, -v30, v40, v36
	v_fmac_f32_e32 v40, v42, v34
	v_fma_f32 v30, -v30, v40, v36
	v_div_fmas_f32 v30, v30, v34, v40
	v_div_fixup_f32 v28, v30, v28, 1.0
	v_pk_fma_f32 v[48:49], v[28:29], v[38:39], v[62:63] op_sel_hi:[0,1,1] neg_lo:[0,0,1] neg_hi:[0,0,1]
	v_pk_fma_f32 v[58:59], v[28:29], v[56:57], v[60:61] op_sel_hi:[0,1,1] neg_lo:[0,0,1] neg_hi:[0,0,1]
	v_pk_mul_f32 v[48:49], v[0:1], v[48:49]
	v_pk_mul_f32 v[58:59], v[2:3], v[58:59]
	v_cvt_pk_bf16_f32 v48, v48, v49
	s_add_i32 s2, s2, 1
	v_cvt_pk_bf16_f32 v49, v58, v59
	global_store_dwordx2 v[32:33], v[48:49], off
	v_lshlrev_b32_e32 v48, 16, v55
	v_and_b32_e32 v49, 0xffff0000, v55
	v_pk_mul_f32 v[54:55], v[26:27], v[52:53] op_sel_hi:[0,1]
	v_pk_mul_f32 v[58:59], v[26:27], v[48:49] op_sel_hi:[0,1]
	v_pk_fma_f32 v[48:49], v[26:27], v[48:49], v[74:75] op_sel_hi:[0,1,1] neg_lo:[0,0,1] neg_hi:[0,0,1]
	v_pk_fma_f32 v[52:53], v[26:27], v[52:53], v[68:69] op_sel_hi:[0,1,1] neg_lo:[0,0,1] neg_hi:[0,0,1]
	v_cvt_f32_i32_e32 v26, s2
	v_pk_add_f32 v[38:39], v[38:39], v[48:49]
	v_pk_add_f32 v[52:53], v[56:57], v[52:53]
	v_and_b32_e32 v45, 0xffff0000, v45
	v_div_scale_f32 v28, s[2:3], v26, v26, 1.0
	v_rcp_f32_e32 v30, v28
	s_max_i32 s2, s66, 1
	s_min_i32 s3, s34, s23
	s_sub_i32 s2, s3, s2
	v_fma_f32 v34, -v28, v30, 1.0
	v_fmac_f32_e32 v30, v34, v30
	v_div_scale_f32 v34, vcc, 1.0, v26, 1.0
	v_mul_f32_e32 v36, v34, v30
	v_fma_f32 v40, -v28, v36, v34
	v_fmac_f32_e32 v36, v40, v30
	v_fma_f32 v28, -v28, v36, v34
	v_div_fmas_f32 v28, v28, v30, v36
	v_div_fixup_f32 v26, v28, v26, 1.0
	v_pk_fma_f32 v[48:49], v[26:27], v[38:39], v[58:59] op_sel_hi:[0,1,1] neg_lo:[0,0,1] neg_hi:[0,0,1]
	v_pk_fma_f32 v[56:57], v[26:27], v[52:53], v[54:55] op_sel_hi:[0,1,1] neg_lo:[0,0,1] neg_hi:[0,0,1]
	v_pk_mul_f32 v[48:49], v[0:1], v[48:49]
	v_pk_mul_f32 v[56:57], v[2:3], v[56:57]
	v_cvt_pk_bf16_f32 v48, v48, v49
	s_add_i32 s2, s2, 1
	v_cvt_pk_bf16_f32 v49, v56, v57
	global_store_dwordx2 v[32:33], v[48:49], off offset:2048
	v_lshlrev_b32_e32 v32, 16, v51
	v_and_b32_e32 v33, 0xffff0000, v51
	v_lshlrev_b32_e32 v48, 16, v21
	v_and_b32_e32 v49, 0xffff0000, v21
	v_pk_mul_f32 v[50:51], v[20:21], v[48:49] op_sel_hi:[0,1]
	v_pk_mul_f32 v[56:57], v[20:21], v[32:33] op_sel_hi:[0,1]
	v_pk_fma_f32 v[32:33], v[20:21], v[32:33], v[62:63] op_sel_hi:[0,1,1] neg_lo:[0,0,1] neg_hi:[0,0,1]
	v_pk_fma_f32 v[20:21], v[20:21], v[48:49], v[60:61] op_sel_hi:[0,1,1] neg_lo:[0,0,1] neg_hi:[0,0,1]
	v_pk_add_f32 v[48:49], v[52:53], v[20:21]
	v_cvt_f32_i32_e32 v20, s2
	v_pk_add_f32 v[32:33], v[38:39], v[32:33]
	v_lshlrev_b32_e32 v36, 16, v37
	v_and_b32_e32 v37, 0xffff0000, v37
	v_div_scale_f32 v21, s[2:3], v20, v20, 1.0
	v_rcp_f32_e32 v26, v21
	s_max_i32 s2, s34, 1
	s_min_i32 s3, s63, s23
	s_sub_i32 s2, s3, s2
	v_fma_f32 v28, -v21, v26, 1.0
	v_fmac_f32_e32 v26, v28, v26
	v_div_scale_f32 v28, vcc, 1.0, v20, 1.0
	v_mul_f32_e32 v30, v28, v26
	v_fma_f32 v34, -v21, v30, v28
	v_fmac_f32_e32 v30, v34, v26
	v_fma_f32 v21, -v21, v30, v28
	v_div_fmas_f32 v21, v21, v26, v30
	v_div_fixup_f32 v20, v21, v20, 1.0
	v_pk_fma_f32 v[38:39], v[20:21], v[32:33], v[56:57] op_sel_hi:[0,1,1] neg_lo:[0,0,1] neg_hi:[0,0,1]
	v_pk_fma_f32 v[20:21], v[20:21], v[48:49], v[50:51] op_sel_hi:[0,1,1] neg_lo:[0,0,1] neg_hi:[0,0,1]
	v_add_co_u32_e32 v52, vcc, s51, v4
	v_pk_mul_f32 v[20:21], v[2:3], v[20:21]
	v_pk_mul_f32 v[38:39], v[0:1], v[38:39]
	v_addc_co_u32_e32 v53, vcc, 0, v5, vcc
	v_cvt_pk_bf16_f32 v38, v38, v39
	v_cvt_pk_bf16_f32 v39, v20, v21
	v_add_co_u32_e32 v20, vcc, s58, v4
	v_lshlrev_b32_e32 v34, 16, v35
	s_nop 0
	v_addc_co_u32_e32 v21, vcc, 0, v5, vcc
	v_and_b32_e32 v35, 0xffff0000, v35
	s_add_i32 s2, s2, 1
	global_store_dwordx2 v[20:21], v[38:39], off offset:-4096
	v_pk_mul_f32 v[38:39], v[24:25], v[34:35] op_sel_hi:[0,1]
	v_pk_mul_f32 v[60:61], v[24:25], v[36:37] op_sel_hi:[0,1]
	v_pk_fma_f32 v[36:37], v[24:25], v[36:37], v[58:59] op_sel_hi:[0,1,1] neg_lo:[0,0,1] neg_hi:[0,0,1]
	v_pk_fma_f32 v[34:35], v[24:25], v[34:35], v[54:55] op_sel_hi:[0,1,1] neg_lo:[0,0,1] neg_hi:[0,0,1]
	v_cvt_f32_i32_e32 v24, s2
	v_pk_add_f32 v[32:33], v[32:33], v[36:37]
	v_pk_add_f32 v[34:35], v[48:49], v[34:35]
	v_lshlrev_b32_e32 v40, 16, v41
	v_div_scale_f32 v26, s[2:3], v24, v24, 1.0
	v_rcp_f32_e32 v28, v26
	s_max_i32 s2, s63, 1
	s_min_i32 s3, s62, s23
	s_sub_i32 s2, s3, s2
	v_fma_f32 v30, -v26, v28, 1.0
	v_fmac_f32_e32 v28, v30, v28
	v_div_scale_f32 v30, vcc, 1.0, v24, 1.0
	v_mul_f32_e32 v36, v30, v28
	v_fma_f32 v37, -v26, v36, v30
	v_fmac_f32_e32 v36, v37, v28
	v_fma_f32 v26, -v26, v36, v30
	v_div_fmas_f32 v26, v26, v28, v36
	v_div_fixup_f32 v24, v26, v24, 1.0
	v_pk_fma_f32 v[36:37], v[24:25], v[32:33], v[60:61] op_sel_hi:[0,1,1] neg_lo:[0,0,1] neg_hi:[0,0,1]
	v_pk_fma_f32 v[48:49], v[24:25], v[34:35], v[38:39] op_sel_hi:[0,1,1] neg_lo:[0,0,1] neg_hi:[0,0,1]
	v_pk_mul_f32 v[36:37], v[0:1], v[36:37]
	v_pk_mul_f32 v[48:49], v[2:3], v[48:49]
	v_cvt_pk_bf16_f32 v36, v36, v37
	s_add_i32 s2, s2, 1
	v_cvt_pk_bf16_f32 v37, v48, v49
	global_store_dwordx2 v[52:53], v[36:37], off offset:2048
	v_lshlrev_b32_e32 v36, 16, v47
	v_and_b32_e32 v37, 0xffff0000, v47
	v_pk_mul_f32 v[46:47], v[22:23], v[44:45] op_sel_hi:[0,1]
	v_pk_mul_f32 v[48:49], v[22:23], v[36:37] op_sel_hi:[0,1]
	v_pk_fma_f32 v[36:37], v[22:23], v[36:37], v[56:57] op_sel_hi:[0,1,1] neg_lo:[0,0,1] neg_hi:[0,0,1]
	v_pk_fma_f32 v[44:45], v[22:23], v[44:45], v[50:51] op_sel_hi:[0,1,1] neg_lo:[0,0,1] neg_hi:[0,0,1]
	v_cvt_f32_i32_e32 v22, s2
	v_pk_add_f32 v[32:33], v[32:33], v[36:37]
	v_pk_add_f32 v[34:35], v[34:35], v[44:45]
	v_and_b32_e32 v41, 0xffff0000, v41
	v_div_scale_f32 v24, s[2:3], v22, v22, 1.0
	v_rcp_f32_e32 v26, v24
	s_max_i32 s2, s62, 1
	s_min_i32 s3, s21, s23
	s_sub_i32 s2, s3, s2
	v_fma_f32 v28, -v24, v26, 1.0
	v_fmac_f32_e32 v26, v28, v26
	v_div_scale_f32 v28, vcc, 1.0, v22, 1.0
	v_mul_f32_e32 v30, v28, v26
	v_fma_f32 v36, -v24, v30, v28
	v_fmac_f32_e32 v30, v36, v26
	v_fma_f32 v24, -v24, v30, v28
	v_div_fmas_f32 v24, v24, v26, v30
	v_div_fixup_f32 v22, v24, v22, 1.0
	v_pk_fma_f32 v[36:37], v[22:23], v[32:33], v[48:49] op_sel_hi:[0,1,1] neg_lo:[0,0,1] neg_hi:[0,0,1]
	v_pk_fma_f32 v[44:45], v[22:23], v[34:35], v[46:47] op_sel_hi:[0,1,1] neg_lo:[0,0,1] neg_hi:[0,0,1]
	v_pk_mul_f32 v[36:37], v[0:1], v[36:37]
	v_pk_mul_f32 v[44:45], v[2:3], v[44:45]
	v_cvt_pk_bf16_f32 v36, v36, v37
	s_add_i32 s2, s2, 1
	v_cvt_pk_bf16_f32 v37, v44, v45
	global_store_dwordx2 v[20:21], v[36:37], off
	v_lshlrev_b32_e32 v36, 16, v43
	v_and_b32_e32 v37, 0xffff0000, v43
	v_pk_mul_f32 v[42:43], v[18:19], v[40:41] op_sel_hi:[0,1]
	v_pk_mul_f32 v[44:45], v[18:19], v[36:37] op_sel_hi:[0,1]
	v_pk_fma_f32 v[36:37], v[18:19], v[36:37], v[60:61] op_sel_hi:[0,1,1] neg_lo:[0,0,1] neg_hi:[0,0,1]
	v_pk_fma_f32 v[38:39], v[18:19], v[40:41], v[38:39] op_sel_hi:[0,1,1] neg_lo:[0,0,1] neg_hi:[0,0,1]
	v_cvt_f32_i32_e32 v18, s2
	v_pk_add_f32 v[32:33], v[32:33], v[36:37]
	v_pk_add_f32 v[34:35], v[34:35], v[38:39]
	v_div_scale_f32 v22, s[2:3], v18, v18, 1.0
	v_rcp_f32_e32 v24, v22
	s_max_i32 s2, s21, 1
	s_min_i32 s3, s20, s23
	s_sub_i32 s2, s3, s2
	v_fma_f32 v26, -v22, v24, 1.0
	v_fmac_f32_e32 v24, v26, v24
	v_div_scale_f32 v26, vcc, 1.0, v18, 1.0
	v_mul_f32_e32 v28, v26, v24
	v_fma_f32 v30, -v22, v28, v26
	v_fmac_f32_e32 v28, v30, v24
	v_fma_f32 v22, -v22, v28, v26
	v_div_fmas_f32 v22, v22, v24, v28
	v_div_fixup_f32 v18, v22, v18, 1.0
	v_pk_fma_f32 v[36:37], v[18:19], v[32:33], v[44:45] op_sel_hi:[0,1,1] neg_lo:[0,0,1] neg_hi:[0,0,1]
	v_pk_fma_f32 v[38:39], v[18:19], v[34:35], v[42:43] op_sel_hi:[0,1,1] neg_lo:[0,0,1] neg_hi:[0,0,1]
	v_pk_mul_f32 v[36:37], v[0:1], v[36:37]
	v_pk_mul_f32 v[38:39], v[2:3], v[38:39]
	v_cvt_pk_bf16_f32 v36, v36, v37
	v_lshlrev_b32_e32 v30, 16, v17
	v_cvt_pk_bf16_f32 v37, v38, v39
	global_store_dwordx2 v[20:21], v[36:37], off offset:2048
	v_lshlrev_b32_e32 v20, 16, v31
	v_and_b32_e32 v21, 0xffff0000, v31
	v_and_b32_e32 v31, 0xffff0000, v17
	v_pk_mul_f32 v[36:37], v[16:17], v[30:31] op_sel_hi:[0,1]
	v_pk_mul_f32 v[38:39], v[16:17], v[20:21] op_sel_hi:[0,1]
	v_pk_fma_f32 v[20:21], v[16:17], v[20:21], v[48:49] op_sel_hi:[0,1,1] neg_lo:[0,0,1] neg_hi:[0,0,1]
	v_pk_fma_f32 v[16:17], v[16:17], v[30:31], v[46:47] op_sel_hi:[0,1,1] neg_lo:[0,0,1] neg_hi:[0,0,1]
	s_add_i32 s2, s2, 1
	v_pk_add_f32 v[30:31], v[34:35], v[16:17]
	v_cvt_f32_i32_e32 v16, s2
	v_pk_add_f32 v[20:21], v[32:33], v[20:21]
	v_lshlrev_b32_e32 v28, 16, v29
	v_and_b32_e32 v29, 0xffff0000, v29
	v_div_scale_f32 v17, s[2:3], v16, v16, 1.0
	v_rcp_f32_e32 v18, v17
	s_max_i32 s2, s20, 1
	s_min_i32 s3, s19, s23
	s_sub_i32 s2, s3, s2
	v_fma_f32 v22, -v17, v18, 1.0
	v_fmac_f32_e32 v18, v22, v18
	v_div_scale_f32 v22, vcc, 1.0, v16, 1.0
	v_mul_f32_e32 v24, v22, v18
	v_fma_f32 v26, -v17, v24, v22
	v_fmac_f32_e32 v24, v26, v18
	v_fma_f32 v17, -v17, v24, v22
	v_div_fmas_f32 v17, v17, v18, v24
	v_div_fixup_f32 v16, v17, v16, 1.0
	v_pk_fma_f32 v[32:33], v[16:17], v[20:21], v[38:39] op_sel_hi:[0,1,1] neg_lo:[0,0,1] neg_hi:[0,0,1]
	v_pk_fma_f32 v[16:17], v[16:17], v[30:31], v[36:37] op_sel_hi:[0,1,1] neg_lo:[0,0,1] neg_hi:[0,0,1]
	v_add_co_u32_e32 v34, vcc, s59, v4
	v_pk_mul_f32 v[16:17], v[2:3], v[16:17]
	v_pk_mul_f32 v[32:33], v[0:1], v[32:33]
	v_addc_co_u32_e32 v35, vcc, 0, v5, vcc
	v_cvt_pk_bf16_f32 v32, v32, v33
	v_cvt_pk_bf16_f32 v33, v16, v17
	v_add_co_u32_e32 v16, vcc, s60, v4
	v_lshlrev_b32_e32 v26, 16, v27
	s_nop 0
	v_addc_co_u32_e32 v17, vcc, 0, v5, vcc
	v_and_b32_e32 v27, 0xffff0000, v27
	s_add_i32 s2, s2, 1
	global_store_dwordx2 v[16:17], v[32:33], off offset:-4096
	v_pk_mul_f32 v[32:33], v[14:15], v[26:27] op_sel_hi:[0,1]
	v_pk_mul_f32 v[40:41], v[14:15], v[28:29] op_sel_hi:[0,1]
	v_pk_fma_f32 v[28:29], v[14:15], v[28:29], v[44:45] op_sel_hi:[0,1,1] neg_lo:[0,0,1] neg_hi:[0,0,1]
	v_pk_fma_f32 v[26:27], v[14:15], v[26:27], v[42:43] op_sel_hi:[0,1,1] neg_lo:[0,0,1] neg_hi:[0,0,1]
	v_cvt_f32_i32_e32 v14, s2
	v_pk_add_f32 v[20:21], v[20:21], v[28:29]
	v_pk_add_f32 v[26:27], v[30:31], v[26:27]
	v_div_scale_f32 v18, s[2:3], v14, v14, 1.0
	v_rcp_f32_e32 v22, v18
	s_max_i32 s2, s19, 1
	s_min_i32 s3, s18, s23
	s_sub_i32 s2, s3, s2
	v_fma_f32 v24, -v18, v22, 1.0
	v_fmac_f32_e32 v22, v24, v22
	v_div_scale_f32 v24, vcc, 1.0, v14, 1.0
	v_mul_f32_e32 v28, v24, v22
	v_fma_f32 v29, -v18, v28, v24
	v_fmac_f32_e32 v28, v29, v22
	v_fma_f32 v18, -v18, v28, v24
	v_div_fmas_f32 v18, v18, v22, v28
	v_div_fixup_f32 v14, v18, v14, 1.0
	v_pk_fma_f32 v[28:29], v[14:15], v[20:21], v[40:41] op_sel_hi:[0,1,1] neg_lo:[0,0,1] neg_hi:[0,0,1]
	v_pk_fma_f32 v[30:31], v[14:15], v[26:27], v[32:33] op_sel_hi:[0,1,1] neg_lo:[0,0,1] neg_hi:[0,0,1]
	v_pk_mul_f32 v[28:29], v[0:1], v[28:29]
	v_pk_mul_f32 v[30:31], v[2:3], v[30:31]
	v_cvt_pk_bf16_f32 v28, v28, v29
	v_lshlrev_b32_e32 v24, 16, v25
	v_cvt_pk_bf16_f32 v29, v30, v31
	v_and_b32_e32 v25, 0xffff0000, v25
	v_lshlrev_b32_e32 v22, 16, v23
	v_and_b32_e32 v23, 0xffff0000, v23
	s_add_i32 s2, s2, 1
	global_store_dwordx2 v[34:35], v[28:29], off offset:2048
	v_pk_mul_f32 v[28:29], v[12:13], v[22:23] op_sel_hi:[0,1]
	v_pk_mul_f32 v[30:31], v[12:13], v[24:25] op_sel_hi:[0,1]
	v_pk_fma_f32 v[24:25], v[12:13], v[24:25], v[38:39] op_sel_hi:[0,1,1] neg_lo:[0,0,1] neg_hi:[0,0,1]
	v_pk_fma_f32 v[22:23], v[12:13], v[22:23], v[36:37] op_sel_hi:[0,1,1] neg_lo:[0,0,1] neg_hi:[0,0,1]
	v_cvt_f32_i32_e32 v12, s2
	v_pk_add_f32 v[20:21], v[20:21], v[24:25]
	v_pk_add_f32 v[22:23], v[26:27], v[22:23]
	v_div_scale_f32 v14, s[2:3], v12, v12, 1.0
	v_rcp_f32_e32 v18, v14
	s_max_i32 s2, s18, 1
	s_min_i32 s3, s15, s23
	s_sub_i32 s2, s3, s2
	v_fma_f32 v24, -v14, v18, 1.0
	v_fmac_f32_e32 v18, v24, v18
	v_div_scale_f32 v24, vcc, 1.0, v12, 1.0
	v_mul_f32_e32 v25, v24, v18
	v_fma_f32 v26, -v14, v25, v24
	v_fmac_f32_e32 v25, v26, v18
	v_fma_f32 v14, -v14, v25, v24
	v_div_fmas_f32 v14, v14, v18, v25
	v_div_fixup_f32 v12, v14, v12, 1.0
	v_pk_fma_f32 v[24:25], v[12:13], v[20:21], v[30:31] op_sel_hi:[0,1,1] neg_lo:[0,0,1] neg_hi:[0,0,1]
	v_pk_fma_f32 v[26:27], v[12:13], v[22:23], v[28:29] op_sel_hi:[0,1,1] neg_lo:[0,0,1] neg_hi:[0,0,1]
	v_pk_mul_f32 v[24:25], v[0:1], v[24:25]
	v_pk_mul_f32 v[26:27], v[2:3], v[26:27]
	v_cvt_pk_bf16_f32 v24, v24, v25
	v_lshlrev_b32_e32 v14, 16, v15
	v_cvt_pk_bf16_f32 v25, v26, v27
	v_and_b32_e32 v15, 0xffff0000, v15
	v_lshlrev_b32_e32 v12, 16, v13
	v_and_b32_e32 v13, 0xffff0000, v13
	s_add_i32 s2, s2, 1
	global_store_dwordx2 v[16:17], v[24:25], off
	v_pk_mul_f32 v[24:25], v[10:11], v[12:13] op_sel_hi:[0,1]
	v_pk_mul_f32 v[26:27], v[10:11], v[14:15] op_sel_hi:[0,1]
	v_pk_fma_f32 v[14:15], v[10:11], v[14:15], v[40:41] op_sel_hi:[0,1,1] neg_lo:[0,0,1] neg_hi:[0,0,1]
	v_pk_fma_f32 v[12:13], v[10:11], v[12:13], v[32:33] op_sel_hi:[0,1,1] neg_lo:[0,0,1] neg_hi:[0,0,1]
	v_cvt_f32_i32_e32 v10, s2
	v_pk_add_f32 v[14:15], v[20:21], v[14:15]
	v_pk_add_f32 v[12:13], v[22:23], v[12:13]
	v_div_scale_f32 v18, s[2:3], v10, v10, 1.0
	v_rcp_f32_e32 v20, v18
	s_max_i32 s2, s15, 1
	s_min_i32 s3, s5, s23
	s_sub_i32 s2, s3, s2
	v_fma_f32 v21, -v18, v20, 1.0
	v_fmac_f32_e32 v20, v21, v20
	v_div_scale_f32 v21, vcc, 1.0, v10, 1.0
	v_mul_f32_e32 v22, v21, v20
	v_fma_f32 v23, -v18, v22, v21
	v_fmac_f32_e32 v22, v23, v20
	v_fma_f32 v18, -v18, v22, v21
	v_div_fmas_f32 v18, v18, v20, v22
	v_div_fixup_f32 v10, v18, v10, 1.0
	v_pk_fma_f32 v[20:21], v[10:11], v[14:15], v[26:27] op_sel_hi:[0,1,1] neg_lo:[0,0,1] neg_hi:[0,0,1]
	v_pk_fma_f32 v[22:23], v[10:11], v[12:13], v[24:25] op_sel_hi:[0,1,1] neg_lo:[0,0,1] neg_hi:[0,0,1]
	v_pk_mul_f32 v[20:21], v[0:1], v[20:21]
	v_pk_mul_f32 v[22:23], v[2:3], v[22:23]
	v_cvt_pk_bf16_f32 v20, v20, v21
	v_lshlrev_b32_e32 v10, 16, v11
	v_cvt_pk_bf16_f32 v21, v22, v23
	global_store_dwordx2 v[16:17], v[20:21], off offset:2048
	v_and_b32_e32 v11, 0xffff0000, v11
	v_lshlrev_b32_e32 v16, 16, v7
	v_and_b32_e32 v17, 0xffff0000, v7
	v_pk_mul_f32 v[20:21], v[6:7], v[16:17] op_sel_hi:[0,1]
	v_pk_mul_f32 v[22:23], v[6:7], v[10:11] op_sel_hi:[0,1]
	v_pk_fma_f32 v[10:11], v[6:7], v[10:11], v[30:31] op_sel_hi:[0,1,1] neg_lo:[0,0,1] neg_hi:[0,0,1]
	v_pk_fma_f32 v[6:7], v[6:7], v[16:17], v[28:29] op_sel_hi:[0,1,1] neg_lo:[0,0,1] neg_hi:[0,0,1]
	s_add_i32 s2, s2, 1
	v_pk_add_f32 v[6:7], v[12:13], v[6:7]
	v_cvt_f32_i32_e32 v12, s2
	v_pk_add_f32 v[10:11], v[14:15], v[10:11]
	v_div_scale_f32 v13, s[2:3], v12, v12, 1.0
	v_rcp_f32_e32 v14, v13
	s_add_i32 s3, s4, 32
	s_max_i32 s2, s5, 1
	s_min_i32 s3, s3, s23
	v_fma_f32 v15, -v13, v14, 1.0
	v_fmac_f32_e32 v14, v15, v14
	v_div_scale_f32 v15, vcc, 1.0, v12, 1.0
	v_mul_f32_e32 v16, v15, v14
	v_fma_f32 v17, -v13, v16, v15
	v_fmac_f32_e32 v16, v17, v14
	v_fma_f32 v13, -v13, v16, v15
	v_div_fmas_f32 v13, v13, v14, v16
	v_div_fixup_f32 v12, v13, v12, 1.0
	v_pk_fma_f32 v[14:15], v[12:13], v[10:11], v[22:23] op_sel_hi:[0,1,1] neg_lo:[0,0,1] neg_hi:[0,0,1]
	v_pk_fma_f32 v[12:13], v[12:13], v[6:7], v[20:21] op_sel_hi:[0,1,1] neg_lo:[0,0,1] neg_hi:[0,0,1]
	v_pk_mul_f32 v[12:13], v[2:3], v[12:13]
	v_pk_mul_f32 v[14:15], v[0:1], v[14:15]
	s_sub_i32 s2, s3, s2
	v_cvt_pk_bf16_f32 v14, v14, v15
	v_cvt_pk_bf16_f32 v15, v12, v13
	v_add_co_u32_e32 v12, vcc, s50, v4
	s_add_i32 s2, s2, 1
	s_nop 0
	v_addc_co_u32_e32 v13, vcc, 0, v5, vcc
	global_store_dwordx2 v[12:13], v[14:15], off
	v_lshlrev_b32_e32 v12, 16, v19
	v_and_b32_e32 v13, 0xffff0000, v19
	v_lshlrev_b32_e32 v14, 16, v9
	v_and_b32_e32 v15, 0xffff0000, v9
	s_waitcnt vmcnt(31)
	v_pk_mul_f32 v[16:17], v[8:9], v[14:15] op_sel_hi:[0,1]
	v_pk_mul_f32 v[18:19], v[8:9], v[12:13] op_sel_hi:[0,1]
	v_pk_fma_f32 v[12:13], v[8:9], v[12:13], v[26:27] op_sel_hi:[0,1,1] neg_lo:[0,0,1] neg_hi:[0,0,1]
	v_pk_fma_f32 v[8:9], v[8:9], v[14:15], v[24:25] op_sel_hi:[0,1,1] neg_lo:[0,0,1] neg_hi:[0,0,1]
	v_pk_add_f32 v[6:7], v[6:7], v[8:9]
	v_pk_add_f32 v[8:9], v[10:11], v[12:13]
	v_cvt_f32_i32_e32 v10, s2
	v_div_scale_f32 v11, s[2:3], v10, v10, 1.0
	v_rcp_f32_e32 v12, v11
	s_nop 0
	v_fma_f32 v13, -v11, v12, 1.0
	v_fmac_f32_e32 v12, v13, v12
	v_div_scale_f32 v13, vcc, 1.0, v10, 1.0
	v_mul_f32_e32 v14, v13, v12
	v_fma_f32 v15, -v11, v14, v13
	v_fmac_f32_e32 v14, v15, v12
	v_fma_f32 v11, -v11, v14, v13
	v_div_fmas_f32 v11, v11, v12, v14
	v_div_fixup_f32 v10, v11, v10, 1.0
	v_pk_fma_f32 v[8:9], v[10:11], v[8:9], v[18:19] op_sel_hi:[0,1,1] neg_lo:[0,0,1] neg_hi:[0,0,1]
	v_pk_fma_f32 v[6:7], v[10:11], v[6:7], v[16:17] op_sel_hi:[0,1,1] neg_lo:[0,0,1] neg_hi:[0,0,1]
	v_pk_mul_f32 v[2:3], v[2:3], v[6:7]
	v_pk_mul_f32 v[0:1], v[0:1], v[8:9]
	s_nop 0
	v_cvt_pk_bf16_f32 v6, v0, v1
	v_cvt_pk_bf16_f32 v7, v2, v3

.LBB0_381:
	s_cmp_gt_i32 s13, 1
	s_cbranch_scc0 .LBB0_400
	s_cmp_eq_u32 s13, 2
	s_mov_b64 s[18:19], -1
	s_cbranch_scc0 .LBB0_384
	s_add_i32 s5, s4, -4
	s_cmp_lt_u32 s5, s23
	s_cselect_b64 vcc, -1, 0
	s_and_b64 s[18:19], vcc, exec
	s_cselect_b32 s18, s5, s4
	v_lshlrev_b32_e32 v96, 1, v11
	s_ashr_i32 s19, s18, 31
	v_lshl_add_u64 v[8:9], s[2:3], 0, v[96:97]
	s_lshl_b64 s[20:21], s[18:19], 11
	v_lshl_add_u64 v[4:5], v[8:9], 0, s[20:21]
	global_load_dwordx2 v[4:5], v[4:5], off offset:1024 nt
	s_add_i32 s18, s18, s14
	s_ashr_i32 s19, s18, 31
	s_lshl_b64 s[18:19], s[18:19], 2
	s_add_u32 s18, s26, s18
	s_addc_u32 s19, s27, s19
	s_add_i32 s5, s4, -3
	s_cmp_lt_u32 s5, s23
	s_mov_b64 s[30:31], 0x400
	s_waitcnt vmcnt(0)
	v_cndmask_b32_e32 v17, 0, v4, vcc
	v_cndmask_b32_e32 v5, 0, v5, vcc
	s_cselect_b64 vcc, -1, 0
	global_load_dword v4, v97, s[18:19]
	s_and_b64 s[18:19], vcc, exec
	s_cselect_b32 s18, s5, s4
	s_ashr_i32 s19, s18, 31
	s_lshl_b64 s[20:21], s[18:19], 11
	v_lshl_add_u64 v[6:7], v[8:9], 0, s[20:21]
	global_load_dwordx2 v[6:7], v[6:7], off offset:1024 nt
	s_add_i32 s18, s18, s14
	s_ashr_i32 s19, s18, 31
	s_lshl_b64 s[18:19], s[18:19], 2
	s_add_u32 s18, s26, s18
	s_addc_u32 s19, s27, s19
	s_add_i32 s5, s4, -2
	s_cmp_lt_u32 s5, s23
	global_load_dword v16, v97, s[18:19]
	v_lshlrev_b32_e32 v82, 16, v17
	v_and_b32_e32 v83, 0xffff0000, v17
	v_lshlrev_b32_e32 v84, 16, v5
	v_and_b32_e32 v85, 0xffff0000, v5
	s_waitcnt vmcnt(2)
	v_pk_mul_f32 v[144:145], v[4:5], v[84:85] op_sel_hi:[0,1]
	v_pk_mul_f32 v[146:147], v[4:5], v[82:83] op_sel_hi:[0,1]
	v_pk_fma_f32 v[82:83], v[4:5], v[82:83], 0 op_sel_hi:[0,1,0]
	v_pk_fma_f32 v[4:5], v[4:5], v[84:85], 0 op_sel_hi:[0,1,0]
	s_waitcnt vmcnt(1)
	v_cndmask_b32_e32 v67, 0, v6, vcc
	v_cndmask_b32_e32 v63, 0, v7, vcc
	s_cselect_b64 vcc, -1, 0
	s_and_b64 s[18:19], vcc, exec
	s_cselect_b32 s18, s5, s4
	s_ashr_i32 s19, s18, 31
	s_lshl_b64 s[20:21], s[18:19], 11
	v_lshl_add_u64 v[6:7], v[8:9], 0, s[20:21]
	global_load_dwordx2 v[6:7], v[6:7], off offset:1024 nt
	s_add_i32 s18, s18, s14
	s_ashr_i32 s19, s18, 31
	s_lshl_b64 s[18:19], s[18:19], 2
	s_add_u32 s18, s26, s18
	s_addc_u32 s19, s27, s19
	s_add_i32 s5, s4, -1
	s_cmp_lt_u32 s5, s23
	global_load_dword v62, v97, s[18:19]
	v_lshlrev_b32_e32 v84, 16, v67
	v_and_b32_e32 v85, 0xffff0000, v67
	v_lshlrev_b32_e32 v86, 16, v63
	v_and_b32_e32 v87, 0xffff0000, v63
	s_waitcnt vmcnt(2)
	v_pk_mul_f32 v[104:105], v[16:17], v[86:87] op_sel_hi:[0,1]
	v_pk_mul_f32 v[106:107], v[16:17], v[84:85] op_sel_hi:[0,1]
	v_pk_fma_f32 v[4:5], v[16:17], v[86:87], v[4:5] op_sel_hi:[0,1,1]
	v_pk_fma_f32 v[16:17], v[16:17], v[84:85], v[82:83] op_sel_hi:[0,1,1]
	s_waitcnt vmcnt(1)
	v_cndmask_b32_e32 v71, 0, v6, vcc
	v_cndmask_b32_e32 v69, 0, v7, vcc
	s_cselect_b64 vcc, -1, 0
	s_and_b64 s[18:19], vcc, exec
	s_cselect_b32 s18, s5, s4
	s_ashr_i32 s19, s18, 31
	s_lshl_b64 s[20:21], s[18:19], 11
	v_lshl_add_u64 v[6:7], v[8:9], 0, s[20:21]
	global_load_dwordx2 v[6:7], v[6:7], off offset:1024 nt
	s_add_i32 s18, s18, s14
	s_ashr_i32 s19, s18, 31
	s_lshl_b64 s[18:19], s[18:19], 2
	s_add_u32 s18, s26, s18
	s_addc_u32 s19, s27, s19
	s_cmp_lt_u32 s4, s23
	global_load_dword v66, v97, s[18:19]
	v_lshlrev_b32_e32 v84, 16, v71
	v_and_b32_e32 v85, 0xffff0000, v71
	v_lshlrev_b32_e32 v86, 16, v69
	v_and_b32_e32 v87, 0xffff0000, v69
	s_waitcnt vmcnt(2)
	v_pk_mul_f32 v[82:83], v[62:63], v[86:87] op_sel_hi:[0,1]
	v_pk_mul_f32 v[102:103], v[62:63], v[84:85] op_sel_hi:[0,1]
	v_pk_fma_f32 v[16:17], v[62:63], v[84:85], v[16:17] op_sel_hi:[0,1,1]
	v_pk_fma_f32 v[4:5], v[62:63], v[86:87], v[4:5] op_sel_hi:[0,1,1]
	s_waitcnt vmcnt(1)
	v_cndmask_b32_e32 v75, 0, v6, vcc
	v_cndmask_b32_e32 v73, 0, v7, vcc
	s_cselect_b64 vcc, -1, 0
	s_ashr_i32 s5, s4, 31
	s_lshl_b64 s[18:19], s[4:5], 11
	v_lshl_add_u64 v[6:7], v[8:9], 0, s[18:19]
	global_load_dwordx2 v[6:7], v[6:7], off offset:1024 nt
	s_ashr_i32 s7, s6, 31
	s_lshl_b64 s[18:19], s[6:7], 2
	s_add_u32 s18, s26, s18
	s_addc_u32 s19, s27, s19
	s_or_b32 s91, s4, 1
	s_cmp_lt_u32 s91, s23
	global_load_dword v68, v97, s[18:19]
	v_lshlrev_b32_e32 v62, 16, v75
	v_and_b32_e32 v63, 0xffff0000, v75
	v_lshlrev_b32_e32 v86, 16, v73
	v_and_b32_e32 v87, 0xffff0000, v73
	s_waitcnt vmcnt(2)
	v_pk_mul_f32 v[100:101], v[66:67], v[62:63] op_sel_hi:[0,1]
	v_pk_fma_f32 v[16:17], v[66:67], v[62:63], v[16:17] op_sel_hi:[0,1,1]
	v_pk_mul_f32 v[84:85], v[66:67], v[86:87] op_sel_hi:[0,1]
	v_pk_fma_f32 v[4:5], v[66:67], v[86:87], v[4:5] op_sel_hi:[0,1,1]
	s_waitcnt vmcnt(1)
	v_cndmask_b32_e32 v79, 0, v6, vcc
	v_cndmask_b32_e32 v77, 0, v7, vcc
	s_cselect_b64 vcc, -1, 0
	s_and_b64 s[18:19], vcc, exec
	s_cselect_b32 s18, s91, s4
	s_ashr_i32 s19, s18, 31
	s_lshl_b64 s[20:21], s[18:19], 11
	v_lshl_add_u64 v[6:7], v[8:9], 0, s[20:21]
	global_load_dwordx2 v[6:7], v[6:7], off offset:1024 nt
	s_add_i32 s18, s18, s14
	s_ashr_i32 s19, s18, 31
	s_lshl_b64 s[18:19], s[18:19], 2
	s_add_u32 s18, s26, s18
	s_addc_u32 s19, s27, s19
	s_or_b32 s90, s4, 2
	s_cmp_lt_u32 s90, s23
	global_load_dword v72, v97, s[18:19]
	v_lshlrev_b32_e32 v62, 16, v79
	v_and_b32_e32 v63, 0xffff0000, v79
	v_lshlrev_b32_e32 v66, 16, v77
	v_and_b32_e32 v67, 0xffff0000, v77
	s_waitcnt vmcnt(2)
	v_pk_mul_f32 v[98:99], v[68:69], v[62:63] op_sel_hi:[0,1]
	v_pk_fma_f32 v[16:17], v[68:69], v[62:63], v[16:17] op_sel_hi:[0,1,1]
	v_pk_mul_f32 v[86:87], v[68:69], v[66:67] op_sel_hi:[0,1]
	v_pk_fma_f32 v[4:5], v[68:69], v[66:67], v[4:5] op_sel_hi:[0,1,1]
	s_waitcnt vmcnt(1)
	v_cndmask_b32_e32 v89, 0, v6, vcc
	v_cndmask_b32_e32 v88, 0, v7, vcc
	s_cselect_b64 vcc, -1, 0
	s_and_b64 s[18:19], vcc, exec
	s_cselect_b32 s18, s90, s4
	s_ashr_i32 s19, s18, 31
	s_lshl_b64 s[20:21], s[18:19], 11
	v_lshl_add_u64 v[6:7], v[8:9], 0, s[20:21]
	global_load_dwordx2 v[6:7], v[6:7], off offset:1024 nt
	s_add_i32 s18, s18, s14
	s_ashr_i32 s19, s18, 31
	s_lshl_b64 s[18:19], s[18:19], 2
	s_add_u32 s18, s26, s18
	s_addc_u32 s19, s27, s19
	s_or_b32 s89, s4, 3
	s_cmp_lt_u32 s89, s23
	global_load_dword v76, v97, s[18:19]
	v_lshlrev_b32_e32 v62, 16, v89
	v_and_b32_e32 v63, 0xffff0000, v89
	v_lshlrev_b32_e32 v66, 16, v88
	v_and_b32_e32 v67, 0xffff0000, v88
	s_waitcnt vmcnt(2)
	v_pk_mul_f32 v[94:95], v[72:73], v[62:63] op_sel_hi:[0,1]
	v_pk_fma_f32 v[16:17], v[72:73], v[62:63], v[16:17] op_sel_hi:[0,1,1]
	v_pk_mul_f32 v[88:89], v[72:73], v[66:67] op_sel_hi:[0,1]
	v_pk_fma_f32 v[4:5], v[72:73], v[66:67], v[4:5] op_sel_hi:[0,1,1]
	s_waitcnt vmcnt(1)
	v_cndmask_b32_e32 v91, 0, v6, vcc
	v_cndmask_b32_e32 v90, 0, v7, vcc
	s_cselect_b64 vcc, -1, 0
	s_and_b64 s[18:19], vcc, exec
	s_cselect_b32 s18, s89, s4
	s_ashr_i32 s19, s18, 31
	s_lshl_b64 s[20:21], s[18:19], 11
	v_lshl_add_u64 v[6:7], v[8:9], 0, s[20:21]
	global_load_dwordx2 v[6:7], v[6:7], off offset:1024 nt
	s_add_i32 s18, s18, s14
	s_ashr_i32 s19, s18, 31
	s_lshl_b64 s[18:19], s[18:19], 2
	s_add_u32 s18, s26, s18
	s_addc_u32 s19, s27, s19
	s_or_b32 s88, s4, 4
	s_cmp_lt_u32 s88, s23
	global_load_dword v80, v97, s[18:19]
	v_lshlrev_b32_e32 v62, 16, v91
	v_and_b32_e32 v63, 0xffff0000, v91
	v_lshlrev_b32_e32 v66, 16, v90
	v_and_b32_e32 v67, 0xffff0000, v90
	s_waitcnt vmcnt(2)
	v_pk_fma_f32 v[16:17], v[76:77], v[62:63], v[16:17] op_sel_hi:[0,1,1]
	v_pk_fma_f32 v[4:5], v[76:77], v[66:67], v[4:5] op_sel_hi:[0,1,1]
	v_pk_mul_f32 v[90:91], v[76:77], v[66:67] op_sel_hi:[0,1]
	v_pk_mul_f32 v[92:93], v[76:77], v[62:63] op_sel_hi:[0,1]
	s_waitcnt vmcnt(1)
	v_cndmask_b32_e32 v143, 0, v6, vcc
	v_cndmask_b32_e32 v142, 0, v7, vcc
	s_cselect_b64 vcc, -1, 0
	s_and_b64 s[18:19], vcc, exec
	s_cselect_b32 s18, s88, s4
	s_ashr_i32 s19, s18, 31
	s_lshl_b64 s[20:21], s[18:19], 11
	v_lshl_add_u64 v[6:7], v[8:9], 0, s[20:21]
	global_load_dwordx2 v[6:7], v[6:7], off offset:1024 nt
	s_add_i32 s18, s18, s14
	s_ashr_i32 s19, s18, 31
	s_lshl_b64 s[18:19], s[18:19], 2
	s_add_u32 s18, s26, s18
	s_addc_u32 s19, s27, s19
	s_or_b32 s86, s4, 5
	s_cmp_lt_u32 s86, s23
	global_load_dword v74, v97, s[18:19]
	v_lshlrev_b32_e32 v68, 16, v143
	v_and_b32_e32 v69, 0xffff0000, v143
	v_lshlrev_b32_e32 v72, 16, v142
	v_and_b32_e32 v73, 0xffff0000, v142
	s_waitcnt vmcnt(1)
	v_cndmask_b32_e32 v141, 0, v6, vcc
	v_cndmask_b32_e32 v140, 0, v7, vcc
	s_cselect_b64 vcc, -1, 0
	s_and_b64 s[18:19], vcc, exec
	s_cselect_b32 s18, s86, s4
	s_ashr_i32 s19, s18, 31
	s_lshl_b64 s[20:21], s[18:19], 11
	v_lshl_add_u64 v[6:7], v[8:9], 0, s[20:21]
	global_load_dwordx2 v[6:7], v[6:7], off offset:1024 nt
	s_add_i32 s18, s18, s14
	s_ashr_i32 s19, s18, 31
	s_lshl_b64 s[18:19], s[18:19], 2
	s_add_u32 s18, s26, s18
	s_addc_u32 s19, s27, s19
	s_or_b32 s87, s4, 6
	s_cmp_lt_u32 s87, s23
	global_load_dword v78, v97, s[18:19]
	v_lshlrev_b32_e32 v148, 16, v141
	v_and_b32_e32 v149, 0xffff0000, v141
	v_lshlrev_b32_e32 v150, 16, v140
	v_and_b32_e32 v151, 0xffff0000, v140
	s_waitcnt vmcnt(1)
	v_cndmask_b32_e32 v137, 0, v6, vcc
	v_cndmask_b32_e32 v81, 0, v7, vcc
	s_cselect_b64 vcc, -1, 0
	s_and_b64 s[18:19], vcc, exec
	s_cselect_b32 s18, s87, s4
	s_ashr_i32 s19, s18, 31
	s_lshl_b64 s[20:21], s[18:19], 11
	v_lshl_add_u64 v[6:7], v[8:9], 0, s[20:21]
	global_load_dwordx2 v[6:7], v[6:7], off offset:1024 nt
	s_add_i32 s18, s18, s14
	s_ashr_i32 s19, s18, 31
	s_lshl_b64 s[18:19], s[18:19], 2
	s_add_u32 s18, s26, s18
	s_addc_u32 s19, s27, s19
	s_or_b32 s85, s4, 7
	s_cmp_lt_u32 s85, s23
	global_load_dword v70, v97, s[18:19]
	v_pk_fma_f32 v[142:143], v[80:81], v[68:69], v[16:17] op_sel_hi:[0,1,1]
	v_pk_fma_f32 v[76:77], v[80:81], v[72:73], v[4:5] op_sel_hi:[0,1,1]
	v_pk_mul_f32 v[66:67], v[80:81], v[68:69] op_sel_hi:[0,1]
	v_pk_mul_f32 v[62:63], v[80:81], v[72:73] op_sel_hi:[0,1]
	s_waitcnt vmcnt(1)
	v_cndmask_b32_e32 v139, 0, v6, vcc
	v_cndmask_b32_e32 v138, 0, v7, vcc
	s_cselect_b64 vcc, -1, 0
	s_and_b64 s[18:19], vcc, exec
	s_cselect_b32 s18, s85, s4
	s_ashr_i32 s19, s18, 31
	s_lshl_b64 s[20:21], s[18:19], 11
	v_lshl_add_u64 v[6:7], v[8:9], 0, s[20:21]
	global_load_dwordx2 v[6:7], v[6:7], off offset:1024 nt
	s_add_i32 s18, s18, s14
	s_ashr_i32 s19, s18, 31
	s_lshl_b64 s[18:19], s[18:19], 2
	s_add_u32 s18, s26, s18
	s_addc_u32 s19, s27, s19
	s_or_b32 s35, s4, 8
	s_cmp_lt_u32 s35, s23
	global_load_dword v64, v97, s[18:19]
	s_waitcnt vmcnt(1)
	v_cndmask_b32_e32 v136, 0, v6, vcc
	v_cndmask_b32_e32 v135, 0, v7, vcc
	s_cselect_b64 vcc, -1, 0
	s_and_b64 s[18:19], vcc, exec
	s_cselect_b32 s18, s35, s4
	s_ashr_i32 s19, s18, 31
	s_lshl_b64 s[20:21], s[18:19], 11
	v_lshl_add_u64 v[6:7], v[8:9], 0, s[20:21]
	global_load_dwordx2 v[6:7], v[6:7], off offset:1024 nt
	s_add_i32 s18, s18, s14
	s_ashr_i32 s19, s18, 31
	s_lshl_b64 s[18:19], s[18:19], 2
	s_add_u32 s18, s26, s18
	s_addc_u32 s19, s27, s19
	s_or_b32 s84, s4, 9
	s_cmp_lt_u32 s84, s23
	global_load_dword v60, v97, s[18:19]
	s_waitcnt vmcnt(1)
	v_cndmask_b32_e32 v134, 0, v6, vcc
	v_cndmask_b32_e32 v65, 0, v7, vcc
	s_cselect_b64 vcc, -1, 0
	s_and_b64 s[18:19], vcc, exec
	s_cselect_b32 s18, s84, s4
	s_ashr_i32 s19, s18, 31
	s_lshl_b64 s[20:21], s[18:19], 11
	v_lshl_add_u64 v[6:7], v[8:9], 0, s[20:21]
	global_load_dwordx2 v[6:7], v[6:7], off offset:1024 nt
	s_add_i32 s18, s18, s14
	s_ashr_i32 s19, s18, 31
	s_lshl_b64 s[18:19], s[18:19], 2
	s_add_u32 s18, s26, s18
	s_addc_u32 s19, s27, s19
	s_or_b32 s83, s4, 10
	s_cmp_lt_u32 s83, s23
	global_load_dword v58, v97, s[18:19]
	s_waitcnt vmcnt(1)
	v_cndmask_b32_e32 v133, 0, v6, vcc
	v_cndmask_b32_e32 v61, 0, v7, vcc
	s_cselect_b64 vcc, -1, 0
	s_and_b64 s[18:19], vcc, exec
	s_cselect_b32 s18, s83, s4
	s_ashr_i32 s19, s18, 31
	s_lshl_b64 s[20:21], s[18:19], 11
	v_lshl_add_u64 v[6:7], v[8:9], 0, s[20:21]
	global_load_dwordx2 v[6:7], v[6:7], off offset:1024 nt
	s_add_i32 s18, s18, s14
	s_ashr_i32 s19, s18, 31
	s_lshl_b64 s[18:19], s[18:19], 2
	s_add_u32 s18, s26, s18
	s_addc_u32 s19, s27, s19
	s_or_b32 s81, s4, 11
	s_cmp_lt_u32 s81, s23
	global_load_dword v54, v97, s[18:19]
	s_waitcnt vmcnt(1)
	v_cndmask_b32_e32 v132, 0, v6, vcc
	v_cndmask_b32_e32 v59, 0, v7, vcc
	s_cselect_b64 vcc, -1, 0
	s_and_b64 s[18:19], vcc, exec
	s_cselect_b32 s18, s81, s4
	s_ashr_i32 s19, s18, 31
	s_lshl_b64 s[20:21], s[18:19], 11
	v_lshl_add_u64 v[6:7], v[8:9], 0, s[20:21]
	global_load_dwordx2 v[6:7], v[6:7], off offset:1024 nt
	s_add_i32 s18, s18, s14
	s_ashr_i32 s19, s18, 31
	s_lshl_b64 s[18:19], s[18:19], 2
	s_add_u32 s18, s26, s18
	s_addc_u32 s19, s27, s19
	s_or_b32 s79, s4, 12
	s_cmp_lt_u32 s79, s23
	global_load_dword v50, v97, s[18:19]
	s_waitcnt vmcnt(1)
	v_cndmask_b32_e32 v57, 0, v6, vcc
	v_cndmask_b32_e32 v55, 0, v7, vcc
	s_cselect_b64 vcc, -1, 0
	s_and_b64 s[18:19], vcc, exec
	s_cselect_b32 s18, s79, s4
	s_ashr_i32 s19, s18, 31
	s_lshl_b64 s[20:21], s[18:19], 11
	v_lshl_add_u64 v[6:7], v[8:9], 0, s[20:21]
	global_load_dwordx2 v[6:7], v[6:7], off offset:1024 nt
	s_add_i32 s18, s18, s14
	s_ashr_i32 s19, s18, 31
	s_lshl_b64 s[18:19], s[18:19], 2
	s_add_u32 s18, s26, s18
	s_addc_u32 s19, s27, s19
	s_or_b32 s82, s4, 13
	s_cmp_lt_u32 s82, s23
	global_load_dword v56, v97, s[18:19]
	s_waitcnt vmcnt(1)
	v_cndmask_b32_e32 v53, 0, v6, vcc
	v_cndmask_b32_e32 v51, 0, v7, vcc
	s_cselect_b64 vcc, -1, 0
	s_and_b64 s[18:19], vcc, exec
	s_cselect_b32 s18, s82, s4
	s_ashr_i32 s19, s18, 31
	s_lshl_b64 s[20:21], s[18:19], 11
	v_lshl_add_u64 v[6:7], v[8:9], 0, s[20:21]
	global_load_dwordx2 v[6:7], v[6:7], off offset:1024 nt
	s_add_i32 s18, s18, s14
	s_ashr_i32 s19, s18, 31
	s_lshl_b64 s[18:19], s[18:19], 2
	s_add_u32 s18, s26, s18
	s_addc_u32 s19, s27, s19
	s_or_b32 s80, s4, 14
	s_cmp_lt_u32 s80, s23
	global_load_dword v52, v97, s[18:19]
	s_waitcnt vmcnt(1)
	v_cndmask_b32_e32 v131, 0, v6, vcc
	v_cndmask_b32_e32 v130, 0, v7, vcc
	s_cselect_b64 vcc, -1, 0
	s_and_b64 s[18:19], vcc, exec
	s_cselect_b32 s18, s80, s4
	s_ashr_i32 s19, s18, 31
	s_lshl_b64 s[20:21], s[18:19], 11
	v_lshl_add_u64 v[6:7], v[8:9], 0, s[20:21]
	global_load_dwordx2 v[6:7], v[6:7], off offset:1024 nt
	s_add_i32 s18, s18, s14
	s_ashr_i32 s19, s18, 31
	s_lshl_b64 s[18:19], s[18:19], 2
	s_add_u32 s18, s26, s18
	s_addc_u32 s19, s27, s19
	s_or_b32 s78, s4, 15
	s_cmp_lt_u32 s78, s23
	global_load_dword v48, v97, s[18:19]
	s_waitcnt vmcnt(1)
	v_cndmask_b32_e32 v129, 0, v6, vcc
	v_cndmask_b32_e32 v128, 0, v7, vcc
	s_cselect_b64 vcc, -1, 0
	s_and_b64 s[18:19], vcc, exec
	s_cselect_b32 s18, s78, s4
	s_ashr_i32 s19, s18, 31
	s_lshl_b64 s[20:21], s[18:19], 11
	v_lshl_add_u64 v[6:7], v[8:9], 0, s[20:21]
	global_load_dwordx2 v[6:7], v[6:7], off offset:1024 nt
	s_add_i32 s18, s18, s14
	s_ashr_i32 s19, s18, 31
	s_lshl_b64 s[18:19], s[18:19], 2
	s_add_u32 s18, s26, s18
	s_addc_u32 s19, s27, s19
	s_or_b32 s77, s4, 16
	s_cmp_lt_u32 s77, s23
	global_load_dword v46, v97, s[18:19]
	s_waitcnt vmcnt(1)
	v_cndmask_b32_e32 v127, 0, v6, vcc
	v_cndmask_b32_e32 v49, 0, v7, vcc
	s_cselect_b64 vcc, -1, 0
	s_and_b64 s[18:19], vcc, exec
	s_cselect_b32 s18, s77, s4
	s_ashr_i32 s19, s18, 31
	s_lshl_b64 s[20:21], s[18:19], 11
	v_lshl_add_u64 v[6:7], v[8:9], 0, s[20:21]
	global_load_dwordx2 v[6:7], v[6:7], off offset:1024 nt
	s_add_i32 s18, s18, s14
	s_ashr_i32 s19, s18, 31
	s_lshl_b64 s[18:19], s[18:19], 2
	s_add_u32 s18, s26, s18
	s_addc_u32 s19, s27, s19
	s_or_b32 s76, s4, 17
	s_cmp_lt_u32 s76, s23
	global_load_dword v44, v97, s[18:19]
	s_waitcnt vmcnt(1)
	v_cndmask_b32_e32 v126, 0, v6, vcc
	v_cndmask_b32_e32 v47, 0, v7, vcc
	s_cselect_b64 vcc, -1, 0
	s_and_b64 s[18:19], vcc, exec
	s_cselect_b32 s18, s76, s4
	s_ashr_i32 s19, s18, 31
	s_lshl_b64 s[20:21], s[18:19], 11
	v_lshl_add_u64 v[6:7], v[8:9], 0, s[20:21]
	global_load_dwordx2 v[6:7], v[6:7], off offset:1024 nt
	s_add_i32 s18, s18, s14
	s_ashr_i32 s19, s18, 31
	s_lshl_b64 s[18:19], s[18:19], 2
	s_add_u32 s18, s26, s18
	s_addc_u32 s19, s27, s19
	s_or_b32 s75, s4, 18
	s_cmp_lt_u32 s75, s23
	global_load_dword v42, v97, s[18:19]
	s_waitcnt vmcnt(1)
	v_cndmask_b32_e32 v125, 0, v6, vcc
	v_cndmask_b32_e32 v45, 0, v7, vcc
	s_cselect_b64 vcc, -1, 0
	s_and_b64 s[18:19], vcc, exec
	s_cselect_b32 s18, s75, s4
	s_ashr_i32 s19, s18, 31
	s_lshl_b64 s[20:21], s[18:19], 11
	v_lshl_add_u64 v[6:7], v[8:9], 0, s[20:21]
	global_load_dwordx2 v[6:7], v[6:7], off offset:1024 nt
	s_add_i32 s18, s18, s14
	s_ashr_i32 s19, s18, 31
	s_lshl_b64 s[18:19], s[18:19], 2
	s_add_u32 s18, s26, s18
	s_addc_u32 s19, s27, s19
	s_or_b32 s74, s4, 19
	s_cmp_lt_u32 s74, s23
	global_load_dword v40, v97, s[18:19]
	s_waitcnt vmcnt(1)
	v_cndmask_b32_e32 v124, 0, v6, vcc
	v_cndmask_b32_e32 v43, 0, v7, vcc
	s_cselect_b64 vcc, -1, 0
	s_and_b64 s[18:19], vcc, exec
	s_cselect_b32 s18, s74, s4
	s_ashr_i32 s19, s18, 31
	s_lshl_b64 s[20:21], s[18:19], 11
	v_lshl_add_u64 v[6:7], v[8:9], 0, s[20:21]
	global_load_dwordx2 v[6:7], v[6:7], off offset:1024 nt
	s_add_i32 s18, s18, s14
	s_ashr_i32 s19, s18, 31
	s_lshl_b64 s[18:19], s[18:19], 2
	s_add_u32 s18, s26, s18
	s_addc_u32 s19, s27, s19
	s_or_b32 s71, s4, 20
	s_cmp_lt_u32 s71, s23
	global_load_dword v34, v97, s[18:19]
	s_waitcnt vmcnt(1)
	v_cndmask_b32_e32 v123, 0, v6, vcc
	v_cndmask_b32_e32 v41, 0, v7, vcc
	s_cselect_b64 vcc, -1, 0
	s_and_b64 s[18:19], vcc, exec
	s_cselect_b32 s18, s71, s4
	s_ashr_i32 s19, s18, 31
	s_lshl_b64 s[20:21], s[18:19], 11
	v_lshl_add_u64 v[6:7], v[8:9], 0, s[20:21]
	global_load_dwordx2 v[6:7], v[6:7], off offset:1024 nt
	s_add_i32 s18, s18, s14
	s_ashr_i32 s19, s18, 31
	s_lshl_b64 s[18:19], s[18:19], 2
	s_add_u32 s18, s26, s18
	s_addc_u32 s19, s27, s19
	s_or_b32 s73, s4, 21
	s_cmp_lt_u32 s73, s23
	global_load_dword v38, v97, s[18:19]
	s_waitcnt vmcnt(1)
	v_cndmask_b32_e32 v37, 0, v6, vcc
	v_cndmask_b32_e32 v35, 0, v7, vcc
	s_cselect_b64 vcc, -1, 0
	s_and_b64 s[18:19], vcc, exec
	s_cselect_b32 s18, s73, s4
	s_ashr_i32 s19, s18, 31
	s_lshl_b64 s[20:21], s[18:19], 11
	v_lshl_add_u64 v[6:7], v[8:9], 0, s[20:21]
	global_load_dwordx2 v[6:7], v[6:7], off offset:1024 nt
	s_add_i32 s18, s18, s14
	s_ashr_i32 s19, s18, 31
	s_lshl_b64 s[18:19], s[18:19], 2
	s_add_u32 s18, s26, s18
	s_addc_u32 s19, s27, s19
	s_or_b32 s72, s4, 22
	s_cmp_lt_u32 s72, s23
	global_load_dword v36, v97, s[18:19]
	s_waitcnt vmcnt(1)
	v_cndmask_b32_e32 v122, 0, v6, vcc
	v_cndmask_b32_e32 v39, 0, v7, vcc
	s_cselect_b64 vcc, -1, 0
	s_and_b64 s[18:19], vcc, exec
	s_cselect_b32 s18, s72, s4
	s_ashr_i32 s19, s18, 31
	s_lshl_b64 s[20:21], s[18:19], 11
	v_lshl_add_u64 v[6:7], v[8:9], 0, s[20:21]
	global_load_dwordx2 v[6:7], v[6:7], off offset:1024 nt
	s_add_i32 s18, s18, s14
	s_ashr_i32 s19, s18, 31
	s_lshl_b64 s[18:19], s[18:19], 2
	s_add_u32 s18, s26, s18
	s_addc_u32 s19, s27, s19
	s_or_b32 s69, s4, 23
	s_cmp_lt_u32 s69, s23
	global_load_dword v32, v97, s[18:19]
	s_waitcnt vmcnt(1)
	v_cndmask_b32_e32 v121, 0, v6, vcc
	v_cndmask_b32_e32 v120, 0, v7, vcc
	s_cselect_b64 vcc, -1, 0
	s_and_b64 s[18:19], vcc, exec
	s_cselect_b32 s18, s69, s4
	s_ashr_i32 s19, s18, 31
	s_lshl_b64 s[20:21], s[18:19], 11
	v_lshl_add_u64 v[6:7], v[8:9], 0, s[20:21]
	global_load_dwordx2 v[6:7], v[6:7], off offset:1024 nt
	s_add_i32 s18, s18, s14
	s_ashr_i32 s19, s18, 31
	s_lshl_b64 s[18:19], s[18:19], 2
	s_add_u32 s18, s26, s18
	s_addc_u32 s19, s27, s19
	s_or_b32 s68, s4, 24
	s_cmp_lt_u32 s68, s23
	global_load_dword v30, v97, s[18:19]
	s_waitcnt vmcnt(1)
	v_cndmask_b32_e32 v119, 0, v6, vcc
	v_cndmask_b32_e32 v33, 0, v7, vcc
	s_cselect_b64 vcc, -1, 0
	s_and_b64 s[18:19], vcc, exec
	s_cselect_b32 s18, s68, s4
	s_ashr_i32 s19, s18, 31
	s_lshl_b64 s[20:21], s[18:19], 11
	v_lshl_add_u64 v[6:7], v[8:9], 0, s[20:21]
	global_load_dwordx2 v[6:7], v[6:7], off offset:1024 nt
	s_add_i32 s18, s18, s14
	s_ashr_i32 s19, s18, 31
	s_lshl_b64 s[18:19], s[18:19], 2
	s_add_u32 s18, s26, s18
	s_addc_u32 s19, s27, s19
	s_or_b32 s63, s4, 25
	s_cmp_lt_u32 s63, s23
	global_load_dword v28, v97, s[18:19]
	s_waitcnt vmcnt(1)
	v_cndmask_b32_e32 v118, 0, v6, vcc
	v_cndmask_b32_e32 v31, 0, v7, vcc
	s_cselect_b64 vcc, -1, 0
	s_and_b64 s[18:19], vcc, exec
	s_cselect_b32 s18, s63, s4
	s_ashr_i32 s19, s18, 31
	s_lshl_b64 s[20:21], s[18:19], 11
	v_lshl_add_u64 v[6:7], v[8:9], 0, s[20:21]
	global_load_dwordx2 v[6:7], v[6:7], off offset:1024 nt
	s_add_i32 s18, s18, s14
	s_ashr_i32 s19, s18, 31
	s_lshl_b64 s[18:19], s[18:19], 2
	s_add_u32 s18, s26, s18
	s_addc_u32 s19, s27, s19
	s_or_b32 s62, s4, 26
	s_cmp_lt_u32 s62, s23
	global_load_dword v26, v97, s[18:19]
	s_waitcnt vmcnt(1)
	v_cndmask_b32_e32 v117, 0, v6, vcc
	v_cndmask_b32_e32 v29, 0, v7, vcc
	s_cselect_b64 vcc, -1, 0
	s_and_b64 s[18:19], vcc, exec
	s_cselect_b32 s18, s62, s4
	s_ashr_i32 s19, s18, 31
	s_lshl_b64 s[20:21], s[18:19], 11
	v_lshl_add_u64 v[6:7], v[8:9], 0, s[20:21]
	global_load_dwordx2 v[6:7], v[6:7], off offset:1024 nt
	s_add_i32 s18, s18, s14
	s_ashr_i32 s19, s18, 31
	s_lshl_b64 s[18:19], s[18:19], 2
	s_add_u32 s18, s26, s18
	s_addc_u32 s19, s27, s19
	s_or_b32 s34, s4, 27
	s_cmp_lt_u32 s34, s23
	global_load_dword v24, v97, s[18:19]
	s_waitcnt vmcnt(1)
	v_cndmask_b32_e32 v116, 0, v6, vcc
	v_cndmask_b32_e32 v27, 0, v7, vcc
	s_cselect_b64 vcc, -1, 0
	s_and_b64 s[18:19], vcc, exec
	s_cselect_b32 s18, s34, s4
	s_ashr_i32 s19, s18, 31
	s_lshl_b64 s[20:21], s[18:19], 11
	v_lshl_add_u64 v[6:7], v[8:9], 0, s[20:21]
	global_load_dwordx2 v[6:7], v[6:7], off offset:1024 nt
	s_add_i32 s18, s18, s14
	s_ashr_i32 s19, s18, 31
	s_lshl_b64 s[18:19], s[18:19], 2
	s_add_u32 s18, s26, s18
	s_addc_u32 s19, s27, s19
	s_or_b32 s20, s4, 28
	s_cmp_lt_u32 s20, s23
	global_load_dword v20, v97, s[18:19]
	s_waitcnt vmcnt(1)
	v_cndmask_b32_e32 v115, 0, v6, vcc
	v_cndmask_b32_e32 v25, 0, v7, vcc
	s_cselect_b64 vcc, -1, 0
	s_and_b64 s[18:19], vcc, exec
	s_cselect_b32 s18, s20, s4
	s_ashr_i32 s19, s18, 31
	s_lshl_b64 s[66:67], s[18:19], 11
	v_lshl_add_u64 v[6:7], v[8:9], 0, s[66:67]
	global_load_dwordx2 v[6:7], v[6:7], off offset:1024 nt
	s_add_i32 s18, s18, s14
	s_ashr_i32 s19, s18, 31
	s_lshl_b64 s[18:19], s[18:19], 2
	s_add_u32 s18, s26, s18
	s_addc_u32 s19, s27, s19
	s_or_b32 s21, s4, 29
	s_cmp_lt_u32 s21, s23
	global_load_dword v22, v97, s[18:19]
	s_waitcnt vmcnt(1)
	v_cndmask_b32_e32 v23, 0, v6, vcc
	v_cndmask_b32_e32 v21, 0, v7, vcc
	s_cselect_b64 vcc, -1, 0
	s_and_b64 s[18:19], vcc, exec
	s_cselect_b32 s18, s21, s4
	s_ashr_i32 s19, s18, 31
	s_lshl_b64 s[66:67], s[18:19], 11
	v_lshl_add_u64 v[6:7], v[8:9], 0, s[66:67]
	global_load_dwordx2 v[6:7], v[6:7], off offset:1024 nt
	s_add_i32 s18, s18, s14
	s_ashr_i32 s19, s18, 31
	s_lshl_b64 s[18:19], s[18:19], 2
	s_add_u32 s18, s26, s18
	s_addc_u32 s19, s27, s19
	s_or_b32 s15, s4, 30
	s_cmp_lt_u32 s15, s23
	global_load_dword v18, v97, s[18:19]
	s_waitcnt vmcnt(1)
	v_cndmask_b32_e32 v114, 0, v6, vcc
	v_cndmask_b32_e32 v113, 0, v7, vcc
	s_cselect_b64 vcc, -1, 0
	s_and_b64 s[18:19], vcc, exec
	s_cselect_b32 s18, s15, s4
	s_ashr_i32 s19, s18, 31
	s_lshl_b64 s[66:67], s[18:19], 11
	v_lshl_add_u64 v[6:7], v[8:9], 0, s[66:67]
	global_load_dwordx2 v[6:7], v[6:7], off offset:1024 nt
	s_add_i32 s18, s18, s14
	s_ashr_i32 s19, s18, 31
	s_lshl_b64 s[18:19], s[18:19], 2
	s_add_u32 s18, s26, s18
	s_addc_u32 s19, s27, s19
	s_or_b32 s5, s4, 31
	s_cmp_lt_u32 s5, s23
	global_load_dword v14, v97, s[18:19]
	s_waitcnt vmcnt(1)
	v_cndmask_b32_e32 v112, 0, v6, vcc
	v_cndmask_b32_e32 v111, 0, v7, vcc
	s_cselect_b64 vcc, -1, 0
	s_and_b64 s[18:19], vcc, exec
	s_cselect_b32 s18, s5, s4
	s_ashr_i32 s19, s18, 31
	s_lshl_b64 s[66:67], s[18:19], 11
	v_lshl_add_u64 v[6:7], v[8:9], 0, s[66:67]
	global_load_dwordx2 v[6:7], v[6:7], off offset:1024 nt
	s_add_i32 s18, s18, s14
	s_ashr_i32 s19, s18, 31
	s_lshl_b64 s[18:19], s[18:19], 2
	s_add_u32 s18, s26, s18
	s_addc_u32 s19, s27, s19
	s_add_i32 s70, s4, 32
	s_cmp_lt_u32 s70, s23
	global_load_dword v12, v97, s[18:19]
	s_waitcnt vmcnt(1)
	v_cndmask_b32_e32 v19, 0, v6, vcc
	v_cndmask_b32_e32 v15, 0, v7, vcc
	s_cselect_b64 vcc, -1, 0
	s_and_b64 s[18:19], vcc, exec
	s_cselect_b32 s18, s70, s4
	s_ashr_i32 s19, s18, 31
	s_lshl_b64 s[66:67], s[18:19], 11
	v_lshl_add_u64 v[6:7], v[8:9], 0, s[66:67]
	global_load_dwordx2 v[6:7], v[6:7], off offset:1024 nt
	s_add_i32 s18, s18, s14
	s_ashr_i32 s19, s18, 31
	s_lshl_b64 s[18:19], s[18:19], 2
	s_add_u32 s18, s26, s18
	s_addc_u32 s19, s27, s19
	s_add_i32 s67, s4, 33
	s_cmp_lt_u32 s67, s23
	global_load_dword v10, v97, s[18:19]
	s_waitcnt vmcnt(1)
	v_cndmask_b32_e32 v110, 0, v6, vcc
	v_cndmask_b32_e32 v109, 0, v7, vcc
	s_cselect_b64 vcc, -1, 0
	s_and_b64 s[18:19], vcc, exec
	s_cselect_b32 s18, s67, s4
	s_ashr_i32 s19, s18, 31
	s_lshl_b64 s[96:97], s[18:19], 11
	v_lshl_add_u64 v[6:7], v[8:9], 0, s[96:97]
	global_load_dwordx2 v[6:7], v[6:7], off offset:1024 nt
	s_add_i32 s18, s18, s14
	s_ashr_i32 s19, s18, 31
	s_lshl_b64 s[18:19], s[18:19], 2
	s_add_u32 s18, s26, s18
	s_addc_u32 s19, s27, s19
	s_add_i32 s66, s4, 34
	s_cmp_lt_u32 s66, s23
	s_waitcnt vmcnt(0)
	v_cndmask_b32_e32 v13, 0, v6, vcc
	v_cndmask_b32_e32 v7, 0, v7, vcc
	s_cselect_b64 vcc, -1, 0
	global_load_dword v6, v97, s[18:19]
	s_and_b64 s[18:19], vcc, exec
	s_cselect_b32 s18, s66, s4
	s_ashr_i32 s19, s18, 31
	s_lshl_b64 s[96:97], s[18:19], 11
	v_lshl_add_u64 v[8:9], v[8:9], 0, s[96:97]
	global_load_dwordx2 v[8:9], v[8:9], off offset:1024 nt
	s_add_i32 s18, s18, s14
	s_ashr_i32 s19, s18, 31
	s_lshl_b64 s[18:19], s[18:19], 2
	s_add_u32 s18, s26, s18
	s_addc_u32 s19, s27, s19
	s_waitcnt vmcnt(0)
	v_cndmask_b32_e32 v108, 0, v8, vcc
	global_load_dword v8, v97, s[18:19]
	s_lshl_b64 s[18:19], s[6:7], 11
	s_add_u32 s18, s24, s18
	s_addc_u32 s19, s25, s19
	v_lshl_add_u64 v[16:17], s[18:19], 0, v[96:97]
	v_lshl_add_u64 v[4:5], v[16:17], 0, s[30:31]
	s_max_i32 s7, s4, 4
	s_min_i32 s30, s88, s23
	s_sub_i32 s7, s30, s7
	s_add_i32 s7, s7, 4
	v_cvt_f32_i32_e32 v68, s7
	v_cndmask_b32_e32 v9, 0, v9, vcc
	s_max_i32 s7, s91, 4
	s_min_i32 s30, s86, s23
	v_div_scale_f32 v69, s[96:97], v68, v68, 1.0
	v_rcp_f32_e32 v71, v69
	s_sub_i32 s7, s30, s7
	s_add_i32 s7, s7, 4
	s_movk_i32 s91, 0x2000
	v_fma_f32 v72, -v69, v71, 1.0
	v_fmac_f32_e32 v71, v72, v71
	v_div_scale_f32 v72, vcc, 1.0, v68, 1.0
	v_mul_f32_e32 v73, v72, v71
	v_fma_f32 v75, -v69, v73, v72
	v_fmac_f32_e32 v73, v75, v71
	v_fma_f32 v69, -v69, v73, v72
	v_div_fmas_f32 v69, v69, v71, v73
	v_div_fixup_f32 v68, v69, v68, 1.0
	v_pk_fma_f32 v[72:73], v[68:69], v[142:143], v[98:99] op_sel_hi:[0,1,1] neg_lo:[0,0,1] neg_hi:[0,0,1]
	v_cvt_f32_i32_e32 v71, s7
	v_pk_fma_f32 v[68:69], v[68:69], v[76:77], v[86:87] op_sel_hi:[0,1,1] neg_lo:[0,0,1] neg_hi:[0,0,1]
	v_pk_mul_f32 v[72:73], v[0:1], v[72:73]
	v_pk_mul_f32 v[68:69], v[2:3], v[68:69]
	v_cvt_pk_bf16_f32 v72, v72, v73
	v_pk_fma_f32 v[140:141], v[74:75], v[148:149], v[146:147] op_sel_hi:[0,1,1] neg_lo:[0,0,1] neg_hi:[0,0,1]
	v_cvt_pk_bf16_f32 v73, v68, v69
	global_store_dwordx2 v96, v[72:73], s[18:19] offset:1024
	v_pk_mul_f32 v[68:69], v[74:75], v[150:151] op_sel_hi:[0,1]
	v_pk_mul_f32 v[72:73], v[74:75], v[148:149] op_sel_hi:[0,1]
	v_pk_fma_f32 v[74:75], v[74:75], v[150:151], v[144:145] op_sel_hi:[0,1,1] neg_lo:[0,0,1] neg_hi:[0,0,1]
	v_pk_add_f32 v[76:77], v[76:77], v[74:75]
	v_div_scale_f32 v74, s[96:97], v71, v71, 1.0
	v_rcp_f32_e32 v75, v74
	v_pk_add_f32 v[140:141], v[142:143], v[140:141]
	s_max_i32 s7, s90, 4
	v_lshlrev_b32_e32 v144, 16, v81
	v_fma_f32 v79, -v74, v75, 1.0
	v_fmac_f32_e32 v75, v79, v75
	v_div_scale_f32 v79, vcc, 1.0, v71, 1.0
	v_mul_f32_e32 v80, v79, v75
	v_fma_f32 v142, -v74, v80, v79
	v_fmac_f32_e32 v80, v142, v75
	v_fma_f32 v74, -v74, v80, v79
	v_div_fmas_f32 v74, v74, v75, v80
	v_div_fixup_f32 v74, v74, v71, 1.0
	v_pk_fma_f32 v[142:143], v[74:75], v[140:141], v[94:95] op_sel_hi:[0,1,1] neg_lo:[0,0,1] neg_hi:[0,0,1]
	v_pk_fma_f32 v[74:75], v[74:75], v[76:77], v[88:89] op_sel_hi:[0,1,1] neg_lo:[0,0,1] neg_hi:[0,0,1]
	v_pk_mul_f32 v[142:143], v[0:1], v[142:143]
	v_pk_mul_f32 v[74:75], v[2:3], v[74:75]
	v_cvt_pk_bf16_f32 v142, v142, v143
	v_and_b32_e32 v145, 0xffff0000, v81
	v_cvt_pk_bf16_f32 v143, v74, v75
	global_store_dwordx2 v96, v[142:143], s[18:19] offset:3072
	s_min_i32 s18, s87, s23
	s_sub_i32 s7, s18, s7
	s_add_i32 s7, s7, 4
	v_cvt_f32_i32_e32 v71, s7
	v_lshlrev_b32_e32 v142, 16, v137
	v_and_b32_e32 v143, 0xffff0000, v137
	v_pk_mul_f32 v[74:75], v[78:79], v[144:145] op_sel_hi:[0,1]
	v_pk_mul_f32 v[80:81], v[78:79], v[142:143] op_sel_hi:[0,1]
	v_pk_fma_f32 v[106:107], v[78:79], v[142:143], v[106:107] op_sel_hi:[0,1,1] neg_lo:[0,0,1] neg_hi:[0,0,1]
	v_pk_fma_f32 v[78:79], v[78:79], v[144:145], v[104:105] op_sel_hi:[0,1,1] neg_lo:[0,0,1] neg_hi:[0,0,1]
	v_pk_add_f32 v[104:105], v[76:77], v[78:79]
	v_div_scale_f32 v76, s[18:19], v71, v71, 1.0
	v_rcp_f32_e32 v77, v76
	v_pk_add_f32 v[106:107], v[140:141], v[106:107]
	s_max_i32 s7, s89, 4
	s_min_i32 s18, s85, s23
	v_fma_f32 v78, -v76, v77, 1.0
	v_fmac_f32_e32 v77, v78, v77
	v_div_scale_f32 v78, vcc, 1.0, v71, 1.0
	v_mul_f32_e32 v79, v78, v77
	v_fma_f32 v96, -v76, v79, v78
	v_fmac_f32_e32 v79, v96, v77
	v_fma_f32 v76, -v76, v79, v78
	v_div_fmas_f32 v76, v76, v77, v79
	v_div_fixup_f32 v76, v76, v71, 1.0
	v_pk_fma_f32 v[78:79], v[76:77], v[106:107], v[92:93] op_sel_hi:[0,1,1] neg_lo:[0,0,1] neg_hi:[0,0,1]
	v_pk_fma_f32 v[76:77], v[76:77], v[104:105], v[90:91] op_sel_hi:[0,1,1] neg_lo:[0,0,1] neg_hi:[0,0,1]
	v_pk_mul_f32 v[78:79], v[0:1], v[78:79]
	v_add_co_u32_e32 v140, vcc, s92, v16
	v_pk_mul_f32 v[76:77], v[2:3], v[76:77]
	v_cvt_pk_bf16_f32 v78, v78, v79
	s_nop 0
	v_addc_co_u32_e32 v141, vcc, 0, v17, vcc
	v_cvt_pk_bf16_f32 v79, v76, v77
	v_lshlrev_b32_e32 v142, 16, v139
	v_and_b32_e32 v143, 0xffff0000, v139
	v_lshlrev_b32_e32 v144, 16, v138
	v_and_b32_e32 v145, 0xffff0000, v138
	s_sub_i32 s7, s18, s7
	global_store_dwordx2 v[140:141], v[78:79], off offset:1024
	v_pk_mul_f32 v[76:77], v[70:71], v[144:145] op_sel_hi:[0,1]
	v_pk_mul_f32 v[78:79], v[70:71], v[142:143] op_sel_hi:[0,1]
	v_pk_fma_f32 v[102:103], v[70:71], v[142:143], v[102:103] op_sel_hi:[0,1,1] neg_lo:[0,0,1] neg_hi:[0,0,1]
	v_pk_fma_f32 v[70:71], v[70:71], v[144:145], v[82:83] op_sel_hi:[0,1,1] neg_lo:[0,0,1] neg_hi:[0,0,1]
	s_add_i32 s7, s7, 4
	v_pk_add_f32 v[104:105], v[104:105], v[70:71]
	v_cvt_f32_i32_e32 v70, s7
	v_pk_add_f32 v[102:103], v[106:107], v[102:103]
	s_max_i32 s7, s88, 4
	v_and_b32_e32 v107, 0xffff0000, v136
	v_div_scale_f32 v71, s[18:19], v70, v70, 1.0
	v_rcp_f32_e32 v82, v71
	s_min_i32 s18, s35, s23
	s_sub_i32 s7, s18, s7
	v_and_b32_e32 v137, 0xffff0000, v135
	v_fma_f32 v83, -v71, v82, 1.0
	v_fmac_f32_e32 v82, v83, v82
	v_div_scale_f32 v83, vcc, 1.0, v70, 1.0
	v_mul_f32_e32 v96, v83, v82
	v_fma_f32 v106, -v71, v96, v83
	v_fmac_f32_e32 v96, v106, v82
	v_fma_f32 v71, -v71, v96, v83
	v_div_fmas_f32 v71, v71, v82, v96
	v_div_fixup_f32 v70, v71, v70, 1.0
	v_pk_fma_f32 v[82:83], v[70:71], v[102:103], v[66:67] op_sel_hi:[0,1,1] neg_lo:[0,0,1] neg_hi:[0,0,1]
	v_pk_fma_f32 v[70:71], v[70:71], v[104:105], v[62:63] op_sel_hi:[0,1,1] neg_lo:[0,0,1] neg_hi:[0,0,1]
	v_pk_mul_f32 v[82:83], v[0:1], v[82:83]
	v_pk_mul_f32 v[70:71], v[2:3], v[70:71]
	v_cvt_pk_bf16_f32 v82, v82, v83
	v_lshlrev_b32_e32 v106, 16, v136
	v_cvt_pk_bf16_f32 v83, v70, v71
	v_lshlrev_b32_e32 v136, 16, v135
	s_add_i32 s7, s7, 4
	global_store_dwordx2 v[140:141], v[82:83], off offset:3072
	v_pk_mul_f32 v[70:71], v[64:65], v[136:137] op_sel_hi:[0,1]
	v_pk_mul_f32 v[82:83], v[64:65], v[106:107] op_sel_hi:[0,1]
	v_pk_fma_f32 v[100:101], v[64:65], v[106:107], v[100:101] op_sel_hi:[0,1,1] neg_lo:[0,0,1] neg_hi:[0,0,1]
	v_pk_fma_f32 v[84:85], v[64:65], v[136:137], v[84:85] op_sel_hi:[0,1,1] neg_lo:[0,0,1] neg_hi:[0,0,1]
	v_cvt_f32_i32_e32 v64, s7
	v_pk_add_f32 v[104:105], v[104:105], v[84:85]
	v_pk_add_f32 v[100:101], v[102:103], v[100:101]
	s_max_i32 s7, s86, 4
	v_div_scale_f32 v84, s[18:19], v64, v64, 1.0
	v_rcp_f32_e32 v85, v84
	s_min_i32 s18, s84, s23
	s_sub_i32 s7, s18, s7
	v_lshlrev_b32_e32 v106, 16, v134
	v_fma_f32 v96, -v84, v85, 1.0
	v_fmac_f32_e32 v85, v96, v85
	v_div_scale_f32 v96, vcc, 1.0, v64, 1.0
	v_mul_f32_e32 v102, v96, v85
	v_fma_f32 v103, -v84, v102, v96
	v_fmac_f32_e32 v102, v103, v85
	v_fma_f32 v84, -v84, v102, v96
	v_div_fmas_f32 v84, v84, v85, v102
	v_div_fixup_f32 v64, v84, v64, 1.0
	v_pk_fma_f32 v[84:85], v[64:65], v[100:101], v[72:73] op_sel_hi:[0,1,1] neg_lo:[0,0,1] neg_hi:[0,0,1]
	v_pk_fma_f32 v[102:103], v[64:65], v[104:105], v[68:69] op_sel_hi:[0,1,1] neg_lo:[0,0,1] neg_hi:[0,0,1]
	v_pk_mul_f32 v[102:103], v[2:3], v[102:103]
	v_pk_mul_f32 v[84:85], v[0:1], v[84:85]
	v_and_b32_e32 v107, 0xffff0000, v134
	v_cvt_pk_bf16_f32 v84, v84, v85
	v_cvt_pk_bf16_f32 v85, v102, v103
	v_add_co_u32_e32 v102, vcc, s91, v16
	v_lshlrev_b32_e32 v134, 16, v65
	s_nop 0
	v_addc_co_u32_e32 v103, vcc, 0, v17, vcc
	v_and_b32_e32 v135, 0xffff0000, v65
	s_add_i32 s7, s7, 4
	global_store_dwordx2 v[102:103], v[84:85], off offset:1024
	v_pk_mul_f32 v[64:65], v[60:61], v[134:135] op_sel_hi:[0,1]
	v_pk_mul_f32 v[84:85], v[60:61], v[106:107] op_sel_hi:[0,1]
	v_pk_fma_f32 v[98:99], v[60:61], v[106:107], v[98:99] op_sel_hi:[0,1,1] neg_lo:[0,0,1] neg_hi:[0,0,1]
	v_pk_fma_f32 v[86:87], v[60:61], v[134:135], v[86:87] op_sel_hi:[0,1,1] neg_lo:[0,0,1] neg_hi:[0,0,1]
	v_cvt_f32_i32_e32 v60, s7
	v_pk_add_f32 v[104:105], v[104:105], v[86:87]
	v_pk_add_f32 v[98:99], v[100:101], v[98:99]
	s_max_i32 s7, s87, 4
	v_div_scale_f32 v86, s[18:19], v60, v60, 1.0
	v_rcp_f32_e32 v87, v86
	s_min_i32 s18, s83, s23
	s_sub_i32 s7, s18, s7
	s_add_i32 s7, s7, 4
	v_fma_f32 v96, -v86, v87, 1.0
	v_fmac_f32_e32 v87, v96, v87
	v_div_scale_f32 v96, vcc, 1.0, v60, 1.0
	v_mul_f32_e32 v100, v96, v87
	v_fma_f32 v101, -v86, v100, v96
	v_fmac_f32_e32 v100, v101, v87
	v_fma_f32 v86, -v86, v100, v96
	v_div_fmas_f32 v86, v86, v87, v100
	v_div_fixup_f32 v60, v86, v60, 1.0
	v_pk_fma_f32 v[86:87], v[60:61], v[98:99], v[80:81] op_sel_hi:[0,1,1] neg_lo:[0,0,1] neg_hi:[0,0,1]
	v_pk_fma_f32 v[100:101], v[60:61], v[104:105], v[74:75] op_sel_hi:[0,1,1] neg_lo:[0,0,1] neg_hi:[0,0,1]
	v_pk_mul_f32 v[100:101], v[2:3], v[100:101]
	v_pk_mul_f32 v[86:87], v[0:1], v[86:87]
	s_movk_i32 s97, 0x800
	v_cvt_pk_bf16_f32 v86, v86, v87
	v_cvt_pk_bf16_f32 v87, v100, v101
	global_store_dwordx2 v[102:103], v[86:87], off offset:3072
	v_lshlrev_b32_e32 v100, 16, v133
	v_and_b32_e32 v101, 0xffff0000, v133
	v_lshlrev_b32_e32 v102, 16, v61
	v_and_b32_e32 v103, 0xffff0000, v61
	v_pk_mul_f32 v[60:61], v[58:59], v[102:103] op_sel_hi:[0,1]
	v_pk_mul_f32 v[86:87], v[58:59], v[100:101] op_sel_hi:[0,1]
	v_pk_fma_f32 v[94:95], v[58:59], v[100:101], v[94:95] op_sel_hi:[0,1,1] neg_lo:[0,0,1] neg_hi:[0,0,1]
	v_pk_fma_f32 v[88:89], v[58:59], v[102:103], v[88:89] op_sel_hi:[0,1,1] neg_lo:[0,0,1] neg_hi:[0,0,1]
	v_cvt_f32_i32_e32 v58, s7
	v_pk_add_f32 v[100:101], v[104:105], v[88:89]
	v_pk_add_f32 v[94:95], v[98:99], v[94:95]
	s_movk_i32 s7, 0x3000
	v_div_scale_f32 v88, s[18:19], v58, v58, 1.0
	v_rcp_f32_e32 v89, v88
	s_min_i32 s18, s81, s23
	v_lshlrev_b32_e32 v102, 16, v132
	v_and_b32_e32 v103, 0xffff0000, v132
	v_fma_f32 v96, -v88, v89, 1.0
	v_fmac_f32_e32 v89, v96, v89
	v_div_scale_f32 v96, vcc, 1.0, v58, 1.0
	v_mul_f32_e32 v98, v96, v89
	v_fma_f32 v99, -v88, v98, v96
	v_fmac_f32_e32 v98, v99, v89
	v_fma_f32 v88, -v88, v98, v96
	v_div_fmas_f32 v88, v88, v89, v98
	v_div_fixup_f32 v58, v88, v58, 1.0
	v_pk_fma_f32 v[88:89], v[58:59], v[94:95], v[78:79] op_sel_hi:[0,1,1] neg_lo:[0,0,1] neg_hi:[0,0,1]
	v_pk_fma_f32 v[98:99], v[58:59], v[100:101], v[76:77] op_sel_hi:[0,1,1] neg_lo:[0,0,1] neg_hi:[0,0,1]
	v_pk_mul_f32 v[98:99], v[2:3], v[98:99]
	v_pk_mul_f32 v[88:89], v[0:1], v[88:89]
	v_lshlrev_b32_e32 v104, 16, v59
	v_cvt_pk_bf16_f32 v88, v88, v89
	v_cvt_pk_bf16_f32 v89, v98, v99
	v_add_co_u32_e32 v98, vcc, s7, v16
	s_max_i32 s7, s85, 4
	s_sub_i32 s7, s18, s7
	v_addc_co_u32_e32 v99, vcc, 0, v17, vcc
	v_and_b32_e32 v105, 0xffff0000, v59
	s_add_i32 s7, s7, 4
	global_store_dwordx2 v[98:99], v[88:89], off offset:1024
	v_pk_mul_f32 v[58:59], v[54:55], v[104:105] op_sel_hi:[0,1]
	v_pk_mul_f32 v[88:89], v[54:55], v[102:103] op_sel_hi:[0,1]
	v_pk_fma_f32 v[92:93], v[54:55], v[102:103], v[92:93] op_sel_hi:[0,1,1] neg_lo:[0,0,1] neg_hi:[0,0,1]
	v_pk_fma_f32 v[90:91], v[54:55], v[104:105], v[90:91] op_sel_hi:[0,1,1] neg_lo:[0,0,1] neg_hi:[0,0,1]
	v_cvt_f32_i32_e32 v54, s7
	v_pk_add_f32 v[100:101], v[100:101], v[90:91]
	v_pk_add_f32 v[92:93], v[94:95], v[92:93]
	s_max_i32 s7, s35, 4
	v_div_scale_f32 v90, s[18:19], v54, v54, 1.0
	v_rcp_f32_e32 v91, v90
	s_min_i32 s18, s79, s23
	s_sub_i32 s7, s18, s7
	s_add_i32 s7, s7, 4
	v_fma_f32 v94, -v90, v91, 1.0
	v_fmac_f32_e32 v91, v94, v91
	v_div_scale_f32 v94, vcc, 1.0, v54, 1.0
	v_mul_f32_e32 v95, v94, v91
	v_fma_f32 v96, -v90, v95, v94
	v_fmac_f32_e32 v95, v96, v91
	v_fma_f32 v90, -v90, v95, v94
	v_div_fmas_f32 v90, v90, v91, v95
	v_div_fixup_f32 v54, v90, v54, 1.0
	v_pk_fma_f32 v[90:91], v[54:55], v[92:93], v[82:83] op_sel_hi:[0,1,1] neg_lo:[0,0,1] neg_hi:[0,0,1]
	v_pk_fma_f32 v[94:95], v[54:55], v[100:101], v[70:71] op_sel_hi:[0,1,1] neg_lo:[0,0,1] neg_hi:[0,0,1]
	v_pk_mul_f32 v[94:95], v[2:3], v[94:95]
	v_pk_mul_f32 v[90:91], v[0:1], v[90:91]
	v_readlane_b32 s96, v255, 13
	v_cvt_pk_bf16_f32 v90, v90, v91
	v_cvt_pk_bf16_f32 v91, v94, v95
	global_store_dwordx2 v[98:99], v[90:91], off offset:3072
	v_lshlrev_b32_e32 v94, 16, v57
	v_and_b32_e32 v95, 0xffff0000, v57
	v_lshlrev_b32_e32 v98, 16, v55
	v_and_b32_e32 v99, 0xffff0000, v55
	v_pk_mul_f32 v[54:55], v[50:51], v[98:99] op_sel_hi:[0,1]
	v_pk_mul_f32 v[90:91], v[50:51], v[94:95] op_sel_hi:[0,1]
	v_pk_fma_f32 v[66:67], v[50:51], v[94:95], v[66:67] op_sel_hi:[0,1,1] neg_lo:[0,0,1] neg_hi:[0,0,1]
	v_pk_fma_f32 v[62:63], v[50:51], v[98:99], v[62:63] op_sel_hi:[0,1,1] neg_lo:[0,0,1] neg_hi:[0,0,1]
	v_cvt_f32_i32_e32 v50, s7
	v_pk_add_f32 v[92:93], v[92:93], v[66:67]
	s_max_i32 s7, s84, 4
	v_pk_add_f32 v[62:63], v[100:101], v[62:63]
	v_div_scale_f32 v57, s[18:19], v50, v50, 1.0
	v_rcp_f32_e32 v66, v57
	s_min_i32 s18, s82, s23
	s_sub_i32 s7, s18, s7
	s_add_i32 s7, s7, 4
	v_fma_f32 v67, -v57, v66, 1.0
	v_fmac_f32_e32 v66, v67, v66
	v_div_scale_f32 v67, vcc, 1.0, v50, 1.0
	v_mul_f32_e32 v94, v67, v66
	v_fma_f32 v95, -v57, v94, v67
	v_fmac_f32_e32 v94, v95, v66
	v_fma_f32 v57, -v57, v94, v67
	v_div_fmas_f32 v57, v57, v66, v94
	v_div_fixup_f32 v50, v57, v50, 1.0
	v_pk_fma_f32 v[66:67], v[50:51], v[92:93], v[84:85] op_sel_hi:[0,1,1] neg_lo:[0,0,1] neg_hi:[0,0,1]
	v_pk_fma_f32 v[94:95], v[50:51], v[62:63], v[64:65] op_sel_hi:[0,1,1] neg_lo:[0,0,1] neg_hi:[0,0,1]
	v_pk_mul_f32 v[94:95], v[2:3], v[94:95]
	v_pk_mul_f32 v[66:67], v[0:1], v[66:67]
	v_lshlrev_b32_e32 v98, 16, v53
	v_and_b32_e32 v99, 0xffff0000, v53
	v_cvt_f32_i32_e32 v53, s7
	v_cvt_pk_bf16_f32 v66, v66, v67
	v_cvt_pk_bf16_f32 v67, v94, v95
	v_add_co_u32_e32 v94, vcc, s9, v16
	v_lshlrev_b32_e32 v100, 16, v51
	s_nop 0
	v_addc_co_u32_e32 v95, vcc, 0, v17, vcc
	v_and_b32_e32 v101, 0xffff0000, v51
	global_store_dwordx2 v[94:95], v[66:67], off offset:1024
	v_pk_mul_f32 v[50:51], v[56:57], v[100:101] op_sel_hi:[0,1]
	v_pk_mul_f32 v[66:67], v[56:57], v[98:99] op_sel_hi:[0,1]
	v_pk_fma_f32 v[72:73], v[56:57], v[98:99], v[72:73] op_sel_hi:[0,1,1] neg_lo:[0,0,1] neg_hi:[0,0,1]
	v_pk_fma_f32 v[56:57], v[56:57], v[100:101], v[68:69] op_sel_hi:[0,1,1] neg_lo:[0,0,1] neg_hi:[0,0,1]
	v_pk_add_f32 v[62:63], v[62:63], v[56:57]
	v_div_scale_f32 v56, s[18:19], v53, v53, 1.0
	v_rcp_f32_e32 v57, v56
	v_pk_add_f32 v[72:73], v[92:93], v[72:73]
	s_max_i32 s7, s83, 4
	s_min_i32 s18, s80, s23
	v_fma_f32 v68, -v56, v57, 1.0
	v_fmac_f32_e32 v57, v68, v57
	v_div_scale_f32 v68, vcc, 1.0, v53, 1.0
	v_mul_f32_e32 v69, v68, v57
	v_fma_f32 v92, -v56, v69, v68
	v_fmac_f32_e32 v69, v92, v57
	v_fma_f32 v56, -v56, v69, v68
	v_div_fmas_f32 v56, v56, v57, v69
	v_div_fixup_f32 v56, v56, v53, 1.0
	v_pk_fma_f32 v[68:69], v[56:57], v[72:73], v[86:87] op_sel_hi:[0,1,1] neg_lo:[0,0,1] neg_hi:[0,0,1]
	v_pk_fma_f32 v[56:57], v[56:57], v[62:63], v[60:61] op_sel_hi:[0,1,1] neg_lo:[0,0,1] neg_hi:[0,0,1]
	v_pk_mul_f32 v[68:69], v[0:1], v[68:69]
	v_pk_mul_f32 v[56:57], v[2:3], v[56:57]
	v_cvt_pk_bf16_f32 v68, v68, v69
	v_lshlrev_b32_e32 v92, 16, v131
	v_cvt_pk_bf16_f32 v69, v56, v57
	global_store_dwordx2 v[94:95], v[68:69], off offset:3072
	v_and_b32_e32 v93, 0xffff0000, v131
	v_lshlrev_b32_e32 v94, 16, v130
	v_and_b32_e32 v95, 0xffff0000, v130
	s_sub_i32 s7, s18, s7
	v_pk_mul_f32 v[56:57], v[52:53], v[94:95] op_sel_hi:[0,1]
	v_pk_mul_f32 v[68:69], v[52:53], v[92:93] op_sel_hi:[0,1]
	v_pk_fma_f32 v[80:81], v[52:53], v[92:93], v[80:81] op_sel_hi:[0,1,1] neg_lo:[0,0,1] neg_hi:[0,0,1]
	v_pk_fma_f32 v[52:53], v[52:53], v[94:95], v[74:75] op_sel_hi:[0,1,1] neg_lo:[0,0,1] neg_hi:[0,0,1]
	s_add_i32 s7, s7, 4
	v_pk_add_f32 v[62:63], v[62:63], v[52:53]
	v_cvt_f32_i32_e32 v52, s7
	v_pk_add_f32 v[74:75], v[72:73], v[80:81]
	s_max_i32 s7, s81, 4
	v_lshlrev_b32_e32 v92, 16, v129
	v_div_scale_f32 v53, s[18:19], v52, v52, 1.0
	v_rcp_f32_e32 v72, v53
	s_min_i32 s18, s78, s23
	s_sub_i32 s7, s18, s7
	v_and_b32_e32 v93, 0xffff0000, v129
	v_fma_f32 v73, -v53, v72, 1.0
	v_fmac_f32_e32 v72, v73, v72
	v_div_scale_f32 v73, vcc, 1.0, v52, 1.0
	v_mul_f32_e32 v80, v73, v72
	v_fma_f32 v81, -v53, v80, v73
	v_fmac_f32_e32 v80, v81, v72
	v_fma_f32 v53, -v53, v80, v73
	v_div_fmas_f32 v53, v53, v72, v80
	v_div_fixup_f32 v52, v53, v52, 1.0
	v_pk_fma_f32 v[72:73], v[52:53], v[74:75], v[88:89] op_sel_hi:[0,1,1] neg_lo:[0,0,1] neg_hi:[0,0,1]
	v_pk_fma_f32 v[52:53], v[52:53], v[62:63], v[58:59] op_sel_hi:[0,1,1] neg_lo:[0,0,1] neg_hi:[0,0,1]
	v_pk_mul_f32 v[72:73], v[0:1], v[72:73]
	v_add_co_u32_e32 v80, vcc, s38, v16
	v_pk_mul_f32 v[52:53], v[2:3], v[52:53]
	v_cvt_pk_bf16_f32 v72, v72, v73
	s_nop 0
	v_addc_co_u32_e32 v81, vcc, 0, v17, vcc
	v_cvt_pk_bf16_f32 v73, v52, v53
	v_lshlrev_b32_e32 v94, 16, v128
	v_and_b32_e32 v95, 0xffff0000, v128
	s_add_i32 s7, s7, 4
	global_store_dwordx2 v[80:81], v[72:73], off offset:1024
	v_pk_mul_f32 v[52:53], v[48:49], v[94:95] op_sel_hi:[0,1]
	v_pk_mul_f32 v[72:73], v[48:49], v[92:93] op_sel_hi:[0,1]
	v_pk_fma_f32 v[78:79], v[48:49], v[92:93], v[78:79] op_sel_hi:[0,1,1] neg_lo:[0,0,1] neg_hi:[0,0,1]
	v_pk_fma_f32 v[76:77], v[48:49], v[94:95], v[76:77] op_sel_hi:[0,1,1] neg_lo:[0,0,1] neg_hi:[0,0,1]
	v_cvt_f32_i32_e32 v48, s7
	v_pk_add_f32 v[62:63], v[62:63], v[76:77]
	v_pk_add_f32 v[76:77], v[74:75], v[78:79]
	s_max_i32 s7, s79, 4
	v_div_scale_f32 v74, s[18:19], v48, v48, 1.0
	v_rcp_f32_e32 v75, v74
	s_min_i32 s18, s77, s23
	s_sub_i32 s7, s18, s7
	s_add_i32 s7, s7, 4
	v_fma_f32 v78, -v74, v75, 1.0
	v_fmac_f32_e32 v75, v78, v75
	v_div_scale_f32 v78, vcc, 1.0, v48, 1.0
	v_mul_f32_e32 v79, v78, v75
	v_fma_f32 v92, -v74, v79, v78
	v_fmac_f32_e32 v79, v92, v75
	v_fma_f32 v74, -v74, v79, v78
	v_div_fmas_f32 v74, v74, v75, v79
	v_div_fixup_f32 v48, v74, v48, 1.0
	v_pk_fma_f32 v[74:75], v[48:49], v[76:77], v[90:91] op_sel_hi:[0,1,1] neg_lo:[0,0,1] neg_hi:[0,0,1]
	v_pk_fma_f32 v[78:79], v[48:49], v[62:63], v[54:55] op_sel_hi:[0,1,1] neg_lo:[0,0,1] neg_hi:[0,0,1]
	v_pk_mul_f32 v[78:79], v[2:3], v[78:79]
	v_pk_mul_f32 v[74:75], v[0:1], v[74:75]
	s_movk_i32 s90, 0xff00
	v_cvt_pk_bf16_f32 v74, v74, v75
	v_cvt_pk_bf16_f32 v75, v78, v79
	global_store_dwordx2 v[80:81], v[74:75], off offset:3072
	v_lshlrev_b32_e32 v78, 16, v127
	v_and_b32_e32 v79, 0xffff0000, v127
	v_lshlrev_b32_e32 v80, 16, v49
	v_and_b32_e32 v81, 0xffff0000, v49
	v_pk_mul_f32 v[48:49], v[46:47], v[80:81] op_sel_hi:[0,1]
	v_pk_mul_f32 v[74:75], v[46:47], v[78:79] op_sel_hi:[0,1]
	v_pk_fma_f32 v[78:79], v[46:47], v[78:79], v[82:83] op_sel_hi:[0,1,1] neg_lo:[0,0,1] neg_hi:[0,0,1]
	v_pk_fma_f32 v[70:71], v[46:47], v[80:81], v[70:71] op_sel_hi:[0,1,1] neg_lo:[0,0,1] neg_hi:[0,0,1]
	v_cvt_f32_i32_e32 v46, s7
	v_pk_add_f32 v[70:71], v[62:63], v[70:71]
	v_pk_add_f32 v[76:77], v[76:77], v[78:79]
	s_max_i32 s7, s82, 4
	v_div_scale_f32 v62, s[18:19], v46, v46, 1.0
	v_rcp_f32_e32 v63, v62
	s_min_i32 s18, s76, s23
	s_sub_i32 s7, s18, s7
	v_and_b32_e32 v81, 0xffff0000, v126
	v_fma_f32 v78, -v62, v63, 1.0
	v_fmac_f32_e32 v63, v78, v63
	v_div_scale_f32 v78, vcc, 1.0, v46, 1.0
	v_mul_f32_e32 v79, v78, v63
	v_fma_f32 v80, -v62, v79, v78
	v_fmac_f32_e32 v79, v80, v63
	v_fma_f32 v62, -v62, v79, v78
	v_div_fmas_f32 v62, v62, v63, v79
	v_div_fixup_f32 v46, v62, v46, 1.0
	v_pk_fma_f32 v[62:63], v[46:47], v[76:77], v[66:67] op_sel_hi:[0,1,1] neg_lo:[0,0,1] neg_hi:[0,0,1]
	v_pk_fma_f32 v[78:79], v[46:47], v[70:71], v[50:51] op_sel_hi:[0,1,1] neg_lo:[0,0,1] neg_hi:[0,0,1]
	v_pk_mul_f32 v[78:79], v[2:3], v[78:79]
	v_pk_mul_f32 v[62:63], v[0:1], v[62:63]
	v_lshlrev_b32_e32 v80, 16, v126
	v_cvt_pk_bf16_f32 v62, v62, v63
	v_cvt_pk_bf16_f32 v63, v78, v79
	v_add_co_u32_e32 v78, vcc, s39, v16
	v_lshlrev_b32_e32 v82, 16, v47
	s_nop 0
	v_addc_co_u32_e32 v79, vcc, 0, v17, vcc
	v_and_b32_e32 v83, 0xffff0000, v47
	s_add_i32 s7, s7, 4
	global_store_dwordx2 v[78:79], v[62:63], off offset:1024
	v_pk_mul_f32 v[46:47], v[44:45], v[82:83] op_sel_hi:[0,1]
	v_pk_mul_f32 v[62:63], v[44:45], v[80:81] op_sel_hi:[0,1]
	v_pk_fma_f32 v[80:81], v[44:45], v[80:81], v[84:85] op_sel_hi:[0,1,1] neg_lo:[0,0,1] neg_hi:[0,0,1]
	v_pk_fma_f32 v[64:65], v[44:45], v[82:83], v[64:65] op_sel_hi:[0,1,1] neg_lo:[0,0,1] neg_hi:[0,0,1]
	v_cvt_f32_i32_e32 v44, s7
	v_pk_add_f32 v[70:71], v[70:71], v[64:65]
	v_pk_add_f32 v[76:77], v[76:77], v[80:81]
	s_max_i32 s7, s80, 4
	v_div_scale_f32 v64, s[18:19], v44, v44, 1.0
	v_rcp_f32_e32 v65, v64
	s_min_i32 s18, s75, s23
	s_sub_i32 s7, s18, s7
	s_add_i32 s7, s7, 4
	v_fma_f32 v80, -v64, v65, 1.0
	v_fmac_f32_e32 v65, v80, v65
	v_div_scale_f32 v80, vcc, 1.0, v44, 1.0
	v_mul_f32_e32 v81, v80, v65
	v_fma_f32 v82, -v64, v81, v80
	v_fmac_f32_e32 v81, v82, v65
	v_fma_f32 v64, -v64, v81, v80
	v_div_fmas_f32 v64, v64, v65, v81
	v_div_fixup_f32 v44, v64, v44, 1.0
	v_pk_fma_f32 v[64:65], v[44:45], v[76:77], v[68:69] op_sel_hi:[0,1,1] neg_lo:[0,0,1] neg_hi:[0,0,1]
	v_pk_fma_f32 v[80:81], v[44:45], v[70:71], v[56:57] op_sel_hi:[0,1,1] neg_lo:[0,0,1] neg_hi:[0,0,1]
	v_pk_mul_f32 v[80:81], v[2:3], v[80:81]
	v_pk_mul_f32 v[64:65], v[0:1], v[64:65]
	v_lshlrev_b32_e32 v82, 16, v43
	v_cvt_pk_bf16_f32 v64, v64, v65
	v_cvt_pk_bf16_f32 v65, v80, v81
	global_store_dwordx2 v[78:79], v[64:65], off offset:3072
	v_lshlrev_b32_e32 v78, 16, v125
	v_and_b32_e32 v79, 0xffff0000, v125
	v_lshlrev_b32_e32 v80, 16, v45
	v_and_b32_e32 v81, 0xffff0000, v45
	v_pk_mul_f32 v[44:45], v[42:43], v[80:81] op_sel_hi:[0,1]
	v_pk_mul_f32 v[64:65], v[42:43], v[78:79] op_sel_hi:[0,1]
	v_pk_fma_f32 v[78:79], v[42:43], v[78:79], v[86:87] op_sel_hi:[0,1,1] neg_lo:[0,0,1] neg_hi:[0,0,1]
	v_pk_fma_f32 v[60:61], v[42:43], v[80:81], v[60:61] op_sel_hi:[0,1,1] neg_lo:[0,0,1] neg_hi:[0,0,1]
	v_cvt_f32_i32_e32 v42, s7
	v_pk_add_f32 v[70:71], v[70:71], v[60:61]
	v_pk_add_f32 v[76:77], v[76:77], v[78:79]
	s_movk_i32 s7, 0x7000
	v_div_scale_f32 v60, s[18:19], v42, v42, 1.0
	v_rcp_f32_e32 v61, v60
	s_min_i32 s18, s74, s23
	v_and_b32_e32 v81, 0xffff0000, v124
	v_and_b32_e32 v83, 0xffff0000, v43
	v_fma_f32 v78, -v60, v61, 1.0
	v_fmac_f32_e32 v61, v78, v61
	v_div_scale_f32 v78, vcc, 1.0, v42, 1.0
	v_mul_f32_e32 v79, v78, v61
	v_fma_f32 v80, -v60, v79, v78
	v_fmac_f32_e32 v79, v80, v61
	v_fma_f32 v60, -v60, v79, v78
	v_div_fmas_f32 v60, v60, v61, v79
	v_div_fixup_f32 v42, v60, v42, 1.0
	v_pk_fma_f32 v[60:61], v[42:43], v[76:77], v[72:73] op_sel_hi:[0,1,1] neg_lo:[0,0,1] neg_hi:[0,0,1]
	v_pk_fma_f32 v[78:79], v[42:43], v[70:71], v[52:53] op_sel_hi:[0,1,1] neg_lo:[0,0,1] neg_hi:[0,0,1]
	v_pk_mul_f32 v[78:79], v[2:3], v[78:79]
	v_pk_mul_f32 v[60:61], v[0:1], v[60:61]
	v_lshlrev_b32_e32 v80, 16, v124
	v_cvt_pk_bf16_f32 v60, v60, v61
	v_cvt_pk_bf16_f32 v61, v78, v79
	v_add_co_u32_e32 v78, vcc, s7, v16
	s_max_i32 s7, s78, 4
	s_sub_i32 s7, s18, s7
	v_addc_co_u32_e32 v79, vcc, 0, v17, vcc
	s_add_i32 s7, s7, 4
	global_store_dwordx2 v[78:79], v[60:61], off offset:1024
	v_pk_mul_f32 v[42:43], v[40:41], v[82:83] op_sel_hi:[0,1]
	v_pk_mul_f32 v[60:61], v[40:41], v[80:81] op_sel_hi:[0,1]
	v_pk_fma_f32 v[80:81], v[40:41], v[80:81], v[88:89] op_sel_hi:[0,1,1] neg_lo:[0,0,1] neg_hi:[0,0,1]
	v_pk_fma_f32 v[58:59], v[40:41], v[82:83], v[58:59] op_sel_hi:[0,1,1] neg_lo:[0,0,1] neg_hi:[0,0,1]
	v_cvt_f32_i32_e32 v40, s7
	v_pk_add_f32 v[70:71], v[70:71], v[58:59]
	v_pk_add_f32 v[76:77], v[76:77], v[80:81]
	s_max_i32 s7, s77, 4
	v_div_scale_f32 v58, s[18:19], v40, v40, 1.0
	v_rcp_f32_e32 v59, v58
	s_min_i32 s18, s71, s23
	s_sub_i32 s7, s18, s7
	s_add_i32 s7, s7, 4
	v_fma_f32 v80, -v58, v59, 1.0
	v_fmac_f32_e32 v59, v80, v59
	v_div_scale_f32 v80, vcc, 1.0, v40, 1.0
	v_mul_f32_e32 v81, v80, v59
	v_fma_f32 v82, -v58, v81, v80
	v_fmac_f32_e32 v81, v82, v59
	v_fma_f32 v58, -v58, v81, v80
	v_div_fmas_f32 v58, v58, v59, v81
	v_div_fixup_f32 v40, v58, v40, 1.0
	v_pk_fma_f32 v[58:59], v[40:41], v[76:77], v[74:75] op_sel_hi:[0,1,1] neg_lo:[0,0,1] neg_hi:[0,0,1]
	v_pk_fma_f32 v[80:81], v[40:41], v[70:71], v[48:49] op_sel_hi:[0,1,1] neg_lo:[0,0,1] neg_hi:[0,0,1]
	v_pk_mul_f32 v[80:81], v[2:3], v[80:81]
	v_pk_mul_f32 v[58:59], v[0:1], v[58:59]
	v_lshlrev_b32_e32 v82, 16, v35
	v_cvt_pk_bf16_f32 v58, v58, v59
	v_cvt_pk_bf16_f32 v59, v80, v81
	global_store_dwordx2 v[78:79], v[58:59], off offset:3072
	v_lshlrev_b32_e32 v78, 16, v123
	v_and_b32_e32 v79, 0xffff0000, v123
	v_lshlrev_b32_e32 v80, 16, v41
	v_and_b32_e32 v81, 0xffff0000, v41
	v_pk_mul_f32 v[40:41], v[34:35], v[80:81] op_sel_hi:[0,1]
	v_pk_mul_f32 v[58:59], v[34:35], v[78:79] op_sel_hi:[0,1]
	v_pk_fma_f32 v[78:79], v[34:35], v[78:79], v[90:91] op_sel_hi:[0,1,1] neg_lo:[0,0,1] neg_hi:[0,0,1]
	v_pk_fma_f32 v[54:55], v[34:35], v[80:81], v[54:55] op_sel_hi:[0,1,1] neg_lo:[0,0,1] neg_hi:[0,0,1]
	v_cvt_f32_i32_e32 v34, s7
	v_pk_add_f32 v[70:71], v[70:71], v[54:55]
	v_pk_add_f32 v[76:77], v[76:77], v[78:79]
	s_max_i32 s7, s76, 4
	v_div_scale_f32 v54, s[18:19], v34, v34, 1.0
	v_rcp_f32_e32 v55, v54
	s_min_i32 s18, s73, s23
	s_sub_i32 s7, s18, s7
	s_add_i32 s7, s7, 4
	v_fma_f32 v78, -v54, v55, 1.0
	v_fmac_f32_e32 v55, v78, v55
	v_div_scale_f32 v78, vcc, 1.0, v34, 1.0
	v_mul_f32_e32 v79, v78, v55
	v_fma_f32 v80, -v54, v79, v78
	v_fmac_f32_e32 v79, v80, v55
	v_fma_f32 v54, -v54, v79, v78
	v_div_fmas_f32 v54, v54, v55, v79
	v_div_fixup_f32 v34, v54, v34, 1.0
	v_pk_fma_f32 v[54:55], v[34:35], v[76:77], v[62:63] op_sel_hi:[0,1,1] neg_lo:[0,0,1] neg_hi:[0,0,1]
	v_pk_fma_f32 v[78:79], v[34:35], v[70:71], v[46:47] op_sel_hi:[0,1,1] neg_lo:[0,0,1] neg_hi:[0,0,1]
	v_lshlrev_b32_e32 v80, 16, v37
	v_and_b32_e32 v81, 0xffff0000, v37
	v_cvt_f32_i32_e32 v37, s7
	v_pk_mul_f32 v[78:79], v[2:3], v[78:79]
	v_pk_mul_f32 v[54:55], v[0:1], v[54:55]
	v_and_b32_e32 v83, 0xffff0000, v35
	v_cvt_pk_bf16_f32 v54, v54, v55
	v_cvt_pk_bf16_f32 v55, v78, v79
	v_add_co_u32_e32 v78, vcc, s61, v16
	v_pk_mul_f32 v[34:35], v[38:39], v[82:83] op_sel_hi:[0,1]
	s_nop 0
	v_addc_co_u32_e32 v79, vcc, 0, v17, vcc
	global_store_dwordx2 v[78:79], v[54:55], off offset:1024
	v_pk_mul_f32 v[54:55], v[38:39], v[80:81] op_sel_hi:[0,1]
	v_pk_fma_f32 v[66:67], v[38:39], v[80:81], v[66:67] op_sel_hi:[0,1,1] neg_lo:[0,0,1] neg_hi:[0,0,1]
	v_pk_fma_f32 v[50:51], v[38:39], v[82:83], v[50:51] op_sel_hi:[0,1,1] neg_lo:[0,0,1] neg_hi:[0,0,1]
	v_div_scale_f32 v38, s[18:19], v37, v37, 1.0
	v_pk_add_f32 v[70:71], v[70:71], v[50:51]
	v_rcp_f32_e32 v50, v38
	v_pk_add_f32 v[66:67], v[76:77], v[66:67]
	s_max_i32 s7, s75, 4
	s_min_i32 s18, s72, s23
	v_fma_f32 v51, -v38, v50, 1.0
	v_fmac_f32_e32 v50, v51, v50
	v_div_scale_f32 v51, vcc, 1.0, v37, 1.0
	v_mul_f32_e32 v76, v51, v50
	v_fma_f32 v77, -v38, v76, v51
	v_fmac_f32_e32 v76, v77, v50
	v_fma_f32 v38, -v38, v76, v51
	v_div_fmas_f32 v38, v38, v50, v76
	v_div_fixup_f32 v38, v38, v37, 1.0
	v_pk_fma_f32 v[50:51], v[38:39], v[66:67], v[64:65] op_sel_hi:[0,1,1] neg_lo:[0,0,1] neg_hi:[0,0,1]
	v_pk_fma_f32 v[76:77], v[38:39], v[70:71], v[44:45] op_sel_hi:[0,1,1] neg_lo:[0,0,1] neg_hi:[0,0,1]
	v_pk_mul_f32 v[76:77], v[2:3], v[76:77]
	v_pk_mul_f32 v[50:51], v[0:1], v[50:51]
	s_sub_i32 s7, s18, s7
	v_cvt_pk_bf16_f32 v50, v50, v51
	v_cvt_pk_bf16_f32 v51, v76, v77
	global_store_dwordx2 v[78:79], v[50:51], off offset:3072
	v_lshlrev_b32_e32 v76, 16, v122
	v_and_b32_e32 v77, 0xffff0000, v122
	v_lshlrev_b32_e32 v78, 16, v39
	v_and_b32_e32 v79, 0xffff0000, v39
	v_pk_mul_f32 v[38:39], v[36:37], v[78:79] op_sel_hi:[0,1]
	v_pk_mul_f32 v[50:51], v[36:37], v[76:77] op_sel_hi:[0,1]
	v_pk_fma_f32 v[68:69], v[36:37], v[76:77], v[68:69] op_sel_hi:[0,1,1] neg_lo:[0,0,1] neg_hi:[0,0,1]
	v_pk_fma_f32 v[36:37], v[36:37], v[78:79], v[56:57] op_sel_hi:[0,1,1] neg_lo:[0,0,1] neg_hi:[0,0,1]
	s_add_i32 s7, s7, 4
	v_pk_add_f32 v[70:71], v[70:71], v[36:37]
	v_cvt_f32_i32_e32 v36, s7
	v_pk_add_f32 v[66:67], v[66:67], v[68:69]
	s_max_i32 s7, s74, 4
	v_lshlrev_b32_e32 v76, 16, v121
	v_div_scale_f32 v37, s[18:19], v36, v36, 1.0
	v_rcp_f32_e32 v56, v37
	s_min_i32 s18, s69, s23
	s_sub_i32 s7, s18, s7
	v_and_b32_e32 v77, 0xffff0000, v121
	v_fma_f32 v57, -v37, v56, 1.0
	v_fmac_f32_e32 v56, v57, v56
	v_div_scale_f32 v57, vcc, 1.0, v36, 1.0
	v_mul_f32_e32 v68, v57, v56
	v_fma_f32 v69, -v37, v68, v57
	v_fmac_f32_e32 v68, v69, v56
	v_fma_f32 v37, -v37, v68, v57
	v_div_fmas_f32 v37, v37, v56, v68
	v_div_fixup_f32 v36, v37, v36, 1.0
	v_pk_fma_f32 v[56:57], v[36:37], v[66:67], v[60:61] op_sel_hi:[0,1,1] neg_lo:[0,0,1] neg_hi:[0,0,1]
	v_pk_fma_f32 v[36:37], v[36:37], v[70:71], v[42:43] op_sel_hi:[0,1,1] neg_lo:[0,0,1] neg_hi:[0,0,1]
	v_pk_mul_f32 v[56:57], v[0:1], v[56:57]
	v_add_co_u32_e32 v68, vcc, s94, v16
	v_pk_mul_f32 v[36:37], v[2:3], v[36:37]
	v_cvt_pk_bf16_f32 v56, v56, v57
	s_nop 0
	v_addc_co_u32_e32 v69, vcc, 0, v17, vcc
	v_cvt_pk_bf16_f32 v57, v36, v37
	v_lshlrev_b32_e32 v78, 16, v120
	v_and_b32_e32 v79, 0xffff0000, v120
	s_add_i32 s7, s7, 4
	global_store_dwordx2 v[68:69], v[56:57], off offset:1024
	v_pk_mul_f32 v[36:37], v[32:33], v[78:79] op_sel_hi:[0,1]
	v_pk_mul_f32 v[56:57], v[32:33], v[76:77] op_sel_hi:[0,1]
	v_pk_fma_f32 v[72:73], v[32:33], v[76:77], v[72:73] op_sel_hi:[0,1,1] neg_lo:[0,0,1] neg_hi:[0,0,1]
	v_pk_fma_f32 v[52:53], v[32:33], v[78:79], v[52:53] op_sel_hi:[0,1,1] neg_lo:[0,0,1] neg_hi:[0,0,1]
	v_cvt_f32_i32_e32 v32, s7
	v_pk_add_f32 v[70:71], v[70:71], v[52:53]
	v_pk_add_f32 v[66:67], v[66:67], v[72:73]
	s_max_i32 s7, s71, 4
	v_div_scale_f32 v52, s[18:19], v32, v32, 1.0
	v_rcp_f32_e32 v53, v52
	s_min_i32 s18, s68, s23
	s_sub_i32 s7, s18, s7
	s_add_i32 s7, s7, 4
	v_fma_f32 v72, -v52, v53, 1.0
	v_fmac_f32_e32 v53, v72, v53
	v_div_scale_f32 v72, vcc, 1.0, v32, 1.0
	v_mul_f32_e32 v73, v72, v53
	v_fma_f32 v76, -v52, v73, v72
	v_fmac_f32_e32 v73, v76, v53
	v_fma_f32 v52, -v52, v73, v72
	v_div_fmas_f32 v52, v52, v53, v73
	v_div_fixup_f32 v32, v52, v32, 1.0
	v_pk_fma_f32 v[52:53], v[32:33], v[66:67], v[58:59] op_sel_hi:[0,1,1] neg_lo:[0,0,1] neg_hi:[0,0,1]
	v_pk_fma_f32 v[72:73], v[32:33], v[70:71], v[40:41] op_sel_hi:[0,1,1] neg_lo:[0,0,1] neg_hi:[0,0,1]
	v_pk_mul_f32 v[72:73], v[2:3], v[72:73]
	v_pk_mul_f32 v[52:53], v[0:1], v[52:53]
	s_nop 0
	v_cvt_pk_bf16_f32 v52, v52, v53
	v_cvt_pk_bf16_f32 v53, v72, v73
	global_store_dwordx2 v[68:69], v[52:53], off offset:3072
	v_lshlrev_b32_e32 v68, 16, v119
	v_and_b32_e32 v69, 0xffff0000, v119
	v_lshlrev_b32_e32 v72, 16, v33
	v_and_b32_e32 v73, 0xffff0000, v33
	v_pk_mul_f32 v[32:33], v[30:31], v[72:73] op_sel_hi:[0,1]
	v_pk_mul_f32 v[52:53], v[30:31], v[68:69] op_sel_hi:[0,1]
	v_pk_fma_f32 v[68:69], v[30:31], v[68:69], v[74:75] op_sel_hi:[0,1,1] neg_lo:[0,0,1] neg_hi:[0,0,1]
	v_pk_fma_f32 v[48:49], v[30:31], v[72:73], v[48:49] op_sel_hi:[0,1,1] neg_lo:[0,0,1] neg_hi:[0,0,1]
	v_cvt_f32_i32_e32 v30, s7
	v_pk_add_f32 v[70:71], v[70:71], v[48:49]
	v_pk_add_f32 v[66:67], v[66:67], v[68:69]
	s_mov_b32 s7, 0xa000
	v_div_scale_f32 v48, s[18:19], v30, v30, 1.0
	v_rcp_f32_e32 v49, v48
	s_min_i32 s18, s63, s23
	v_and_b32_e32 v73, 0xffff0000, v118
	v_lshlrev_b32_e32 v74, 16, v31
	v_fma_f32 v68, -v48, v49, 1.0
	v_fmac_f32_e32 v49, v68, v49
	v_div_scale_f32 v68, vcc, 1.0, v30, 1.0
	v_mul_f32_e32 v69, v68, v49
	v_fma_f32 v72, -v48, v69, v68
	v_fmac_f32_e32 v69, v72, v49
	v_fma_f32 v48, -v48, v69, v68
	v_div_fmas_f32 v48, v48, v49, v69
	v_div_fixup_f32 v30, v48, v30, 1.0
	v_pk_fma_f32 v[48:49], v[30:31], v[66:67], v[54:55] op_sel_hi:[0,1,1] neg_lo:[0,0,1] neg_hi:[0,0,1]
	v_pk_fma_f32 v[68:69], v[30:31], v[70:71], v[34:35] op_sel_hi:[0,1,1] neg_lo:[0,0,1] neg_hi:[0,0,1]
	v_pk_mul_f32 v[68:69], v[2:3], v[68:69]
	v_pk_mul_f32 v[48:49], v[0:1], v[48:49]
	v_lshlrev_b32_e32 v72, 16, v118
	v_cvt_pk_bf16_f32 v48, v48, v49
	v_cvt_pk_bf16_f32 v49, v68, v69
	v_add_co_u32_e32 v68, vcc, s7, v16
	s_max_i32 s7, s73, 4
	s_sub_i32 s7, s18, s7
	v_addc_co_u32_e32 v69, vcc, 0, v17, vcc
	v_and_b32_e32 v75, 0xffff0000, v31
	s_add_i32 s7, s7, 4
	global_store_dwordx2 v[68:69], v[48:49], off offset:1024
	v_pk_mul_f32 v[30:31], v[28:29], v[74:75] op_sel_hi:[0,1]
	v_pk_mul_f32 v[48:49], v[28:29], v[72:73] op_sel_hi:[0,1]
	v_pk_fma_f32 v[62:63], v[28:29], v[72:73], v[62:63] op_sel_hi:[0,1,1] neg_lo:[0,0,1] neg_hi:[0,0,1]
	v_pk_fma_f32 v[46:47], v[28:29], v[74:75], v[46:47] op_sel_hi:[0,1,1] neg_lo:[0,0,1] neg_hi:[0,0,1]
	v_cvt_f32_i32_e32 v28, s7
	v_pk_add_f32 v[70:71], v[70:71], v[46:47]
	v_pk_add_f32 v[62:63], v[66:67], v[62:63]
	s_max_i32 s7, s72, 4
	v_div_scale_f32 v46, s[18:19], v28, v28, 1.0
	v_rcp_f32_e32 v47, v46
	s_min_i32 s18, s62, s23
	s_sub_i32 s7, s18, s7
	s_add_i32 s7, s7, 4
	v_fma_f32 v66, -v46, v47, 1.0
	v_fmac_f32_e32 v47, v66, v47
	v_div_scale_f32 v66, vcc, 1.0, v28, 1.0
	v_mul_f32_e32 v67, v66, v47
	v_fma_f32 v72, -v46, v67, v66
	v_fmac_f32_e32 v67, v72, v47
	v_fma_f32 v46, -v46, v67, v66
	v_div_fmas_f32 v46, v46, v47, v67
	v_div_fixup_f32 v28, v46, v28, 1.0
	v_pk_fma_f32 v[46:47], v[28:29], v[62:63], v[50:51] op_sel_hi:[0,1,1] neg_lo:[0,0,1] neg_hi:[0,0,1]
	v_pk_fma_f32 v[66:67], v[28:29], v[70:71], v[38:39] op_sel_hi:[0,1,1] neg_lo:[0,0,1] neg_hi:[0,0,1]
	v_pk_mul_f32 v[66:67], v[2:3], v[66:67]
	v_pk_mul_f32 v[46:47], v[0:1], v[46:47]
	s_nop 0
	v_cvt_pk_bf16_f32 v46, v46, v47
	v_cvt_pk_bf16_f32 v47, v66, v67
	global_store_dwordx2 v[68:69], v[46:47], off offset:3072
	v_lshlrev_b32_e32 v66, 16, v117
	v_and_b32_e32 v67, 0xffff0000, v117
	v_lshlrev_b32_e32 v68, 16, v29
	v_and_b32_e32 v69, 0xffff0000, v29
	v_pk_mul_f32 v[28:29], v[26:27], v[68:69] op_sel_hi:[0,1]
	v_pk_mul_f32 v[46:47], v[26:27], v[66:67] op_sel_hi:[0,1]
	v_pk_fma_f32 v[64:65], v[26:27], v[66:67], v[64:65] op_sel_hi:[0,1,1] neg_lo:[0,0,1] neg_hi:[0,0,1]
	v_pk_fma_f32 v[44:45], v[26:27], v[68:69], v[44:45] op_sel_hi:[0,1,1] neg_lo:[0,0,1] neg_hi:[0,0,1]
	v_cvt_f32_i32_e32 v26, s7
	v_pk_add_f32 v[66:67], v[70:71], v[44:45]
	v_pk_add_f32 v[62:63], v[62:63], v[64:65]
	s_max_i32 s7, s69, 4
	v_div_scale_f32 v44, s[18:19], v26, v26, 1.0
	v_rcp_f32_e32 v45, v44
	s_min_i32 s18, s34, s23
	s_sub_i32 s7, s18, s7
	v_and_b32_e32 v69, 0xffff0000, v116
	v_fma_f32 v64, -v44, v45, 1.0
	v_fmac_f32_e32 v45, v64, v45
	v_div_scale_f32 v64, vcc, 1.0, v26, 1.0
	v_mul_f32_e32 v65, v64, v45
	v_fma_f32 v68, -v44, v65, v64
	v_fmac_f32_e32 v65, v68, v45
	v_fma_f32 v44, -v44, v65, v64
	v_div_fmas_f32 v44, v44, v45, v65
	v_div_fixup_f32 v26, v44, v26, 1.0
	v_pk_fma_f32 v[44:45], v[26:27], v[62:63], v[56:57] op_sel_hi:[0,1,1] neg_lo:[0,0,1] neg_hi:[0,0,1]
	v_pk_fma_f32 v[64:65], v[26:27], v[66:67], v[36:37] op_sel_hi:[0,1,1] neg_lo:[0,0,1] neg_hi:[0,0,1]
	v_pk_mul_f32 v[64:65], v[2:3], v[64:65]
	v_pk_mul_f32 v[44:45], v[0:1], v[44:45]
	v_lshlrev_b32_e32 v68, 16, v116
	v_cvt_pk_bf16_f32 v44, v44, v45
	v_cvt_pk_bf16_f32 v45, v64, v65
	v_add_co_u32_e32 v64, vcc, s51, v16
	v_lshlrev_b32_e32 v70, 16, v27
	s_nop 0
	v_addc_co_u32_e32 v65, vcc, 0, v17, vcc
	v_and_b32_e32 v71, 0xffff0000, v27
	s_add_i32 s7, s7, 4
	global_store_dwordx2 v[64:65], v[44:45], off offset:1024
	v_pk_mul_f32 v[26:27], v[24:25], v[70:71] op_sel_hi:[0,1]
	v_pk_mul_f32 v[44:45], v[24:25], v[68:69] op_sel_hi:[0,1]
	v_pk_fma_f32 v[60:61], v[24:25], v[68:69], v[60:61] op_sel_hi:[0,1,1] neg_lo:[0,0,1] neg_hi:[0,0,1]
	v_pk_fma_f32 v[42:43], v[24:25], v[70:71], v[42:43] op_sel_hi:[0,1,1] neg_lo:[0,0,1] neg_hi:[0,0,1]
	v_cvt_f32_i32_e32 v24, s7
	v_pk_add_f32 v[66:67], v[66:67], v[42:43]
	v_pk_add_f32 v[60:61], v[62:63], v[60:61]
	s_max_i32 s7, s68, 4
	v_div_scale_f32 v42, s[18:19], v24, v24, 1.0
	v_rcp_f32_e32 v43, v42
	s_min_i32 s18, s20, s23
	s_sub_i32 s7, s18, s7
	s_add_i32 s7, s7, 4
	v_fma_f32 v62, -v42, v43, 1.0
	v_fmac_f32_e32 v43, v62, v43
	v_div_scale_f32 v62, vcc, 1.0, v24, 1.0
	v_mul_f32_e32 v63, v62, v43
	v_fma_f32 v68, -v42, v63, v62
	v_fmac_f32_e32 v63, v68, v43
	v_fma_f32 v42, -v42, v63, v62
	v_div_fmas_f32 v42, v42, v43, v63
	v_div_fixup_f32 v24, v42, v24, 1.0
	v_pk_fma_f32 v[42:43], v[24:25], v[60:61], v[52:53] op_sel_hi:[0,1,1] neg_lo:[0,0,1] neg_hi:[0,0,1]
	v_pk_fma_f32 v[62:63], v[24:25], v[66:67], v[32:33] op_sel_hi:[0,1,1] neg_lo:[0,0,1] neg_hi:[0,0,1]
	v_pk_mul_f32 v[62:63], v[2:3], v[62:63]
	v_pk_mul_f32 v[42:43], v[0:1], v[42:43]
	s_nop 0
	v_cvt_pk_bf16_f32 v42, v42, v43
	v_cvt_pk_bf16_f32 v43, v62, v63
	global_store_dwordx2 v[64:65], v[42:43], off offset:3072
	v_lshlrev_b32_e32 v62, 16, v115
	v_and_b32_e32 v63, 0xffff0000, v115
	v_lshlrev_b32_e32 v64, 16, v25
	v_and_b32_e32 v65, 0xffff0000, v25
	v_pk_mul_f32 v[24:25], v[20:21], v[64:65] op_sel_hi:[0,1]
	v_pk_mul_f32 v[42:43], v[20:21], v[62:63] op_sel_hi:[0,1]
	v_pk_fma_f32 v[58:59], v[20:21], v[62:63], v[58:59] op_sel_hi:[0,1,1] neg_lo:[0,0,1] neg_hi:[0,0,1]
	v_pk_fma_f32 v[40:41], v[20:21], v[64:65], v[40:41] op_sel_hi:[0,1,1] neg_lo:[0,0,1] neg_hi:[0,0,1]
	v_cvt_f32_i32_e32 v20, s7
	v_pk_add_f32 v[62:63], v[66:67], v[40:41]
	v_pk_add_f32 v[60:61], v[60:61], v[58:59]
	s_max_i32 s7, s63, 4
	v_div_scale_f32 v40, s[18:19], v20, v20, 1.0
	v_rcp_f32_e32 v41, v40
	s_min_i32 s18, s21, s23
	s_sub_i32 s7, s18, s7
	s_add_i32 s7, s7, 4
	v_fma_f32 v58, -v40, v41, 1.0
	v_fmac_f32_e32 v41, v58, v41
	v_div_scale_f32 v58, vcc, 1.0, v20, 1.0
	v_mul_f32_e32 v59, v58, v41
	v_fma_f32 v64, -v40, v59, v58
	v_fmac_f32_e32 v59, v64, v41
	v_fma_f32 v40, -v40, v59, v58
	v_div_fmas_f32 v40, v40, v41, v59
	v_div_fixup_f32 v20, v40, v20, 1.0
	v_pk_fma_f32 v[40:41], v[20:21], v[60:61], v[48:49] op_sel_hi:[0,1,1] neg_lo:[0,0,1] neg_hi:[0,0,1]
	v_pk_fma_f32 v[58:59], v[20:21], v[62:63], v[30:31] op_sel_hi:[0,1,1] neg_lo:[0,0,1] neg_hi:[0,0,1]
	v_pk_mul_f32 v[40:41], v[0:1], v[40:41]
	v_add_co_u32_e32 v64, vcc, s58, v16
	v_pk_mul_f32 v[58:59], v[2:3], v[58:59]
	v_cvt_pk_bf16_f32 v40, v40, v41
	s_nop 0
	v_addc_co_u32_e32 v65, vcc, 0, v17, vcc
	v_cvt_pk_bf16_f32 v41, v58, v59
	v_lshlrev_b32_e32 v20, 16, v21
	v_and_b32_e32 v21, 0xffff0000, v21
	global_store_dwordx2 v[64:65], v[40:41], off offset:1024
	v_pk_mul_f32 v[40:41], v[22:23], v[20:21] op_sel_hi:[0,1]
	v_pk_fma_f32 v[20:21], v[22:23], v[20:21], v[34:35] op_sel_hi:[0,1,1] neg_lo:[0,0,1] neg_hi:[0,0,1]
	v_pk_add_f32 v[34:35], v[62:63], v[20:21]
	v_cvt_f32_i32_e32 v20, s7
	v_lshlrev_b32_e32 v66, 16, v23
	v_and_b32_e32 v67, 0xffff0000, v23
	v_pk_mul_f32 v[58:59], v[22:23], v[66:67] op_sel_hi:[0,1]
	v_div_scale_f32 v21, s[18:19], v20, v20, 1.0
	v_pk_fma_f32 v[54:55], v[22:23], v[66:67], v[54:55] op_sel_hi:[0,1,1] neg_lo:[0,0,1] neg_hi:[0,0,1]
	v_rcp_f32_e32 v22, v21
	v_pk_add_f32 v[54:55], v[60:61], v[54:55]
	s_max_i32 s7, s62, 4
	s_min_i32 s18, s15, s23
	v_fma_f32 v23, -v21, v22, 1.0
	v_fmac_f32_e32 v22, v23, v22
	v_div_scale_f32 v23, vcc, 1.0, v20, 1.0
	v_mul_f32_e32 v60, v23, v22
	v_fma_f32 v61, -v21, v60, v23
	v_fmac_f32_e32 v60, v61, v22
	v_fma_f32 v21, -v21, v60, v23
	v_div_fmas_f32 v21, v21, v22, v60
	v_div_fixup_f32 v20, v21, v20, 1.0
	v_pk_fma_f32 v[22:23], v[20:21], v[54:55], v[46:47] op_sel_hi:[0,1,1] neg_lo:[0,0,1] neg_hi:[0,0,1]
	v_pk_fma_f32 v[20:21], v[20:21], v[34:35], v[28:29] op_sel_hi:[0,1,1] neg_lo:[0,0,1] neg_hi:[0,0,1]
	v_pk_mul_f32 v[22:23], v[0:1], v[22:23]
	s_sub_i32 s7, s18, s7
	v_pk_mul_f32 v[20:21], v[2:3], v[20:21]
	v_cvt_pk_bf16_f32 v22, v22, v23
	v_lshlrev_b32_e32 v60, 16, v114
	v_cvt_pk_bf16_f32 v23, v20, v21
	v_and_b32_e32 v61, 0xffff0000, v114
	v_lshlrev_b32_e32 v62, 16, v113
	v_and_b32_e32 v63, 0xffff0000, v113
	s_add_i32 s7, s7, 4
	global_store_dwordx2 v[64:65], v[22:23], off offset:3072
	v_pk_mul_f32 v[20:21], v[18:19], v[62:63] op_sel_hi:[0,1]
	v_pk_mul_f32 v[22:23], v[18:19], v[60:61] op_sel_hi:[0,1]
	v_pk_fma_f32 v[50:51], v[18:19], v[60:61], v[50:51] op_sel_hi:[0,1,1] neg_lo:[0,0,1] neg_hi:[0,0,1]
	v_pk_fma_f32 v[38:39], v[18:19], v[62:63], v[38:39] op_sel_hi:[0,1,1] neg_lo:[0,0,1] neg_hi:[0,0,1]
	v_cvt_f32_i32_e32 v18, s7
	v_pk_add_f32 v[60:61], v[34:35], v[38:39]
	v_pk_add_f32 v[50:51], v[54:55], v[50:51]
	s_max_i32 s7, s34, 4
	v_div_scale_f32 v34, s[18:19], v18, v18, 1.0
	v_rcp_f32_e32 v35, v34
	s_min_i32 s18, s5, s23
	s_sub_i32 s7, s18, s7
	v_lshlrev_b32_e32 v62, 16, v112
	v_fma_f32 v38, -v34, v35, 1.0
	v_fmac_f32_e32 v35, v38, v35
	v_div_scale_f32 v38, vcc, 1.0, v18, 1.0
	v_mul_f32_e32 v39, v38, v35
	v_fma_f32 v54, -v34, v39, v38
	v_fmac_f32_e32 v39, v54, v35
	v_fma_f32 v34, -v34, v39, v38
	v_div_fmas_f32 v34, v34, v35, v39
	v_div_fixup_f32 v18, v34, v18, 1.0
	v_pk_fma_f32 v[34:35], v[18:19], v[50:51], v[44:45] op_sel_hi:[0,1,1] neg_lo:[0,0,1] neg_hi:[0,0,1]
	v_pk_fma_f32 v[38:39], v[18:19], v[60:61], v[26:27] op_sel_hi:[0,1,1] neg_lo:[0,0,1] neg_hi:[0,0,1]
	v_pk_mul_f32 v[34:35], v[0:1], v[34:35]
	v_add_co_u32_e32 v54, vcc, s59, v16
	v_pk_mul_f32 v[38:39], v[2:3], v[38:39]
	v_cvt_pk_bf16_f32 v34, v34, v35
	s_nop 0
	v_addc_co_u32_e32 v55, vcc, 0, v17, vcc
	v_cvt_pk_bf16_f32 v35, v38, v39
	v_and_b32_e32 v63, 0xffff0000, v112
	v_lshlrev_b32_e32 v64, 16, v111
	v_and_b32_e32 v65, 0xffff0000, v111
	s_add_i32 s7, s7, 4
	global_store_dwordx2 v[54:55], v[34:35], off offset:1024
	v_pk_mul_f32 v[34:35], v[14:15], v[64:65] op_sel_hi:[0,1]
	v_pk_mul_f32 v[38:39], v[14:15], v[62:63] op_sel_hi:[0,1]
	v_pk_fma_f32 v[56:57], v[14:15], v[62:63], v[56:57] op_sel_hi:[0,1,1] neg_lo:[0,0,1] neg_hi:[0,0,1]
	v_pk_fma_f32 v[36:37], v[14:15], v[64:65], v[36:37] op_sel_hi:[0,1,1] neg_lo:[0,0,1] neg_hi:[0,0,1]
	v_cvt_f32_i32_e32 v14, s7
	v_pk_add_f32 v[50:51], v[50:51], v[56:57]
	v_pk_add_f32 v[36:37], v[60:61], v[36:37]
	s_max_i32 s7, s20, 4
	v_div_scale_f32 v18, s[18:19], v14, v14, 1.0
	v_rcp_f32_e32 v56, v18
	s_min_i32 s18, s70, s23
	s_sub_i32 s7, s18, s7
	s_add_i32 s7, s7, 4
	v_fma_f32 v57, -v18, v56, 1.0
	v_fmac_f32_e32 v56, v57, v56
	v_div_scale_f32 v57, vcc, 1.0, v14, 1.0
	v_mul_f32_e32 v60, v57, v56
	v_fma_f32 v61, -v18, v60, v57
	v_fmac_f32_e32 v60, v61, v56
	v_fma_f32 v18, -v18, v60, v57
	v_div_fmas_f32 v18, v18, v56, v60
	v_div_fixup_f32 v14, v18, v14, 1.0
	v_pk_fma_f32 v[42:43], v[14:15], v[50:51], v[42:43] op_sel_hi:[0,1,1] neg_lo:[0,0,1] neg_hi:[0,0,1]
	v_pk_fma_f32 v[24:25], v[14:15], v[36:37], v[24:25] op_sel_hi:[0,1,1] neg_lo:[0,0,1] neg_hi:[0,0,1]
	v_pk_mul_f32 v[42:43], v[0:1], v[42:43]
	v_pk_mul_f32 v[24:25], v[2:3], v[24:25]
	v_cvt_pk_bf16_f32 v42, v42, v43
	s_max_i32 s5, s5, 4
	v_cvt_pk_bf16_f32 v43, v24, v25
	global_store_dwordx2 v[54:55], v[42:43], off offset:3072
	v_lshlrev_b32_e32 v24, 16, v19
	v_and_b32_e32 v25, 0xffff0000, v19
	v_lshlrev_b32_e32 v42, 16, v15
	v_and_b32_e32 v43, 0xffff0000, v15
	v_pk_mul_f32 v[14:15], v[12:13], v[42:43] op_sel_hi:[0,1]
	v_pk_mul_f32 v[18:19], v[12:13], v[24:25] op_sel_hi:[0,1]
	v_pk_fma_f32 v[24:25], v[12:13], v[24:25], v[52:53] op_sel_hi:[0,1,1] neg_lo:[0,0,1] neg_hi:[0,0,1]
	v_pk_fma_f32 v[32:33], v[12:13], v[42:43], v[32:33] op_sel_hi:[0,1,1] neg_lo:[0,0,1] neg_hi:[0,0,1]
	v_cvt_f32_i32_e32 v12, s7
	v_pk_add_f32 v[32:33], v[36:37], v[32:33]
	v_pk_add_f32 v[24:25], v[50:51], v[24:25]
	s_max_i32 s7, s21, 4
	v_div_scale_f32 v36, s[18:19], v12, v12, 1.0
	v_rcp_f32_e32 v37, v36
	s_min_i32 s18, s67, s23
	s_sub_i32 s7, s18, s7
	s_add_i32 s7, s7, 4
	v_fma_f32 v42, -v36, v37, 1.0
	v_fmac_f32_e32 v37, v42, v37
	v_div_scale_f32 v42, vcc, 1.0, v12, 1.0
	v_mul_f32_e32 v43, v42, v37
	v_fma_f32 v50, -v36, v43, v42
	v_fmac_f32_e32 v43, v50, v37
	v_fma_f32 v36, -v36, v43, v42
	v_div_fmas_f32 v36, v36, v37, v43
	v_div_fixup_f32 v12, v36, v12, 1.0
	v_pk_fma_f32 v[36:37], v[12:13], v[24:25], v[58:59] op_sel_hi:[0,1,1] neg_lo:[0,0,1] neg_hi:[0,0,1]
	v_pk_fma_f32 v[40:41], v[12:13], v[32:33], v[40:41] op_sel_hi:[0,1,1] neg_lo:[0,0,1] neg_hi:[0,0,1]
	v_pk_mul_f32 v[40:41], v[2:3], v[40:41]
	v_pk_mul_f32 v[36:37], v[0:1], v[36:37]
	v_lshlrev_b32_e32 v42, 16, v109
	v_cvt_pk_bf16_f32 v36, v36, v37
	v_cvt_pk_bf16_f32 v37, v40, v41
	v_add_co_u32_e32 v40, vcc, s60, v16
	v_and_b32_e32 v43, 0xffff0000, v109
	s_nop 0
	v_addc_co_u32_e32 v41, vcc, 0, v17, vcc
	global_store_dwordx2 v[40:41], v[36:37], off offset:1024
	v_lshlrev_b32_e32 v36, 16, v110
	v_and_b32_e32 v37, 0xffff0000, v110
	v_pk_fma_f32 v[36:37], v[10:11], v[36:37], v[48:49] op_sel_hi:[0,1,1] neg_lo:[0,0,1] neg_hi:[0,0,1]
	v_pk_fma_f32 v[30:31], v[10:11], v[42:43], v[30:31] op_sel_hi:[0,1,1] neg_lo:[0,0,1] neg_hi:[0,0,1]
	v_cvt_f32_i32_e32 v10, s7
	v_pk_add_f32 v[30:31], v[32:33], v[30:31]
	v_pk_add_f32 v[24:25], v[24:25], v[36:37]
	s_max_i32 s7, s15, 4
	v_div_scale_f32 v12, s[18:19], v10, v10, 1.0
	v_rcp_f32_e32 v32, v12
	s_min_i32 s15, s66, s23
	s_sub_i32 s7, s15, s7
	s_add_i32 s7, s7, 4
	v_fma_f32 v33, -v12, v32, 1.0
	v_fmac_f32_e32 v32, v33, v32
	v_div_scale_f32 v33, vcc, 1.0, v10, 1.0
	v_mul_f32_e32 v36, v33, v32
	v_fma_f32 v37, -v12, v36, v33
	v_fmac_f32_e32 v36, v37, v32
	v_fma_f32 v12, -v12, v36, v33
	v_div_fmas_f32 v12, v12, v32, v36
	v_div_fixup_f32 v10, v12, v10, 1.0
	v_pk_fma_f32 v[22:23], v[10:11], v[24:25], v[22:23] op_sel_hi:[0,1,1] neg_lo:[0,0,1] neg_hi:[0,0,1]
	v_pk_fma_f32 v[20:21], v[10:11], v[30:31], v[20:21] op_sel_hi:[0,1,1] neg_lo:[0,0,1] neg_hi:[0,0,1]
	v_cvt_f32_i32_e32 v10, s7
	v_pk_mul_f32 v[20:21], v[2:3], v[20:21]
	v_pk_mul_f32 v[22:23], v[0:1], v[22:23]
	v_lshlrev_b32_e32 v12, 16, v13
	v_cvt_pk_bf16_f32 v22, v22, v23
	v_cvt_pk_bf16_f32 v23, v20, v21
	v_and_b32_e32 v13, 0xffff0000, v13
	v_lshlrev_b32_e32 v20, 16, v7
	v_and_b32_e32 v21, 0xffff0000, v7
	v_pk_fma_f32 v[12:13], v[6:7], v[12:13], v[46:47] op_sel_hi:[0,1,1] neg_lo:[0,0,1] neg_hi:[0,0,1]
	v_pk_fma_f32 v[6:7], v[6:7], v[20:21], v[28:29] op_sel_hi:[0,1,1] neg_lo:[0,0,1] neg_hi:[0,0,1]
	v_div_scale_f32 v20, s[18:19], v10, v10, 1.0
	v_rcp_f32_e32 v21, v20
	global_store_dwordx2 v[40:41], v[22:23], off offset:3072
	v_pk_add_f32 v[12:13], v[24:25], v[12:13]
	s_add_i32 s7, s4, 35
	v_fma_f32 v22, -v20, v21, 1.0
	v_fmac_f32_e32 v21, v22, v21
	v_div_scale_f32 v22, vcc, 1.0, v10, 1.0
	v_mul_f32_e32 v23, v22, v21
	v_fma_f32 v24, -v20, v23, v22
	v_fmac_f32_e32 v23, v24, v21
	v_fma_f32 v20, -v20, v23, v22
	v_div_fmas_f32 v20, v20, v21, v23
	s_min_i32 s7, s7, s23
	v_div_fixup_f32 v10, v20, v10, 1.0
	s_sub_i32 s5, s7, s5
	v_pk_add_f32 v[6:7], v[30:31], v[6:7]
	v_pk_fma_f32 v[20:21], v[10:11], v[12:13], v[38:39] op_sel_hi:[0,1,1] neg_lo:[0,0,1] neg_hi:[0,0,1]
	s_add_i32 s5, s5, 4
	v_pk_fma_f32 v[22:23], v[10:11], v[6:7], v[34:35] op_sel_hi:[0,1,1] neg_lo:[0,0,1] neg_hi:[0,0,1]
	v_pk_mul_f32 v[20:21], v[0:1], v[20:21]
	v_add_co_u32_e32 v16, vcc, s50, v16
	v_cvt_f32_i32_e32 v10, s5
	v_pk_mul_f32 v[22:23], v[2:3], v[22:23]
	v_cvt_pk_bf16_f32 v20, v20, v21
	v_addc_co_u32_e32 v17, vcc, 0, v17, vcc
	v_cvt_pk_bf16_f32 v21, v22, v23
	global_store_dwordx2 v[16:17], v[20:21], off offset:1024
	v_lshlrev_b32_e32 v16, 16, v108
	v_and_b32_e32 v17, 0xffff0000, v108
	v_lshlrev_b32_e32 v20, 16, v9
	v_and_b32_e32 v21, 0xffff0000, v9
	s_waitcnt vmcnt(31)
	v_pk_fma_f32 v[16:17], v[8:9], v[16:17], v[44:45] op_sel_hi:[0,1,1] neg_lo:[0,0,1] neg_hi:[0,0,1]
	v_pk_fma_f32 v[8:9], v[8:9], v[20:21], v[26:27] op_sel_hi:[0,1,1] neg_lo:[0,0,1] neg_hi:[0,0,1]
	v_pk_add_f32 v[6:7], v[6:7], v[8:9]
	v_pk_add_f32 v[8:9], v[12:13], v[16:17]
	v_div_scale_f32 v12, s[18:19], v10, v10, 1.0
	v_rcp_f32_e32 v13, v12
	s_mov_b64 s[18:19], 0
	v_fma_f32 v16, -v12, v13, 1.0
	v_fmac_f32_e32 v13, v16, v13
	v_div_scale_f32 v16, vcc, 1.0, v10, 1.0
	v_mul_f32_e32 v17, v16, v13
	v_fma_f32 v20, -v12, v17, v16
	v_fmac_f32_e32 v17, v20, v13
	v_fma_f32 v12, -v12, v17, v16
	v_div_fmas_f32 v12, v12, v13, v17
	v_div_fixup_f32 v10, v12, v10, 1.0
	v_pk_fma_f32 v[8:9], v[10:11], v[8:9], v[18:19] op_sel_hi:[0,1,1] neg_lo:[0,0,1] neg_hi:[0,0,1]
	v_pk_fma_f32 v[6:7], v[10:11], v[6:7], v[14:15] op_sel_hi:[0,1,1] neg_lo:[0,0,1] neg_hi:[0,0,1]
	v_pk_mul_f32 v[12:13], v[2:3], v[6:7]
	v_pk_mul_f32 v[6:7], v[0:1], v[8:9]
	s_nop 0
	v_cvt_pk_bf16_f32 v6, v6, v7
	v_cvt_pk_bf16_f32 v7, v12, v13

.LBB0_400:
	s_and_b64 vcc, exec, s[20:21]
	s_cbranch_vccz .LBB0_402
	s_add_i32 s5, s4, -2
	s_cmp_lt_u32 s5, s23
	s_cselect_b64 vcc, -1, 0
	s_and_b64 s[20:21], vcc, exec
	s_cselect_b32 s20, s5, s4
	v_lshlrev_b32_e32 v96, 1, v11
	s_ashr_i32 s21, s20, 31
	v_lshl_add_u64 v[8:9], s[2:3], 0, v[96:97]
	s_lshl_b64 s[34:35], s[20:21], 11
	v_lshl_add_u64 v[4:5], v[8:9], 0, s[34:35]
	global_load_dwordx2 v[4:5], v[4:5], off offset:512 nt
	s_add_i32 s20, s20, s14
	s_ashr_i32 s21, s20, 31
	s_lshl_b64 s[20:21], s[20:21], 2
	s_add_u32 s20, s26, s20
	s_addc_u32 s21, s27, s21
	s_add_i32 s5, s4, -1
	s_cmp_lt_u32 s5, s23
	s_mov_b64 s[30:31], 0x200
	s_waitcnt vmcnt(0)
	v_cndmask_b32_e32 v15, 0, v4, vcc
	v_cndmask_b32_e32 v5, 0, v5, vcc
	s_cselect_b64 vcc, -1, 0
	global_load_dword v4, v97, s[20:21]
	s_and_b64 s[20:21], vcc, exec
	s_cselect_b32 s20, s5, s4
	s_ashr_i32 s21, s20, 31
	s_lshl_b64 s[34:35], s[20:21], 11
	v_lshl_add_u64 v[6:7], v[8:9], 0, s[34:35]
	global_load_dwordx2 v[6:7], v[6:7], off offset:512 nt
	s_add_i32 s20, s20, s14
	s_ashr_i32 s21, s20, 31
	s_lshl_b64 s[20:21], s[20:21], 2
	s_add_u32 s20, s26, s20
	s_addc_u32 s21, s27, s21
	s_cmp_lt_u32 s4, s23
	global_load_dword v14, v97, s[20:21]
	v_lshlrev_b32_e32 v82, 16, v15
	v_and_b32_e32 v83, 0xffff0000, v15
	v_lshlrev_b32_e32 v84, 16, v5
	v_and_b32_e32 v85, 0xffff0000, v5
	s_waitcnt vmcnt(2)
	v_pk_mul_f32 v[116:117], v[4:5], v[84:85] op_sel_hi:[0,1]
	v_pk_mul_f32 v[118:119], v[4:5], v[82:83] op_sel_hi:[0,1]
	v_pk_fma_f32 v[82:83], v[4:5], v[82:83], 0 op_sel_hi:[0,1,0]
	v_pk_fma_f32 v[4:5], v[4:5], v[84:85], 0 op_sel_hi:[0,1,0]
	s_waitcnt vmcnt(1)
	v_cndmask_b32_e32 v74, 0, v6, vcc
	v_cndmask_b32_e32 v71, 0, v7, vcc
	s_cselect_b64 vcc, -1, 0
	s_ashr_i32 s5, s4, 31
	s_lshl_b64 s[20:21], s[4:5], 11
	v_lshl_add_u64 v[6:7], v[8:9], 0, s[20:21]
	global_load_dwordx2 v[6:7], v[6:7], off offset:512 nt
	s_ashr_i32 s7, s6, 31
	s_lshl_b64 s[20:21], s[6:7], 2
	s_add_u32 s20, s26, s20
	s_addc_u32 s21, s27, s21
	s_or_b32 s91, s4, 1
	s_cmp_lt_u32 s91, s23
	global_load_dword v70, v97, s[20:21]
	v_lshlrev_b32_e32 v84, 16, v74
	v_and_b32_e32 v85, 0xffff0000, v74
	v_lshlrev_b32_e32 v120, 16, v71
	v_and_b32_e32 v121, 0xffff0000, v71
	s_waitcnt vmcnt(2)
	v_pk_mul_f32 v[122:123], v[14:15], v[120:121] op_sel_hi:[0,1]
	v_pk_mul_f32 v[124:125], v[14:15], v[84:85] op_sel_hi:[0,1]
	v_pk_fma_f32 v[4:5], v[14:15], v[120:121], v[4:5] op_sel_hi:[0,1,1]
	v_pk_fma_f32 v[14:15], v[14:15], v[84:85], v[82:83] op_sel_hi:[0,1,1]
	s_waitcnt vmcnt(1)
	v_cndmask_b32_e32 v77, 0, v6, vcc
	v_cndmask_b32_e32 v75, 0, v7, vcc
	s_cselect_b64 vcc, -1, 0
	s_and_b64 s[20:21], vcc, exec
	s_cselect_b32 s20, s91, s4
	s_ashr_i32 s21, s20, 31
	s_lshl_b64 s[34:35], s[20:21], 11
	v_lshl_add_u64 v[6:7], v[8:9], 0, s[34:35]
	global_load_dwordx2 v[6:7], v[6:7], off offset:512 nt
	s_add_i32 s20, s20, s14
	s_ashr_i32 s21, s20, 31
	s_lshl_b64 s[20:21], s[20:21], 2
	s_add_u32 s20, s26, s20
	s_addc_u32 s21, s27, s21
	s_or_b32 s90, s4, 2
	s_cmp_lt_u32 s90, s23
	global_load_dword v72, v97, s[20:21]
	v_lshlrev_b32_e32 v120, 16, v77
	v_and_b32_e32 v121, 0xffff0000, v77
	v_lshlrev_b32_e32 v74, 16, v75
	v_and_b32_e32 v75, 0xffff0000, v75
	s_waitcnt vmcnt(2)
	v_pk_mul_f32 v[84:85], v[70:71], v[120:121] op_sel_hi:[0,1]
	v_pk_fma_f32 v[14:15], v[70:71], v[120:121], v[14:15] op_sel_hi:[0,1,1]
	v_pk_mul_f32 v[82:83], v[70:71], v[74:75] op_sel_hi:[0,1]
	v_pk_fma_f32 v[4:5], v[70:71], v[74:75], v[4:5] op_sel_hi:[0,1,1]
	s_waitcnt vmcnt(1)
	v_cndmask_b32_e32 v81, 0, v6, vcc
	v_cndmask_b32_e32 v79, 0, v7, vcc
	s_cselect_b64 vcc, -1, 0
	s_and_b64 s[20:21], vcc, exec
	s_cselect_b32 s20, s90, s4
	s_ashr_i32 s21, s20, 31
	s_lshl_b64 s[34:35], s[20:21], 11
	v_lshl_add_u64 v[6:7], v[8:9], 0, s[34:35]
	global_load_dwordx2 v[6:7], v[6:7], off offset:512 nt
	s_add_i32 s20, s20, s14
	s_ashr_i32 s21, s20, 31
	s_lshl_b64 s[20:21], s[20:21], 2
	s_add_u32 s20, s26, s20
	s_addc_u32 s21, s27, s21
	s_or_b32 s89, s4, 3
	s_cmp_lt_u32 s89, s23
	global_load_dword v68, v97, s[20:21]
	v_lshlrev_b32_e32 v120, 16, v81
	v_and_b32_e32 v121, 0xffff0000, v81
	v_lshlrev_b32_e32 v126, 16, v79
	v_and_b32_e32 v127, 0xffff0000, v79
	s_waitcnt vmcnt(1)
	v_cndmask_b32_e32 v76, 0, v6, vcc
	v_cndmask_b32_e32 v73, 0, v7, vcc
	s_cselect_b64 vcc, -1, 0
	s_and_b64 s[20:21], vcc, exec
	s_cselect_b32 s20, s89, s4
	s_ashr_i32 s21, s20, 31
	s_lshl_b64 s[34:35], s[20:21], 11
	v_lshl_add_u64 v[6:7], v[8:9], 0, s[34:35]
	global_load_dwordx2 v[6:7], v[6:7], off offset:512 nt
	s_add_i32 s20, s20, s14
	s_ashr_i32 s21, s20, 31
	s_lshl_b64 s[20:21], s[20:21], 2
	s_add_u32 s20, s26, s20
	s_addc_u32 s21, s27, s21
	s_or_b32 s88, s4, 4
	s_cmp_lt_u32 s88, s23
	global_load_dword v66, v97, s[20:21]
	v_pk_mul_f32 v[74:75], v[72:73], v[120:121] op_sel_hi:[0,1]
	v_pk_fma_f32 v[120:121], v[72:73], v[120:121], v[14:15] op_sel_hi:[0,1,1]
	v_pk_mul_f32 v[70:71], v[72:73], v[126:127] op_sel_hi:[0,1]
	v_pk_fma_f32 v[126:127], v[72:73], v[126:127], v[4:5] op_sel_hi:[0,1,1]
	s_waitcnt vmcnt(1)
	v_cndmask_b32_e32 v78, 0, v6, vcc
	v_cndmask_b32_e32 v69, 0, v7, vcc
	s_cselect_b64 vcc, -1, 0
	s_and_b64 s[20:21], vcc, exec
	s_cselect_b32 s20, s88, s4
	s_ashr_i32 s21, s20, 31
	s_lshl_b64 s[34:35], s[20:21], 11
	v_lshl_add_u64 v[6:7], v[8:9], 0, s[34:35]
	global_load_dwordx2 v[6:7], v[6:7], off offset:512 nt
	s_add_i32 s20, s20, s14
	s_ashr_i32 s21, s20, 31
	s_lshl_b64 s[20:21], s[20:21], 2
	s_add_u32 s20, s26, s20
	s_addc_u32 s21, s27, s21
	s_or_b32 s87, s4, 5
	s_cmp_lt_u32 s87, s23
	global_load_dword v64, v97, s[20:21]
	s_waitcnt vmcnt(1)
	v_cndmask_b32_e32 v80, 0, v6, vcc
	v_cndmask_b32_e32 v67, 0, v7, vcc
	s_cselect_b64 vcc, -1, 0
	s_and_b64 s[20:21], vcc, exec
	s_cselect_b32 s20, s87, s4
	s_ashr_i32 s21, s20, 31
	s_lshl_b64 s[34:35], s[20:21], 11
	v_lshl_add_u64 v[6:7], v[8:9], 0, s[34:35]
	global_load_dwordx2 v[6:7], v[6:7], off offset:512 nt
	s_add_i32 s20, s20, s14
	s_ashr_i32 s21, s20, 31
	s_lshl_b64 s[20:21], s[20:21], 2
	s_add_u32 s20, s26, s20
	s_addc_u32 s21, s27, s21
	s_or_b32 s86, s4, 6
	s_cmp_lt_u32 s86, s23
	global_load_dword v62, v97, s[20:21]
	s_waitcnt vmcnt(1)
	v_cndmask_b32_e32 v115, 0, v6, vcc
	v_cndmask_b32_e32 v65, 0, v7, vcc
	s_cselect_b64 vcc, -1, 0
	s_and_b64 s[20:21], vcc, exec
	s_cselect_b32 s20, s86, s4
	s_ashr_i32 s21, s20, 31
	s_lshl_b64 s[34:35], s[20:21], 11
	v_lshl_add_u64 v[6:7], v[8:9], 0, s[34:35]
	global_load_dwordx2 v[6:7], v[6:7], off offset:512 nt
	s_add_i32 s20, s20, s14
	s_ashr_i32 s21, s20, 31
	s_lshl_b64 s[20:21], s[20:21], 2
	s_add_u32 s20, s26, s20
	s_addc_u32 s21, s27, s21
	s_or_b32 s85, s4, 7
	s_cmp_lt_u32 s85, s23
	global_load_dword v60, v97, s[20:21]
	s_waitcnt vmcnt(1)
	v_cndmask_b32_e32 v114, 0, v6, vcc
	v_cndmask_b32_e32 v63, 0, v7, vcc
	s_cselect_b64 vcc, -1, 0
	s_and_b64 s[20:21], vcc, exec
	s_cselect_b32 s20, s85, s4
	s_ashr_i32 s21, s20, 31
	s_lshl_b64 s[34:35], s[20:21], 11
	v_lshl_add_u64 v[6:7], v[8:9], 0, s[34:35]
	global_load_dwordx2 v[6:7], v[6:7], off offset:512 nt
	s_add_i32 s20, s20, s14
	s_ashr_i32 s21, s20, 31
	s_lshl_b64 s[20:21], s[20:21], 2
	s_add_u32 s20, s26, s20
	s_addc_u32 s21, s27, s21
	s_or_b32 s84, s4, 8
	s_cmp_lt_u32 s84, s23
	global_load_dword v58, v97, s[20:21]
	s_waitcnt vmcnt(1)
	v_cndmask_b32_e32 v113, 0, v6, vcc
	v_cndmask_b32_e32 v61, 0, v7, vcc
	s_cselect_b64 vcc, -1, 0
	s_and_b64 s[20:21], vcc, exec
	s_cselect_b32 s20, s84, s4
	s_ashr_i32 s21, s20, 31
	s_lshl_b64 s[34:35], s[20:21], 11
	v_lshl_add_u64 v[6:7], v[8:9], 0, s[34:35]
	global_load_dwordx2 v[6:7], v[6:7], off offset:512 nt
	s_add_i32 s20, s20, s14
	s_ashr_i32 s21, s20, 31
	s_lshl_b64 s[20:21], s[20:21], 2
	s_add_u32 s20, s26, s20
	s_addc_u32 s21, s27, s21
	s_or_b32 s83, s4, 9
	s_cmp_lt_u32 s83, s23
	global_load_dword v56, v97, s[20:21]
	s_waitcnt vmcnt(1)
	v_cndmask_b32_e32 v112, 0, v6, vcc
	v_cndmask_b32_e32 v59, 0, v7, vcc
	s_cselect_b64 vcc, -1, 0
	s_and_b64 s[20:21], vcc, exec
	s_cselect_b32 s20, s83, s4
	s_ashr_i32 s21, s20, 31
	s_lshl_b64 s[34:35], s[20:21], 11
	v_lshl_add_u64 v[6:7], v[8:9], 0, s[34:35]
	global_load_dwordx2 v[6:7], v[6:7], off offset:512 nt
	s_add_i32 s20, s20, s14
	s_ashr_i32 s21, s20, 31
	s_lshl_b64 s[20:21], s[20:21], 2
	s_add_u32 s20, s26, s20
	s_addc_u32 s21, s27, s21
	s_or_b32 s82, s4, 10
	s_cmp_lt_u32 s82, s23
	global_load_dword v54, v97, s[20:21]
	s_waitcnt vmcnt(1)
	v_cndmask_b32_e32 v111, 0, v6, vcc
	v_cndmask_b32_e32 v57, 0, v7, vcc
	s_cselect_b64 vcc, -1, 0
	s_and_b64 s[20:21], vcc, exec
	s_cselect_b32 s20, s82, s4
	s_ashr_i32 s21, s20, 31
	s_lshl_b64 s[34:35], s[20:21], 11
	v_lshl_add_u64 v[6:7], v[8:9], 0, s[34:35]
	global_load_dwordx2 v[6:7], v[6:7], off offset:512 nt
	s_add_i32 s20, s20, s14
	s_ashr_i32 s21, s20, 31
	s_lshl_b64 s[20:21], s[20:21], 2
	s_add_u32 s20, s26, s20
	s_addc_u32 s21, s27, s21
	s_or_b32 s81, s4, 11
	s_cmp_lt_u32 s81, s23
	global_load_dword v52, v97, s[20:21]
	s_waitcnt vmcnt(1)
	v_cndmask_b32_e32 v110, 0, v6, vcc
	v_cndmask_b32_e32 v55, 0, v7, vcc
	s_cselect_b64 vcc, -1, 0
	s_and_b64 s[20:21], vcc, exec
	s_cselect_b32 s20, s81, s4
	s_ashr_i32 s21, s20, 31
	s_lshl_b64 s[34:35], s[20:21], 11
	v_lshl_add_u64 v[6:7], v[8:9], 0, s[34:35]
	global_load_dwordx2 v[6:7], v[6:7], off offset:512 nt
	s_add_i32 s20, s20, s14
	s_ashr_i32 s21, s20, 31
	s_lshl_b64 s[20:21], s[20:21], 2
	s_add_u32 s20, s26, s20
	s_addc_u32 s21, s27, s21
	s_or_b32 s80, s4, 12
	s_cmp_lt_u32 s80, s23
	global_load_dword v50, v97, s[20:21]
	s_waitcnt vmcnt(1)
	v_cndmask_b32_e32 v109, 0, v6, vcc
	v_cndmask_b32_e32 v53, 0, v7, vcc
	s_cselect_b64 vcc, -1, 0
	s_and_b64 s[20:21], vcc, exec
	s_cselect_b32 s20, s80, s4
	s_ashr_i32 s21, s20, 31
	s_lshl_b64 s[34:35], s[20:21], 11
	v_lshl_add_u64 v[6:7], v[8:9], 0, s[34:35]
	global_load_dwordx2 v[6:7], v[6:7], off offset:512 nt
	s_add_i32 s20, s20, s14
	s_ashr_i32 s21, s20, 31
	s_lshl_b64 s[20:21], s[20:21], 2
	s_add_u32 s20, s26, s20
	s_addc_u32 s21, s27, s21
	s_or_b32 s79, s4, 13
	s_cmp_lt_u32 s79, s23
	global_load_dword v46, v97, s[20:21]
	s_waitcnt vmcnt(1)
	v_cndmask_b32_e32 v51, 0, v6, vcc
	v_cndmask_b32_e32 v47, 0, v7, vcc
	s_cselect_b64 vcc, -1, 0
	s_and_b64 s[20:21], vcc, exec
	s_cselect_b32 s20, s79, s4
	s_ashr_i32 s21, s20, 31
	s_lshl_b64 s[34:35], s[20:21], 11
	v_lshl_add_u64 v[6:7], v[8:9], 0, s[34:35]
	global_load_dwordx2 v[6:7], v[6:7], off offset:512 nt
	s_add_i32 s20, s20, s14
	s_ashr_i32 s21, s20, 31
	s_lshl_b64 s[20:21], s[20:21], 2
	s_add_u32 s20, s26, s20
	s_addc_u32 s21, s27, s21
	s_or_b32 s35, s4, 14
	s_cmp_lt_u32 s35, s23
	global_load_dword v48, v97, s[20:21]
	s_waitcnt vmcnt(1)
	v_cndmask_b32_e32 v108, 0, v6, vcc
	v_cndmask_b32_e32 v107, 0, v7, vcc
	s_cselect_b64 vcc, -1, 0
	s_and_b64 s[20:21], vcc, exec
	s_cselect_b32 s20, s35, s4
	s_ashr_i32 s21, s20, 31
	s_lshl_b64 s[62:63], s[20:21], 11
	v_lshl_add_u64 v[6:7], v[8:9], 0, s[62:63]
	global_load_dwordx2 v[6:7], v[6:7], off offset:512 nt
	s_add_i32 s20, s20, s14
	s_ashr_i32 s21, s20, 31
	s_lshl_b64 s[20:21], s[20:21], 2
	s_add_u32 s20, s26, s20
	s_addc_u32 s21, s27, s21
	s_or_b32 s78, s4, 15
	s_cmp_lt_u32 s78, s23
	global_load_dword v44, v97, s[20:21]
	s_waitcnt vmcnt(1)
	v_cndmask_b32_e32 v106, 0, v6, vcc
	v_cndmask_b32_e32 v49, 0, v7, vcc
	s_cselect_b64 vcc, -1, 0
	s_and_b64 s[20:21], vcc, exec
	s_cselect_b32 s20, s78, s4
	s_ashr_i32 s21, s20, 31
	s_lshl_b64 s[62:63], s[20:21], 11
	v_lshl_add_u64 v[6:7], v[8:9], 0, s[62:63]
	global_load_dwordx2 v[6:7], v[6:7], off offset:512 nt
	s_add_i32 s20, s20, s14
	s_ashr_i32 s21, s20, 31
	s_lshl_b64 s[20:21], s[20:21], 2
	s_add_u32 s20, s26, s20
	s_addc_u32 s21, s27, s21
	s_or_b32 s77, s4, 16
	s_cmp_lt_u32 s77, s23
	global_load_dword v42, v97, s[20:21]
	s_waitcnt vmcnt(1)
	v_cndmask_b32_e32 v105, 0, v6, vcc
	v_cndmask_b32_e32 v45, 0, v7, vcc
	s_cselect_b64 vcc, -1, 0
	s_and_b64 s[20:21], vcc, exec
	s_cselect_b32 s20, s77, s4
	s_ashr_i32 s21, s20, 31
	s_lshl_b64 s[62:63], s[20:21], 11
	v_lshl_add_u64 v[6:7], v[8:9], 0, s[62:63]
	global_load_dwordx2 v[6:7], v[6:7], off offset:512 nt
	s_add_i32 s20, s20, s14
	s_ashr_i32 s21, s20, 31
	s_lshl_b64 s[20:21], s[20:21], 2
	s_add_u32 s20, s26, s20
	s_addc_u32 s21, s27, s21
	s_or_b32 s76, s4, 17
	s_cmp_lt_u32 s76, s23
	global_load_dword v40, v97, s[20:21]
	s_waitcnt vmcnt(1)
	v_cndmask_b32_e32 v104, 0, v6, vcc
	v_cndmask_b32_e32 v43, 0, v7, vcc
	s_cselect_b64 vcc, -1, 0
	s_and_b64 s[20:21], vcc, exec
	s_cselect_b32 s20, s76, s4
	s_ashr_i32 s21, s20, 31
	s_lshl_b64 s[62:63], s[20:21], 11
	v_lshl_add_u64 v[6:7], v[8:9], 0, s[62:63]
	global_load_dwordx2 v[6:7], v[6:7], off offset:512 nt
	s_add_i32 s20, s20, s14
	s_ashr_i32 s21, s20, 31
	s_lshl_b64 s[20:21], s[20:21], 2
	s_add_u32 s20, s26, s20
	s_addc_u32 s21, s27, s21
	s_or_b32 s75, s4, 18
	s_cmp_lt_u32 s75, s23
	global_load_dword v38, v97, s[20:21]
	s_waitcnt vmcnt(1)
	v_cndmask_b32_e32 v103, 0, v6, vcc
	v_cndmask_b32_e32 v41, 0, v7, vcc
	s_cselect_b64 vcc, -1, 0
	s_and_b64 s[20:21], vcc, exec
	s_cselect_b32 s20, s75, s4
	s_ashr_i32 s21, s20, 31
	s_lshl_b64 s[62:63], s[20:21], 11
	v_lshl_add_u64 v[6:7], v[8:9], 0, s[62:63]
	global_load_dwordx2 v[6:7], v[6:7], off offset:512 nt
	s_add_i32 s20, s20, s14
	s_ashr_i32 s21, s20, 31
	s_lshl_b64 s[20:21], s[20:21], 2
	s_add_u32 s20, s26, s20
	s_addc_u32 s21, s27, s21
	s_or_b32 s74, s4, 19
	s_cmp_lt_u32 s74, s23
	global_load_dword v36, v97, s[20:21]
	s_waitcnt vmcnt(1)
	v_cndmask_b32_e32 v102, 0, v6, vcc
	v_cndmask_b32_e32 v39, 0, v7, vcc
	s_cselect_b64 vcc, -1, 0
	s_and_b64 s[20:21], vcc, exec
	s_cselect_b32 s20, s74, s4
	s_ashr_i32 s21, s20, 31
	s_lshl_b64 s[62:63], s[20:21], 11
	v_lshl_add_u64 v[6:7], v[8:9], 0, s[62:63]
	global_load_dwordx2 v[6:7], v[6:7], off offset:512 nt
	s_add_i32 s20, s20, s14
	s_ashr_i32 s21, s20, 31
	s_lshl_b64 s[20:21], s[20:21], 2
	s_add_u32 s20, s26, s20
	s_addc_u32 s21, s27, s21
	s_or_b32 s72, s4, 20
	s_cmp_lt_u32 s72, s23
	global_load_dword v32, v97, s[20:21]
	s_waitcnt vmcnt(1)
	v_cndmask_b32_e32 v101, 0, v6, vcc
	v_cndmask_b32_e32 v37, 0, v7, vcc
	s_cselect_b64 vcc, -1, 0
	s_and_b64 s[20:21], vcc, exec
	s_cselect_b32 s20, s72, s4
	s_ashr_i32 s21, s20, 31
	s_lshl_b64 s[62:63], s[20:21], 11
	v_lshl_add_u64 v[6:7], v[8:9], 0, s[62:63]
	global_load_dwordx2 v[6:7], v[6:7], off offset:512 nt
	s_add_i32 s20, s20, s14
	s_ashr_i32 s21, s20, 31
	s_lshl_b64 s[20:21], s[20:21], 2
	s_add_u32 s20, s26, s20
	s_addc_u32 s21, s27, s21
	s_or_b32 s73, s4, 21
	s_cmp_lt_u32 s73, s23
	global_load_dword v34, v97, s[20:21]
	s_waitcnt vmcnt(1)
	v_cndmask_b32_e32 v35, 0, v6, vcc
	v_cndmask_b32_e32 v33, 0, v7, vcc
	s_cselect_b64 vcc, -1, 0
	s_and_b64 s[20:21], vcc, exec
	s_cselect_b32 s20, s73, s4
	s_ashr_i32 s21, s20, 31
	s_lshl_b64 s[62:63], s[20:21], 11
	v_lshl_add_u64 v[6:7], v[8:9], 0, s[62:63]
	global_load_dwordx2 v[6:7], v[6:7], off offset:512 nt
	s_add_i32 s20, s20, s14
	s_ashr_i32 s21, s20, 31
	s_lshl_b64 s[20:21], s[20:21], 2
	s_add_u32 s20, s26, s20
	s_addc_u32 s21, s27, s21
	s_or_b32 s71, s4, 22
	s_cmp_lt_u32 s71, s23
	global_load_dword v30, v97, s[20:21]
	s_waitcnt vmcnt(1)
	v_cndmask_b32_e32 v100, 0, v6, vcc
	v_cndmask_b32_e32 v99, 0, v7, vcc
	s_cselect_b64 vcc, -1, 0
	s_and_b64 s[20:21], vcc, exec
	s_cselect_b32 s20, s71, s4
	s_ashr_i32 s21, s20, 31
	s_lshl_b64 s[62:63], s[20:21], 11
	v_lshl_add_u64 v[6:7], v[8:9], 0, s[62:63]
	global_load_dwordx2 v[6:7], v[6:7], off offset:512 nt
	s_add_i32 s20, s20, s14
	s_ashr_i32 s21, s20, 31
	s_lshl_b64 s[20:21], s[20:21], 2
	s_add_u32 s20, s26, s20
	s_addc_u32 s21, s27, s21
	s_or_b32 s70, s4, 23
	s_cmp_lt_u32 s70, s23
	global_load_dword v28, v97, s[20:21]
	s_waitcnt vmcnt(1)
	v_cndmask_b32_e32 v98, 0, v6, vcc
	v_cndmask_b32_e32 v31, 0, v7, vcc
	s_cselect_b64 vcc, -1, 0
	s_and_b64 s[20:21], vcc, exec
	s_cselect_b32 s20, s70, s4
	s_ashr_i32 s21, s20, 31
	s_lshl_b64 s[62:63], s[20:21], 11
	v_lshl_add_u64 v[6:7], v[8:9], 0, s[62:63]
	global_load_dwordx2 v[6:7], v[6:7], off offset:512 nt
	s_add_i32 s20, s20, s14
	s_ashr_i32 s21, s20, 31
	s_lshl_b64 s[20:21], s[20:21], 2
	s_add_u32 s20, s26, s20
	s_addc_u32 s21, s27, s21
	s_or_b32 s69, s4, 24
	s_cmp_lt_u32 s69, s23
	global_load_dword v26, v97, s[20:21]
	s_waitcnt vmcnt(1)
	v_cndmask_b32_e32 v95, 0, v6, vcc
	v_cndmask_b32_e32 v29, 0, v7, vcc
	s_cselect_b64 vcc, -1, 0
	s_and_b64 s[20:21], vcc, exec
	s_cselect_b32 s20, s69, s4
	s_ashr_i32 s21, s20, 31
	s_lshl_b64 s[62:63], s[20:21], 11
	v_lshl_add_u64 v[6:7], v[8:9], 0, s[62:63]
	global_load_dwordx2 v[6:7], v[6:7], off offset:512 nt
	s_add_i32 s20, s20, s14
	s_ashr_i32 s21, s20, 31
	s_lshl_b64 s[20:21], s[20:21], 2
	s_add_u32 s20, s26, s20
	s_addc_u32 s21, s27, s21
	s_or_b32 s68, s4, 25
	s_cmp_lt_u32 s68, s23
	global_load_dword v24, v97, s[20:21]
	s_waitcnt vmcnt(1)
	v_cndmask_b32_e32 v94, 0, v6, vcc
	v_cndmask_b32_e32 v27, 0, v7, vcc
	s_cselect_b64 vcc, -1, 0
	s_and_b64 s[20:21], vcc, exec
	s_cselect_b32 s20, s68, s4
	s_ashr_i32 s21, s20, 31
	s_lshl_b64 s[62:63], s[20:21], 11
	v_lshl_add_u64 v[6:7], v[8:9], 0, s[62:63]
	global_load_dwordx2 v[6:7], v[6:7], off offset:512 nt
	s_add_i32 s20, s20, s14
	s_ashr_i32 s21, s20, 31
	s_lshl_b64 s[20:21], s[20:21], 2
	s_add_u32 s20, s26, s20
	s_addc_u32 s21, s27, s21
	s_or_b32 s66, s4, 26
	s_cmp_lt_u32 s66, s23
	global_load_dword v20, v97, s[20:21]
	s_waitcnt vmcnt(1)
	v_cndmask_b32_e32 v93, 0, v6, vcc
	v_cndmask_b32_e32 v25, 0, v7, vcc
	s_cselect_b64 vcc, -1, 0
	s_and_b64 s[20:21], vcc, exec
	s_cselect_b32 s20, s66, s4
	s_ashr_i32 s21, s20, 31
	s_lshl_b64 s[62:63], s[20:21], 11
	v_lshl_add_u64 v[6:7], v[8:9], 0, s[62:63]
	global_load_dwordx2 v[6:7], v[6:7], off offset:512 nt
	s_add_i32 s20, s20, s14
	s_ashr_i32 s21, s20, 31
	s_lshl_b64 s[20:21], s[20:21], 2
	s_add_u32 s20, s26, s20
	s_addc_u32 s21, s27, s21
	s_or_b32 s67, s4, 27
	s_cmp_lt_u32 s67, s23
	global_load_dword v22, v97, s[20:21]
	s_waitcnt vmcnt(1)
	v_cndmask_b32_e32 v23, 0, v6, vcc
	v_cndmask_b32_e32 v21, 0, v7, vcc
	s_cselect_b64 vcc, -1, 0
	s_and_b64 s[20:21], vcc, exec
	s_cselect_b32 s20, s67, s4
	s_ashr_i32 s21, s20, 31
	s_lshl_b64 s[62:63], s[20:21], 11
	v_lshl_add_u64 v[6:7], v[8:9], 0, s[62:63]
	global_load_dwordx2 v[6:7], v[6:7], off offset:512 nt
	s_add_i32 s20, s20, s14
	s_ashr_i32 s21, s20, 31
	s_lshl_b64 s[20:21], s[20:21], 2
	s_add_u32 s20, s26, s20
	s_addc_u32 s21, s27, s21
	s_or_b32 s63, s4, 28
	s_cmp_lt_u32 s63, s23
	global_load_dword v18, v97, s[20:21]
	s_waitcnt vmcnt(1)
	v_cndmask_b32_e32 v92, 0, v6, vcc
	v_cndmask_b32_e32 v91, 0, v7, vcc
	s_cselect_b64 vcc, -1, 0
	s_and_b64 s[20:21], vcc, exec
	s_cselect_b32 s20, s63, s4
	s_ashr_i32 s21, s20, 31
	s_lshl_b64 s[96:97], s[20:21], 11
	v_lshl_add_u64 v[6:7], v[8:9], 0, s[96:97]
	global_load_dwordx2 v[6:7], v[6:7], off offset:512 nt
	s_add_i32 s20, s20, s14
	s_ashr_i32 s21, s20, 31
	s_lshl_b64 s[20:21], s[20:21], 2
	s_add_u32 s20, s26, s20
	s_addc_u32 s21, s27, s21
	s_or_b32 s34, s4, 29
	s_cmp_lt_u32 s34, s23
	global_load_dword v16, v97, s[20:21]
	s_waitcnt vmcnt(1)
	v_cndmask_b32_e32 v90, 0, v6, vcc
	v_cndmask_b32_e32 v19, 0, v7, vcc
	s_cselect_b64 vcc, -1, 0
	s_and_b64 s[20:21], vcc, exec
	s_cselect_b32 s20, s34, s4
	s_ashr_i32 s21, s20, 31
	s_lshl_b64 s[96:97], s[20:21], 11
	v_lshl_add_u64 v[6:7], v[8:9], 0, s[96:97]
	global_load_dwordx2 v[6:7], v[6:7], off offset:512 nt
	s_add_i32 s20, s20, s14
	s_ashr_i32 s21, s20, 31
	s_lshl_b64 s[20:21], s[20:21], 2
	s_add_u32 s20, s26, s20
	s_addc_u32 s21, s27, s21
	s_or_b32 s15, s4, 30
	s_cmp_lt_u32 s15, s23
	global_load_dword v12, v97, s[20:21]
	s_waitcnt vmcnt(1)
	v_cndmask_b32_e32 v89, 0, v6, vcc
	v_cndmask_b32_e32 v88, 0, v7, vcc
	s_cselect_b64 vcc, -1, 0
	s_and_b64 s[20:21], vcc, exec
	s_cselect_b32 s20, s15, s4
	s_ashr_i32 s21, s20, 31
	s_lshl_b64 s[96:97], s[20:21], 11
	v_lshl_add_u64 v[6:7], v[8:9], 0, s[96:97]
	global_load_dwordx2 v[6:7], v[6:7], off offset:512 nt
	s_add_i32 s20, s20, s14
	s_ashr_i32 s21, s20, 31
	s_lshl_b64 s[20:21], s[20:21], 2
	s_add_u32 s20, s26, s20
	s_addc_u32 s21, s27, s21
	s_or_b32 s5, s4, 31
	s_cmp_lt_u32 s5, s23
	global_load_dword v10, v97, s[20:21]
	s_waitcnt vmcnt(1)
	v_cndmask_b32_e32 v87, 0, v6, vcc
	v_cndmask_b32_e32 v86, 0, v7, vcc
	s_cselect_b64 vcc, -1, 0
	s_and_b64 s[20:21], vcc, exec
	s_cselect_b32 s20, s5, s4
	s_ashr_i32 s21, s20, 31
	s_lshl_b64 s[96:97], s[20:21], 11
	v_lshl_add_u64 v[6:7], v[8:9], 0, s[96:97]
	global_load_dwordx2 v[6:7], v[6:7], off offset:512 nt
	s_add_i32 s20, s20, s14
	s_ashr_i32 s21, s20, 31
	s_lshl_b64 s[20:21], s[20:21], 2
	s_add_u32 s20, s26, s20
	s_addc_u32 s21, s27, s21
	s_add_i32 s62, s4, 32
	s_cmp_lt_u32 s62, s23
	s_waitcnt vmcnt(0)
	v_cndmask_b32_e32 v13, 0, v6, vcc
	v_cndmask_b32_e32 v7, 0, v7, vcc
	s_cselect_b64 vcc, -1, 0
	global_load_dword v6, v97, s[20:21]
	s_and_b64 s[20:21], vcc, exec
	s_cselect_b32 s20, s62, s4
	s_ashr_i32 s21, s20, 31
	s_lshl_b64 s[96:97], s[20:21], 11
	v_lshl_add_u64 v[8:9], v[8:9], 0, s[96:97]
	global_load_dwordx2 v[8:9], v[8:9], off offset:512 nt
	s_add_i32 s20, s20, s14
	s_ashr_i32 s21, s20, 31
	s_lshl_b64 s[20:21], s[20:21], 2
	s_add_u32 s20, s26, s20
	s_addc_u32 s21, s27, s21
	s_waitcnt vmcnt(0)
	v_cndmask_b32_e32 v17, 0, v8, vcc
	global_load_dword v8, v97, s[20:21]
	s_lshl_b64 s[20:21], s[6:7], 11
	s_add_u32 s20, s24, s20
	s_addc_u32 s21, s25, s21
	v_lshl_add_u64 v[14:15], s[20:21], 0, v[96:97]
	v_lshl_add_u64 v[4:5], v[14:15], 0, s[30:31]
	s_max_i32 s7, s4, 2
	s_min_i32 s30, s90, s23
	s_sub_i32 s7, s30, s7
	s_add_i32 s7, s7, 2
	v_cvt_f32_i32_e32 v72, s7
	v_cndmask_b32_e32 v9, 0, v9, vcc
	s_max_i32 s7, s91, 2
	s_min_i32 s30, s89, s23
	v_div_scale_f32 v77, s[96:97], v72, v72, 1.0
	v_rcp_f32_e32 v79, v77
	s_sub_i32 s7, s30, s7
	s_add_i32 s7, s7, 2
	s_movk_i32 s91, 0x2000
	v_fma_f32 v81, -v77, v79, 1.0
	v_fmac_f32_e32 v79, v81, v79
	v_div_scale_f32 v81, vcc, 1.0, v72, 1.0
	v_mul_f32_e32 v128, v81, v79
	v_fma_f32 v129, -v77, v128, v81
	v_fmac_f32_e32 v128, v129, v79
	v_fma_f32 v77, -v77, v128, v81
	v_div_fmas_f32 v77, v77, v79, v128
	v_div_fixup_f32 v72, v77, v72, 1.0
	v_pk_fma_f32 v[128:129], v[72:73], v[120:121], v[84:85] op_sel_hi:[0,1,1] neg_lo:[0,0,1] neg_hi:[0,0,1]
	v_pk_fma_f32 v[130:131], v[72:73], v[126:127], v[82:83] op_sel_hi:[0,1,1] neg_lo:[0,0,1] neg_hi:[0,0,1]
	v_pk_mul_f32 v[128:129], v[0:1], v[128:129]
	v_pk_mul_f32 v[130:131], v[2:3], v[130:131]
	v_cvt_pk_bf16_f32 v128, v128, v129
	s_nop 0
	v_cvt_pk_bf16_f32 v129, v130, v131
	global_store_dwordx2 v96, v[128:129], s[20:21] offset:512
	v_lshlrev_b32_e32 v128, 16, v76
	v_and_b32_e32 v129, 0xffff0000, v76
	v_lshlrev_b32_e32 v130, 16, v73
	v_and_b32_e32 v131, 0xffff0000, v73
	v_pk_mul_f32 v[72:73], v[68:69], v[130:131] op_sel_hi:[0,1]
	v_pk_mul_f32 v[76:77], v[68:69], v[128:129] op_sel_hi:[0,1]
	v_pk_fma_f32 v[118:119], v[68:69], v[128:129], v[118:119] op_sel_hi:[0,1,1] neg_lo:[0,0,1] neg_hi:[0,0,1]
	v_pk_fma_f32 v[116:117], v[68:69], v[130:131], v[116:117] op_sel_hi:[0,1,1] neg_lo:[0,0,1] neg_hi:[0,0,1]
	v_cvt_f32_i32_e32 v68, s7
	v_pk_add_f32 v[118:119], v[120:121], v[118:119]
	v_pk_add_f32 v[116:117], v[126:127], v[116:117]
	s_max_i32 s7, s90, 2
	v_div_scale_f32 v79, s[96:97], v68, v68, 1.0
	v_rcp_f32_e32 v81, v79
	s_movk_i32 s97, 0x800
	v_readlane_b32 s96, v255, 13
	s_movk_i32 s90, 0xff00
	v_fma_f32 v120, -v79, v81, 1.0
	v_fmac_f32_e32 v81, v120, v81
	v_div_scale_f32 v120, vcc, 1.0, v68, 1.0
	v_mul_f32_e32 v121, v120, v81
	v_fma_f32 v126, -v79, v121, v120
	v_fmac_f32_e32 v121, v126, v81
	v_fma_f32 v79, -v79, v121, v120
	v_div_fmas_f32 v79, v79, v81, v121
	v_div_fixup_f32 v68, v79, v68, 1.0
	v_pk_fma_f32 v[120:121], v[68:69], v[118:119], v[74:75] op_sel_hi:[0,1,1] neg_lo:[0,0,1] neg_hi:[0,0,1]
	v_pk_fma_f32 v[126:127], v[68:69], v[116:117], v[70:71] op_sel_hi:[0,1,1] neg_lo:[0,0,1] neg_hi:[0,0,1]
	v_pk_mul_f32 v[120:121], v[0:1], v[120:121]
	v_pk_mul_f32 v[126:127], v[2:3], v[126:127]
	v_cvt_pk_bf16_f32 v120, v120, v121
	s_nop 0
	v_cvt_pk_bf16_f32 v121, v126, v127
	global_store_dwordx2 v96, v[120:121], s[20:21] offset:2560
	s_min_i32 s20, s88, s23
	s_sub_i32 s7, s20, s7
	v_lshlrev_b32_e32 v120, 16, v78
	v_and_b32_e32 v121, 0xffff0000, v78
	v_lshlrev_b32_e32 v126, 16, v69
	v_and_b32_e32 v127, 0xffff0000, v69
	s_add_i32 s7, s7, 2
	v_pk_mul_f32 v[68:69], v[66:67], v[126:127] op_sel_hi:[0,1]
	v_pk_mul_f32 v[78:79], v[66:67], v[120:121] op_sel_hi:[0,1]
	v_pk_fma_f32 v[120:121], v[66:67], v[120:121], v[124:125] op_sel_hi:[0,1,1] neg_lo:[0,0,1] neg_hi:[0,0,1]
	v_pk_fma_f32 v[122:123], v[66:67], v[126:127], v[122:123] op_sel_hi:[0,1,1] neg_lo:[0,0,1] neg_hi:[0,0,1]
	v_cvt_f32_i32_e32 v66, s7
	v_pk_add_f32 v[118:119], v[118:119], v[120:121]
	v_pk_add_f32 v[116:117], v[116:117], v[122:123]
	s_max_i32 s7, s89, 2
	v_div_scale_f32 v81, s[20:21], v66, v66, 1.0
	v_rcp_f32_e32 v96, v81
	s_min_i32 s20, s87, s23
	s_sub_i32 s7, s20, s7
	v_lshlrev_b32_e32 v124, 16, v67
	v_fma_f32 v120, -v81, v96, 1.0
	v_fmac_f32_e32 v96, v120, v96
	v_div_scale_f32 v120, vcc, 1.0, v66, 1.0
	v_mul_f32_e32 v121, v120, v96
	v_fma_f32 v122, -v81, v121, v120
	v_fmac_f32_e32 v121, v122, v96
	v_fma_f32 v81, -v81, v121, v120
	v_div_fmas_f32 v81, v81, v96, v121
	v_div_fixup_f32 v66, v81, v66, 1.0
	v_pk_fma_f32 v[120:121], v[66:67], v[118:119], v[76:77] op_sel_hi:[0,1,1] neg_lo:[0,0,1] neg_hi:[0,0,1]
	v_pk_fma_f32 v[122:123], v[66:67], v[116:117], v[72:73] op_sel_hi:[0,1,1] neg_lo:[0,0,1] neg_hi:[0,0,1]
	v_pk_mul_f32 v[122:123], v[2:3], v[122:123]
	v_pk_mul_f32 v[120:121], v[0:1], v[120:121]
	v_and_b32_e32 v125, 0xffff0000, v67
	v_cvt_pk_bf16_f32 v120, v120, v121
	v_cvt_pk_bf16_f32 v121, v122, v123
	v_add_co_u32_e32 v122, vcc, s92, v14
	s_add_i32 s7, s7, 2
	s_nop 0
	v_addc_co_u32_e32 v123, vcc, 0, v15, vcc
	global_store_dwordx2 v[122:123], v[120:121], off offset:512
	v_lshlrev_b32_e32 v120, 16, v80
	v_and_b32_e32 v121, 0xffff0000, v80
	v_pk_mul_f32 v[66:67], v[64:65], v[124:125] op_sel_hi:[0,1]
	v_pk_mul_f32 v[80:81], v[64:65], v[120:121] op_sel_hi:[0,1]
	v_pk_fma_f32 v[84:85], v[64:65], v[120:121], v[84:85] op_sel_hi:[0,1,1] neg_lo:[0,0,1] neg_hi:[0,0,1]
	v_pk_fma_f32 v[82:83], v[64:65], v[124:125], v[82:83] op_sel_hi:[0,1,1] neg_lo:[0,0,1] neg_hi:[0,0,1]
	v_cvt_f32_i32_e32 v64, s7
	v_pk_add_f32 v[116:117], v[116:117], v[82:83]
	v_pk_add_f32 v[84:85], v[118:119], v[84:85]
	s_max_i32 s7, s88, 2
	v_div_scale_f32 v82, s[20:21], v64, v64, 1.0
	v_rcp_f32_e32 v83, v82
	s_min_i32 s20, s86, s23
	s_sub_i32 s7, s20, s7
	v_lshlrev_b32_e32 v120, 16, v65
	v_fma_f32 v96, -v82, v83, 1.0
	v_fmac_f32_e32 v83, v96, v83
	v_div_scale_f32 v96, vcc, 1.0, v64, 1.0
	v_mul_f32_e32 v118, v96, v83
	v_fma_f32 v119, -v82, v118, v96
	v_fmac_f32_e32 v118, v119, v83
	v_fma_f32 v82, -v82, v118, v96
	v_div_fmas_f32 v82, v82, v83, v118
	v_div_fixup_f32 v64, v82, v64, 1.0
	v_pk_fma_f32 v[82:83], v[64:65], v[84:85], v[78:79] op_sel_hi:[0,1,1] neg_lo:[0,0,1] neg_hi:[0,0,1]
	v_pk_fma_f32 v[118:119], v[64:65], v[116:117], v[68:69] op_sel_hi:[0,1,1] neg_lo:[0,0,1] neg_hi:[0,0,1]
	v_pk_mul_f32 v[118:119], v[2:3], v[118:119]
	v_pk_mul_f32 v[82:83], v[0:1], v[82:83]
	v_and_b32_e32 v121, 0xffff0000, v65
	v_cvt_pk_bf16_f32 v82, v82, v83
	v_cvt_pk_bf16_f32 v83, v118, v119
	v_lshlrev_b32_e32 v118, 16, v115
	v_and_b32_e32 v119, 0xffff0000, v115
	s_add_i32 s7, s7, 2
	global_store_dwordx2 v[122:123], v[82:83], off offset:2560
	v_pk_mul_f32 v[64:65], v[62:63], v[120:121] op_sel_hi:[0,1]
	v_pk_mul_f32 v[82:83], v[62:63], v[118:119] op_sel_hi:[0,1]
	v_pk_fma_f32 v[74:75], v[62:63], v[118:119], v[74:75] op_sel_hi:[0,1,1] neg_lo:[0,0,1] neg_hi:[0,0,1]
	v_pk_fma_f32 v[70:71], v[62:63], v[120:121], v[70:71] op_sel_hi:[0,1,1] neg_lo:[0,0,1] neg_hi:[0,0,1]
	v_cvt_f32_i32_e32 v62, s7
	v_pk_add_f32 v[116:117], v[116:117], v[70:71]
	v_pk_add_f32 v[74:75], v[84:85], v[74:75]
	s_max_i32 s7, s87, 2
	v_div_scale_f32 v70, s[20:21], v62, v62, 1.0
	v_rcp_f32_e32 v71, v70
	s_min_i32 s20, s85, s23
	s_sub_i32 s7, s20, s7
	v_lshlrev_b32_e32 v118, 16, v114
	v_fma_f32 v84, -v70, v71, 1.0
	v_fmac_f32_e32 v71, v84, v71
	v_div_scale_f32 v84, vcc, 1.0, v62, 1.0
	v_mul_f32_e32 v85, v84, v71
	v_fma_f32 v96, -v70, v85, v84
	v_fmac_f32_e32 v85, v96, v71
	v_fma_f32 v70, -v70, v85, v84
	v_div_fmas_f32 v70, v70, v71, v85
	v_div_fixup_f32 v62, v70, v62, 1.0
	v_pk_fma_f32 v[70:71], v[62:63], v[74:75], v[80:81] op_sel_hi:[0,1,1] neg_lo:[0,0,1] neg_hi:[0,0,1]
	v_pk_fma_f32 v[84:85], v[62:63], v[116:117], v[66:67] op_sel_hi:[0,1,1] neg_lo:[0,0,1] neg_hi:[0,0,1]
	v_pk_mul_f32 v[84:85], v[2:3], v[84:85]
	v_pk_mul_f32 v[70:71], v[0:1], v[70:71]
	v_and_b32_e32 v119, 0xffff0000, v114
	v_cvt_pk_bf16_f32 v70, v70, v71
	v_cvt_pk_bf16_f32 v71, v84, v85
	v_add_co_u32_e32 v84, vcc, s91, v14
	v_lshlrev_b32_e32 v114, 16, v63
	s_nop 0
	v_addc_co_u32_e32 v85, vcc, 0, v15, vcc
	v_and_b32_e32 v115, 0xffff0000, v63
	s_add_i32 s7, s7, 2
	global_store_dwordx2 v[84:85], v[70:71], off offset:512
	v_pk_mul_f32 v[62:63], v[60:61], v[114:115] op_sel_hi:[0,1]
	v_pk_mul_f32 v[70:71], v[60:61], v[118:119] op_sel_hi:[0,1]
	v_pk_fma_f32 v[76:77], v[60:61], v[118:119], v[76:77] op_sel_hi:[0,1,1] neg_lo:[0,0,1] neg_hi:[0,0,1]
	v_pk_fma_f32 v[72:73], v[60:61], v[114:115], v[72:73] op_sel_hi:[0,1,1] neg_lo:[0,0,1] neg_hi:[0,0,1]
	v_cvt_f32_i32_e32 v60, s7
	v_pk_add_f32 v[114:115], v[116:117], v[72:73]
	v_pk_add_f32 v[74:75], v[74:75], v[76:77]
	s_max_i32 s7, s86, 2
	v_div_scale_f32 v72, s[20:21], v60, v60, 1.0
	v_rcp_f32_e32 v73, v72
	s_min_i32 s20, s84, s23
	s_sub_i32 s7, s20, s7
	s_add_i32 s7, s7, 2
	v_fma_f32 v76, -v72, v73, 1.0
	v_fmac_f32_e32 v73, v76, v73
	v_div_scale_f32 v76, vcc, 1.0, v60, 1.0
	v_mul_f32_e32 v77, v76, v73
	v_fma_f32 v96, -v72, v77, v76
	v_fmac_f32_e32 v77, v96, v73
	v_fma_f32 v72, -v72, v77, v76
	v_div_fmas_f32 v72, v72, v73, v77
	v_div_fixup_f32 v60, v72, v60, 1.0
	v_pk_fma_f32 v[72:73], v[60:61], v[74:75], v[82:83] op_sel_hi:[0,1,1] neg_lo:[0,0,1] neg_hi:[0,0,1]
	v_pk_fma_f32 v[76:77], v[60:61], v[114:115], v[64:65] op_sel_hi:[0,1,1] neg_lo:[0,0,1] neg_hi:[0,0,1]
	v_pk_mul_f32 v[76:77], v[2:3], v[76:77]
	v_pk_mul_f32 v[72:73], v[0:1], v[72:73]
	s_nop 0
	v_cvt_pk_bf16_f32 v72, v72, v73
	v_cvt_pk_bf16_f32 v73, v76, v77
	global_store_dwordx2 v[84:85], v[72:73], off offset:2560
	v_lshlrev_b32_e32 v76, 16, v113
	v_and_b32_e32 v77, 0xffff0000, v113
	v_lshlrev_b32_e32 v84, 16, v61
	v_and_b32_e32 v85, 0xffff0000, v61
	v_pk_mul_f32 v[60:61], v[58:59], v[84:85] op_sel_hi:[0,1]
	v_pk_mul_f32 v[72:73], v[58:59], v[76:77] op_sel_hi:[0,1]
	v_pk_fma_f32 v[76:77], v[58:59], v[76:77], v[78:79] op_sel_hi:[0,1,1] neg_lo:[0,0,1] neg_hi:[0,0,1]
	v_pk_fma_f32 v[68:69], v[58:59], v[84:85], v[68:69] op_sel_hi:[0,1,1] neg_lo:[0,0,1] neg_hi:[0,0,1]
	v_cvt_f32_i32_e32 v58, s7
	v_pk_add_f32 v[78:79], v[114:115], v[68:69]
	v_pk_add_f32 v[74:75], v[74:75], v[76:77]
	s_movk_i32 s7, 0x3000
	v_div_scale_f32 v68, s[20:21], v58, v58, 1.0
	v_rcp_f32_e32 v69, v68
	s_min_i32 s20, s83, s23
	v_and_b32_e32 v85, 0xffff0000, v112
	v_and_b32_e32 v113, 0xffff0000, v59
	v_fma_f32 v76, -v68, v69, 1.0
	v_fmac_f32_e32 v69, v76, v69
	v_div_scale_f32 v76, vcc, 1.0, v58, 1.0
	v_mul_f32_e32 v77, v76, v69
	v_fma_f32 v84, -v68, v77, v76
	v_fmac_f32_e32 v77, v84, v69
	v_fma_f32 v68, -v68, v77, v76
	v_div_fmas_f32 v68, v68, v69, v77
	v_div_fixup_f32 v58, v68, v58, 1.0
	v_pk_fma_f32 v[68:69], v[58:59], v[74:75], v[70:71] op_sel_hi:[0,1,1] neg_lo:[0,0,1] neg_hi:[0,0,1]
	v_pk_fma_f32 v[76:77], v[58:59], v[78:79], v[62:63] op_sel_hi:[0,1,1] neg_lo:[0,0,1] neg_hi:[0,0,1]
	v_pk_mul_f32 v[76:77], v[2:3], v[76:77]
	v_pk_mul_f32 v[68:69], v[0:1], v[68:69]
	v_lshlrev_b32_e32 v84, 16, v112
	v_cvt_pk_bf16_f32 v68, v68, v69
	v_cvt_pk_bf16_f32 v69, v76, v77
	v_add_co_u32_e32 v76, vcc, s7, v14
	s_max_i32 s7, s85, 2
	s_sub_i32 s7, s20, s7
	v_addc_co_u32_e32 v77, vcc, 0, v15, vcc
	v_lshlrev_b32_e32 v112, 16, v59
	s_add_i32 s7, s7, 2
	global_store_dwordx2 v[76:77], v[68:69], off offset:512
	v_pk_mul_f32 v[58:59], v[56:57], v[112:113] op_sel_hi:[0,1]
	v_pk_mul_f32 v[68:69], v[56:57], v[84:85] op_sel_hi:[0,1]
	v_pk_fma_f32 v[80:81], v[56:57], v[84:85], v[80:81] op_sel_hi:[0,1,1] neg_lo:[0,0,1] neg_hi:[0,0,1]
	v_pk_fma_f32 v[66:67], v[56:57], v[112:113], v[66:67] op_sel_hi:[0,1,1] neg_lo:[0,0,1] neg_hi:[0,0,1]
	v_cvt_f32_i32_e32 v56, s7
	v_pk_add_f32 v[78:79], v[78:79], v[66:67]
	v_pk_add_f32 v[74:75], v[74:75], v[80:81]
	s_max_i32 s7, s84, 2
	v_div_scale_f32 v66, s[20:21], v56, v56, 1.0
	v_rcp_f32_e32 v67, v66
	s_min_i32 s20, s82, s23
	s_sub_i32 s7, s20, s7
	s_add_i32 s7, s7, 2
	v_fma_f32 v80, -v66, v67, 1.0
	v_fmac_f32_e32 v67, v80, v67
	v_div_scale_f32 v80, vcc, 1.0, v56, 1.0
	v_mul_f32_e32 v81, v80, v67
	v_fma_f32 v84, -v66, v81, v80
	v_fmac_f32_e32 v81, v84, v67
	v_fma_f32 v66, -v66, v81, v80
	v_div_fmas_f32 v66, v66, v67, v81
	v_div_fixup_f32 v56, v66, v56, 1.0
	v_pk_fma_f32 v[66:67], v[56:57], v[74:75], v[72:73] op_sel_hi:[0,1,1] neg_lo:[0,0,1] neg_hi:[0,0,1]
	v_pk_fma_f32 v[80:81], v[56:57], v[78:79], v[60:61] op_sel_hi:[0,1,1] neg_lo:[0,0,1] neg_hi:[0,0,1]
	v_pk_mul_f32 v[80:81], v[2:3], v[80:81]
	v_pk_mul_f32 v[66:67], v[0:1], v[66:67]
	s_nop 0
	v_cvt_pk_bf16_f32 v66, v66, v67
	v_cvt_pk_bf16_f32 v67, v80, v81
	global_store_dwordx2 v[76:77], v[66:67], off offset:2560
	v_lshlrev_b32_e32 v76, 16, v111
	v_and_b32_e32 v77, 0xffff0000, v111
	v_lshlrev_b32_e32 v80, 16, v57
	v_and_b32_e32 v81, 0xffff0000, v57
	v_pk_mul_f32 v[56:57], v[54:55], v[80:81] op_sel_hi:[0,1]
	v_pk_mul_f32 v[66:67], v[54:55], v[76:77] op_sel_hi:[0,1]
	v_pk_fma_f32 v[76:77], v[54:55], v[76:77], v[82:83] op_sel_hi:[0,1,1] neg_lo:[0,0,1] neg_hi:[0,0,1]
	v_pk_fma_f32 v[64:65], v[54:55], v[80:81], v[64:65] op_sel_hi:[0,1,1] neg_lo:[0,0,1] neg_hi:[0,0,1]
	v_cvt_f32_i32_e32 v54, s7
	v_pk_add_f32 v[78:79], v[78:79], v[64:65]
	v_pk_add_f32 v[74:75], v[74:75], v[76:77]
	s_max_i32 s7, s83, 2
	v_div_scale_f32 v64, s[20:21], v54, v54, 1.0
	v_rcp_f32_e32 v65, v64
	s_min_i32 s20, s81, s23
	s_sub_i32 s7, s20, s7
	v_and_b32_e32 v81, 0xffff0000, v110
	v_fma_f32 v76, -v64, v65, 1.0
	v_fmac_f32_e32 v65, v76, v65
	v_div_scale_f32 v76, vcc, 1.0, v54, 1.0
	v_mul_f32_e32 v77, v76, v65
	v_fma_f32 v80, -v64, v77, v76
	v_fmac_f32_e32 v77, v80, v65
	v_fma_f32 v64, -v64, v77, v76
	v_div_fmas_f32 v64, v64, v65, v77
	v_div_fixup_f32 v54, v64, v54, 1.0
	v_pk_fma_f32 v[64:65], v[54:55], v[74:75], v[68:69] op_sel_hi:[0,1,1] neg_lo:[0,0,1] neg_hi:[0,0,1]
	v_pk_fma_f32 v[76:77], v[54:55], v[78:79], v[58:59] op_sel_hi:[0,1,1] neg_lo:[0,0,1] neg_hi:[0,0,1]
	v_pk_mul_f32 v[76:77], v[2:3], v[76:77]
	v_pk_mul_f32 v[64:65], v[0:1], v[64:65]
	v_lshlrev_b32_e32 v80, 16, v110
	v_cvt_pk_bf16_f32 v64, v64, v65
	v_cvt_pk_bf16_f32 v65, v76, v77
	v_add_co_u32_e32 v76, vcc, s9, v14
	v_lshlrev_b32_e32 v82, 16, v55
	s_nop 0
	v_addc_co_u32_e32 v77, vcc, 0, v15, vcc
	v_and_b32_e32 v83, 0xffff0000, v55
	s_add_i32 s7, s7, 2
	global_store_dwordx2 v[76:77], v[64:65], off offset:512
	v_pk_mul_f32 v[54:55], v[52:53], v[82:83] op_sel_hi:[0,1]
	v_pk_mul_f32 v[64:65], v[52:53], v[80:81] op_sel_hi:[0,1]
	v_pk_fma_f32 v[70:71], v[52:53], v[80:81], v[70:71] op_sel_hi:[0,1,1] neg_lo:[0,0,1] neg_hi:[0,0,1]
	v_pk_fma_f32 v[62:63], v[52:53], v[82:83], v[62:63] op_sel_hi:[0,1,1] neg_lo:[0,0,1] neg_hi:[0,0,1]
	v_cvt_f32_i32_e32 v52, s7
	v_pk_add_f32 v[78:79], v[78:79], v[62:63]
	v_pk_add_f32 v[70:71], v[74:75], v[70:71]
	s_max_i32 s7, s82, 2
	v_div_scale_f32 v62, s[20:21], v52, v52, 1.0
	v_rcp_f32_e32 v63, v62
	s_min_i32 s20, s80, s23
	s_sub_i32 s7, s20, s7
	s_add_i32 s7, s7, 2
	v_fma_f32 v74, -v62, v63, 1.0
	v_fmac_f32_e32 v63, v74, v63
	v_div_scale_f32 v74, vcc, 1.0, v52, 1.0
	v_mul_f32_e32 v75, v74, v63
	v_fma_f32 v80, -v62, v75, v74
	v_fmac_f32_e32 v75, v80, v63
	v_fma_f32 v62, -v62, v75, v74
	v_div_fmas_f32 v62, v62, v63, v75
	v_div_fixup_f32 v52, v62, v52, 1.0
	v_pk_fma_f32 v[62:63], v[52:53], v[70:71], v[66:67] op_sel_hi:[0,1,1] neg_lo:[0,0,1] neg_hi:[0,0,1]
	v_pk_fma_f32 v[74:75], v[52:53], v[78:79], v[56:57] op_sel_hi:[0,1,1] neg_lo:[0,0,1] neg_hi:[0,0,1]
	v_pk_mul_f32 v[74:75], v[2:3], v[74:75]
	v_pk_mul_f32 v[62:63], v[0:1], v[62:63]
	s_nop 0
	v_cvt_pk_bf16_f32 v62, v62, v63
	v_cvt_pk_bf16_f32 v63, v74, v75
	global_store_dwordx2 v[76:77], v[62:63], off offset:2560
	v_lshlrev_b32_e32 v74, 16, v109
	v_and_b32_e32 v75, 0xffff0000, v109
	v_lshlrev_b32_e32 v76, 16, v53
	v_and_b32_e32 v77, 0xffff0000, v53
	v_pk_mul_f32 v[52:53], v[50:51], v[76:77] op_sel_hi:[0,1]
	v_pk_mul_f32 v[62:63], v[50:51], v[74:75] op_sel_hi:[0,1]
	v_pk_fma_f32 v[72:73], v[50:51], v[74:75], v[72:73] op_sel_hi:[0,1,1] neg_lo:[0,0,1] neg_hi:[0,0,1]
	v_pk_fma_f32 v[60:61], v[50:51], v[76:77], v[60:61] op_sel_hi:[0,1,1] neg_lo:[0,0,1] neg_hi:[0,0,1]
	v_cvt_f32_i32_e32 v50, s7
	v_pk_add_f32 v[74:75], v[78:79], v[60:61]
	v_pk_add_f32 v[70:71], v[70:71], v[72:73]
	s_max_i32 s7, s81, 2
	v_div_scale_f32 v60, s[20:21], v50, v50, 1.0
	v_rcp_f32_e32 v61, v60
	s_min_i32 s20, s79, s23
	v_and_b32_e32 v77, 0xffff0000, v51
	v_lshlrev_b32_e32 v78, 16, v47
	v_fma_f32 v72, -v60, v61, 1.0
	v_fmac_f32_e32 v61, v72, v61
	v_div_scale_f32 v72, vcc, 1.0, v50, 1.0
	v_mul_f32_e32 v73, v72, v61
	v_fma_f32 v76, -v60, v73, v72
	v_fmac_f32_e32 v73, v76, v61
	v_fma_f32 v60, -v60, v73, v72
	v_div_fmas_f32 v60, v60, v61, v73
	v_div_fixup_f32 v50, v60, v50, 1.0
	v_pk_fma_f32 v[60:61], v[50:51], v[70:71], v[64:65] op_sel_hi:[0,1,1] neg_lo:[0,0,1] neg_hi:[0,0,1]
	v_pk_fma_f32 v[72:73], v[50:51], v[74:75], v[54:55] op_sel_hi:[0,1,1] neg_lo:[0,0,1] neg_hi:[0,0,1]
	v_pk_mul_f32 v[72:73], v[2:3], v[72:73]
	v_pk_mul_f32 v[60:61], v[0:1], v[60:61]
	v_lshlrev_b32_e32 v76, 16, v51
	v_cvt_pk_bf16_f32 v60, v60, v61
	v_cvt_pk_bf16_f32 v61, v72, v73
	v_add_co_u32_e32 v72, vcc, s38, v14
	v_and_b32_e32 v79, 0xffff0000, v47
	s_nop 0
	v_addc_co_u32_e32 v73, vcc, 0, v15, vcc
	s_sub_i32 s7, s20, s7
	global_store_dwordx2 v[72:73], v[60:61], off offset:512
	v_pk_mul_f32 v[50:51], v[46:47], v[78:79] op_sel_hi:[0,1]
	v_pk_mul_f32 v[60:61], v[46:47], v[76:77] op_sel_hi:[0,1]
	v_pk_fma_f32 v[68:69], v[46:47], v[76:77], v[68:69] op_sel_hi:[0,1,1] neg_lo:[0,0,1] neg_hi:[0,0,1]
	v_pk_fma_f32 v[46:47], v[46:47], v[78:79], v[58:59] op_sel_hi:[0,1,1] neg_lo:[0,0,1] neg_hi:[0,0,1]
	s_add_i32 s7, s7, 2
	v_pk_add_f32 v[74:75], v[74:75], v[46:47]
	v_cvt_f32_i32_e32 v46, s7
	v_pk_add_f32 v[68:69], v[70:71], v[68:69]
	s_max_i32 s7, s80, 2
	v_div_scale_f32 v47, s[20:21], v46, v46, 1.0
	v_rcp_f32_e32 v58, v47
	s_min_i32 s20, s35, s23
	s_sub_i32 s7, s20, s7
	s_add_i32 s7, s7, 2
	v_fma_f32 v59, -v47, v58, 1.0
	v_fmac_f32_e32 v58, v59, v58
	v_div_scale_f32 v59, vcc, 1.0, v46, 1.0
	v_mul_f32_e32 v70, v59, v58
	v_fma_f32 v71, -v47, v70, v59
	v_fmac_f32_e32 v70, v71, v58
	v_fma_f32 v47, -v47, v70, v59
	v_div_fmas_f32 v47, v47, v58, v70
	v_div_fixup_f32 v46, v47, v46, 1.0
	v_pk_fma_f32 v[58:59], v[46:47], v[68:69], v[62:63] op_sel_hi:[0,1,1] neg_lo:[0,0,1] neg_hi:[0,0,1]
	v_pk_fma_f32 v[46:47], v[46:47], v[74:75], v[52:53] op_sel_hi:[0,1,1] neg_lo:[0,0,1] neg_hi:[0,0,1]
	v_pk_mul_f32 v[58:59], v[0:1], v[58:59]
	v_pk_mul_f32 v[46:47], v[2:3], v[46:47]
	v_cvt_pk_bf16_f32 v58, v58, v59
	v_lshlrev_b32_e32 v70, 16, v108
	v_cvt_pk_bf16_f32 v59, v46, v47
	global_store_dwordx2 v[72:73], v[58:59], off offset:2560
	v_and_b32_e32 v71, 0xffff0000, v108
	v_lshlrev_b32_e32 v72, 16, v107
	v_and_b32_e32 v73, 0xffff0000, v107
	v_pk_mul_f32 v[46:47], v[48:49], v[72:73] op_sel_hi:[0,1]
	v_pk_mul_f32 v[58:59], v[48:49], v[70:71] op_sel_hi:[0,1]
	v_pk_fma_f32 v[66:67], v[48:49], v[70:71], v[66:67] op_sel_hi:[0,1,1] neg_lo:[0,0,1] neg_hi:[0,0,1]
	v_pk_fma_f32 v[56:57], v[48:49], v[72:73], v[56:57] op_sel_hi:[0,1,1] neg_lo:[0,0,1] neg_hi:[0,0,1]
	v_cvt_f32_i32_e32 v48, s7
	v_pk_add_f32 v[70:71], v[74:75], v[56:57]
	v_pk_add_f32 v[66:67], v[68:69], v[66:67]
	s_max_i32 s7, s79, 2
	v_div_scale_f32 v56, s[20:21], v48, v48, 1.0
	v_rcp_f32_e32 v57, v56
	s_min_i32 s20, s78, s23
	s_sub_i32 s7, s20, s7
	v_and_b32_e32 v73, 0xffff0000, v106
	v_fma_f32 v68, -v56, v57, 1.0
	v_fmac_f32_e32 v57, v68, v57
	v_div_scale_f32 v68, vcc, 1.0, v48, 1.0
	v_mul_f32_e32 v69, v68, v57
	v_fma_f32 v72, -v56, v69, v68
	v_fmac_f32_e32 v69, v72, v57
	v_fma_f32 v56, -v56, v69, v68
	v_div_fmas_f32 v56, v56, v57, v69
	v_div_fixup_f32 v48, v56, v48, 1.0
	v_pk_fma_f32 v[56:57], v[48:49], v[66:67], v[60:61] op_sel_hi:[0,1,1] neg_lo:[0,0,1] neg_hi:[0,0,1]
	v_pk_fma_f32 v[68:69], v[48:49], v[70:71], v[50:51] op_sel_hi:[0,1,1] neg_lo:[0,0,1] neg_hi:[0,0,1]
	v_pk_mul_f32 v[68:69], v[2:3], v[68:69]
	v_pk_mul_f32 v[56:57], v[0:1], v[56:57]
	v_lshlrev_b32_e32 v72, 16, v106
	v_cvt_pk_bf16_f32 v56, v56, v57
	v_cvt_pk_bf16_f32 v57, v68, v69
	v_add_co_u32_e32 v68, vcc, s39, v14
	v_lshlrev_b32_e32 v74, 16, v49
	s_nop 0
	v_addc_co_u32_e32 v69, vcc, 0, v15, vcc
	v_and_b32_e32 v75, 0xffff0000, v49
	s_add_i32 s7, s7, 2
	global_store_dwordx2 v[68:69], v[56:57], off offset:512
	v_pk_mul_f32 v[48:49], v[44:45], v[74:75] op_sel_hi:[0,1]
	v_pk_mul_f32 v[56:57], v[44:45], v[72:73] op_sel_hi:[0,1]
	v_pk_fma_f32 v[64:65], v[44:45], v[72:73], v[64:65] op_sel_hi:[0,1,1] neg_lo:[0,0,1] neg_hi:[0,0,1]
	v_pk_fma_f32 v[54:55], v[44:45], v[74:75], v[54:55] op_sel_hi:[0,1,1] neg_lo:[0,0,1] neg_hi:[0,0,1]
	v_cvt_f32_i32_e32 v44, s7
	v_pk_add_f32 v[70:71], v[70:71], v[54:55]
	v_pk_add_f32 v[64:65], v[66:67], v[64:65]
	s_max_i32 s7, s35, 2
	v_div_scale_f32 v54, s[20:21], v44, v44, 1.0
	v_rcp_f32_e32 v55, v54
	s_min_i32 s20, s77, s23
	s_sub_i32 s7, s20, s7
	s_add_i32 s7, s7, 2
	v_fma_f32 v66, -v54, v55, 1.0
	v_fmac_f32_e32 v55, v66, v55
	v_div_scale_f32 v66, vcc, 1.0, v44, 1.0
	v_mul_f32_e32 v67, v66, v55
	v_fma_f32 v72, -v54, v67, v66
	v_fmac_f32_e32 v67, v72, v55
	v_fma_f32 v54, -v54, v67, v66
	v_div_fmas_f32 v54, v54, v55, v67
	v_div_fixup_f32 v44, v54, v44, 1.0
	v_pk_fma_f32 v[54:55], v[44:45], v[64:65], v[58:59] op_sel_hi:[0,1,1] neg_lo:[0,0,1] neg_hi:[0,0,1]
	v_pk_fma_f32 v[66:67], v[44:45], v[70:71], v[46:47] op_sel_hi:[0,1,1] neg_lo:[0,0,1] neg_hi:[0,0,1]
	v_pk_mul_f32 v[66:67], v[2:3], v[66:67]
	v_pk_mul_f32 v[54:55], v[0:1], v[54:55]
	s_nop 0
	v_cvt_pk_bf16_f32 v54, v54, v55
	v_cvt_pk_bf16_f32 v55, v66, v67
	global_store_dwordx2 v[68:69], v[54:55], off offset:2560
	v_lshlrev_b32_e32 v66, 16, v105
	v_and_b32_e32 v67, 0xffff0000, v105
	v_lshlrev_b32_e32 v68, 16, v45
	v_and_b32_e32 v69, 0xffff0000, v45
	v_pk_mul_f32 v[44:45], v[42:43], v[68:69] op_sel_hi:[0,1]
	v_pk_mul_f32 v[54:55], v[42:43], v[66:67] op_sel_hi:[0,1]
	v_pk_fma_f32 v[62:63], v[42:43], v[66:67], v[62:63] op_sel_hi:[0,1,1] neg_lo:[0,0,1] neg_hi:[0,0,1]
	v_pk_fma_f32 v[52:53], v[42:43], v[68:69], v[52:53] op_sel_hi:[0,1,1] neg_lo:[0,0,1] neg_hi:[0,0,1]
	v_cvt_f32_i32_e32 v42, s7
	v_pk_add_f32 v[66:67], v[70:71], v[52:53]
	v_pk_add_f32 v[62:63], v[64:65], v[62:63]
	s_movk_i32 s7, 0x7000
	v_div_scale_f32 v52, s[20:21], v42, v42, 1.0
	v_rcp_f32_e32 v53, v52
	s_min_i32 s20, s76, s23
	v_and_b32_e32 v69, 0xffff0000, v104
	v_lshlrev_b32_e32 v70, 16, v43
	v_fma_f32 v64, -v52, v53, 1.0
	v_fmac_f32_e32 v53, v64, v53
	v_div_scale_f32 v64, vcc, 1.0, v42, 1.0
	v_mul_f32_e32 v65, v64, v53
	v_fma_f32 v68, -v52, v65, v64
	v_fmac_f32_e32 v65, v68, v53
	v_fma_f32 v52, -v52, v65, v64
	v_div_fmas_f32 v52, v52, v53, v65
	v_div_fixup_f32 v42, v52, v42, 1.0
	v_pk_fma_f32 v[52:53], v[42:43], v[62:63], v[56:57] op_sel_hi:[0,1,1] neg_lo:[0,0,1] neg_hi:[0,0,1]
	v_pk_fma_f32 v[64:65], v[42:43], v[66:67], v[48:49] op_sel_hi:[0,1,1] neg_lo:[0,0,1] neg_hi:[0,0,1]
	v_pk_mul_f32 v[64:65], v[2:3], v[64:65]
	v_pk_mul_f32 v[52:53], v[0:1], v[52:53]
	v_lshlrev_b32_e32 v68, 16, v104
	v_cvt_pk_bf16_f32 v52, v52, v53
	v_cvt_pk_bf16_f32 v53, v64, v65
	v_add_co_u32_e32 v64, vcc, s7, v14
	s_max_i32 s7, s78, 2
	s_sub_i32 s7, s20, s7
	v_addc_co_u32_e32 v65, vcc, 0, v15, vcc
	v_and_b32_e32 v71, 0xffff0000, v43
	s_add_i32 s7, s7, 2
	global_store_dwordx2 v[64:65], v[52:53], off offset:512
	v_pk_mul_f32 v[42:43], v[40:41], v[70:71] op_sel_hi:[0,1]
	v_pk_mul_f32 v[52:53], v[40:41], v[68:69] op_sel_hi:[0,1]
	v_pk_fma_f32 v[60:61], v[40:41], v[68:69], v[60:61] op_sel_hi:[0,1,1] neg_lo:[0,0,1] neg_hi:[0,0,1]
	v_pk_fma_f32 v[50:51], v[40:41], v[70:71], v[50:51] op_sel_hi:[0,1,1] neg_lo:[0,0,1] neg_hi:[0,0,1]
	v_cvt_f32_i32_e32 v40, s7
	v_pk_add_f32 v[66:67], v[66:67], v[50:51]
	v_pk_add_f32 v[60:61], v[62:63], v[60:61]
	s_max_i32 s7, s77, 2
	v_div_scale_f32 v50, s[20:21], v40, v40, 1.0
	v_rcp_f32_e32 v51, v50
	s_min_i32 s20, s75, s23
	s_sub_i32 s7, s20, s7
	s_add_i32 s7, s7, 2
	v_fma_f32 v62, -v50, v51, 1.0
	v_fmac_f32_e32 v51, v62, v51
	v_div_scale_f32 v62, vcc, 1.0, v40, 1.0
	v_mul_f32_e32 v63, v62, v51
	v_fma_f32 v68, -v50, v63, v62
	v_fmac_f32_e32 v63, v68, v51
	v_fma_f32 v50, -v50, v63, v62
	v_div_fmas_f32 v50, v50, v51, v63
	v_div_fixup_f32 v40, v50, v40, 1.0
	v_pk_fma_f32 v[50:51], v[40:41], v[60:61], v[54:55] op_sel_hi:[0,1,1] neg_lo:[0,0,1] neg_hi:[0,0,1]
	v_pk_fma_f32 v[62:63], v[40:41], v[66:67], v[44:45] op_sel_hi:[0,1,1] neg_lo:[0,0,1] neg_hi:[0,0,1]
	v_pk_mul_f32 v[62:63], v[2:3], v[62:63]
	v_pk_mul_f32 v[50:51], v[0:1], v[50:51]
	s_nop 0
	v_cvt_pk_bf16_f32 v50, v50, v51
	v_cvt_pk_bf16_f32 v51, v62, v63
	global_store_dwordx2 v[64:65], v[50:51], off offset:2560
	v_lshlrev_b32_e32 v62, 16, v103
	v_and_b32_e32 v63, 0xffff0000, v103
	v_lshlrev_b32_e32 v64, 16, v41
	v_and_b32_e32 v65, 0xffff0000, v41
	v_pk_mul_f32 v[40:41], v[38:39], v[64:65] op_sel_hi:[0,1]
	v_pk_mul_f32 v[50:51], v[38:39], v[62:63] op_sel_hi:[0,1]
	v_pk_fma_f32 v[58:59], v[38:39], v[62:63], v[58:59] op_sel_hi:[0,1,1] neg_lo:[0,0,1] neg_hi:[0,0,1]
	v_pk_fma_f32 v[46:47], v[38:39], v[64:65], v[46:47] op_sel_hi:[0,1,1] neg_lo:[0,0,1] neg_hi:[0,0,1]
	v_cvt_f32_i32_e32 v38, s7
	v_pk_add_f32 v[62:63], v[66:67], v[46:47]
	v_pk_add_f32 v[58:59], v[60:61], v[58:59]
	s_max_i32 s7, s76, 2
	v_div_scale_f32 v46, s[20:21], v38, v38, 1.0
	v_rcp_f32_e32 v47, v46
	s_min_i32 s20, s74, s23
	s_sub_i32 s7, s20, s7
	v_and_b32_e32 v65, 0xffff0000, v102
	v_fma_f32 v60, -v46, v47, 1.0
	v_fmac_f32_e32 v47, v60, v47
	v_div_scale_f32 v60, vcc, 1.0, v38, 1.0
	v_mul_f32_e32 v61, v60, v47
	v_fma_f32 v64, -v46, v61, v60
	v_fmac_f32_e32 v61, v64, v47
	v_fma_f32 v46, -v46, v61, v60
	v_div_fmas_f32 v46, v46, v47, v61
	v_div_fixup_f32 v38, v46, v38, 1.0
	v_pk_fma_f32 v[46:47], v[38:39], v[58:59], v[52:53] op_sel_hi:[0,1,1] neg_lo:[0,0,1] neg_hi:[0,0,1]
	v_pk_fma_f32 v[60:61], v[38:39], v[62:63], v[42:43] op_sel_hi:[0,1,1] neg_lo:[0,0,1] neg_hi:[0,0,1]
	v_pk_mul_f32 v[60:61], v[2:3], v[60:61]
	v_pk_mul_f32 v[46:47], v[0:1], v[46:47]
	v_lshlrev_b32_e32 v64, 16, v102
	v_cvt_pk_bf16_f32 v46, v46, v47
	v_cvt_pk_bf16_f32 v47, v60, v61
	v_add_co_u32_e32 v60, vcc, s61, v14
	v_lshlrev_b32_e32 v66, 16, v39
	s_nop 0
	v_addc_co_u32_e32 v61, vcc, 0, v15, vcc
	v_and_b32_e32 v67, 0xffff0000, v39
	s_add_i32 s7, s7, 2
	global_store_dwordx2 v[60:61], v[46:47], off offset:512
	v_pk_mul_f32 v[38:39], v[36:37], v[66:67] op_sel_hi:[0,1]
	v_pk_mul_f32 v[46:47], v[36:37], v[64:65] op_sel_hi:[0,1]
	v_pk_fma_f32 v[56:57], v[36:37], v[64:65], v[56:57] op_sel_hi:[0,1,1] neg_lo:[0,0,1] neg_hi:[0,0,1]
	v_pk_fma_f32 v[48:49], v[36:37], v[66:67], v[48:49] op_sel_hi:[0,1,1] neg_lo:[0,0,1] neg_hi:[0,0,1]
	v_cvt_f32_i32_e32 v36, s7
	v_pk_add_f32 v[62:63], v[62:63], v[48:49]
	v_pk_add_f32 v[56:57], v[58:59], v[56:57]
	s_max_i32 s7, s75, 2
	v_div_scale_f32 v48, s[20:21], v36, v36, 1.0
	v_rcp_f32_e32 v49, v48
	s_min_i32 s20, s72, s23
	s_sub_i32 s7, s20, s7
	s_add_i32 s7, s7, 2
	v_fma_f32 v58, -v48, v49, 1.0
	v_fmac_f32_e32 v49, v58, v49
	v_div_scale_f32 v58, vcc, 1.0, v36, 1.0
	v_mul_f32_e32 v59, v58, v49
	v_fma_f32 v64, -v48, v59, v58
	v_fmac_f32_e32 v59, v64, v49
	v_fma_f32 v48, -v48, v59, v58
	v_div_fmas_f32 v48, v48, v49, v59
	v_div_fixup_f32 v36, v48, v36, 1.0
	v_pk_fma_f32 v[48:49], v[36:37], v[56:57], v[50:51] op_sel_hi:[0,1,1] neg_lo:[0,0,1] neg_hi:[0,0,1]
	v_pk_fma_f32 v[58:59], v[36:37], v[62:63], v[40:41] op_sel_hi:[0,1,1] neg_lo:[0,0,1] neg_hi:[0,0,1]
	v_pk_mul_f32 v[58:59], v[2:3], v[58:59]
	v_pk_mul_f32 v[48:49], v[0:1], v[48:49]
	s_nop 0
	v_cvt_pk_bf16_f32 v48, v48, v49
	v_cvt_pk_bf16_f32 v49, v58, v59
	global_store_dwordx2 v[60:61], v[48:49], off offset:2560
	v_lshlrev_b32_e32 v58, 16, v101
	v_and_b32_e32 v59, 0xffff0000, v101
	v_lshlrev_b32_e32 v60, 16, v37
	v_and_b32_e32 v61, 0xffff0000, v37
	v_pk_mul_f32 v[36:37], v[32:33], v[60:61] op_sel_hi:[0,1]
	v_pk_mul_f32 v[48:49], v[32:33], v[58:59] op_sel_hi:[0,1]
	v_pk_fma_f32 v[54:55], v[32:33], v[58:59], v[54:55] op_sel_hi:[0,1,1] neg_lo:[0,0,1] neg_hi:[0,0,1]
	v_pk_fma_f32 v[44:45], v[32:33], v[60:61], v[44:45] op_sel_hi:[0,1,1] neg_lo:[0,0,1] neg_hi:[0,0,1]
	v_cvt_f32_i32_e32 v32, s7
	v_pk_add_f32 v[58:59], v[62:63], v[44:45]
	v_pk_add_f32 v[54:55], v[56:57], v[54:55]
	s_max_i32 s7, s74, 2
	v_div_scale_f32 v44, s[20:21], v32, v32, 1.0
	v_rcp_f32_e32 v45, v44
	s_min_i32 s20, s73, s23
	v_and_b32_e32 v61, 0xffff0000, v35
	v_lshlrev_b32_e32 v62, 16, v33
	v_fma_f32 v56, -v44, v45, 1.0
	v_fmac_f32_e32 v45, v56, v45
	v_div_scale_f32 v56, vcc, 1.0, v32, 1.0
	v_mul_f32_e32 v57, v56, v45
	v_fma_f32 v60, -v44, v57, v56
	v_fmac_f32_e32 v57, v60, v45
	v_fma_f32 v44, -v44, v57, v56
	v_div_fmas_f32 v44, v44, v45, v57
	v_div_fixup_f32 v32, v44, v32, 1.0
	v_pk_fma_f32 v[44:45], v[32:33], v[54:55], v[46:47] op_sel_hi:[0,1,1] neg_lo:[0,0,1] neg_hi:[0,0,1]
	v_pk_fma_f32 v[56:57], v[32:33], v[58:59], v[38:39] op_sel_hi:[0,1,1] neg_lo:[0,0,1] neg_hi:[0,0,1]
	v_pk_mul_f32 v[56:57], v[2:3], v[56:57]
	v_pk_mul_f32 v[44:45], v[0:1], v[44:45]
	v_lshlrev_b32_e32 v60, 16, v35
	v_cvt_pk_bf16_f32 v44, v44, v45
	v_cvt_pk_bf16_f32 v45, v56, v57
	v_add_co_u32_e32 v56, vcc, s94, v14
	v_and_b32_e32 v63, 0xffff0000, v33
	s_nop 0
	v_addc_co_u32_e32 v57, vcc, 0, v15, vcc
	s_sub_i32 s7, s20, s7
	global_store_dwordx2 v[56:57], v[44:45], off offset:512
	v_pk_mul_f32 v[32:33], v[34:35], v[62:63] op_sel_hi:[0,1]
	v_pk_mul_f32 v[44:45], v[34:35], v[60:61] op_sel_hi:[0,1]
	v_pk_fma_f32 v[52:53], v[34:35], v[60:61], v[52:53] op_sel_hi:[0,1,1] neg_lo:[0,0,1] neg_hi:[0,0,1]
	v_pk_fma_f32 v[34:35], v[34:35], v[62:63], v[42:43] op_sel_hi:[0,1,1] neg_lo:[0,0,1] neg_hi:[0,0,1]
	s_add_i32 s7, s7, 2
	v_pk_add_f32 v[58:59], v[58:59], v[34:35]
	v_cvt_f32_i32_e32 v34, s7
	v_pk_add_f32 v[52:53], v[54:55], v[52:53]
	s_max_i32 s7, s72, 2
	v_div_scale_f32 v35, s[20:21], v34, v34, 1.0
	v_rcp_f32_e32 v42, v35
	s_min_i32 s20, s71, s23
	s_sub_i32 s7, s20, s7
	s_add_i32 s7, s7, 2
	v_fma_f32 v43, -v35, v42, 1.0
	v_fmac_f32_e32 v42, v43, v42
	v_div_scale_f32 v43, vcc, 1.0, v34, 1.0
	v_mul_f32_e32 v54, v43, v42
	v_fma_f32 v55, -v35, v54, v43
	v_fmac_f32_e32 v54, v55, v42
	v_fma_f32 v35, -v35, v54, v43
	v_div_fmas_f32 v35, v35, v42, v54
	v_div_fixup_f32 v34, v35, v34, 1.0
	v_pk_fma_f32 v[42:43], v[34:35], v[52:53], v[48:49] op_sel_hi:[0,1,1] neg_lo:[0,0,1] neg_hi:[0,0,1]
	v_pk_fma_f32 v[34:35], v[34:35], v[58:59], v[36:37] op_sel_hi:[0,1,1] neg_lo:[0,0,1] neg_hi:[0,0,1]
	v_pk_mul_f32 v[42:43], v[0:1], v[42:43]
	v_pk_mul_f32 v[34:35], v[2:3], v[34:35]
	v_cvt_pk_bf16_f32 v42, v42, v43
	v_lshlrev_b32_e32 v54, 16, v100
	v_cvt_pk_bf16_f32 v43, v34, v35
	global_store_dwordx2 v[56:57], v[42:43], off offset:2560
	v_and_b32_e32 v55, 0xffff0000, v100
	v_lshlrev_b32_e32 v56, 16, v99
	v_and_b32_e32 v57, 0xffff0000, v99
	v_pk_mul_f32 v[34:35], v[30:31], v[56:57] op_sel_hi:[0,1]
	v_pk_mul_f32 v[42:43], v[30:31], v[54:55] op_sel_hi:[0,1]
	v_pk_fma_f32 v[50:51], v[30:31], v[54:55], v[50:51] op_sel_hi:[0,1,1] neg_lo:[0,0,1] neg_hi:[0,0,1]
	v_pk_fma_f32 v[40:41], v[30:31], v[56:57], v[40:41] op_sel_hi:[0,1,1] neg_lo:[0,0,1] neg_hi:[0,0,1]
	v_cvt_f32_i32_e32 v30, s7
	v_pk_add_f32 v[54:55], v[58:59], v[40:41]
	v_pk_add_f32 v[50:51], v[52:53], v[50:51]
	s_mov_b32 s7, 0xa000
	v_div_scale_f32 v40, s[20:21], v30, v30, 1.0
	v_rcp_f32_e32 v41, v40
	s_min_i32 s20, s70, s23
	v_and_b32_e32 v57, 0xffff0000, v98
	v_lshlrev_b32_e32 v58, 16, v31
	v_fma_f32 v52, -v40, v41, 1.0
	v_fmac_f32_e32 v41, v52, v41
	v_div_scale_f32 v52, vcc, 1.0, v30, 1.0
	v_mul_f32_e32 v53, v52, v41
	v_fma_f32 v56, -v40, v53, v52
	v_fmac_f32_e32 v53, v56, v41
	v_fma_f32 v40, -v40, v53, v52
	v_div_fmas_f32 v40, v40, v41, v53
	v_div_fixup_f32 v30, v40, v30, 1.0
	v_pk_fma_f32 v[40:41], v[30:31], v[50:51], v[44:45] op_sel_hi:[0,1,1] neg_lo:[0,0,1] neg_hi:[0,0,1]
	v_pk_fma_f32 v[52:53], v[30:31], v[54:55], v[32:33] op_sel_hi:[0,1,1] neg_lo:[0,0,1] neg_hi:[0,0,1]
	v_pk_mul_f32 v[52:53], v[2:3], v[52:53]
	v_pk_mul_f32 v[40:41], v[0:1], v[40:41]
	v_lshlrev_b32_e32 v56, 16, v98
	v_cvt_pk_bf16_f32 v40, v40, v41
	v_cvt_pk_bf16_f32 v41, v52, v53
	v_add_co_u32_e32 v52, vcc, s7, v14
	s_max_i32 s7, s73, 2
	s_sub_i32 s7, s20, s7
	v_addc_co_u32_e32 v53, vcc, 0, v15, vcc
	v_and_b32_e32 v59, 0xffff0000, v31
	s_add_i32 s7, s7, 2
	global_store_dwordx2 v[52:53], v[40:41], off offset:512
	v_pk_mul_f32 v[30:31], v[28:29], v[58:59] op_sel_hi:[0,1]
	v_pk_mul_f32 v[40:41], v[28:29], v[56:57] op_sel_hi:[0,1]
	v_pk_fma_f32 v[46:47], v[28:29], v[56:57], v[46:47] op_sel_hi:[0,1,1] neg_lo:[0,0,1] neg_hi:[0,0,1]
	v_pk_fma_f32 v[38:39], v[28:29], v[58:59], v[38:39] op_sel_hi:[0,1,1] neg_lo:[0,0,1] neg_hi:[0,0,1]
	v_cvt_f32_i32_e32 v28, s7
	v_pk_add_f32 v[54:55], v[54:55], v[38:39]
	v_pk_add_f32 v[46:47], v[50:51], v[46:47]
	s_max_i32 s7, s71, 2
	v_div_scale_f32 v38, s[20:21], v28, v28, 1.0
	v_rcp_f32_e32 v39, v38
	s_min_i32 s20, s69, s23
	s_sub_i32 s7, s20, s7
	s_add_i32 s7, s7, 2
	v_fma_f32 v50, -v38, v39, 1.0
	v_fmac_f32_e32 v39, v50, v39
	v_div_scale_f32 v50, vcc, 1.0, v28, 1.0
	v_mul_f32_e32 v51, v50, v39
	v_fma_f32 v56, -v38, v51, v50
	v_fmac_f32_e32 v51, v56, v39
	v_fma_f32 v38, -v38, v51, v50
	v_div_fmas_f32 v38, v38, v39, v51
	v_div_fixup_f32 v28, v38, v28, 1.0
	v_pk_fma_f32 v[38:39], v[28:29], v[46:47], v[42:43] op_sel_hi:[0,1,1] neg_lo:[0,0,1] neg_hi:[0,0,1]
	v_pk_fma_f32 v[50:51], v[28:29], v[54:55], v[34:35] op_sel_hi:[0,1,1] neg_lo:[0,0,1] neg_hi:[0,0,1]
	v_pk_mul_f32 v[50:51], v[2:3], v[50:51]
	v_pk_mul_f32 v[38:39], v[0:1], v[38:39]
	s_nop 0
	v_cvt_pk_bf16_f32 v38, v38, v39
	v_cvt_pk_bf16_f32 v39, v50, v51
	global_store_dwordx2 v[52:53], v[38:39], off offset:2560
	v_lshlrev_b32_e32 v50, 16, v95
	v_and_b32_e32 v51, 0xffff0000, v95
	v_lshlrev_b32_e32 v52, 16, v29
	v_and_b32_e32 v53, 0xffff0000, v29
	v_pk_mul_f32 v[28:29], v[26:27], v[52:53] op_sel_hi:[0,1]
	v_pk_mul_f32 v[38:39], v[26:27], v[50:51] op_sel_hi:[0,1]
	v_pk_fma_f32 v[48:49], v[26:27], v[50:51], v[48:49] op_sel_hi:[0,1,1] neg_lo:[0,0,1] neg_hi:[0,0,1]
	v_pk_fma_f32 v[36:37], v[26:27], v[52:53], v[36:37] op_sel_hi:[0,1,1] neg_lo:[0,0,1] neg_hi:[0,0,1]
	v_cvt_f32_i32_e32 v26, s7
	v_pk_add_f32 v[50:51], v[54:55], v[36:37]
	v_pk_add_f32 v[46:47], v[46:47], v[48:49]
	s_max_i32 s7, s70, 2
	v_div_scale_f32 v36, s[20:21], v26, v26, 1.0
	v_rcp_f32_e32 v37, v36
	s_min_i32 s20, s68, s23
	s_sub_i32 s7, s20, s7
	v_and_b32_e32 v53, 0xffff0000, v94
	v_fma_f32 v48, -v36, v37, 1.0
	v_fmac_f32_e32 v37, v48, v37
	v_div_scale_f32 v48, vcc, 1.0, v26, 1.0
	v_mul_f32_e32 v49, v48, v37
	v_fma_f32 v52, -v36, v49, v48
	v_fmac_f32_e32 v49, v52, v37
	v_fma_f32 v36, -v36, v49, v48
	v_div_fmas_f32 v36, v36, v37, v49
	v_div_fixup_f32 v26, v36, v26, 1.0
	v_pk_fma_f32 v[36:37], v[26:27], v[46:47], v[40:41] op_sel_hi:[0,1,1] neg_lo:[0,0,1] neg_hi:[0,0,1]
	v_pk_fma_f32 v[48:49], v[26:27], v[50:51], v[30:31] op_sel_hi:[0,1,1] neg_lo:[0,0,1] neg_hi:[0,0,1]
	v_pk_mul_f32 v[48:49], v[2:3], v[48:49]
	v_pk_mul_f32 v[36:37], v[0:1], v[36:37]
	v_lshlrev_b32_e32 v52, 16, v94
	v_cvt_pk_bf16_f32 v36, v36, v37
	v_cvt_pk_bf16_f32 v37, v48, v49
	v_add_co_u32_e32 v48, vcc, s51, v14
	v_lshlrev_b32_e32 v54, 16, v27
	s_nop 0
	v_addc_co_u32_e32 v49, vcc, 0, v15, vcc
	v_and_b32_e32 v55, 0xffff0000, v27
	s_add_i32 s7, s7, 2
	global_store_dwordx2 v[48:49], v[36:37], off offset:512
	v_pk_mul_f32 v[26:27], v[24:25], v[54:55] op_sel_hi:[0,1]
	v_pk_mul_f32 v[36:37], v[24:25], v[52:53] op_sel_hi:[0,1]
	v_pk_fma_f32 v[44:45], v[24:25], v[52:53], v[44:45] op_sel_hi:[0,1,1] neg_lo:[0,0,1] neg_hi:[0,0,1]
	v_pk_fma_f32 v[32:33], v[24:25], v[54:55], v[32:33] op_sel_hi:[0,1,1] neg_lo:[0,0,1] neg_hi:[0,0,1]
	v_cvt_f32_i32_e32 v24, s7
	v_pk_add_f32 v[50:51], v[50:51], v[32:33]
	v_pk_add_f32 v[44:45], v[46:47], v[44:45]
	s_max_i32 s7, s69, 2
	v_div_scale_f32 v32, s[20:21], v24, v24, 1.0
	v_rcp_f32_e32 v33, v32
	s_min_i32 s20, s66, s23
	s_sub_i32 s7, s20, s7
	s_add_i32 s7, s7, 2
	v_fma_f32 v46, -v32, v33, 1.0
	v_fmac_f32_e32 v33, v46, v33
	v_div_scale_f32 v46, vcc, 1.0, v24, 1.0
	v_mul_f32_e32 v47, v46, v33
	v_fma_f32 v52, -v32, v47, v46
	v_fmac_f32_e32 v47, v52, v33
	v_fma_f32 v32, -v32, v47, v46
	v_div_fmas_f32 v32, v32, v33, v47
	v_div_fixup_f32 v24, v32, v24, 1.0
	v_pk_fma_f32 v[32:33], v[24:25], v[44:45], v[38:39] op_sel_hi:[0,1,1] neg_lo:[0,0,1] neg_hi:[0,0,1]
	v_pk_fma_f32 v[46:47], v[24:25], v[50:51], v[28:29] op_sel_hi:[0,1,1] neg_lo:[0,0,1] neg_hi:[0,0,1]
	v_pk_mul_f32 v[46:47], v[2:3], v[46:47]
	v_pk_mul_f32 v[32:33], v[0:1], v[32:33]
	s_nop 0
	v_cvt_pk_bf16_f32 v32, v32, v33
	v_cvt_pk_bf16_f32 v33, v46, v47
	global_store_dwordx2 v[48:49], v[32:33], off offset:2560
	v_lshlrev_b32_e32 v46, 16, v93
	v_and_b32_e32 v47, 0xffff0000, v93
	v_lshlrev_b32_e32 v48, 16, v25
	v_and_b32_e32 v49, 0xffff0000, v25
	v_pk_mul_f32 v[24:25], v[20:21], v[48:49] op_sel_hi:[0,1]
	v_pk_mul_f32 v[32:33], v[20:21], v[46:47] op_sel_hi:[0,1]
	v_pk_fma_f32 v[42:43], v[20:21], v[46:47], v[42:43] op_sel_hi:[0,1,1] neg_lo:[0,0,1] neg_hi:[0,0,1]
	v_pk_fma_f32 v[34:35], v[20:21], v[48:49], v[34:35] op_sel_hi:[0,1,1] neg_lo:[0,0,1] neg_hi:[0,0,1]
	v_cvt_f32_i32_e32 v20, s7
	v_pk_add_f32 v[46:47], v[50:51], v[34:35]
	v_pk_add_f32 v[42:43], v[44:45], v[42:43]
	s_max_i32 s7, s68, 2
	v_div_scale_f32 v34, s[20:21], v20, v20, 1.0
	v_rcp_f32_e32 v35, v34
	s_min_i32 s20, s67, s23
	v_and_b32_e32 v49, 0xffff0000, v23
	v_lshlrev_b32_e32 v50, 16, v21
	v_fma_f32 v44, -v34, v35, 1.0
	v_fmac_f32_e32 v35, v44, v35
	v_div_scale_f32 v44, vcc, 1.0, v20, 1.0
	v_mul_f32_e32 v45, v44, v35
	v_fma_f32 v48, -v34, v45, v44
	v_fmac_f32_e32 v45, v48, v35
	v_fma_f32 v34, -v34, v45, v44
	v_div_fmas_f32 v34, v34, v35, v45
	v_div_fixup_f32 v20, v34, v20, 1.0
	v_pk_fma_f32 v[34:35], v[20:21], v[42:43], v[36:37] op_sel_hi:[0,1,1] neg_lo:[0,0,1] neg_hi:[0,0,1]
	v_pk_fma_f32 v[44:45], v[20:21], v[46:47], v[26:27] op_sel_hi:[0,1,1] neg_lo:[0,0,1] neg_hi:[0,0,1]
	v_pk_mul_f32 v[44:45], v[2:3], v[44:45]
	v_pk_mul_f32 v[34:35], v[0:1], v[34:35]
	v_lshlrev_b32_e32 v48, 16, v23
	v_cvt_pk_bf16_f32 v34, v34, v35
	v_cvt_pk_bf16_f32 v35, v44, v45
	v_add_co_u32_e32 v44, vcc, s58, v14
	v_and_b32_e32 v51, 0xffff0000, v21
	s_nop 0
	v_addc_co_u32_e32 v45, vcc, 0, v15, vcc
	s_sub_i32 s7, s20, s7
	global_store_dwordx2 v[44:45], v[34:35], off offset:512
	v_pk_mul_f32 v[20:21], v[22:23], v[50:51] op_sel_hi:[0,1]
	v_pk_mul_f32 v[34:35], v[22:23], v[48:49] op_sel_hi:[0,1]
	v_pk_fma_f32 v[40:41], v[22:23], v[48:49], v[40:41] op_sel_hi:[0,1,1] neg_lo:[0,0,1] neg_hi:[0,0,1]
	v_pk_fma_f32 v[22:23], v[22:23], v[50:51], v[30:31] op_sel_hi:[0,1,1] neg_lo:[0,0,1] neg_hi:[0,0,1]
	s_add_i32 s7, s7, 2
	v_pk_add_f32 v[46:47], v[46:47], v[22:23]
	v_cvt_f32_i32_e32 v22, s7
	v_pk_add_f32 v[40:41], v[42:43], v[40:41]
	s_max_i32 s7, s66, 2
	v_div_scale_f32 v23, s[20:21], v22, v22, 1.0
	v_rcp_f32_e32 v30, v23
	s_min_i32 s20, s63, s23
	s_sub_i32 s7, s20, s7
	s_add_i32 s7, s7, 2
	v_fma_f32 v31, -v23, v30, 1.0
	v_fmac_f32_e32 v30, v31, v30
	v_div_scale_f32 v31, vcc, 1.0, v22, 1.0
	v_mul_f32_e32 v42, v31, v30
	v_fma_f32 v43, -v23, v42, v31
	v_fmac_f32_e32 v42, v43, v30
	v_fma_f32 v23, -v23, v42, v31
	v_div_fmas_f32 v23, v23, v30, v42
	v_div_fixup_f32 v22, v23, v22, 1.0
	v_pk_fma_f32 v[30:31], v[22:23], v[40:41], v[32:33] op_sel_hi:[0,1,1] neg_lo:[0,0,1] neg_hi:[0,0,1]
	v_pk_fma_f32 v[22:23], v[22:23], v[46:47], v[24:25] op_sel_hi:[0,1,1] neg_lo:[0,0,1] neg_hi:[0,0,1]
	v_pk_mul_f32 v[30:31], v[0:1], v[30:31]
	v_pk_mul_f32 v[22:23], v[2:3], v[22:23]
	v_cvt_pk_bf16_f32 v30, v30, v31
	v_lshlrev_b32_e32 v42, 16, v92
	v_cvt_pk_bf16_f32 v31, v22, v23
	global_store_dwordx2 v[44:45], v[30:31], off offset:2560
	v_and_b32_e32 v43, 0xffff0000, v92
	v_lshlrev_b32_e32 v44, 16, v91
	v_and_b32_e32 v45, 0xffff0000, v91
	v_pk_mul_f32 v[22:23], v[18:19], v[44:45] op_sel_hi:[0,1]
	v_pk_mul_f32 v[30:31], v[18:19], v[42:43] op_sel_hi:[0,1]
	v_pk_fma_f32 v[38:39], v[18:19], v[42:43], v[38:39] op_sel_hi:[0,1,1] neg_lo:[0,0,1] neg_hi:[0,0,1]
	v_pk_fma_f32 v[28:29], v[18:19], v[44:45], v[28:29] op_sel_hi:[0,1,1] neg_lo:[0,0,1] neg_hi:[0,0,1]
	v_cvt_f32_i32_e32 v18, s7
	v_pk_add_f32 v[42:43], v[46:47], v[28:29]
	v_pk_add_f32 v[38:39], v[40:41], v[38:39]
	s_max_i32 s7, s67, 2
	v_div_scale_f32 v28, s[20:21], v18, v18, 1.0
	v_rcp_f32_e32 v29, v28
	s_min_i32 s20, s34, s23
	s_sub_i32 s7, s20, s7
	v_and_b32_e32 v45, 0xffff0000, v90
	v_fma_f32 v40, -v28, v29, 1.0
	v_fmac_f32_e32 v29, v40, v29
	v_div_scale_f32 v40, vcc, 1.0, v18, 1.0
	v_mul_f32_e32 v41, v40, v29
	v_fma_f32 v44, -v28, v41, v40
	v_fmac_f32_e32 v41, v44, v29
	v_fma_f32 v28, -v28, v41, v40
	v_div_fmas_f32 v28, v28, v29, v41
	v_div_fixup_f32 v18, v28, v18, 1.0
	v_pk_fma_f32 v[28:29], v[18:19], v[38:39], v[34:35] op_sel_hi:[0,1,1] neg_lo:[0,0,1] neg_hi:[0,0,1]
	v_pk_fma_f32 v[40:41], v[18:19], v[42:43], v[20:21] op_sel_hi:[0,1,1] neg_lo:[0,0,1] neg_hi:[0,0,1]
	v_pk_mul_f32 v[40:41], v[2:3], v[40:41]
	v_pk_mul_f32 v[28:29], v[0:1], v[28:29]
	v_lshlrev_b32_e32 v44, 16, v90
	v_cvt_pk_bf16_f32 v28, v28, v29
	v_cvt_pk_bf16_f32 v29, v40, v41
	v_add_co_u32_e32 v40, vcc, s59, v14
	v_lshlrev_b32_e32 v46, 16, v19
	s_nop 0
	v_addc_co_u32_e32 v41, vcc, 0, v15, vcc
	v_and_b32_e32 v47, 0xffff0000, v19
	s_add_i32 s7, s7, 2
	global_store_dwordx2 v[40:41], v[28:29], off offset:512
	v_pk_mul_f32 v[18:19], v[16:17], v[46:47] op_sel_hi:[0,1]
	v_pk_mul_f32 v[28:29], v[16:17], v[44:45] op_sel_hi:[0,1]
	v_pk_fma_f32 v[36:37], v[16:17], v[44:45], v[36:37] op_sel_hi:[0,1,1] neg_lo:[0,0,1] neg_hi:[0,0,1]
	v_pk_fma_f32 v[26:27], v[16:17], v[46:47], v[26:27] op_sel_hi:[0,1,1] neg_lo:[0,0,1] neg_hi:[0,0,1]
	v_cvt_f32_i32_e32 v16, s7
	v_pk_add_f32 v[36:37], v[38:39], v[36:37]
	v_pk_add_f32 v[26:27], v[42:43], v[26:27]
	s_max_i32 s7, s63, 2
	v_div_scale_f32 v38, s[20:21], v16, v16, 1.0
	v_rcp_f32_e32 v39, v38
	s_min_i32 s20, s15, s23
	s_sub_i32 s7, s20, s7
	s_add_i32 s7, s7, 2
	v_fma_f32 v42, -v38, v39, 1.0
	v_fmac_f32_e32 v39, v42, v39
	v_div_scale_f32 v42, vcc, 1.0, v16, 1.0
	v_mul_f32_e32 v43, v42, v39
	v_fma_f32 v44, -v38, v43, v42
	v_fmac_f32_e32 v43, v44, v39
	v_fma_f32 v38, -v38, v43, v42
	v_div_fmas_f32 v38, v38, v39, v43
	v_div_fixup_f32 v16, v38, v16, 1.0
	v_pk_fma_f32 v[38:39], v[16:17], v[36:37], v[30:31] op_sel_hi:[0,1,1] neg_lo:[0,0,1] neg_hi:[0,0,1]
	v_pk_fma_f32 v[42:43], v[16:17], v[26:27], v[22:23] op_sel_hi:[0,1,1] neg_lo:[0,0,1] neg_hi:[0,0,1]
	v_pk_mul_f32 v[38:39], v[0:1], v[38:39]
	v_pk_mul_f32 v[42:43], v[2:3], v[42:43]
	v_cvt_pk_bf16_f32 v38, v38, v39
	s_nop 0
	v_cvt_pk_bf16_f32 v39, v42, v43
	global_store_dwordx2 v[40:41], v[38:39], off offset:2560
	v_lshlrev_b32_e32 v38, 16, v89
	v_and_b32_e32 v39, 0xffff0000, v89
	v_lshlrev_b32_e32 v40, 16, v88
	v_and_b32_e32 v41, 0xffff0000, v88
	v_pk_mul_f32 v[42:43], v[12:13], v[40:41] op_sel_hi:[0,1]
	v_pk_mul_f32 v[44:45], v[12:13], v[38:39] op_sel_hi:[0,1]
	v_pk_fma_f32 v[32:33], v[12:13], v[38:39], v[32:33] op_sel_hi:[0,1,1] neg_lo:[0,0,1] neg_hi:[0,0,1]
	v_pk_fma_f32 v[24:25], v[12:13], v[40:41], v[24:25] op_sel_hi:[0,1,1] neg_lo:[0,0,1] neg_hi:[0,0,1]
	v_cvt_f32_i32_e32 v12, s7
	v_pk_add_f32 v[24:25], v[26:27], v[24:25]
	v_pk_add_f32 v[26:27], v[36:37], v[32:33]
	s_max_i32 s7, s34, 2
	v_div_scale_f32 v16, s[20:21], v12, v12, 1.0
	v_rcp_f32_e32 v32, v16
	s_min_i32 s20, s5, s23
	s_sub_i32 s7, s20, s7
	v_lshlrev_b32_e32 v38, 16, v86
	v_fma_f32 v33, -v16, v32, 1.0
	v_fmac_f32_e32 v32, v33, v32
	v_div_scale_f32 v33, vcc, 1.0, v12, 1.0
	v_mul_f32_e32 v36, v33, v32
	v_fma_f32 v37, -v16, v36, v33
	v_fmac_f32_e32 v36, v37, v32
	v_fma_f32 v16, -v16, v36, v33
	v_div_fmas_f32 v16, v16, v32, v36
	v_div_fixup_f32 v12, v16, v12, 1.0
	v_pk_fma_f32 v[32:33], v[12:13], v[26:27], v[28:29] op_sel_hi:[0,1,1] neg_lo:[0,0,1] neg_hi:[0,0,1]
	v_pk_fma_f32 v[36:37], v[12:13], v[24:25], v[18:19] op_sel_hi:[0,1,1] neg_lo:[0,0,1] neg_hi:[0,0,1]
	v_pk_mul_f32 v[36:37], v[2:3], v[36:37]
	v_pk_mul_f32 v[32:33], v[0:1], v[32:33]
	v_and_b32_e32 v39, 0xffff0000, v86
	v_cvt_pk_bf16_f32 v32, v32, v33
	v_cvt_pk_bf16_f32 v33, v36, v37
	v_add_co_u32_e32 v36, vcc, s60, v14
	s_add_i32 s7, s7, 2
	s_nop 0
	v_addc_co_u32_e32 v37, vcc, 0, v15, vcc
	global_store_dwordx2 v[36:37], v[32:33], off offset:512
	v_lshlrev_b32_e32 v32, 16, v87
	v_and_b32_e32 v33, 0xffff0000, v87
	v_pk_mul_f32 v[40:41], v[10:11], v[38:39] op_sel_hi:[0,1]
	v_pk_mul_f32 v[46:47], v[10:11], v[32:33] op_sel_hi:[0,1]
	v_pk_fma_f32 v[32:33], v[10:11], v[32:33], v[34:35] op_sel_hi:[0,1,1] neg_lo:[0,0,1] neg_hi:[0,0,1]
	v_pk_fma_f32 v[20:21], v[10:11], v[38:39], v[20:21] op_sel_hi:[0,1,1] neg_lo:[0,0,1] neg_hi:[0,0,1]
	v_cvt_f32_i32_e32 v10, s7
	v_pk_add_f32 v[20:21], v[24:25], v[20:21]
	v_pk_add_f32 v[24:25], v[26:27], v[32:33]
	s_max_i32 s7, s15, 2
	v_div_scale_f32 v12, s[20:21], v10, v10, 1.0
	v_rcp_f32_e32 v16, v12
	s_min_i32 s15, s62, s23
	s_sub_i32 s7, s15, s7
	s_add_i32 s7, s7, 2
	v_fma_f32 v26, -v12, v16, 1.0
	v_fmac_f32_e32 v16, v26, v16
	v_div_scale_f32 v26, vcc, 1.0, v10, 1.0
	v_mul_f32_e32 v27, v26, v16
	v_fma_f32 v32, -v12, v27, v26
	v_fmac_f32_e32 v27, v32, v16
	v_fma_f32 v12, -v12, v27, v26
	v_div_fmas_f32 v12, v12, v16, v27
	v_div_fixup_f32 v10, v12, v10, 1.0
	v_pk_fma_f32 v[26:27], v[10:11], v[24:25], v[44:45] op_sel_hi:[0,1,1] neg_lo:[0,0,1] neg_hi:[0,0,1]
	v_pk_fma_f32 v[32:33], v[10:11], v[20:21], v[42:43] op_sel_hi:[0,1,1] neg_lo:[0,0,1] neg_hi:[0,0,1]
	v_cvt_f32_i32_e32 v10, s7
	v_pk_mul_f32 v[26:27], v[0:1], v[26:27]
	v_pk_mul_f32 v[32:33], v[2:3], v[32:33]
	v_cvt_pk_bf16_f32 v26, v26, v27
	v_lshlrev_b32_e32 v12, 16, v13
	v_cvt_pk_bf16_f32 v27, v32, v33
	global_store_dwordx2 v[36:37], v[26:27], off offset:2560
	v_and_b32_e32 v13, 0xffff0000, v13
	v_lshlrev_b32_e32 v26, 16, v7
	v_and_b32_e32 v27, 0xffff0000, v7
	v_pk_mul_f32 v[32:33], v[6:7], v[26:27] op_sel_hi:[0,1]
	v_pk_mul_f32 v[34:35], v[6:7], v[12:13] op_sel_hi:[0,1]
	v_pk_fma_f32 v[12:13], v[6:7], v[12:13], v[30:31] op_sel_hi:[0,1,1] neg_lo:[0,0,1] neg_hi:[0,0,1]
	v_pk_fma_f32 v[6:7], v[6:7], v[26:27], v[22:23] op_sel_hi:[0,1,1] neg_lo:[0,0,1] neg_hi:[0,0,1]
	v_div_scale_f32 v16, s[20:21], v10, v10, 1.0
	v_pk_add_f32 v[6:7], v[20:21], v[6:7]
	v_rcp_f32_e32 v20, v16
	s_add_i32 s7, s4, 33
	s_max_i32 s5, s5, 2
	s_min_i32 s7, s7, s23
	v_fma_f32 v21, -v16, v20, 1.0
	v_fmac_f32_e32 v20, v21, v20
	v_div_scale_f32 v21, vcc, 1.0, v10, 1.0
	v_mul_f32_e32 v22, v21, v20
	v_fma_f32 v23, -v16, v22, v21
	v_fmac_f32_e32 v22, v23, v20
	v_fma_f32 v16, -v16, v22, v21
	v_div_fmas_f32 v16, v16, v20, v22
	s_sub_i32 s5, s7, s5
	v_pk_add_f32 v[12:13], v[24:25], v[12:13]
	v_div_fixup_f32 v10, v16, v10, 1.0
	s_add_i32 s5, s5, 2
	v_pk_fma_f32 v[20:21], v[10:11], v[12:13], v[46:47] op_sel_hi:[0,1,1] neg_lo:[0,0,1] neg_hi:[0,0,1]
	v_pk_fma_f32 v[22:23], v[10:11], v[6:7], v[40:41] op_sel_hi:[0,1,1] neg_lo:[0,0,1] neg_hi:[0,0,1]
	v_add_co_u32_e32 v14, vcc, s50, v14
	v_cvt_f32_i32_e32 v10, s5
	v_pk_mul_f32 v[20:21], v[0:1], v[20:21]
	v_addc_co_u32_e32 v15, vcc, 0, v15, vcc
	v_pk_mul_f32 v[22:23], v[2:3], v[22:23]
	v_cvt_pk_bf16_f32 v20, v20, v21
	v_lshlrev_b32_e32 v16, 16, v9
	v_cvt_pk_bf16_f32 v21, v22, v23
	global_store_dwordx2 v[14:15], v[20:21], off offset:512
	v_lshlrev_b32_e32 v14, 16, v17
	v_and_b32_e32 v15, 0xffff0000, v17
	v_and_b32_e32 v17, 0xffff0000, v9
	s_waitcnt vmcnt(31)
	v_pk_fma_f32 v[14:15], v[8:9], v[14:15], v[28:29] op_sel_hi:[0,1,1] neg_lo:[0,0,1] neg_hi:[0,0,1]
	v_pk_fma_f32 v[8:9], v[8:9], v[16:17], v[18:19] op_sel_hi:[0,1,1] neg_lo:[0,0,1] neg_hi:[0,0,1]
	v_pk_add_f32 v[6:7], v[6:7], v[8:9]
	v_pk_add_f32 v[8:9], v[12:13], v[14:15]
	v_div_scale_f32 v12, s[20:21], v10, v10, 1.0
	v_rcp_f32_e32 v13, v12
	s_nop 0
	v_fma_f32 v14, -v12, v13, 1.0
	v_fmac_f32_e32 v13, v14, v13
	v_div_scale_f32 v14, vcc, 1.0, v10, 1.0
	v_mul_f32_e32 v15, v14, v13
	v_fma_f32 v16, -v12, v15, v14
	v_fmac_f32_e32 v15, v16, v13
	v_fma_f32 v12, -v12, v15, v14
	v_div_fmas_f32 v12, v12, v13, v15
	v_div_fixup_f32 v10, v12, v10, 1.0
	v_pk_fma_f32 v[8:9], v[10:11], v[8:9], v[34:35] op_sel_hi:[0,1,1] neg_lo:[0,0,1] neg_hi:[0,0,1]
	v_pk_fma_f32 v[6:7], v[10:11], v[6:7], v[32:33] op_sel_hi:[0,1,1] neg_lo:[0,0,1] neg_hi:[0,0,1]
	v_pk_mul_f32 v[12:13], v[2:3], v[6:7]
	v_pk_mul_f32 v[6:7], v[0:1], v[8:9]
	s_nop 0
	v_cvt_pk_bf16_f32 v6, v6, v7
	v_cvt_pk_bf16_f32 v7, v12, v13

.LBB0_404:
	s_add_i32 s5, s4, -8
	s_cmp_lt_u32 s5, s23
	s_cselect_b64 vcc, -1, 0
	s_and_b64 s[16:17], vcc, exec
	s_cselect_b32 s16, s5, s4
	s_ashr_i32 s17, s16, 31
	v_lshl_add_u64 v[8:9], s[2:3], 0, v[96:97]
	s_lshl_b64 s[18:19], s[16:17], 11
	v_lshl_add_u64 v[4:5], v[8:9], 0, s[18:19]
	global_load_dwordx2 v[4:5], v[4:5], off offset:1536 nt
	s_add_i32 s16, s16, s14
	s_ashr_i32 s17, s16, 31
	s_lshl_b64 s[16:17], s[16:17], 2
	s_add_u32 s16, s26, s16
	s_addc_u32 s17, s27, s17
	s_add_i32 s5, s4, -7
	s_cmp_lt_u32 s5, s23
	s_waitcnt vmcnt(0)
	v_cndmask_b32_e32 v23, 0, v4, vcc
	v_cndmask_b32_e32 v5, 0, v5, vcc
	s_cselect_b64 vcc, -1, 0
	global_load_dword v4, v97, s[16:17]
	s_and_b64 s[16:17], vcc, exec
	s_cselect_b32 s16, s5, s4
	s_ashr_i32 s17, s16, 31
	s_lshl_b64 s[18:19], s[16:17], 11
	v_lshl_add_u64 v[6:7], v[8:9], 0, s[18:19]
	global_load_dwordx2 v[6:7], v[6:7], off offset:1536 nt
	s_add_i32 s16, s16, s14
	s_ashr_i32 s17, s16, 31
	s_lshl_b64 s[16:17], s[16:17], 2
	s_add_u32 s16, s26, s16
	s_addc_u32 s17, s27, s17
	s_add_i32 s5, s4, -6
	s_cmp_lt_u32 s5, s23
	global_load_dword v22, v97, s[16:17]
	v_lshlrev_b32_e32 v100, 16, v23
	v_and_b32_e32 v101, 0xffff0000, v23
	v_lshlrev_b32_e32 v110, 16, v5
	v_and_b32_e32 v111, 0xffff0000, v5
	s_waitcnt vmcnt(2)
	v_pk_mul_f32 v[156:157], v[4:5], v[110:111] op_sel_hi:[0,1]
	v_pk_mul_f32 v[158:159], v[4:5], v[100:101] op_sel_hi:[0,1]
	v_pk_fma_f32 v[100:101], v[4:5], v[100:101], 0 op_sel_hi:[0,1,0]
	v_pk_fma_f32 v[4:5], v[4:5], v[110:111], 0 op_sel_hi:[0,1,0]
	s_waitcnt vmcnt(1)
	v_cndmask_b32_e32 v47, 0, v6, vcc
	v_cndmask_b32_e32 v43, 0, v7, vcc
	s_cselect_b64 vcc, -1, 0
	s_and_b64 s[16:17], vcc, exec
	s_cselect_b32 s16, s5, s4
	s_ashr_i32 s17, s16, 31
	s_lshl_b64 s[18:19], s[16:17], 11
	v_lshl_add_u64 v[6:7], v[8:9], 0, s[18:19]
	global_load_dwordx2 v[6:7], v[6:7], off offset:1536 nt
	s_add_i32 s16, s16, s14
	s_ashr_i32 s17, s16, 31
	s_lshl_b64 s[16:17], s[16:17], 2
	s_add_u32 s16, s26, s16
	s_addc_u32 s17, s27, s17
	s_add_i32 s5, s4, -5
	s_cmp_lt_u32 s5, s23
	global_load_dword v42, v97, s[16:17]
	v_lshlrev_b32_e32 v110, 16, v47
	v_and_b32_e32 v111, 0xffff0000, v47
	v_lshlrev_b32_e32 v112, 16, v43
	v_and_b32_e32 v113, 0xffff0000, v43
	s_waitcnt vmcnt(2)
	v_pk_mul_f32 v[152:153], v[22:23], v[112:113] op_sel_hi:[0,1]
	v_pk_mul_f32 v[154:155], v[22:23], v[110:111] op_sel_hi:[0,1]
	v_pk_fma_f32 v[4:5], v[22:23], v[112:113], v[4:5] op_sel_hi:[0,1,1]
	v_pk_fma_f32 v[22:23], v[22:23], v[110:111], v[100:101] op_sel_hi:[0,1,1]
	s_waitcnt vmcnt(1)
	v_cndmask_b32_e32 v51, 0, v6, vcc
	v_cndmask_b32_e32 v49, 0, v7, vcc
	s_cselect_b64 vcc, -1, 0
	s_and_b64 s[16:17], vcc, exec
	s_cselect_b32 s16, s5, s4
	s_ashr_i32 s17, s16, 31
	s_lshl_b64 s[18:19], s[16:17], 11
	v_lshl_add_u64 v[6:7], v[8:9], 0, s[18:19]
	global_load_dwordx2 v[6:7], v[6:7], off offset:1536 nt
	s_add_i32 s16, s16, s14
	s_ashr_i32 s17, s16, 31
	s_lshl_b64 s[16:17], s[16:17], 2
	s_add_u32 s16, s26, s16
	s_addc_u32 s17, s27, s17
	s_add_i32 s5, s4, -4
	s_cmp_lt_u32 s5, s23
	global_load_dword v46, v97, s[16:17]
	v_lshlrev_b32_e32 v100, 16, v51
	v_and_b32_e32 v101, 0xffff0000, v51
	v_lshlrev_b32_e32 v110, 16, v49
	v_and_b32_e32 v111, 0xffff0000, v49
	s_waitcnt vmcnt(2)
	v_pk_mul_f32 v[148:149], v[42:43], v[110:111] op_sel_hi:[0,1]
	v_pk_mul_f32 v[150:151], v[42:43], v[100:101] op_sel_hi:[0,1]
	v_pk_fma_f32 v[22:23], v[42:43], v[100:101], v[22:23] op_sel_hi:[0,1,1]
	v_pk_fma_f32 v[4:5], v[42:43], v[110:111], v[4:5] op_sel_hi:[0,1,1]
	s_waitcnt vmcnt(1)
	v_cndmask_b32_e32 v57, 0, v6, vcc
	v_cndmask_b32_e32 v53, 0, v7, vcc
	s_cselect_b64 vcc, -1, 0
	s_and_b64 s[16:17], vcc, exec
	s_cselect_b32 s16, s5, s4
	s_ashr_i32 s17, s16, 31
	s_lshl_b64 s[18:19], s[16:17], 11
	v_lshl_add_u64 v[6:7], v[8:9], 0, s[18:19]
	global_load_dwordx2 v[6:7], v[6:7], off offset:1536 nt
	s_add_i32 s16, s16, s14
	s_ashr_i32 s17, s16, 31
	s_lshl_b64 s[16:17], s[16:17], 2
	s_add_u32 s16, s26, s16
	s_addc_u32 s17, s27, s17
	s_add_i32 s5, s4, -3
	s_cmp_lt_u32 s5, s23
	global_load_dword v48, v97, s[16:17]
	v_lshlrev_b32_e32 v42, 16, v57
	v_and_b32_e32 v43, 0xffff0000, v57
	v_lshlrev_b32_e32 v100, 16, v53
	v_and_b32_e32 v101, 0xffff0000, v53
	s_waitcnt vmcnt(2)
	v_pk_mul_f32 v[146:147], v[46:47], v[42:43] op_sel_hi:[0,1]
	v_pk_fma_f32 v[22:23], v[46:47], v[42:43], v[22:23] op_sel_hi:[0,1,1]
	v_pk_mul_f32 v[144:145], v[46:47], v[100:101] op_sel_hi:[0,1]
	v_pk_fma_f32 v[4:5], v[46:47], v[100:101], v[4:5] op_sel_hi:[0,1,1]
	s_waitcnt vmcnt(1)
	v_cndmask_b32_e32 v61, 0, v6, vcc
	v_cndmask_b32_e32 v59, 0, v7, vcc
	s_cselect_b64 vcc, -1, 0
	s_and_b64 s[16:17], vcc, exec
	s_cselect_b32 s16, s5, s4
	s_ashr_i32 s17, s16, 31
	s_lshl_b64 s[18:19], s[16:17], 11
	v_lshl_add_u64 v[6:7], v[8:9], 0, s[18:19]
	global_load_dwordx2 v[6:7], v[6:7], off offset:1536 nt
	s_add_i32 s16, s16, s14
	s_ashr_i32 s17, s16, 31
	s_lshl_b64 s[16:17], s[16:17], 2
	s_add_u32 s16, s26, s16
	s_addc_u32 s17, s27, s17
	s_add_i32 s5, s4, -2
	s_cmp_lt_u32 s5, s23
	global_load_dword v52, v97, s[16:17]
	v_lshlrev_b32_e32 v42, 16, v61
	v_and_b32_e32 v43, 0xffff0000, v61
	v_lshlrev_b32_e32 v46, 16, v59
	v_and_b32_e32 v47, 0xffff0000, v59
	s_waitcnt vmcnt(2)
	v_pk_mul_f32 v[142:143], v[48:49], v[42:43] op_sel_hi:[0,1]
	v_pk_fma_f32 v[22:23], v[48:49], v[42:43], v[22:23] op_sel_hi:[0,1,1]
	v_pk_mul_f32 v[140:141], v[48:49], v[46:47] op_sel_hi:[0,1]
	v_pk_fma_f32 v[4:5], v[48:49], v[46:47], v[4:5] op_sel_hi:[0,1,1]
	s_waitcnt vmcnt(1)
	v_cndmask_b32_e32 v65, 0, v6, vcc
	v_cndmask_b32_e32 v63, 0, v7, vcc
	s_cselect_b64 vcc, -1, 0
	s_and_b64 s[16:17], vcc, exec
	s_cselect_b32 s16, s5, s4
	s_ashr_i32 s17, s16, 31
	s_lshl_b64 s[18:19], s[16:17], 11
	v_lshl_add_u64 v[6:7], v[8:9], 0, s[18:19]
	global_load_dwordx2 v[6:7], v[6:7], off offset:1536 nt
	s_add_i32 s16, s16, s14
	s_ashr_i32 s17, s16, 31
	s_lshl_b64 s[16:17], s[16:17], 2
	s_add_u32 s16, s26, s16
	s_addc_u32 s17, s27, s17
	s_add_i32 s5, s4, -1
	s_cmp_lt_u32 s5, s23
	global_load_dword v56, v97, s[16:17]
	v_lshlrev_b32_e32 v42, 16, v65
	v_and_b32_e32 v43, 0xffff0000, v65
	v_lshlrev_b32_e32 v46, 16, v63
	v_and_b32_e32 v47, 0xffff0000, v63
	s_waitcnt vmcnt(2)
	v_pk_mul_f32 v[138:139], v[52:53], v[42:43] op_sel_hi:[0,1]
	v_pk_fma_f32 v[22:23], v[52:53], v[42:43], v[22:23] op_sel_hi:[0,1,1]
	v_pk_mul_f32 v[136:137], v[52:53], v[46:47] op_sel_hi:[0,1]
	v_pk_fma_f32 v[4:5], v[52:53], v[46:47], v[4:5] op_sel_hi:[0,1,1]
	s_waitcnt vmcnt(1)
	v_cndmask_b32_e32 v69, 0, v6, vcc
	v_cndmask_b32_e32 v67, 0, v7, vcc
	s_cselect_b64 vcc, -1, 0
	s_and_b64 s[16:17], vcc, exec
	s_cselect_b32 s16, s5, s4
	s_ashr_i32 s17, s16, 31
	s_lshl_b64 s[18:19], s[16:17], 11
	v_lshl_add_u64 v[6:7], v[8:9], 0, s[18:19]
	global_load_dwordx2 v[6:7], v[6:7], off offset:1536 nt
	s_add_i32 s16, s16, s14
	s_ashr_i32 s17, s16, 31
	s_lshl_b64 s[16:17], s[16:17], 2
	s_add_u32 s16, s26, s16
	s_addc_u32 s17, s27, s17
	s_cmp_lt_u32 s4, s23
	global_load_dword v60, v97, s[16:17]
	v_lshlrev_b32_e32 v42, 16, v69
	v_and_b32_e32 v43, 0xffff0000, v69
	v_lshlrev_b32_e32 v46, 16, v67
	v_and_b32_e32 v47, 0xffff0000, v67
	s_waitcnt vmcnt(2)
	v_pk_mul_f32 v[134:135], v[56:57], v[42:43] op_sel_hi:[0,1]
	v_pk_fma_f32 v[22:23], v[56:57], v[42:43], v[22:23] op_sel_hi:[0,1,1]
	v_pk_mul_f32 v[132:133], v[56:57], v[46:47] op_sel_hi:[0,1]
	v_pk_fma_f32 v[4:5], v[56:57], v[46:47], v[4:5] op_sel_hi:[0,1,1]
	s_waitcnt vmcnt(1)
	v_cndmask_b32_e32 v73, 0, v6, vcc
	v_cndmask_b32_e32 v71, 0, v7, vcc
	s_cselect_b64 vcc, -1, 0
	s_ashr_i32 s5, s4, 31
	s_lshl_b64 s[16:17], s[4:5], 11
	v_lshl_add_u64 v[6:7], v[8:9], 0, s[16:17]
	global_load_dwordx2 v[6:7], v[6:7], off offset:1536 nt
	s_ashr_i32 s7, s6, 31
	s_lshl_b64 s[16:17], s[6:7], 2
	s_add_u32 s16, s26, s16
	s_addc_u32 s17, s27, s17
	s_or_b32 s35, s4, 1
	s_cmp_lt_u32 s35, s23
	global_load_dword v66, v97, s[16:17]
	v_lshlrev_b32_e32 v42, 16, v73
	v_and_b32_e32 v43, 0xffff0000, v73
	v_lshlrev_b32_e32 v46, 16, v71
	v_and_b32_e32 v47, 0xffff0000, v71
	s_waitcnt vmcnt(2)
	v_pk_mul_f32 v[130:131], v[60:61], v[42:43] op_sel_hi:[0,1]
	v_pk_fma_f32 v[22:23], v[60:61], v[42:43], v[22:23] op_sel_hi:[0,1,1]
	v_pk_mul_f32 v[128:129], v[60:61], v[46:47] op_sel_hi:[0,1]
	v_pk_fma_f32 v[4:5], v[60:61], v[46:47], v[4:5] op_sel_hi:[0,1,1]
	s_waitcnt vmcnt(1)
	v_cndmask_b32_e32 v77, 0, v6, vcc
	v_cndmask_b32_e32 v75, 0, v7, vcc
	s_cselect_b64 vcc, -1, 0
	s_and_b64 s[16:17], vcc, exec
	s_cselect_b32 s16, s35, s4
	s_ashr_i32 s17, s16, 31
	s_lshl_b64 s[18:19], s[16:17], 11
	v_lshl_add_u64 v[6:7], v[8:9], 0, s[18:19]
	global_load_dwordx2 v[6:7], v[6:7], off offset:1536 nt
	s_add_i32 s16, s16, s14
	s_ashr_i32 s17, s16, 31
	s_lshl_b64 s[16:17], s[16:17], 2
	s_add_u32 s16, s26, s16
	s_addc_u32 s17, s27, s17
	s_or_b32 s97, s4, 2
	s_cmp_lt_u32 s97, s23
	global_load_dword v72, v97, s[16:17]
	v_lshlrev_b32_e32 v42, 16, v77
	v_and_b32_e32 v43, 0xffff0000, v77
	v_lshlrev_b32_e32 v46, 16, v75
	v_and_b32_e32 v47, 0xffff0000, v75
	s_waitcnt vmcnt(2)
	v_pk_mul_f32 v[126:127], v[66:67], v[42:43] op_sel_hi:[0,1]
	v_pk_fma_f32 v[22:23], v[66:67], v[42:43], v[22:23] op_sel_hi:[0,1,1]
	v_pk_mul_f32 v[124:125], v[66:67], v[46:47] op_sel_hi:[0,1]
	v_pk_fma_f32 v[4:5], v[66:67], v[46:47], v[4:5] op_sel_hi:[0,1,1]
	s_waitcnt vmcnt(1)
	v_cndmask_b32_e32 v81, 0, v6, vcc
	v_cndmask_b32_e32 v79, 0, v7, vcc
	s_cselect_b64 vcc, -1, 0
	s_and_b64 s[16:17], vcc, exec
	s_cselect_b32 s16, s97, s4
	s_ashr_i32 s17, s16, 31
	s_lshl_b64 s[18:19], s[16:17], 11
	v_lshl_add_u64 v[6:7], v[8:9], 0, s[18:19]
	global_load_dwordx2 v[6:7], v[6:7], off offset:1536 nt
	s_add_i32 s16, s16, s14
	s_ashr_i32 s17, s16, 31
	s_lshl_b64 s[16:17], s[16:17], 2
	s_add_u32 s16, s26, s16
	s_addc_u32 s17, s27, s17
	s_or_b32 s96, s4, 3
	s_cmp_lt_u32 s96, s23
	global_load_dword v76, v97, s[16:17]
	v_lshlrev_b32_e32 v42, 16, v81
	v_and_b32_e32 v43, 0xffff0000, v81
	v_lshlrev_b32_e32 v46, 16, v79
	v_and_b32_e32 v47, 0xffff0000, v79
	s_waitcnt vmcnt(2)
	v_pk_mul_f32 v[122:123], v[72:73], v[42:43] op_sel_hi:[0,1]
	v_pk_fma_f32 v[22:23], v[72:73], v[42:43], v[22:23] op_sel_hi:[0,1,1]
	v_pk_mul_f32 v[120:121], v[72:73], v[46:47] op_sel_hi:[0,1]
	v_pk_fma_f32 v[4:5], v[72:73], v[46:47], v[4:5] op_sel_hi:[0,1,1]
	s_waitcnt vmcnt(1)
	v_cndmask_b32_e32 v85, 0, v6, vcc
	v_cndmask_b32_e32 v83, 0, v7, vcc
	s_cselect_b64 vcc, -1, 0
	s_and_b64 s[16:17], vcc, exec
	s_cselect_b32 s16, s96, s4
	s_ashr_i32 s17, s16, 31
	s_lshl_b64 s[18:19], s[16:17], 11
	v_lshl_add_u64 v[6:7], v[8:9], 0, s[18:19]
	global_load_dwordx2 v[6:7], v[6:7], off offset:1536 nt
	s_add_i32 s16, s16, s14
	s_ashr_i32 s17, s16, 31
	s_lshl_b64 s[16:17], s[16:17], 2
	s_add_u32 s16, s26, s16
	s_addc_u32 s17, s27, s17
	s_or_b32 s91, s4, 4
	s_cmp_lt_u32 s91, s23
	global_load_dword v80, v97, s[16:17]
	v_lshlrev_b32_e32 v42, 16, v85
	v_and_b32_e32 v43, 0xffff0000, v85
	v_lshlrev_b32_e32 v46, 16, v83
	v_and_b32_e32 v47, 0xffff0000, v83
	s_waitcnt vmcnt(2)
	v_pk_mul_f32 v[118:119], v[76:77], v[42:43] op_sel_hi:[0,1]
	v_pk_fma_f32 v[22:23], v[76:77], v[42:43], v[22:23] op_sel_hi:[0,1,1]
	v_pk_mul_f32 v[100:101], v[76:77], v[46:47] op_sel_hi:[0,1]
	v_pk_fma_f32 v[4:5], v[76:77], v[46:47], v[4:5] op_sel_hi:[0,1,1]
	s_waitcnt vmcnt(1)
	v_cndmask_b32_e32 v103, 0, v6, vcc
	v_cndmask_b32_e32 v102, 0, v7, vcc
	s_cselect_b64 vcc, -1, 0
	s_and_b64 s[16:17], vcc, exec
	s_cselect_b32 s16, s91, s4
	s_ashr_i32 s17, s16, 31
	s_lshl_b64 s[18:19], s[16:17], 11
	v_lshl_add_u64 v[6:7], v[8:9], 0, s[18:19]
	global_load_dwordx2 v[6:7], v[6:7], off offset:1536 nt
	s_add_i32 s16, s16, s14
	s_ashr_i32 s17, s16, 31
	s_lshl_b64 s[16:17], s[16:17], 2
	s_add_u32 s16, s26, s16
	s_addc_u32 s17, s27, s17
	s_or_b32 s90, s4, 5
	s_cmp_lt_u32 s90, s23
	global_load_dword v82, v97, s[16:17]
	v_lshlrev_b32_e32 v42, 16, v103
	v_and_b32_e32 v43, 0xffff0000, v103
	v_lshlrev_b32_e32 v46, 16, v102
	v_and_b32_e32 v47, 0xffff0000, v102
	s_waitcnt vmcnt(2)
	v_pk_mul_f32 v[116:117], v[80:81], v[42:43] op_sel_hi:[0,1]
	v_pk_fma_f32 v[22:23], v[80:81], v[42:43], v[22:23] op_sel_hi:[0,1,1]
	v_pk_mul_f32 v[102:103], v[80:81], v[46:47] op_sel_hi:[0,1]
	v_pk_fma_f32 v[4:5], v[80:81], v[46:47], v[4:5] op_sel_hi:[0,1,1]
	s_waitcnt vmcnt(1)
	v_cndmask_b32_e32 v105, 0, v6, vcc
	v_cndmask_b32_e32 v104, 0, v7, vcc
	s_cselect_b64 vcc, -1, 0
	s_and_b64 s[16:17], vcc, exec
	s_cselect_b32 s16, s90, s4
	s_ashr_i32 s17, s16, 31
	s_lshl_b64 s[18:19], s[16:17], 11
	v_lshl_add_u64 v[6:7], v[8:9], 0, s[18:19]
	global_load_dwordx2 v[6:7], v[6:7], off offset:1536 nt
	s_add_i32 s16, s16, s14
	s_ashr_i32 s17, s16, 31
	s_lshl_b64 s[16:17], s[16:17], 2
	s_add_u32 s16, s26, s16
	s_addc_u32 s17, s27, s17
	s_or_b32 s89, s4, 6
	s_cmp_lt_u32 s89, s23
	global_load_dword v86, v97, s[16:17]
	v_lshlrev_b32_e32 v42, 16, v105
	v_and_b32_e32 v43, 0xffff0000, v105
	v_lshlrev_b32_e32 v46, 16, v104
	v_and_b32_e32 v47, 0xffff0000, v104
	s_waitcnt vmcnt(2)
	v_pk_mul_f32 v[114:115], v[82:83], v[42:43] op_sel_hi:[0,1]
	v_pk_fma_f32 v[22:23], v[82:83], v[42:43], v[22:23] op_sel_hi:[0,1,1]
	v_pk_mul_f32 v[104:105], v[82:83], v[46:47] op_sel_hi:[0,1]
	v_pk_fma_f32 v[4:5], v[82:83], v[46:47], v[4:5] op_sel_hi:[0,1,1]
	s_waitcnt vmcnt(1)
	v_cndmask_b32_e32 v107, 0, v6, vcc
	v_cndmask_b32_e32 v106, 0, v7, vcc
	s_cselect_b64 vcc, -1, 0
	s_and_b64 s[16:17], vcc, exec
	s_cselect_b32 s16, s89, s4
	s_ashr_i32 s17, s16, 31
	s_lshl_b64 s[18:19], s[16:17], 11
	v_lshl_add_u64 v[6:7], v[8:9], 0, s[18:19]
	global_load_dwordx2 v[6:7], v[6:7], off offset:1536 nt
	s_add_i32 s16, s16, s14
	s_ashr_i32 s17, s16, 31
	s_lshl_b64 s[16:17], s[16:17], 2
	s_add_u32 s16, s26, s16
	s_addc_u32 s17, s27, s17
	s_or_b32 s87, s4, 7
	s_cmp_lt_u32 s87, s23
	global_load_dword v90, v97, s[16:17]
	v_lshlrev_b32_e32 v42, 16, v107
	v_and_b32_e32 v43, 0xffff0000, v107
	v_lshlrev_b32_e32 v46, 16, v106
	v_and_b32_e32 v47, 0xffff0000, v106
	s_waitcnt vmcnt(1)
	v_cndmask_b32_e32 v109, 0, v6, vcc
	v_cndmask_b32_e32 v108, 0, v7, vcc
	s_cselect_b64 vcc, -1, 0
	s_and_b64 s[16:17], vcc, exec
	s_cselect_b32 s16, s87, s4
	s_ashr_i32 s17, s16, 31
	s_lshl_b64 s[18:19], s[16:17], 11
	v_lshl_add_u64 v[6:7], v[8:9], 0, s[18:19]
	global_load_dwordx2 v[6:7], v[6:7], off offset:1536 nt
	s_add_i32 s16, s16, s14
	s_ashr_i32 s17, s16, 31
	s_lshl_b64 s[16:17], s[16:17], 2
	s_add_u32 s16, s26, s16
	s_addc_u32 s17, s27, s17
	s_or_b32 s85, s4, 8
	s_cmp_lt_u32 s85, s23
	global_load_dword v92, v97, s[16:17]
	s_waitcnt vmcnt(1)
	v_cndmask_b32_e32 v196, 0, v6, vcc
	v_cndmask_b32_e32 v195, 0, v7, vcc
	s_cselect_b64 vcc, -1, 0
	s_and_b64 s[16:17], vcc, exec
	s_cselect_b32 s16, s85, s4
	s_ashr_i32 s17, s16, 31
	s_lshl_b64 s[18:19], s[16:17], 11
	v_lshl_add_u64 v[6:7], v[8:9], 0, s[18:19]
	global_load_dwordx2 v[6:7], v[6:7], off offset:1536 nt
	s_add_i32 s16, s16, s14
	s_ashr_i32 s17, s16, 31
	s_lshl_b64 s[16:17], s[16:17], 2
	s_add_u32 s16, s26, s16
	s_addc_u32 s17, s27, s17
	s_or_b32 s88, s4, 9
	s_cmp_lt_u32 s88, s23
	global_load_dword v98, v97, s[16:17]
	v_lshlrev_b32_e32 v48, 16, v196
	v_and_b32_e32 v49, 0xffff0000, v196
	v_lshlrev_b32_e32 v52, 16, v195
	v_and_b32_e32 v53, 0xffff0000, v195
	s_waitcnt vmcnt(1)
	v_cndmask_b32_e32 v194, 0, v6, vcc
	v_cndmask_b32_e32 v193, 0, v7, vcc
	s_cselect_b64 vcc, -1, 0
	s_and_b64 s[16:17], vcc, exec
	s_cselect_b32 s16, s88, s4
	s_ashr_i32 s17, s16, 31
	s_lshl_b64 s[18:19], s[16:17], 11
	v_lshl_add_u64 v[6:7], v[8:9], 0, s[18:19]
	global_load_dwordx2 v[6:7], v[6:7], off offset:1536 nt
	s_add_i32 s16, s16, s14
	s_ashr_i32 s17, s16, 31
	s_lshl_b64 s[16:17], s[16:17], 2
	s_add_u32 s16, s26, s16
	s_addc_u32 s17, s27, s17
	s_or_b32 s86, s4, 10
	s_cmp_lt_u32 s86, s23
	global_load_dword v94, v97, s[16:17]
	v_lshlrev_b32_e32 v72, 16, v193
	v_and_b32_e32 v73, 0xffff0000, v193
	v_lshlrev_b32_e32 v66, 16, v194
	v_and_b32_e32 v67, 0xffff0000, v194
	s_waitcnt vmcnt(1)
	v_cndmask_b32_e32 v198, 0, v6, vcc
	v_cndmask_b32_e32 v197, 0, v7, vcc
	s_cselect_b64 vcc, -1, 0
	s_and_b64 s[16:17], vcc, exec
	s_cselect_b32 s16, s86, s4
	s_ashr_i32 s17, s16, 31
	s_lshl_b64 s[18:19], s[16:17], 11
	v_lshl_add_u64 v[6:7], v[8:9], 0, s[18:19]
	global_load_dwordx2 v[6:7], v[6:7], off offset:1536 nt
	s_add_i32 s16, s16, s14
	s_ashr_i32 s17, s16, 31
	s_lshl_b64 s[16:17], s[16:17], 2
	s_add_u32 s16, s26, s16
	s_addc_u32 s17, s27, s17
	s_or_b32 s84, s4, 11
	s_cmp_lt_u32 s84, s23
	global_load_dword v88, v97, s[16:17]
	v_lshlrev_b32_e32 v76, 16, v198
	v_and_b32_e32 v77, 0xffff0000, v198
	v_lshlrev_b32_e32 v80, 16, v197
	v_and_b32_e32 v81, 0xffff0000, v197
	s_waitcnt vmcnt(1)
	v_cndmask_b32_e32 v192, 0, v6, vcc
	v_cndmask_b32_e32 v191, 0, v7, vcc
	s_cselect_b64 vcc, -1, 0
	s_and_b64 s[16:17], vcc, exec
	s_cselect_b32 s16, s84, s4
	s_ashr_i32 s17, s16, 31
	s_lshl_b64 s[18:19], s[16:17], 11
	v_lshl_add_u64 v[6:7], v[8:9], 0, s[18:19]
	global_load_dwordx2 v[6:7], v[6:7], off offset:1536 nt
	s_add_i32 s16, s16, s14
	s_ashr_i32 s17, s16, 31
	s_lshl_b64 s[16:17], s[16:17], 2
	s_add_u32 s16, s26, s16
	s_addc_u32 s17, s27, s17
	s_or_b32 s83, s4, 12
	s_cmp_lt_u32 s83, s23
	global_load_dword v84, v97, s[16:17]
	s_waitcnt vmcnt(1)
	v_cndmask_b32_e32 v190, 0, v6, vcc
	v_cndmask_b32_e32 v189, 0, v7, vcc
	s_cselect_b64 vcc, -1, 0
	s_and_b64 s[16:17], vcc, exec
	s_cselect_b32 s16, s83, s4
	s_ashr_i32 s17, s16, 31
	s_lshl_b64 s[18:19], s[16:17], 11
	v_lshl_add_u64 v[6:7], v[8:9], 0, s[18:19]
	global_load_dwordx2 v[6:7], v[6:7], off offset:1536 nt
	s_add_i32 s16, s16, s14
	s_ashr_i32 s17, s16, 31
	s_lshl_b64 s[16:17], s[16:17], 2
	s_add_u32 s16, s26, s16
	s_addc_u32 s17, s27, s17
	s_or_b32 s81, s4, 13
	s_cmp_lt_u32 s81, s23
	global_load_dword v78, v97, s[16:17]
	s_waitcnt vmcnt(1)
	v_cndmask_b32_e32 v188, 0, v6, vcc
	v_cndmask_b32_e32 v187, 0, v7, vcc
	s_cselect_b64 vcc, -1, 0
	s_and_b64 s[16:17], vcc, exec
	s_cselect_b32 s16, s81, s4
	s_ashr_i32 s17, s16, 31
	s_lshl_b64 s[18:19], s[16:17], 11
	v_lshl_add_u64 v[6:7], v[8:9], 0, s[18:19]
	global_load_dwordx2 v[6:7], v[6:7], off offset:1536 nt
	s_add_i32 s16, s16, s14
	s_ashr_i32 s17, s16, 31
	s_lshl_b64 s[16:17], s[16:17], 2
	s_add_u32 s16, s26, s16
	s_addc_u32 s17, s27, s17
	s_or_b32 s78, s4, 14
	s_cmp_lt_u32 s78, s23
	global_load_dword v74, v97, s[16:17]
	s_waitcnt vmcnt(1)
	v_cndmask_b32_e32 v186, 0, v6, vcc
	v_cndmask_b32_e32 v87, 0, v7, vcc
	s_cselect_b64 vcc, -1, 0
	s_and_b64 s[16:17], vcc, exec
	s_cselect_b32 s16, s78, s4
	s_ashr_i32 s17, s16, 31
	s_lshl_b64 s[18:19], s[16:17], 11
	v_lshl_add_u64 v[6:7], v[8:9], 0, s[18:19]
	global_load_dwordx2 v[6:7], v[6:7], off offset:1536 nt
	s_add_i32 s16, s16, s14
	s_ashr_i32 s17, s16, 31
	s_lshl_b64 s[16:17], s[16:17], 2
	s_add_u32 s16, s26, s16
	s_addc_u32 s17, s27, s17
	s_or_b32 s76, s4, 15
	s_cmp_lt_u32 s76, s23
	global_load_dword v70, v97, s[16:17]
	v_pk_mul_f32 v[112:113], v[86:87], v[42:43] op_sel_hi:[0,1]
	v_pk_fma_f32 v[22:23], v[86:87], v[42:43], v[22:23] op_sel_hi:[0,1,1]
	v_lshlrev_b32_e32 v42, 16, v109
	v_and_b32_e32 v43, 0xffff0000, v109
	v_pk_mul_f32 v[106:107], v[86:87], v[46:47] op_sel_hi:[0,1]
	v_pk_fma_f32 v[4:5], v[86:87], v[46:47], v[4:5] op_sel_hi:[0,1,1]
	v_lshlrev_b32_e32 v46, 16, v108
	v_and_b32_e32 v47, 0xffff0000, v108
	s_waitcnt vmcnt(1)
	v_cndmask_b32_e32 v185, 0, v6, vcc
	v_cndmask_b32_e32 v89, 0, v7, vcc
	s_cselect_b64 vcc, -1, 0
	s_and_b64 s[16:17], vcc, exec
	s_cselect_b32 s16, s76, s4
	s_ashr_i32 s17, s16, 31
	s_lshl_b64 s[18:19], s[16:17], 11
	v_lshl_add_u64 v[6:7], v[8:9], 0, s[18:19]
	global_load_dwordx2 v[6:7], v[6:7], off offset:1536 nt
	s_add_i32 s16, s16, s14
	s_ashr_i32 s17, s16, 31
	s_lshl_b64 s[16:17], s[16:17], 2
	s_add_u32 s16, s26, s16
	s_addc_u32 s17, s27, s17
	s_or_b32 s73, s4, 16
	s_cmp_lt_u32 s73, s23
	global_load_dword v64, v97, s[16:17]
	s_waitcnt vmcnt(1)
	v_cndmask_b32_e32 v184, 0, v6, vcc
	v_cndmask_b32_e32 v91, 0, v7, vcc
	s_cselect_b64 vcc, -1, 0
	s_and_b64 s[16:17], vcc, exec
	s_cselect_b32 s16, s73, s4
	s_ashr_i32 s17, s16, 31
	s_lshl_b64 s[18:19], s[16:17], 11
	v_lshl_add_u64 v[6:7], v[8:9], 0, s[18:19]
	global_load_dwordx2 v[6:7], v[6:7], off offset:1536 nt
	s_add_i32 s16, s16, s14
	s_ashr_i32 s17, s16, 31
	s_lshl_b64 s[16:17], s[16:17], 2
	s_add_u32 s16, s26, s16
	s_addc_u32 s17, s27, s17
	s_or_b32 s74, s4, 17
	s_cmp_lt_u32 s74, s23
	global_load_dword v68, v97, s[16:17]
	v_pk_fma_f32 v[22:23], v[90:91], v[42:43], v[22:23] op_sel_hi:[0,1,1]
	v_pk_fma_f32 v[4:5], v[90:91], v[46:47], v[4:5] op_sel_hi:[0,1,1]
	v_pk_mul_f32 v[110:111], v[90:91], v[42:43] op_sel_hi:[0,1]
	v_pk_mul_f32 v[108:109], v[90:91], v[46:47] op_sel_hi:[0,1]
	s_waitcnt vmcnt(1)
	v_cndmask_b32_e32 v95, 0, v6, vcc
	v_cndmask_b32_e32 v93, 0, v7, vcc
	s_cselect_b64 vcc, -1, 0
	s_and_b64 s[16:17], vcc, exec
	s_cselect_b32 s16, s74, s4
	s_ashr_i32 s17, s16, 31
	s_lshl_b64 s[18:19], s[16:17], 11
	v_lshl_add_u64 v[6:7], v[8:9], 0, s[18:19]
	global_load_dwordx2 v[6:7], v[6:7], off offset:1536 nt
	s_add_i32 s16, s16, s14
	s_ashr_i32 s17, s16, 31
	s_lshl_b64 s[16:17], s[16:17], 2
	s_add_u32 s16, s26, s16
	s_addc_u32 s17, s27, s17
	s_or_b32 s71, s4, 18
	s_cmp_lt_u32 s71, s23
	global_load_dword v62, v97, s[16:17]
	v_pk_fma_f32 v[56:57], v[92:93], v[48:49], v[22:23] op_sel_hi:[0,1,1]
	v_pk_mul_f32 v[42:43], v[92:93], v[52:53] op_sel_hi:[0,1]
	v_pk_fma_f32 v[52:53], v[92:93], v[52:53], v[4:5] op_sel_hi:[0,1,1]
	v_pk_mul_f32 v[46:47], v[92:93], v[48:49] op_sel_hi:[0,1]
	s_waitcnt vmcnt(1)
	v_cndmask_b32_e32 v183, 0, v6, vcc
	v_cndmask_b32_e32 v182, 0, v7, vcc
	s_cselect_b64 vcc, -1, 0
	s_and_b64 s[16:17], vcc, exec
	s_cselect_b32 s16, s71, s4
	s_ashr_i32 s17, s16, 31
	s_lshl_b64 s[18:19], s[16:17], 11
	v_lshl_add_u64 v[6:7], v[8:9], 0, s[18:19]
	global_load_dwordx2 v[6:7], v[6:7], off offset:1536 nt
	s_add_i32 s16, s16, s14
	s_ashr_i32 s17, s16, 31
	s_lshl_b64 s[16:17], s[16:17], 2
	s_add_u32 s16, s26, s16
	s_addc_u32 s17, s27, s17
	s_or_b32 s69, s4, 19
	s_cmp_lt_u32 s69, s23
	global_load_dword v58, v97, s[16:17]
	s_waitcnt vmcnt(1)
	v_cndmask_b32_e32 v181, 0, v6, vcc
	v_cndmask_b32_e32 v99, 0, v7, vcc
	s_cselect_b64 vcc, -1, 0
	s_and_b64 s[16:17], vcc, exec
	s_cselect_b32 s16, s69, s4
	s_ashr_i32 s17, s16, 31
	s_lshl_b64 s[18:19], s[16:17], 11
	v_lshl_add_u64 v[6:7], v[8:9], 0, s[18:19]
	global_load_dwordx2 v[6:7], v[6:7], off offset:1536 nt
	s_add_i32 s16, s16, s14
	s_ashr_i32 s17, s16, 31
	s_lshl_b64 s[16:17], s[16:17], 2
	s_add_u32 s16, s26, s16
	s_addc_u32 s17, s27, s17
	s_or_b32 s68, s4, 20
	s_cmp_lt_u32 s68, s23
	global_load_dword v54, v97, s[16:17]
	s_waitcnt vmcnt(1)
	v_cndmask_b32_e32 v180, 0, v6, vcc
	v_cndmask_b32_e32 v179, 0, v7, vcc
	s_cselect_b64 vcc, -1, 0
	s_and_b64 s[16:17], vcc, exec
	s_cselect_b32 s16, s68, s4
	s_ashr_i32 s17, s16, 31
	s_lshl_b64 s[18:19], s[16:17], 11
	v_lshl_add_u64 v[6:7], v[8:9], 0, s[18:19]
	global_load_dwordx2 v[6:7], v[6:7], off offset:1536 nt
	s_add_i32 s16, s16, s14
	s_ashr_i32 s17, s16, 31
	s_lshl_b64 s[16:17], s[16:17], 2
	s_add_u32 s16, s26, s16
	s_addc_u32 s17, s27, s17
	s_or_b32 s67, s4, 21
	s_cmp_lt_u32 s67, s23
	global_load_dword v50, v97, s[16:17]
	s_waitcnt vmcnt(1)
	v_cndmask_b32_e32 v178, 0, v6, vcc
	v_cndmask_b32_e32 v55, 0, v7, vcc
	s_cselect_b64 vcc, -1, 0
	s_and_b64 s[16:17], vcc, exec
	s_cselect_b32 s16, s67, s4
	s_ashr_i32 s17, s16, 31
	s_lshl_b64 s[18:19], s[16:17], 11
	v_lshl_add_u64 v[6:7], v[8:9], 0, s[18:19]
	global_load_dwordx2 v[6:7], v[6:7], off offset:1536 nt
	s_add_i32 s16, s16, s14
	s_ashr_i32 s17, s16, 31
	s_lshl_b64 s[16:17], s[16:17], 2
	s_add_u32 s16, s26, s16
	s_addc_u32 s17, s27, s17
	s_or_b32 s66, s4, 22
	s_cmp_lt_u32 s66, s23
	global_load_dword v44, v97, s[16:17]
	s_waitcnt vmcnt(1)
	v_cndmask_b32_e32 v177, 0, v6, vcc
	v_cndmask_b32_e32 v176, 0, v7, vcc
	s_cselect_b64 vcc, -1, 0
	s_and_b64 s[16:17], vcc, exec
	s_cselect_b32 s16, s66, s4
	s_ashr_i32 s17, s16, 31
	s_lshl_b64 s[18:19], s[16:17], 11
	v_lshl_add_u64 v[6:7], v[8:9], 0, s[18:19]
	global_load_dwordx2 v[6:7], v[6:7], off offset:1536 nt
	s_add_i32 s16, s16, s14
	s_ashr_i32 s17, s16, 31
	s_lshl_b64 s[16:17], s[16:17], 2
	s_add_u32 s16, s26, s16
	s_addc_u32 s17, s27, s17
	s_or_b32 s63, s4, 23
	s_cmp_lt_u32 s63, s23
	global_load_dword v40, v97, s[16:17]
	s_waitcnt vmcnt(1)
	v_cndmask_b32_e32 v175, 0, v6, vcc
	v_cndmask_b32_e32 v45, 0, v7, vcc
	s_cselect_b64 vcc, -1, 0
	s_and_b64 s[16:17], vcc, exec
	s_cselect_b32 s16, s63, s4
	s_ashr_i32 s17, s16, 31
	s_lshl_b64 s[18:19], s[16:17], 11
	v_lshl_add_u64 v[6:7], v[8:9], 0, s[18:19]
	global_load_dwordx2 v[6:7], v[6:7], off offset:1536 nt
	s_add_i32 s16, s16, s14
	s_ashr_i32 s17, s16, 31
	s_lshl_b64 s[16:17], s[16:17], 2
	s_add_u32 s16, s26, s16
	s_addc_u32 s17, s27, s17
	s_or_b32 s62, s4, 24
	s_cmp_lt_u32 s62, s23
	global_load_dword v38, v97, s[16:17]
	s_waitcnt vmcnt(1)
	v_cndmask_b32_e32 v174, 0, v6, vcc
	v_cndmask_b32_e32 v41, 0, v7, vcc
	s_cselect_b64 vcc, -1, 0
	s_and_b64 s[16:17], vcc, exec
	s_cselect_b32 s16, s62, s4
	s_ashr_i32 s17, s16, 31
	s_lshl_b64 s[18:19], s[16:17], 11
	v_lshl_add_u64 v[6:7], v[8:9], 0, s[18:19]
	global_load_dwordx2 v[6:7], v[6:7], off offset:1536 nt
	s_add_i32 s16, s16, s14
	s_ashr_i32 s17, s16, 31
	s_lshl_b64 s[16:17], s[16:17], 2
	s_add_u32 s16, s26, s16
	s_addc_u32 s17, s27, s17
	s_or_b32 s21, s4, 25
	s_cmp_lt_u32 s21, s23
	global_load_dword v34, v97, s[16:17]
	s_waitcnt vmcnt(1)
	v_cndmask_b32_e32 v173, 0, v6, vcc
	v_cndmask_b32_e32 v39, 0, v7, vcc
	s_cselect_b64 vcc, -1, 0
	s_and_b64 s[16:17], vcc, exec
	s_cselect_b32 s16, s21, s4
	s_ashr_i32 s17, s16, 31
	s_lshl_b64 s[18:19], s[16:17], 11
	v_lshl_add_u64 v[6:7], v[8:9], 0, s[18:19]
	global_load_dwordx2 v[6:7], v[6:7], off offset:1536 nt
	s_add_i32 s16, s16, s14
	s_ashr_i32 s17, s16, 31
	s_lshl_b64 s[16:17], s[16:17], 2
	s_add_u32 s16, s26, s16
	s_addc_u32 s17, s27, s17
	s_or_b32 s34, s4, 26
	s_cmp_lt_u32 s34, s23
	global_load_dword v36, v97, s[16:17]
	s_waitcnt vmcnt(1)
	v_cndmask_b32_e32 v172, 0, v6, vcc
	v_cndmask_b32_e32 v35, 0, v7, vcc
	s_cselect_b64 vcc, -1, 0
	s_and_b64 s[16:17], vcc, exec
	s_cselect_b32 s16, s34, s4
	s_ashr_i32 s17, s16, 31
	s_lshl_b64 s[18:19], s[16:17], 11
	v_lshl_add_u64 v[6:7], v[8:9], 0, s[18:19]
	global_load_dwordx2 v[6:7], v[6:7], off offset:1536 nt
	s_add_i32 s16, s16, s14
	s_ashr_i32 s17, s16, 31
	s_lshl_b64 s[16:17], s[16:17], 2
	s_add_u32 s16, s26, s16
	s_addc_u32 s17, s27, s17
	s_or_b32 s19, s4, 27
	s_cmp_lt_u32 s19, s23
	global_load_dword v30, v97, s[16:17]
	s_waitcnt vmcnt(1)
	v_cndmask_b32_e32 v171, 0, v6, vcc
	v_cndmask_b32_e32 v37, 0, v7, vcc
	s_cselect_b64 vcc, -1, 0
	s_and_b64 s[16:17], vcc, exec
	s_cselect_b32 s16, s19, s4
	s_ashr_i32 s17, s16, 31
	s_lshl_b64 s[30:31], s[16:17], 11
	v_lshl_add_u64 v[6:7], v[8:9], 0, s[30:31]
	global_load_dwordx2 v[6:7], v[6:7], off offset:1536 nt
	s_add_i32 s16, s16, s14
	s_ashr_i32 s17, s16, 31
	s_lshl_b64 s[16:17], s[16:17], 2
	s_add_u32 s16, s26, s16
	s_addc_u32 s17, s27, s17
	s_or_b32 s20, s4, 28
	s_cmp_lt_u32 s20, s23
	global_load_dword v32, v97, s[16:17]
	s_waitcnt vmcnt(1)
	v_cndmask_b32_e32 v170, 0, v6, vcc
	v_cndmask_b32_e32 v31, 0, v7, vcc
	s_cselect_b64 vcc, -1, 0
	s_and_b64 s[16:17], vcc, exec
	s_cselect_b32 s16, s20, s4
	s_ashr_i32 s17, s16, 31
	s_lshl_b64 s[30:31], s[16:17], 11
	v_lshl_add_u64 v[6:7], v[8:9], 0, s[30:31]
	global_load_dwordx2 v[6:7], v[6:7], off offset:1536 nt
	s_add_i32 s16, s16, s14
	s_ashr_i32 s17, s16, 31
	s_lshl_b64 s[16:17], s[16:17], 2
	s_add_u32 s16, s26, s16
	s_addc_u32 s17, s27, s17
	s_or_b32 s18, s4, 29
	s_cmp_lt_u32 s18, s23
	global_load_dword v28, v97, s[16:17]
	s_waitcnt vmcnt(1)
	v_cndmask_b32_e32 v169, 0, v6, vcc
	v_cndmask_b32_e32 v33, 0, v7, vcc
	s_cselect_b64 vcc, -1, 0
	s_and_b64 s[16:17], vcc, exec
	s_cselect_b32 s16, s18, s4
	s_ashr_i32 s17, s16, 31
	s_lshl_b64 s[30:31], s[16:17], 11
	v_lshl_add_u64 v[6:7], v[8:9], 0, s[30:31]
	global_load_dwordx2 v[6:7], v[6:7], off offset:1536 nt
	s_add_i32 s16, s16, s14
	s_ashr_i32 s17, s16, 31
	s_lshl_b64 s[16:17], s[16:17], 2
	s_add_u32 s16, s26, s16
	s_addc_u32 s17, s27, s17
	s_or_b32 s15, s4, 30
	s_cmp_lt_u32 s15, s23
	global_load_dword v26, v97, s[16:17]
	s_waitcnt vmcnt(1)
	v_cndmask_b32_e32 v168, 0, v6, vcc
	v_cndmask_b32_e32 v29, 0, v7, vcc
	s_cselect_b64 vcc, -1, 0
	s_and_b64 s[16:17], vcc, exec
	s_cselect_b32 s16, s15, s4
	s_ashr_i32 s17, s16, 31
	s_lshl_b64 s[30:31], s[16:17], 11
	v_lshl_add_u64 v[6:7], v[8:9], 0, s[30:31]
	global_load_dwordx2 v[6:7], v[6:7], off offset:1536 nt
	s_add_i32 s16, s16, s14
	s_ashr_i32 s17, s16, 31
	s_lshl_b64 s[16:17], s[16:17], 2
	s_add_u32 s16, s26, s16
	s_addc_u32 s17, s27, s17
	s_or_b32 s5, s4, 31
	s_cmp_lt_u32 s5, s23
	global_load_dword v24, v97, s[16:17]
	s_waitcnt vmcnt(1)
	v_cndmask_b32_e32 v167, 0, v6, vcc
	v_cndmask_b32_e32 v166, 0, v7, vcc
	s_cselect_b64 vcc, -1, 0
	s_and_b64 s[16:17], vcc, exec
	s_cselect_b32 s16, s5, s4
	s_ashr_i32 s17, s16, 31
	s_lshl_b64 s[30:31], s[16:17], 11
	v_lshl_add_u64 v[6:7], v[8:9], 0, s[30:31]
	global_load_dwordx2 v[6:7], v[6:7], off offset:1536 nt
	s_add_i32 s16, s16, s14
	s_ashr_i32 s17, s16, 31
	s_lshl_b64 s[16:17], s[16:17], 2
	s_add_u32 s16, s26, s16
	s_addc_u32 s17, s27, s17
	s_add_i32 s80, s4, 32
	s_cmp_lt_u32 s80, s23
	global_load_dword v18, v97, s[16:17]
	s_waitcnt vmcnt(1)
	v_cndmask_b32_e32 v27, 0, v6, vcc
	v_cndmask_b32_e32 v25, 0, v7, vcc
	s_cselect_b64 vcc, -1, 0
	s_and_b64 s[16:17], vcc, exec
	s_cselect_b32 s16, s80, s4
	s_ashr_i32 s17, s16, 31
	s_lshl_b64 s[30:31], s[16:17], 11
	v_lshl_add_u64 v[6:7], v[8:9], 0, s[30:31]
	global_load_dwordx2 v[6:7], v[6:7], off offset:1536 nt
	s_add_i32 s16, s16, s14
	s_ashr_i32 s17, s16, 31
	s_lshl_b64 s[16:17], s[16:17], 2
	s_add_u32 s16, s26, s16
	s_addc_u32 s17, s27, s17
	s_add_i32 s82, s4, 33
	s_cmp_lt_u32 s82, s23
	global_load_dword v20, v97, s[16:17]
	s_waitcnt vmcnt(1)
	v_cndmask_b32_e32 v163, 0, v6, vcc
	v_cndmask_b32_e32 v162, 0, v7, vcc
	s_cselect_b64 vcc, -1, 0
	s_and_b64 s[16:17], vcc, exec
	s_cselect_b32 s16, s82, s4
	s_ashr_i32 s17, s16, 31
	s_lshl_b64 s[30:31], s[16:17], 11
	v_lshl_add_u64 v[6:7], v[8:9], 0, s[30:31]
	global_load_dwordx2 v[6:7], v[6:7], off offset:1536 nt
	s_add_i32 s16, s16, s14
	s_ashr_i32 s17, s16, 31
	s_lshl_b64 s[16:17], s[16:17], 2
	s_add_u32 s16, s26, s16
	s_addc_u32 s17, s27, s17
	s_add_i32 s79, s4, 34
	s_cmp_lt_u32 s79, s23
	global_load_dword v16, v97, s[16:17]
	s_waitcnt vmcnt(1)
	v_cndmask_b32_e32 v165, 0, v6, vcc
	v_cndmask_b32_e32 v164, 0, v7, vcc
	s_cselect_b64 vcc, -1, 0
	s_and_b64 s[16:17], vcc, exec
	s_cselect_b32 s16, s79, s4
	s_ashr_i32 s17, s16, 31
	s_lshl_b64 s[30:31], s[16:17], 11
	v_lshl_add_u64 v[6:7], v[8:9], 0, s[30:31]
	global_load_dwordx2 v[6:7], v[6:7], off offset:1536 nt
	s_add_i32 s16, s16, s14
	s_ashr_i32 s17, s16, 31
	s_lshl_b64 s[16:17], s[16:17], 2
	s_add_u32 s16, s26, s16
	s_addc_u32 s17, s27, s17
	s_add_i32 s77, s4, 35
	s_cmp_lt_u32 s77, s23
	global_load_dword v14, v97, s[16:17]
	s_waitcnt vmcnt(1)
	v_cndmask_b32_e32 v161, 0, v6, vcc
	v_cndmask_b32_e32 v160, 0, v7, vcc
	s_cselect_b64 vcc, -1, 0
	s_and_b64 s[16:17], vcc, exec
	s_cselect_b32 s16, s77, s4
	s_ashr_i32 s17, s16, 31
	s_lshl_b64 s[30:31], s[16:17], 11
	v_lshl_add_u64 v[6:7], v[8:9], 0, s[30:31]
	global_load_dwordx2 v[6:7], v[6:7], off offset:1536 nt
	s_add_i32 s16, s16, s14
	s_ashr_i32 s17, s16, 31
	s_lshl_b64 s[16:17], s[16:17], 2
	s_add_u32 s16, s26, s16
	s_addc_u32 s17, s27, s17
	s_add_i32 s75, s4, 36
	s_cmp_lt_u32 s75, s23
	global_load_dword v12, v97, s[16:17]
	s_waitcnt vmcnt(1)
	v_cndmask_b32_e32 v21, 0, v6, vcc
	v_cndmask_b32_e32 v19, 0, v7, vcc
	s_cselect_b64 vcc, -1, 0
	s_and_b64 s[16:17], vcc, exec
	s_cselect_b32 s16, s75, s4
	s_ashr_i32 s17, s16, 31
	s_lshl_b64 s[30:31], s[16:17], 11
	v_lshl_add_u64 v[6:7], v[8:9], 0, s[30:31]
	global_load_dwordx2 v[6:7], v[6:7], off offset:1536 nt
	s_add_i32 s16, s16, s14
	s_ashr_i32 s17, s16, 31
	s_lshl_b64 s[16:17], s[16:17], 2
	s_add_u32 s16, s26, s16
	s_addc_u32 s17, s27, s17
	s_add_i32 s72, s4, 37
	s_cmp_lt_u32 s72, s23
	global_load_dword v10, v97, s[16:17]
	s_waitcnt vmcnt(1)
	v_cndmask_b32_e32 v17, 0, v6, vcc
	v_cndmask_b32_e32 v15, 0, v7, vcc
	s_cselect_b64 vcc, -1, 0
	s_and_b64 s[16:17], vcc, exec
	s_cselect_b32 s16, s72, s4
	s_ashr_i32 s17, s16, 31
	s_lshl_b64 s[30:31], s[16:17], 11
	v_lshl_add_u64 v[6:7], v[8:9], 0, s[30:31]
	global_load_dwordx2 v[6:7], v[6:7], off offset:1536 nt
	s_add_i32 s16, s16, s14
	s_ashr_i32 s17, s16, 31
	s_lshl_b64 s[16:17], s[16:17], 2
	s_add_u32 s16, s26, s16
	s_addc_u32 s17, s27, s17
	s_add_i32 s70, s4, 38
	s_cmp_lt_u32 s70, s23
	s_waitcnt vmcnt(0)
	v_cndmask_b32_e32 v11, 0, v6, vcc
	v_cndmask_b32_e32 v7, 0, v7, vcc
	s_cselect_b64 vcc, -1, 0
	global_load_dword v6, v97, s[16:17]
	s_and_b64 s[16:17], vcc, exec
	s_cselect_b32 s16, s70, s4
	s_ashr_i32 s17, s16, 31
	s_lshl_b64 s[30:31], s[16:17], 11
	v_lshl_add_u64 v[8:9], v[8:9], 0, s[30:31]
	global_load_dwordx2 v[8:9], v[8:9], off offset:1536 nt
	s_add_i32 s16, s16, s14
	s_ashr_i32 s17, s16, 31
	s_lshl_b64 s[16:17], s[16:17], 2
	s_add_u32 s16, s26, s16
	s_addc_u32 s17, s27, s17
	s_mov_b64 s[30:31], 0x600
	s_waitcnt vmcnt(0)
	v_cndmask_b32_e32 v13, 0, v8, vcc
	global_load_dword v8, v97, s[16:17]
	s_lshl_b64 s[16:17], s[6:7], 11
	s_add_u32 s16, s24, s16
	s_addc_u32 s17, s25, s17
	v_lshl_add_u64 v[22:23], s[16:17], 0, v[96:97]
	v_lshl_add_u64 v[4:5], v[22:23], 0, s[30:31]
	s_max_i32 s7, s4, 8
	s_min_i32 s30, s85, s23
	s_sub_i32 s7, s30, s7
	s_add_i32 s7, s7, 8
	v_cvt_f32_i32_e32 v48, s7
	v_cndmask_b32_e32 v9, 0, v9, vcc
	s_max_i32 s7, s35, 8
	v_div_scale_f32 v49, s[30:31], v48, v48, 1.0
	v_rcp_f32_e32 v51, v49
	s_min_i32 s30, s88, s23
	s_sub_i32 s7, s30, s7
	s_add_i32 s7, s7, 8
	v_fma_f32 v59, -v49, v51, 1.0
	v_fmac_f32_e32 v51, v59, v51
	v_div_scale_f32 v59, vcc, 1.0, v48, 1.0
	v_mul_f32_e32 v60, v59, v51
	v_fma_f32 v61, -v49, v60, v59
	v_fmac_f32_e32 v60, v61, v51
	v_fma_f32 v49, -v49, v60, v59
	v_div_fmas_f32 v49, v49, v51, v60
	v_div_fixup_f32 v48, v49, v48, 1.0
	v_cvt_f32_i32_e32 v51, s7
	v_pk_fma_f32 v[60:61], v[48:49], v[56:57], v[126:127] op_sel_hi:[0,1,1] neg_lo:[0,0,1] neg_hi:[0,0,1]
	v_pk_fma_f32 v[48:49], v[48:49], v[52:53], v[124:125] op_sel_hi:[0,1,1] neg_lo:[0,0,1] neg_hi:[0,0,1]
	v_pk_mul_f32 v[48:49], v[2:3], v[48:49]
	v_pk_mul_f32 v[60:61], v[0:1], v[60:61]
	s_max_i32 s7, s97, 8
	v_cvt_pk_bf16_f32 v60, v60, v61
	v_cvt_pk_bf16_f32 v61, v48, v49
	v_pk_mul_f32 v[48:49], v[98:99], v[72:73] op_sel_hi:[0,1]
	v_pk_fma_f32 v[72:73], v[98:99], v[72:73], v[156:157] op_sel_hi:[0,1,1] neg_lo:[0,0,1] neg_hi:[0,0,1]
	v_pk_add_f32 v[72:73], v[52:53], v[72:73]
	v_div_scale_f32 v52, s[30:31], v51, v51, 1.0
	v_rcp_f32_e32 v53, v52
	global_store_dwordx2 v96, v[60:61], s[16:17] offset:1536
	v_pk_mul_f32 v[60:61], v[98:99], v[66:67] op_sel_hi:[0,1]
	v_pk_fma_f32 v[66:67], v[98:99], v[66:67], v[158:159] op_sel_hi:[0,1,1] neg_lo:[0,0,1] neg_hi:[0,0,1]
	v_fma_f32 v59, -v52, v53, 1.0
	v_fmac_f32_e32 v53, v59, v53
	v_div_scale_f32 v59, vcc, 1.0, v51, 1.0
	v_mul_f32_e32 v63, v59, v53
	v_fma_f32 v65, -v52, v63, v59
	v_fmac_f32_e32 v63, v65, v53
	v_fma_f32 v52, -v52, v63, v59
	v_div_fmas_f32 v52, v52, v53, v63
	v_pk_add_f32 v[56:57], v[56:57], v[66:67]
	v_div_fixup_f32 v52, v52, v51, 1.0
	v_pk_fma_f32 v[66:67], v[52:53], v[56:57], v[122:123] op_sel_hi:[0,1,1] neg_lo:[0,0,1] neg_hi:[0,0,1]
	v_pk_fma_f32 v[52:53], v[52:53], v[72:73], v[120:121] op_sel_hi:[0,1,1] neg_lo:[0,0,1] neg_hi:[0,0,1]
	v_pk_mul_f32 v[66:67], v[0:1], v[66:67]
	v_pk_mul_f32 v[52:53], v[2:3], v[52:53]
	v_cvt_pk_bf16_f32 v66, v66, v67
	s_movk_i32 s97, 0x800
	v_cvt_pk_bf16_f32 v67, v52, v53
	global_store_dwordx2 v96, v[66:67], s[16:17] offset:3584
	s_min_i32 s16, s86, s23
	s_sub_i32 s7, s16, s7
	s_add_i32 s7, s7, 8
	v_cvt_f32_i32_e32 v51, s7
	v_pk_mul_f32 v[66:67], v[94:95], v[76:77] op_sel_hi:[0,1]
	v_pk_fma_f32 v[76:77], v[94:95], v[76:77], v[154:155] op_sel_hi:[0,1,1] neg_lo:[0,0,1] neg_hi:[0,0,1]
	v_pk_add_f32 v[76:77], v[56:57], v[76:77]
	v_div_scale_f32 v56, s[16:17], v51, v51, 1.0
	v_rcp_f32_e32 v57, v56
	s_max_i32 s7, s96, 8
	s_min_i32 s16, s84, s23
	s_sub_i32 s7, s16, s7
	v_fma_f32 v59, -v56, v57, 1.0
	v_fmac_f32_e32 v57, v59, v57
	v_div_scale_f32 v59, vcc, 1.0, v51, 1.0
	v_mul_f32_e32 v63, v59, v57
	v_fma_f32 v65, -v56, v63, v59
	v_fmac_f32_e32 v63, v65, v57
	v_fma_f32 v56, -v56, v63, v59
	v_div_fmas_f32 v56, v56, v57, v63
	s_add_i32 s7, s7, 8
	v_div_fixup_f32 v56, v56, v51, 1.0
	v_cvt_f32_i32_e32 v51, s7
	v_add_co_u32_e32 v82, vcc, s92, v22
	s_max_i32 s7, s91, 8
	v_div_scale_f32 v59, s[16:17], v51, v51, 1.0
	v_rcp_f32_e32 v63, v59
	v_addc_co_u32_e32 v83, vcc, 0, v23, vcc
	s_min_i32 s16, s83, s23
	v_fma_f32 v65, -v59, v63, 1.0
	v_fmac_f32_e32 v63, v65, v63
	v_div_scale_f32 v65, vcc, 1.0, v51, 1.0
	v_mul_f32_e32 v69, v65, v63
	v_fma_f32 v71, -v59, v69, v65
	v_fmac_f32_e32 v69, v71, v63
	v_pk_mul_f32 v[52:53], v[94:95], v[80:81] op_sel_hi:[0,1]
	v_pk_fma_f32 v[80:81], v[94:95], v[80:81], v[152:153] op_sel_hi:[0,1,1] neg_lo:[0,0,1] neg_hi:[0,0,1]
	v_lshlrev_b32_e32 v154, 16, v191
	v_and_b32_e32 v155, 0xffff0000, v191
	v_fma_f32 v59, -v59, v69, v65
	s_sub_i32 s7, s16, s7
	v_pk_add_f32 v[72:73], v[72:73], v[80:81]
	v_pk_fma_f32 v[148:149], v[88:89], v[154:155], v[148:149] op_sel_hi:[0,1,1] neg_lo:[0,0,1] neg_hi:[0,0,1]
	v_div_fmas_f32 v59, v59, v63, v69
	s_add_i32 s7, s7, 8
	v_pk_fma_f32 v[80:81], v[56:57], v[76:77], v[118:119] op_sel_hi:[0,1,1] neg_lo:[0,0,1] neg_hi:[0,0,1]
	v_pk_fma_f32 v[56:57], v[56:57], v[72:73], v[100:101] op_sel_hi:[0,1,1] neg_lo:[0,0,1] neg_hi:[0,0,1]
	v_pk_add_f32 v[148:149], v[72:73], v[148:149]
	v_div_fixup_f32 v72, v59, v51, 1.0
	v_cvt_f32_i32_e32 v51, s7
	v_lshlrev_b32_e32 v152, 16, v192
	v_and_b32_e32 v153, 0xffff0000, v192
	v_pk_fma_f32 v[150:151], v[88:89], v[152:153], v[150:151] op_sel_hi:[0,1,1] neg_lo:[0,0,1] neg_hi:[0,0,1]
	v_div_scale_f32 v59, s[16:17], v51, v51, 1.0
	v_rcp_f32_e32 v63, v59
	v_pk_add_f32 v[76:77], v[76:77], v[150:151]
	v_pk_mul_f32 v[80:81], v[0:1], v[80:81]
	v_pk_fma_f32 v[150:151], v[72:73], v[76:77], v[116:117] op_sel_hi:[0,1,1] neg_lo:[0,0,1] neg_hi:[0,0,1]
	v_fma_f32 v65, -v59, v63, 1.0
	v_fmac_f32_e32 v63, v65, v63
	v_div_scale_f32 v65, vcc, 1.0, v51, 1.0
	v_mul_f32_e32 v69, v65, v63
	v_pk_fma_f32 v[72:73], v[72:73], v[148:149], v[102:103] op_sel_hi:[0,1,1] neg_lo:[0,0,1] neg_hi:[0,0,1]
	v_pk_mul_f32 v[150:151], v[0:1], v[150:151]
	v_fma_f32 v71, -v59, v69, v65
	v_pk_mul_f32 v[56:57], v[2:3], v[56:57]
	v_cvt_pk_bf16_f32 v80, v80, v81
	v_pk_mul_f32 v[72:73], v[2:3], v[72:73]
	v_cvt_pk_bf16_f32 v81, v56, v57
	global_store_dwordx2 v[82:83], v[80:81], off offset:1536
	v_cvt_pk_bf16_f32 v150, v150, v151
	v_cvt_pk_bf16_f32 v151, v72, v73
	v_fmac_f32_e32 v69, v71, v63
	s_max_i32 s7, s90, 8
	s_min_i32 s16, s81, s23
	global_store_dwordx2 v[82:83], v[150:151], off offset:3584
	v_lshlrev_b32_e32 v150, 16, v190
	v_and_b32_e32 v151, 0xffff0000, v190
	v_fma_f32 v59, -v59, v69, v65
	s_sub_i32 s7, s16, s7
	v_pk_fma_f32 v[146:147], v[84:85], v[150:151], v[146:147] op_sel_hi:[0,1,1] neg_lo:[0,0,1] neg_hi:[0,0,1]
	v_div_fmas_f32 v59, v59, v63, v69
	s_add_i32 s7, s7, 8
	v_pk_add_f32 v[146:147], v[76:77], v[146:147]
	v_div_fixup_f32 v76, v59, v51, 1.0
	v_cvt_f32_i32_e32 v51, s7
	v_pk_mul_f32 v[80:81], v[88:89], v[152:153] op_sel_hi:[0,1]
	v_lshlrev_b32_e32 v152, 16, v189
	v_and_b32_e32 v153, 0xffff0000, v189
	v_div_scale_f32 v59, s[16:17], v51, v51, 1.0
	v_rcp_f32_e32 v63, v59
	v_pk_mul_f32 v[72:73], v[84:85], v[152:153] op_sel_hi:[0,1]
	v_pk_mul_f32 v[82:83], v[84:85], v[150:151] op_sel_hi:[0,1]
	v_pk_fma_f32 v[84:85], v[84:85], v[152:153], v[144:145] op_sel_hi:[0,1,1] neg_lo:[0,0,1] neg_hi:[0,0,1]
	s_movk_i32 s91, 0x2000
	v_pk_add_f32 v[144:145], v[148:149], v[84:85]
	v_add_co_u32_e32 v148, vcc, s91, v22
	v_fma_f32 v65, -v59, v63, 1.0
	s_nop 0
	v_addc_co_u32_e32 v149, vcc, 0, v23, vcc
	v_fmac_f32_e32 v63, v65, v63
	v_div_scale_f32 v65, vcc, 1.0, v51, 1.0
	v_mul_f32_e32 v69, v65, v63
	v_pk_fma_f32 v[84:85], v[76:77], v[146:147], v[114:115] op_sel_hi:[0,1,1] neg_lo:[0,0,1] neg_hi:[0,0,1]
	v_fma_f32 v71, -v59, v69, v65
	v_pk_fma_f32 v[76:77], v[76:77], v[144:145], v[104:105] op_sel_hi:[0,1,1] neg_lo:[0,0,1] neg_hi:[0,0,1]
	v_pk_mul_f32 v[84:85], v[0:1], v[84:85]
	v_fmac_f32_e32 v69, v71, v63
	s_max_i32 s7, s89, 8
	s_min_i32 s16, s78, s23
	v_pk_mul_f32 v[76:77], v[2:3], v[76:77]
	v_cvt_pk_bf16_f32 v84, v84, v85
	v_lshlrev_b32_e32 v150, 16, v188
	v_cvt_pk_bf16_f32 v85, v76, v77
	v_and_b32_e32 v151, 0xffff0000, v188
	v_lshlrev_b32_e32 v152, 16, v187
	v_and_b32_e32 v153, 0xffff0000, v187
	v_fma_f32 v59, -v59, v69, v65
	s_sub_i32 s7, s16, s7
	global_store_dwordx2 v[148:149], v[84:85], off offset:1536
	v_pk_mul_f32 v[76:77], v[78:79], v[152:153] op_sel_hi:[0,1]
	v_pk_mul_f32 v[84:85], v[78:79], v[150:151] op_sel_hi:[0,1]
	v_pk_fma_f32 v[142:143], v[78:79], v[150:151], v[142:143] op_sel_hi:[0,1,1] neg_lo:[0,0,1] neg_hi:[0,0,1]
	v_pk_fma_f32 v[78:79], v[78:79], v[152:153], v[140:141] op_sel_hi:[0,1,1] neg_lo:[0,0,1] neg_hi:[0,0,1]
	v_div_fmas_f32 v59, v59, v63, v69
	s_add_i32 s7, s7, 8
	v_pk_add_f32 v[140:141], v[144:145], v[78:79]
	v_div_fixup_f32 v78, v59, v51, 1.0
	v_cvt_f32_i32_e32 v51, s7
	v_pk_add_f32 v[142:143], v[146:147], v[142:143]
	s_movk_i32 s7, 0x3000
	v_pk_fma_f32 v[144:145], v[78:79], v[142:143], v[112:113] op_sel_hi:[0,1,1] neg_lo:[0,0,1] neg_hi:[0,0,1]
	v_div_scale_f32 v59, s[16:17], v51, v51, 1.0
	v_rcp_f32_e32 v63, v59
	v_pk_fma_f32 v[78:79], v[78:79], v[140:141], v[106:107] op_sel_hi:[0,1,1] neg_lo:[0,0,1] neg_hi:[0,0,1]
	v_pk_mul_f32 v[144:145], v[0:1], v[144:145]
	v_pk_mul_f32 v[78:79], v[2:3], v[78:79]
	v_fma_f32 v65, -v59, v63, 1.0
	v_fmac_f32_e32 v63, v65, v63
	v_div_scale_f32 v65, vcc, 1.0, v51, 1.0
	v_mul_f32_e32 v69, v65, v63
	v_cvt_pk_bf16_f32 v144, v144, v145
	v_cvt_pk_bf16_f32 v145, v78, v79
	v_fma_f32 v71, -v59, v69, v65
	global_store_dwordx2 v[148:149], v[144:145], off offset:3584
	v_lshlrev_b32_e32 v144, 16, v186
	v_and_b32_e32 v145, 0xffff0000, v186
	v_fmac_f32_e32 v69, v71, v63
	v_pk_fma_f32 v[138:139], v[74:75], v[144:145], v[138:139] op_sel_hi:[0,1,1] neg_lo:[0,0,1] neg_hi:[0,0,1]
	v_fma_f32 v59, -v59, v69, v65
	v_pk_add_f32 v[138:139], v[142:143], v[138:139]
	v_div_fmas_f32 v59, v59, v63, v69
	v_add_co_u32_e32 v142, vcc, s7, v22
	s_max_i32 s7, s87, 8
	s_min_i32 s16, s76, s23
	v_lshlrev_b32_e32 v146, 16, v87
	v_and_b32_e32 v147, 0xffff0000, v87
	s_sub_i32 s7, s16, s7
	v_pk_mul_f32 v[78:79], v[74:75], v[146:147] op_sel_hi:[0,1]
	v_pk_mul_f32 v[86:87], v[74:75], v[144:145] op_sel_hi:[0,1]
	v_pk_fma_f32 v[74:75], v[74:75], v[146:147], v[136:137] op_sel_hi:[0,1,1] neg_lo:[0,0,1] neg_hi:[0,0,1]
	s_add_i32 s7, s7, 8
	v_pk_add_f32 v[136:137], v[140:141], v[74:75]
	v_div_fixup_f32 v74, v59, v51, 1.0
	v_cvt_f32_i32_e32 v51, s7
	v_pk_fma_f32 v[140:141], v[74:75], v[138:139], v[110:111] op_sel_hi:[0,1,1] neg_lo:[0,0,1] neg_hi:[0,0,1]
	v_pk_fma_f32 v[74:75], v[74:75], v[136:137], v[108:109] op_sel_hi:[0,1,1] neg_lo:[0,0,1] neg_hi:[0,0,1]
	v_pk_mul_f32 v[140:141], v[0:1], v[140:141]
	v_div_scale_f32 v59, s[16:17], v51, v51, 1.0
	v_rcp_f32_e32 v63, v59
	v_pk_mul_f32 v[74:75], v[2:3], v[74:75]
	v_cvt_pk_bf16_f32 v140, v140, v141
	v_addc_co_u32_e32 v143, vcc, 0, v23, vcc
	v_cvt_pk_bf16_f32 v141, v74, v75
	v_fma_f32 v65, -v59, v63, 1.0
	global_store_dwordx2 v[142:143], v[140:141], off offset:1536
	v_lshlrev_b32_e32 v140, 16, v185
	v_and_b32_e32 v141, 0xffff0000, v185
	v_lshlrev_b32_e32 v144, 16, v89
	v_and_b32_e32 v145, 0xffff0000, v89
	v_fmac_f32_e32 v63, v65, v63
	v_div_scale_f32 v65, vcc, 1.0, v51, 1.0
	v_pk_mul_f32 v[56:57], v[88:89], v[154:155] op_sel_hi:[0,1]
	v_pk_mul_f32 v[74:75], v[70:71], v[144:145] op_sel_hi:[0,1]
	v_pk_mul_f32 v[88:89], v[70:71], v[140:141] op_sel_hi:[0,1]
	v_pk_fma_f32 v[134:135], v[70:71], v[140:141], v[134:135] op_sel_hi:[0,1,1] neg_lo:[0,0,1] neg_hi:[0,0,1]
	v_pk_fma_f32 v[70:71], v[70:71], v[144:145], v[132:133] op_sel_hi:[0,1,1] neg_lo:[0,0,1] neg_hi:[0,0,1]
	v_mul_f32_e32 v69, v65, v63
	v_pk_add_f32 v[132:133], v[136:137], v[70:71]
	v_fma_f32 v70, -v59, v69, v65
	v_fmac_f32_e32 v69, v70, v63
	s_max_i32 s7, s85, 8
	s_min_i32 s16, s73, s23
	v_fma_f32 v59, -v59, v69, v65
	s_sub_i32 s7, s16, s7
	v_div_fmas_f32 v59, v59, v63, v69
	s_add_i32 s7, s7, 8
	v_div_fixup_f32 v70, v59, v51, 1.0
	v_cvt_f32_i32_e32 v51, s7
	v_pk_add_f32 v[134:135], v[138:139], v[134:135]
	v_lshlrev_b32_e32 v138, 16, v91
	v_pk_fma_f32 v[136:137], v[70:71], v[134:135], v[46:47] op_sel_hi:[0,1,1] neg_lo:[0,0,1] neg_hi:[0,0,1]
	v_div_scale_f32 v59, s[16:17], v51, v51, 1.0
	v_pk_fma_f32 v[70:71], v[70:71], v[132:133], v[42:43] op_sel_hi:[0,1,1] neg_lo:[0,0,1] neg_hi:[0,0,1]
	v_pk_mul_f32 v[136:137], v[0:1], v[136:137]
	v_rcp_f32_e32 v63, v59
	v_pk_mul_f32 v[70:71], v[2:3], v[70:71]
	v_cvt_pk_bf16_f32 v136, v136, v137
	v_and_b32_e32 v139, 0xffff0000, v91
	v_cvt_pk_bf16_f32 v137, v70, v71
	global_store_dwordx2 v[142:143], v[136:137], off offset:3584
	v_lshlrev_b32_e32 v136, 16, v184
	v_and_b32_e32 v137, 0xffff0000, v184
	v_pk_mul_f32 v[70:71], v[64:65], v[138:139] op_sel_hi:[0,1]
	v_pk_mul_f32 v[90:91], v[64:65], v[136:137] op_sel_hi:[0,1]
	v_pk_fma_f32 v[130:131], v[64:65], v[136:137], v[130:131] op_sel_hi:[0,1,1] neg_lo:[0,0,1] neg_hi:[0,0,1]
	v_pk_fma_f32 v[64:65], v[64:65], v[138:139], v[128:129] op_sel_hi:[0,1,1] neg_lo:[0,0,1] neg_hi:[0,0,1]
	v_pk_add_f32 v[128:129], v[132:133], v[64:65]
	v_fma_f32 v64, -v59, v63, 1.0
	v_fmac_f32_e32 v63, v64, v63
	v_div_scale_f32 v64, vcc, 1.0, v51, 1.0
	v_mul_f32_e32 v65, v64, v63
	v_fma_f32 v69, -v59, v65, v64
	v_fmac_f32_e32 v65, v69, v63
	s_max_i32 s7, s88, 8
	s_min_i32 s16, s74, s23
	v_fma_f32 v59, -v59, v65, v64
	s_sub_i32 s7, s16, s7
	v_div_fmas_f32 v59, v59, v63, v65
	s_add_i32 s7, s7, 8
	v_div_fixup_f32 v64, v59, v51, 1.0
	v_cvt_f32_i32_e32 v51, s7
	v_pk_add_f32 v[130:131], v[134:135], v[130:131]
	v_add_co_u32_e32 v134, vcc, s9, v22
	v_pk_fma_f32 v[132:133], v[64:65], v[130:131], v[60:61] op_sel_hi:[0,1,1] neg_lo:[0,0,1] neg_hi:[0,0,1]
	v_div_scale_f32 v59, s[16:17], v51, v51, 1.0
	v_pk_fma_f32 v[64:65], v[64:65], v[128:129], v[48:49] op_sel_hi:[0,1,1] neg_lo:[0,0,1] neg_hi:[0,0,1]
	v_pk_mul_f32 v[132:133], v[0:1], v[132:133]
	v_rcp_f32_e32 v63, v59
	v_pk_mul_f32 v[64:65], v[2:3], v[64:65]
	v_cvt_pk_bf16_f32 v132, v132, v133
	v_addc_co_u32_e32 v135, vcc, 0, v23, vcc
	v_cvt_pk_bf16_f32 v133, v64, v65
	global_store_dwordx2 v[134:135], v[132:133], off offset:1536
	v_lshlrev_b32_e32 v94, 16, v95
	v_and_b32_e32 v95, 0xffff0000, v95
	v_lshlrev_b32_e32 v132, 16, v93
	v_and_b32_e32 v133, 0xffff0000, v93
	v_pk_mul_f32 v[64:65], v[68:69], v[132:133] op_sel_hi:[0,1]
	v_pk_mul_f32 v[92:93], v[68:69], v[94:95] op_sel_hi:[0,1]
	v_pk_fma_f32 v[94:95], v[68:69], v[94:95], v[126:127] op_sel_hi:[0,1,1] neg_lo:[0,0,1] neg_hi:[0,0,1]
	v_pk_fma_f32 v[68:69], v[68:69], v[132:133], v[124:125] op_sel_hi:[0,1,1] neg_lo:[0,0,1] neg_hi:[0,0,1]
	v_pk_add_f32 v[124:125], v[128:129], v[68:69]
	v_fma_f32 v68, -v59, v63, 1.0
	v_fmac_f32_e32 v63, v68, v63
	v_div_scale_f32 v68, vcc, 1.0, v51, 1.0
	v_mul_f32_e32 v69, v68, v63
	v_pk_add_f32 v[126:127], v[130:131], v[94:95]
	v_fma_f32 v94, -v59, v69, v68
	v_fmac_f32_e32 v69, v94, v63
	s_max_i32 s7, s86, 8
	s_min_i32 s16, s71, s23
	v_fma_f32 v59, -v59, v69, v68
	s_sub_i32 s7, s16, s7
	v_div_fmas_f32 v59, v59, v63, v69
	s_add_i32 s7, s7, 8
	v_div_fixup_f32 v68, v59, v51, 1.0
	v_cvt_f32_i32_e32 v51, s7
	v_pk_fma_f32 v[94:95], v[68:69], v[126:127], v[66:67] op_sel_hi:[0,1,1] neg_lo:[0,0,1] neg_hi:[0,0,1]
	v_pk_fma_f32 v[68:69], v[68:69], v[124:125], v[52:53] op_sel_hi:[0,1,1] neg_lo:[0,0,1] neg_hi:[0,0,1]
	v_pk_mul_f32 v[94:95], v[0:1], v[94:95]
	v_pk_mul_f32 v[68:69], v[2:3], v[68:69]
	v_cvt_pk_bf16_f32 v94, v94, v95
	v_lshlrev_b32_e32 v128, 16, v183
	v_cvt_pk_bf16_f32 v95, v68, v69
	v_and_b32_e32 v129, 0xffff0000, v183
	v_lshlrev_b32_e32 v130, 16, v182
	v_and_b32_e32 v131, 0xffff0000, v182
	global_store_dwordx2 v[134:135], v[94:95], off offset:3584
	v_pk_mul_f32 v[68:69], v[62:63], v[130:131] op_sel_hi:[0,1]
	v_pk_mul_f32 v[94:95], v[62:63], v[128:129] op_sel_hi:[0,1]
	v_pk_fma_f32 v[122:123], v[62:63], v[128:129], v[122:123] op_sel_hi:[0,1,1] neg_lo:[0,0,1] neg_hi:[0,0,1]
	v_pk_fma_f32 v[62:63], v[62:63], v[130:131], v[120:121] op_sel_hi:[0,1,1] neg_lo:[0,0,1] neg_hi:[0,0,1]
	v_div_scale_f32 v59, s[16:17], v51, v51, 1.0
	v_pk_add_f32 v[120:121], v[124:125], v[62:63]
	v_rcp_f32_e32 v62, v59
	s_max_i32 s7, s84, 8
	s_min_i32 s16, s69, s23
	v_pk_add_f32 v[122:123], v[126:127], v[122:123]
	v_fma_f32 v63, -v59, v62, 1.0
	v_fmac_f32_e32 v62, v63, v62
	v_div_scale_f32 v63, vcc, 1.0, v51, 1.0
	v_mul_f32_e32 v98, v63, v62
	v_fma_f32 v124, -v59, v98, v63
	v_fmac_f32_e32 v98, v124, v62
	v_fma_f32 v59, -v59, v98, v63
	v_div_fmas_f32 v59, v59, v62, v98
	v_div_fixup_f32 v62, v59, v51, 1.0
	s_sub_i32 s7, s16, s7
	v_pk_fma_f32 v[124:125], v[62:63], v[122:123], v[80:81] op_sel_hi:[0,1,1] neg_lo:[0,0,1] neg_hi:[0,0,1]
	s_add_i32 s7, s7, 8
	v_pk_fma_f32 v[62:63], v[62:63], v[120:121], v[56:57] op_sel_hi:[0,1,1] neg_lo:[0,0,1] neg_hi:[0,0,1]
	v_pk_mul_f32 v[124:125], v[0:1], v[124:125]
	v_add_co_u32_e32 v126, vcc, s38, v22
	v_cvt_f32_i32_e32 v51, s7
	v_pk_mul_f32 v[62:63], v[2:3], v[62:63]
	v_cvt_pk_bf16_f32 v124, v124, v125
	v_addc_co_u32_e32 v127, vcc, 0, v23, vcc
	v_cvt_pk_bf16_f32 v125, v62, v63
	global_store_dwordx2 v[126:127], v[124:125], off offset:1536
	v_lshlrev_b32_e32 v124, 16, v181
	v_and_b32_e32 v125, 0xffff0000, v181
	v_lshlrev_b32_e32 v128, 16, v99
	v_and_b32_e32 v129, 0xffff0000, v99
	v_pk_mul_f32 v[62:63], v[58:59], v[128:129] op_sel_hi:[0,1]
	v_pk_mul_f32 v[98:99], v[58:59], v[124:125] op_sel_hi:[0,1]
	v_pk_fma_f32 v[118:119], v[58:59], v[124:125], v[118:119] op_sel_hi:[0,1,1] neg_lo:[0,0,1] neg_hi:[0,0,1]
	v_pk_fma_f32 v[58:59], v[58:59], v[128:129], v[100:101] op_sel_hi:[0,1,1] neg_lo:[0,0,1] neg_hi:[0,0,1]
	v_pk_add_f32 v[120:121], v[120:121], v[58:59]
	v_div_scale_f32 v58, s[16:17], v51, v51, 1.0
	v_rcp_f32_e32 v59, v58
	v_pk_add_f32 v[118:119], v[122:123], v[118:119]
	s_max_i32 s7, s83, 8
	s_min_i32 s16, s68, s23
	v_fma_f32 v100, -v58, v59, 1.0
	v_fmac_f32_e32 v59, v100, v59
	v_div_scale_f32 v100, vcc, 1.0, v51, 1.0
	v_mul_f32_e32 v101, v100, v59
	v_fma_f32 v122, -v58, v101, v100
	v_fmac_f32_e32 v101, v122, v59
	v_fma_f32 v58, -v58, v101, v100
	s_sub_i32 s7, s16, s7
	v_div_fmas_f32 v58, v58, v59, v101
	s_add_i32 s7, s7, 8
	v_div_fixup_f32 v58, v58, v51, 1.0
	v_cvt_f32_i32_e32 v51, s7
	v_pk_fma_f32 v[100:101], v[58:59], v[118:119], v[82:83] op_sel_hi:[0,1,1] neg_lo:[0,0,1] neg_hi:[0,0,1]
	v_pk_fma_f32 v[58:59], v[58:59], v[120:121], v[72:73] op_sel_hi:[0,1,1] neg_lo:[0,0,1] neg_hi:[0,0,1]
	v_pk_mul_f32 v[100:101], v[0:1], v[100:101]
	v_pk_mul_f32 v[58:59], v[2:3], v[58:59]
	v_cvt_pk_bf16_f32 v100, v100, v101
	v_lshlrev_b32_e32 v122, 16, v180
	v_cvt_pk_bf16_f32 v101, v58, v59
	v_and_b32_e32 v123, 0xffff0000, v180
	v_lshlrev_b32_e32 v124, 16, v179
	v_and_b32_e32 v125, 0xffff0000, v179
	global_store_dwordx2 v[126:127], v[100:101], off offset:3584
	v_pk_mul_f32 v[58:59], v[54:55], v[124:125] op_sel_hi:[0,1]
	v_pk_mul_f32 v[100:101], v[54:55], v[122:123] op_sel_hi:[0,1]
	v_pk_fma_f32 v[116:117], v[54:55], v[122:123], v[116:117] op_sel_hi:[0,1,1] neg_lo:[0,0,1] neg_hi:[0,0,1]
	v_pk_fma_f32 v[102:103], v[54:55], v[124:125], v[102:103] op_sel_hi:[0,1,1] neg_lo:[0,0,1] neg_hi:[0,0,1]
	v_div_scale_f32 v54, s[16:17], v51, v51, 1.0
	v_pk_add_f32 v[120:121], v[120:121], v[102:103]
	v_rcp_f32_e32 v102, v54
	v_pk_add_f32 v[116:117], v[118:119], v[116:117]
	s_max_i32 s7, s81, 8
	s_min_i32 s16, s67, s23
	v_fma_f32 v103, -v54, v102, 1.0
	v_fmac_f32_e32 v102, v103, v102
	v_div_scale_f32 v103, vcc, 1.0, v51, 1.0
	v_mul_f32_e32 v118, v103, v102
	v_fma_f32 v119, -v54, v118, v103
	v_fmac_f32_e32 v118, v119, v102
	v_fma_f32 v54, -v54, v118, v103
	v_div_fmas_f32 v54, v54, v102, v118
	v_div_fixup_f32 v54, v54, v51, 1.0
	v_pk_fma_f32 v[102:103], v[54:55], v[116:117], v[84:85] op_sel_hi:[0,1,1] neg_lo:[0,0,1] neg_hi:[0,0,1]
	v_pk_fma_f32 v[118:119], v[54:55], v[120:121], v[76:77] op_sel_hi:[0,1,1] neg_lo:[0,0,1] neg_hi:[0,0,1]
	v_pk_mul_f32 v[118:119], v[2:3], v[118:119]
	v_pk_mul_f32 v[102:103], v[0:1], v[102:103]
	v_lshlrev_b32_e32 v122, 16, v178
	v_cvt_pk_bf16_f32 v102, v102, v103
	v_cvt_pk_bf16_f32 v103, v118, v119
	v_add_co_u32_e32 v118, vcc, s39, v22
	v_and_b32_e32 v123, 0xffff0000, v178
	s_nop 0
	v_addc_co_u32_e32 v119, vcc, 0, v23, vcc
	v_lshlrev_b32_e32 v124, 16, v55
	v_and_b32_e32 v125, 0xffff0000, v55
	s_sub_i32 s7, s16, s7
	global_store_dwordx2 v[118:119], v[102:103], off offset:1536
	v_pk_mul_f32 v[54:55], v[50:51], v[124:125] op_sel_hi:[0,1]
	v_pk_mul_f32 v[102:103], v[50:51], v[122:123] op_sel_hi:[0,1]
	v_pk_fma_f32 v[114:115], v[50:51], v[122:123], v[114:115] op_sel_hi:[0,1,1] neg_lo:[0,0,1] neg_hi:[0,0,1]
	v_pk_fma_f32 v[50:51], v[50:51], v[124:125], v[104:105] op_sel_hi:[0,1,1] neg_lo:[0,0,1] neg_hi:[0,0,1]
	s_add_i32 s7, s7, 8
	v_pk_add_f32 v[120:121], v[120:121], v[50:51]
	v_cvt_f32_i32_e32 v50, s7
	v_pk_add_f32 v[114:115], v[116:117], v[114:115]
	s_max_i32 s7, s78, 8
	v_readlane_b32 s96, v255, 13
	v_div_scale_f32 v51, s[16:17], v50, v50, 1.0
	v_rcp_f32_e32 v104, v51
	s_min_i32 s16, s66, s23
	s_sub_i32 s7, s16, s7
	s_add_i32 s7, s7, 8
	v_fma_f32 v105, -v51, v104, 1.0
	v_fmac_f32_e32 v104, v105, v104
	v_div_scale_f32 v105, vcc, 1.0, v50, 1.0
	v_mul_f32_e32 v116, v105, v104
	v_fma_f32 v117, -v51, v116, v105
	v_fmac_f32_e32 v116, v117, v104
	v_fma_f32 v51, -v51, v116, v105
	v_div_fmas_f32 v51, v51, v104, v116
	v_div_fixup_f32 v50, v51, v50, 1.0
	v_pk_fma_f32 v[104:105], v[50:51], v[114:115], v[86:87] op_sel_hi:[0,1,1] neg_lo:[0,0,1] neg_hi:[0,0,1]
	v_pk_fma_f32 v[50:51], v[50:51], v[120:121], v[78:79] op_sel_hi:[0,1,1] neg_lo:[0,0,1] neg_hi:[0,0,1]
	v_pk_mul_f32 v[104:105], v[0:1], v[104:105]
	v_pk_mul_f32 v[50:51], v[2:3], v[50:51]
	v_cvt_pk_bf16_f32 v104, v104, v105
	v_lshlrev_b32_e32 v116, 16, v177
	v_cvt_pk_bf16_f32 v105, v50, v51
	global_store_dwordx2 v[118:119], v[104:105], off offset:3584
	v_and_b32_e32 v117, 0xffff0000, v177
	v_lshlrev_b32_e32 v118, 16, v176
	v_and_b32_e32 v119, 0xffff0000, v176
	v_pk_mul_f32 v[50:51], v[44:45], v[118:119] op_sel_hi:[0,1]
	v_pk_mul_f32 v[104:105], v[44:45], v[116:117] op_sel_hi:[0,1]
	v_pk_fma_f32 v[112:113], v[44:45], v[116:117], v[112:113] op_sel_hi:[0,1,1] neg_lo:[0,0,1] neg_hi:[0,0,1]
	v_pk_fma_f32 v[106:107], v[44:45], v[118:119], v[106:107] op_sel_hi:[0,1,1] neg_lo:[0,0,1] neg_hi:[0,0,1]
	v_cvt_f32_i32_e32 v44, s7
	v_pk_add_f32 v[116:117], v[120:121], v[106:107]
	v_pk_add_f32 v[112:113], v[114:115], v[112:113]
	s_movk_i32 s7, 0x7000
	v_div_scale_f32 v106, s[16:17], v44, v44, 1.0
	v_rcp_f32_e32 v107, v106
	s_min_i32 s16, s63, s23
	v_and_b32_e32 v119, 0xffff0000, v175
	v_lshlrev_b32_e32 v120, 16, v45
	v_fma_f32 v114, -v106, v107, 1.0
	v_fmac_f32_e32 v107, v114, v107
	v_div_scale_f32 v114, vcc, 1.0, v44, 1.0
	v_mul_f32_e32 v115, v114, v107
	v_fma_f32 v118, -v106, v115, v114
	v_fmac_f32_e32 v115, v118, v107
	v_fma_f32 v106, -v106, v115, v114
	v_div_fmas_f32 v106, v106, v107, v115
	v_div_fixup_f32 v44, v106, v44, 1.0
	v_pk_fma_f32 v[106:107], v[44:45], v[112:113], v[88:89] op_sel_hi:[0,1,1] neg_lo:[0,0,1] neg_hi:[0,0,1]
	v_pk_fma_f32 v[114:115], v[44:45], v[116:117], v[74:75] op_sel_hi:[0,1,1] neg_lo:[0,0,1] neg_hi:[0,0,1]
	v_pk_mul_f32 v[114:115], v[2:3], v[114:115]
	v_pk_mul_f32 v[106:107], v[0:1], v[106:107]
	v_lshlrev_b32_e32 v118, 16, v175
	v_cvt_pk_bf16_f32 v106, v106, v107
	v_cvt_pk_bf16_f32 v107, v114, v115
	v_add_co_u32_e32 v114, vcc, s7, v22
	s_max_i32 s7, s76, 8
	s_sub_i32 s7, s16, s7
	v_addc_co_u32_e32 v115, vcc, 0, v23, vcc
	v_and_b32_e32 v121, 0xffff0000, v45
	s_add_i32 s7, s7, 8
	global_store_dwordx2 v[114:115], v[106:107], off offset:1536
	v_pk_mul_f32 v[44:45], v[40:41], v[120:121] op_sel_hi:[0,1]
	v_pk_mul_f32 v[106:107], v[40:41], v[118:119] op_sel_hi:[0,1]
	v_pk_fma_f32 v[110:111], v[40:41], v[118:119], v[110:111] op_sel_hi:[0,1,1] neg_lo:[0,0,1] neg_hi:[0,0,1]
	v_pk_fma_f32 v[108:109], v[40:41], v[120:121], v[108:109] op_sel_hi:[0,1,1] neg_lo:[0,0,1] neg_hi:[0,0,1]
	v_cvt_f32_i32_e32 v40, s7
	v_pk_add_f32 v[116:117], v[116:117], v[108:109]
	v_pk_add_f32 v[110:111], v[112:113], v[110:111]
	s_max_i32 s7, s73, 8
	v_div_scale_f32 v108, s[16:17], v40, v40, 1.0
	v_rcp_f32_e32 v109, v108
	s_min_i32 s16, s62, s23
	s_sub_i32 s7, s16, s7
	s_add_i32 s7, s7, 8
	v_fma_f32 v112, -v108, v109, 1.0
	v_fmac_f32_e32 v109, v112, v109
	v_div_scale_f32 v112, vcc, 1.0, v40, 1.0
	v_mul_f32_e32 v113, v112, v109
	v_fma_f32 v118, -v108, v113, v112
	v_fmac_f32_e32 v113, v118, v109
	v_fma_f32 v108, -v108, v113, v112
	v_div_fmas_f32 v108, v108, v109, v113
	v_div_fixup_f32 v40, v108, v40, 1.0
	v_pk_fma_f32 v[108:109], v[40:41], v[110:111], v[90:91] op_sel_hi:[0,1,1] neg_lo:[0,0,1] neg_hi:[0,0,1]
	v_pk_fma_f32 v[112:113], v[40:41], v[116:117], v[70:71] op_sel_hi:[0,1,1] neg_lo:[0,0,1] neg_hi:[0,0,1]
	v_pk_mul_f32 v[112:113], v[2:3], v[112:113]
	v_pk_mul_f32 v[108:109], v[0:1], v[108:109]
	s_movk_i32 s90, 0xff00
	v_cvt_pk_bf16_f32 v108, v108, v109
	v_cvt_pk_bf16_f32 v109, v112, v113
	global_store_dwordx2 v[114:115], v[108:109], off offset:3584
	v_lshlrev_b32_e32 v112, 16, v174
	v_and_b32_e32 v113, 0xffff0000, v174
	v_lshlrev_b32_e32 v114, 16, v41
	v_and_b32_e32 v115, 0xffff0000, v41
	v_pk_mul_f32 v[40:41], v[38:39], v[114:115] op_sel_hi:[0,1]
	v_pk_mul_f32 v[108:109], v[38:39], v[112:113] op_sel_hi:[0,1]
	v_pk_fma_f32 v[46:47], v[38:39], v[112:113], v[46:47] op_sel_hi:[0,1,1] neg_lo:[0,0,1] neg_hi:[0,0,1]
	v_pk_fma_f32 v[42:43], v[38:39], v[114:115], v[42:43] op_sel_hi:[0,1,1] neg_lo:[0,0,1] neg_hi:[0,0,1]
	v_cvt_f32_i32_e32 v38, s7
	v_pk_add_f32 v[110:111], v[110:111], v[46:47]
	v_pk_add_f32 v[42:43], v[116:117], v[42:43]
	s_max_i32 s7, s74, 8
	v_div_scale_f32 v46, s[16:17], v38, v38, 1.0
	v_rcp_f32_e32 v47, v46
	s_min_i32 s16, s21, s23
	s_sub_i32 s7, s16, s7
	v_and_b32_e32 v115, 0xffff0000, v173
	v_fma_f32 v112, -v46, v47, 1.0
	v_fmac_f32_e32 v47, v112, v47
	v_div_scale_f32 v112, vcc, 1.0, v38, 1.0
	v_mul_f32_e32 v113, v112, v47
	v_fma_f32 v114, -v46, v113, v112
	v_fmac_f32_e32 v113, v114, v47
	v_fma_f32 v46, -v46, v113, v112
	v_div_fmas_f32 v46, v46, v47, v113
	v_div_fixup_f32 v38, v46, v38, 1.0
	v_pk_fma_f32 v[46:47], v[38:39], v[110:111], v[92:93] op_sel_hi:[0,1,1] neg_lo:[0,0,1] neg_hi:[0,0,1]
	v_pk_fma_f32 v[112:113], v[38:39], v[42:43], v[64:65] op_sel_hi:[0,1,1] neg_lo:[0,0,1] neg_hi:[0,0,1]
	v_pk_mul_f32 v[112:113], v[2:3], v[112:113]
	v_pk_mul_f32 v[46:47], v[0:1], v[46:47]
	v_lshlrev_b32_e32 v114, 16, v173
	v_cvt_pk_bf16_f32 v46, v46, v47
	v_cvt_pk_bf16_f32 v47, v112, v113
	v_add_co_u32_e32 v112, vcc, s61, v22
	v_lshlrev_b32_e32 v116, 16, v39
	s_nop 0
	v_addc_co_u32_e32 v113, vcc, 0, v23, vcc
	v_and_b32_e32 v117, 0xffff0000, v39
	s_add_i32 s7, s7, 8
	global_store_dwordx2 v[112:113], v[46:47], off offset:1536
	v_pk_mul_f32 v[38:39], v[34:35], v[116:117] op_sel_hi:[0,1]
	v_pk_mul_f32 v[46:47], v[34:35], v[114:115] op_sel_hi:[0,1]
	v_pk_fma_f32 v[60:61], v[34:35], v[114:115], v[60:61] op_sel_hi:[0,1,1] neg_lo:[0,0,1] neg_hi:[0,0,1]
	v_pk_fma_f32 v[48:49], v[34:35], v[116:117], v[48:49] op_sel_hi:[0,1,1] neg_lo:[0,0,1] neg_hi:[0,0,1]
	v_cvt_f32_i32_e32 v34, s7
	v_pk_add_f32 v[48:49], v[42:43], v[48:49]
	v_pk_add_f32 v[60:61], v[110:111], v[60:61]
	s_max_i32 s7, s71, 8
	v_div_scale_f32 v42, s[16:17], v34, v34, 1.0
	v_rcp_f32_e32 v43, v42
	s_min_i32 s16, s34, s23
	s_sub_i32 s7, s16, s7
	s_add_i32 s7, s7, 8
	v_fma_f32 v110, -v42, v43, 1.0
	v_fmac_f32_e32 v43, v110, v43
	v_div_scale_f32 v110, vcc, 1.0, v34, 1.0
	v_mul_f32_e32 v111, v110, v43
	v_fma_f32 v114, -v42, v111, v110
	v_fmac_f32_e32 v111, v114, v43
	v_fma_f32 v42, -v42, v111, v110
	v_div_fmas_f32 v42, v42, v43, v111
	v_div_fixup_f32 v34, v42, v34, 1.0
	v_pk_fma_f32 v[42:43], v[34:35], v[60:61], v[94:95] op_sel_hi:[0,1,1] neg_lo:[0,0,1] neg_hi:[0,0,1]
	v_pk_fma_f32 v[110:111], v[34:35], v[48:49], v[68:69] op_sel_hi:[0,1,1] neg_lo:[0,0,1] neg_hi:[0,0,1]
	v_pk_mul_f32 v[110:111], v[2:3], v[110:111]
	v_pk_mul_f32 v[42:43], v[0:1], v[42:43]
	s_nop 0
	v_cvt_pk_bf16_f32 v42, v42, v43
	v_cvt_pk_bf16_f32 v43, v110, v111
	global_store_dwordx2 v[112:113], v[42:43], off offset:3584
	v_lshlrev_b32_e32 v110, 16, v172
	v_and_b32_e32 v111, 0xffff0000, v172
	v_lshlrev_b32_e32 v112, 16, v35
	v_and_b32_e32 v113, 0xffff0000, v35
	v_pk_mul_f32 v[34:35], v[36:37], v[112:113] op_sel_hi:[0,1]
	v_pk_mul_f32 v[42:43], v[36:37], v[110:111] op_sel_hi:[0,1]
	v_pk_fma_f32 v[66:67], v[36:37], v[110:111], v[66:67] op_sel_hi:[0,1,1] neg_lo:[0,0,1] neg_hi:[0,0,1]
	v_pk_fma_f32 v[52:53], v[36:37], v[112:113], v[52:53] op_sel_hi:[0,1,1] neg_lo:[0,0,1] neg_hi:[0,0,1]
	v_cvt_f32_i32_e32 v36, s7
	v_pk_add_f32 v[48:49], v[48:49], v[52:53]
	v_pk_add_f32 v[60:61], v[60:61], v[66:67]
	s_max_i32 s7, s69, 8
	v_div_scale_f32 v52, s[16:17], v36, v36, 1.0
	v_rcp_f32_e32 v53, v52
	s_min_i32 s16, s19, s23
	s_sub_i32 s7, s16, s7
	v_and_b32_e32 v111, 0xffff0000, v171
	v_fma_f32 v66, -v52, v53, 1.0
	v_fmac_f32_e32 v53, v66, v53
	v_div_scale_f32 v66, vcc, 1.0, v36, 1.0
	v_mul_f32_e32 v67, v66, v53
	v_fma_f32 v110, -v52, v67, v66
	v_fmac_f32_e32 v67, v110, v53
	v_fma_f32 v52, -v52, v67, v66
	v_div_fmas_f32 v52, v52, v53, v67
	v_div_fixup_f32 v36, v52, v36, 1.0
	v_pk_fma_f32 v[52:53], v[36:37], v[60:61], v[98:99] op_sel_hi:[0,1,1] neg_lo:[0,0,1] neg_hi:[0,0,1]
	v_pk_fma_f32 v[66:67], v[36:37], v[48:49], v[62:63] op_sel_hi:[0,1,1] neg_lo:[0,0,1] neg_hi:[0,0,1]
	v_pk_mul_f32 v[66:67], v[2:3], v[66:67]
	v_pk_mul_f32 v[52:53], v[0:1], v[52:53]
	v_lshlrev_b32_e32 v110, 16, v171
	v_cvt_pk_bf16_f32 v52, v52, v53
	v_cvt_pk_bf16_f32 v53, v66, v67
	v_add_co_u32_e32 v66, vcc, s94, v22
	v_lshlrev_b32_e32 v112, 16, v37
	s_nop 0
	v_addc_co_u32_e32 v67, vcc, 0, v23, vcc
	v_and_b32_e32 v113, 0xffff0000, v37
	s_add_i32 s7, s7, 8
	global_store_dwordx2 v[66:67], v[52:53], off offset:1536
	v_pk_mul_f32 v[36:37], v[30:31], v[112:113] op_sel_hi:[0,1]
	v_pk_mul_f32 v[52:53], v[30:31], v[110:111] op_sel_hi:[0,1]
	v_pk_fma_f32 v[80:81], v[30:31], v[110:111], v[80:81] op_sel_hi:[0,1,1] neg_lo:[0,0,1] neg_hi:[0,0,1]
	v_pk_fma_f32 v[56:57], v[30:31], v[112:113], v[56:57] op_sel_hi:[0,1,1] neg_lo:[0,0,1] neg_hi:[0,0,1]
	v_cvt_f32_i32_e32 v30, s7
	v_pk_add_f32 v[56:57], v[48:49], v[56:57]
	v_pk_add_f32 v[60:61], v[60:61], v[80:81]
	s_max_i32 s7, s68, 8
	v_div_scale_f32 v48, s[16:17], v30, v30, 1.0
	v_rcp_f32_e32 v49, v48
	s_min_i32 s16, s20, s23
	s_sub_i32 s7, s16, s7
	s_add_i32 s7, s7, 8
	v_fma_f32 v80, -v48, v49, 1.0
	v_fmac_f32_e32 v49, v80, v49
	v_div_scale_f32 v80, vcc, 1.0, v30, 1.0
	v_mul_f32_e32 v81, v80, v49
	v_fma_f32 v110, -v48, v81, v80
	v_fmac_f32_e32 v81, v110, v49
	v_fma_f32 v48, -v48, v81, v80
	v_div_fmas_f32 v48, v48, v49, v81
	v_div_fixup_f32 v30, v48, v30, 1.0
	v_pk_fma_f32 v[48:49], v[30:31], v[60:61], v[100:101] op_sel_hi:[0,1,1] neg_lo:[0,0,1] neg_hi:[0,0,1]
	v_pk_fma_f32 v[80:81], v[30:31], v[56:57], v[58:59] op_sel_hi:[0,1,1] neg_lo:[0,0,1] neg_hi:[0,0,1]
	v_pk_mul_f32 v[80:81], v[2:3], v[80:81]
	v_pk_mul_f32 v[48:49], v[0:1], v[48:49]
	s_nop 0
	v_cvt_pk_bf16_f32 v48, v48, v49
	v_cvt_pk_bf16_f32 v49, v80, v81
	global_store_dwordx2 v[66:67], v[48:49], off offset:3584
	v_lshlrev_b32_e32 v66, 16, v170
	v_and_b32_e32 v67, 0xffff0000, v170
	v_lshlrev_b32_e32 v80, 16, v31
	v_and_b32_e32 v81, 0xffff0000, v31
	v_pk_mul_f32 v[30:31], v[32:33], v[80:81] op_sel_hi:[0,1]
	v_pk_mul_f32 v[48:49], v[32:33], v[66:67] op_sel_hi:[0,1]
	v_pk_fma_f32 v[66:67], v[32:33], v[66:67], v[82:83] op_sel_hi:[0,1,1] neg_lo:[0,0,1] neg_hi:[0,0,1]
	v_pk_fma_f32 v[72:73], v[32:33], v[80:81], v[72:73] op_sel_hi:[0,1,1] neg_lo:[0,0,1] neg_hi:[0,0,1]
	v_cvt_f32_i32_e32 v32, s7
	v_pk_add_f32 v[66:67], v[60:61], v[66:67]
	v_pk_add_f32 v[56:57], v[56:57], v[72:73]
	s_mov_b32 s7, 0xa000
	v_div_scale_f32 v60, s[16:17], v32, v32, 1.0
	v_rcp_f32_e32 v61, v60
	s_min_i32 s16, s18, s23
	v_and_b32_e32 v81, 0xffff0000, v169
	v_lshlrev_b32_e32 v82, 16, v33
	v_fma_f32 v72, -v60, v61, 1.0
	v_fmac_f32_e32 v61, v72, v61
	v_div_scale_f32 v72, vcc, 1.0, v32, 1.0
	v_mul_f32_e32 v73, v72, v61
	v_fma_f32 v80, -v60, v73, v72
	v_fmac_f32_e32 v73, v80, v61
	v_fma_f32 v60, -v60, v73, v72
	v_div_fmas_f32 v60, v60, v61, v73
	v_div_fixup_f32 v32, v60, v32, 1.0
	v_pk_fma_f32 v[60:61], v[32:33], v[66:67], v[102:103] op_sel_hi:[0,1,1] neg_lo:[0,0,1] neg_hi:[0,0,1]
	v_pk_fma_f32 v[72:73], v[32:33], v[56:57], v[54:55] op_sel_hi:[0,1,1] neg_lo:[0,0,1] neg_hi:[0,0,1]
	v_pk_mul_f32 v[72:73], v[2:3], v[72:73]
	v_pk_mul_f32 v[60:61], v[0:1], v[60:61]
	v_lshlrev_b32_e32 v80, 16, v169
	v_cvt_pk_bf16_f32 v60, v60, v61
	v_cvt_pk_bf16_f32 v61, v72, v73
	v_add_co_u32_e32 v72, vcc, s7, v22
	s_max_i32 s7, s67, 8
	s_sub_i32 s7, s16, s7
	v_addc_co_u32_e32 v73, vcc, 0, v23, vcc
	v_and_b32_e32 v83, 0xffff0000, v33
	s_add_i32 s7, s7, 8
	global_store_dwordx2 v[72:73], v[60:61], off offset:1536
	v_pk_mul_f32 v[32:33], v[28:29], v[82:83] op_sel_hi:[0,1]
	v_pk_mul_f32 v[60:61], v[28:29], v[80:81] op_sel_hi:[0,1]
	v_pk_fma_f32 v[80:81], v[28:29], v[80:81], v[84:85] op_sel_hi:[0,1,1] neg_lo:[0,0,1] neg_hi:[0,0,1]
	v_pk_fma_f32 v[76:77], v[28:29], v[82:83], v[76:77] op_sel_hi:[0,1,1] neg_lo:[0,0,1] neg_hi:[0,0,1]
	v_cvt_f32_i32_e32 v28, s7
	v_pk_add_f32 v[76:77], v[56:57], v[76:77]
	v_pk_add_f32 v[66:67], v[66:67], v[80:81]
	s_max_i32 s7, s66, 8
	v_div_scale_f32 v56, s[16:17], v28, v28, 1.0
	v_rcp_f32_e32 v57, v56
	s_min_i32 s16, s15, s23
	s_sub_i32 s7, s16, s7
	s_add_i32 s7, s7, 8
	v_fma_f32 v80, -v56, v57, 1.0
	v_fmac_f32_e32 v57, v80, v57
	v_div_scale_f32 v80, vcc, 1.0, v28, 1.0
	v_mul_f32_e32 v81, v80, v57
	v_fma_f32 v82, -v56, v81, v80
	v_fmac_f32_e32 v81, v82, v57
	v_fma_f32 v56, -v56, v81, v80
	v_div_fmas_f32 v56, v56, v57, v81
	v_div_fixup_f32 v28, v56, v28, 1.0
	v_pk_fma_f32 v[56:57], v[28:29], v[66:67], v[104:105] op_sel_hi:[0,1,1] neg_lo:[0,0,1] neg_hi:[0,0,1]
	v_pk_fma_f32 v[80:81], v[28:29], v[76:77], v[50:51] op_sel_hi:[0,1,1] neg_lo:[0,0,1] neg_hi:[0,0,1]
	v_pk_mul_f32 v[80:81], v[2:3], v[80:81]
	v_pk_mul_f32 v[56:57], v[0:1], v[56:57]
	v_lshlrev_b32_e32 v82, 16, v167
	v_cvt_pk_bf16_f32 v56, v56, v57
	v_cvt_pk_bf16_f32 v57, v80, v81
	global_store_dwordx2 v[72:73], v[56:57], off offset:3584
	v_lshlrev_b32_e32 v72, 16, v168
	v_and_b32_e32 v73, 0xffff0000, v168
	v_lshlrev_b32_e32 v80, 16, v29
	v_and_b32_e32 v81, 0xffff0000, v29
	v_pk_mul_f32 v[28:29], v[26:27], v[80:81] op_sel_hi:[0,1]
	v_pk_mul_f32 v[56:57], v[26:27], v[72:73] op_sel_hi:[0,1]
	v_pk_fma_f32 v[72:73], v[26:27], v[72:73], v[86:87] op_sel_hi:[0,1,1] neg_lo:[0,0,1] neg_hi:[0,0,1]
	v_pk_fma_f32 v[78:79], v[26:27], v[80:81], v[78:79] op_sel_hi:[0,1,1] neg_lo:[0,0,1] neg_hi:[0,0,1]
	v_cvt_f32_i32_e32 v26, s7
	v_pk_add_f32 v[76:77], v[76:77], v[78:79]
	v_pk_add_f32 v[78:79], v[66:67], v[72:73]
	s_max_i32 s7, s63, 8
	v_div_scale_f32 v66, s[16:17], v26, v26, 1.0
	v_rcp_f32_e32 v67, v66
	s_min_i32 s16, s5, s23
	s_sub_i32 s7, s16, s7
	v_and_b32_e32 v83, 0xffff0000, v167
	v_fma_f32 v72, -v66, v67, 1.0
	v_fmac_f32_e32 v67, v72, v67
	v_div_scale_f32 v72, vcc, 1.0, v26, 1.0
	v_mul_f32_e32 v73, v72, v67
	v_fma_f32 v80, -v66, v73, v72
	v_fmac_f32_e32 v73, v80, v67
	v_fma_f32 v66, -v66, v73, v72
	v_div_fmas_f32 v66, v66, v67, v73
	v_div_fixup_f32 v26, v66, v26, 1.0
	v_pk_fma_f32 v[66:67], v[26:27], v[78:79], v[106:107] op_sel_hi:[0,1,1] neg_lo:[0,0,1] neg_hi:[0,0,1]
	v_pk_fma_f32 v[72:73], v[26:27], v[76:77], v[44:45] op_sel_hi:[0,1,1] neg_lo:[0,0,1] neg_hi:[0,0,1]
	v_pk_mul_f32 v[66:67], v[0:1], v[66:67]
	v_add_co_u32_e32 v80, vcc, s51, v22
	v_pk_mul_f32 v[72:73], v[2:3], v[72:73]
	v_cvt_pk_bf16_f32 v66, v66, v67
	s_nop 0
	v_addc_co_u32_e32 v81, vcc, 0, v23, vcc
	v_cvt_pk_bf16_f32 v67, v72, v73
	v_lshlrev_b32_e32 v84, 16, v166
	v_and_b32_e32 v85, 0xffff0000, v166
	s_add_i32 s7, s7, 8
	global_store_dwordx2 v[80:81], v[66:67], off offset:1536
	v_pk_mul_f32 v[66:67], v[24:25], v[84:85] op_sel_hi:[0,1]
	v_pk_mul_f32 v[72:73], v[24:25], v[82:83] op_sel_hi:[0,1]
	v_pk_fma_f32 v[82:83], v[24:25], v[82:83], v[88:89] op_sel_hi:[0,1,1] neg_lo:[0,0,1] neg_hi:[0,0,1]
	v_pk_fma_f32 v[74:75], v[24:25], v[84:85], v[74:75] op_sel_hi:[0,1,1] neg_lo:[0,0,1] neg_hi:[0,0,1]
	v_cvt_f32_i32_e32 v24, s7
	v_pk_add_f32 v[74:75], v[76:77], v[74:75]
	v_pk_add_f32 v[76:77], v[78:79], v[82:83]
	s_max_i32 s7, s62, 8
	v_div_scale_f32 v26, s[16:17], v24, v24, 1.0
	v_rcp_f32_e32 v78, v26
	s_min_i32 s16, s80, s23
	s_sub_i32 s7, s16, s7
	s_add_i32 s7, s7, 8
	v_fma_f32 v79, -v26, v78, 1.0
	v_fmac_f32_e32 v78, v79, v78
	v_div_scale_f32 v79, vcc, 1.0, v24, 1.0
	v_mul_f32_e32 v82, v79, v78
	v_fma_f32 v83, -v26, v82, v79
	v_fmac_f32_e32 v82, v83, v78
	v_fma_f32 v26, -v26, v82, v79
	v_div_fmas_f32 v26, v26, v78, v82
	v_div_fixup_f32 v24, v26, v24, 1.0
	v_pk_fma_f32 v[78:79], v[24:25], v[76:77], v[108:109] op_sel_hi:[0,1,1] neg_lo:[0,0,1] neg_hi:[0,0,1]
	v_pk_fma_f32 v[40:41], v[24:25], v[74:75], v[40:41] op_sel_hi:[0,1,1] neg_lo:[0,0,1] neg_hi:[0,0,1]
	v_pk_mul_f32 v[78:79], v[0:1], v[78:79]
	v_pk_mul_f32 v[40:41], v[2:3], v[40:41]
	v_cvt_pk_bf16_f32 v78, v78, v79
	s_max_i32 s5, s5, 8
	v_cvt_pk_bf16_f32 v79, v40, v41
	global_store_dwordx2 v[80:81], v[78:79], off offset:3584
	v_lshlrev_b32_e32 v40, 16, v27
	v_and_b32_e32 v41, 0xffff0000, v27
	v_lshlrev_b32_e32 v78, 16, v25
	v_and_b32_e32 v79, 0xffff0000, v25
	v_pk_mul_f32 v[24:25], v[18:19], v[78:79] op_sel_hi:[0,1]
	v_pk_mul_f32 v[26:27], v[18:19], v[40:41] op_sel_hi:[0,1]
	v_pk_fma_f32 v[40:41], v[18:19], v[40:41], v[90:91] op_sel_hi:[0,1,1] neg_lo:[0,0,1] neg_hi:[0,0,1]
	v_pk_fma_f32 v[70:71], v[18:19], v[78:79], v[70:71] op_sel_hi:[0,1,1] neg_lo:[0,0,1] neg_hi:[0,0,1]
	v_cvt_f32_i32_e32 v18, s7
	v_pk_add_f32 v[70:71], v[74:75], v[70:71]
	v_pk_add_f32 v[40:41], v[76:77], v[40:41]
	s_max_i32 s7, s21, 8
	v_div_scale_f32 v74, s[16:17], v18, v18, 1.0
	v_rcp_f32_e32 v75, v74
	s_min_i32 s16, s82, s23
	s_sub_i32 s7, s16, s7
	s_add_i32 s7, s7, 8
	v_fma_f32 v76, -v74, v75, 1.0
	v_fmac_f32_e32 v75, v76, v75
	v_div_scale_f32 v76, vcc, 1.0, v18, 1.0
	v_mul_f32_e32 v77, v76, v75
	v_fma_f32 v78, -v74, v77, v76
	v_fmac_f32_e32 v77, v78, v75
	v_fma_f32 v74, -v74, v77, v76
	v_div_fmas_f32 v74, v74, v75, v77
	v_div_fixup_f32 v18, v74, v18, 1.0
	v_pk_fma_f32 v[46:47], v[18:19], v[40:41], v[46:47] op_sel_hi:[0,1,1] neg_lo:[0,0,1] neg_hi:[0,0,1]
	v_pk_fma_f32 v[38:39], v[18:19], v[70:71], v[38:39] op_sel_hi:[0,1,1] neg_lo:[0,0,1] neg_hi:[0,0,1]
	v_pk_mul_f32 v[38:39], v[2:3], v[38:39]
	v_pk_mul_f32 v[46:47], v[0:1], v[46:47]
	v_cvt_f32_i32_e32 v18, s7
	v_cvt_pk_bf16_f32 v46, v46, v47
	v_cvt_pk_bf16_f32 v47, v38, v39
	v_add_co_u32_e32 v38, vcc, s58, v22
	v_lshlrev_b32_e32 v74, 16, v162
	s_nop 0
	v_addc_co_u32_e32 v39, vcc, 0, v23, vcc
	global_store_dwordx2 v[38:39], v[46:47], off offset:1536
	v_lshlrev_b32_e32 v46, 16, v163
	v_and_b32_e32 v47, 0xffff0000, v163
	v_and_b32_e32 v75, 0xffff0000, v162
	v_pk_fma_f32 v[46:47], v[20:21], v[46:47], v[92:93] op_sel_hi:[0,1,1] neg_lo:[0,0,1] neg_hi:[0,0,1]
	v_pk_fma_f32 v[64:65], v[20:21], v[74:75], v[64:65] op_sel_hi:[0,1,1] neg_lo:[0,0,1] neg_hi:[0,0,1]
	v_div_scale_f32 v20, s[16:17], v18, v18, 1.0
	v_pk_add_f32 v[40:41], v[40:41], v[46:47]
	v_rcp_f32_e32 v46, v20
	v_pk_add_f32 v[64:65], v[70:71], v[64:65]
	s_max_i32 s7, s34, 8
	s_min_i32 s16, s79, s23
	v_fma_f32 v47, -v20, v46, 1.0
	v_fmac_f32_e32 v46, v47, v46
	v_div_scale_f32 v47, vcc, 1.0, v18, 1.0
	v_mul_f32_e32 v70, v47, v46
	v_fma_f32 v71, -v20, v70, v47
	v_fmac_f32_e32 v70, v71, v46
	v_fma_f32 v20, -v20, v70, v47
	v_div_fmas_f32 v20, v20, v46, v70
	v_div_fixup_f32 v18, v20, v18, 1.0
	v_pk_fma_f32 v[42:43], v[18:19], v[40:41], v[42:43] op_sel_hi:[0,1,1] neg_lo:[0,0,1] neg_hi:[0,0,1]
	v_pk_fma_f32 v[34:35], v[18:19], v[64:65], v[34:35] op_sel_hi:[0,1,1] neg_lo:[0,0,1] neg_hi:[0,0,1]
	v_pk_mul_f32 v[34:35], v[2:3], v[34:35]
	v_pk_mul_f32 v[42:43], v[0:1], v[42:43]
	s_sub_i32 s7, s16, s7
	v_cvt_pk_bf16_f32 v42, v42, v43
	v_cvt_pk_bf16_f32 v43, v34, v35
	global_store_dwordx2 v[38:39], v[42:43], off offset:3584
	v_lshlrev_b32_e32 v34, 16, v165
	v_and_b32_e32 v35, 0xffff0000, v165
	v_lshlrev_b32_e32 v38, 16, v164
	v_and_b32_e32 v39, 0xffff0000, v164
	s_add_i32 s7, s7, 8
	v_pk_fma_f32 v[34:35], v[16:17], v[34:35], v[94:95] op_sel_hi:[0,1,1] neg_lo:[0,0,1] neg_hi:[0,0,1]
	v_pk_fma_f32 v[38:39], v[16:17], v[38:39], v[68:69] op_sel_hi:[0,1,1] neg_lo:[0,0,1] neg_hi:[0,0,1]
	v_cvt_f32_i32_e32 v16, s7
	v_pk_add_f32 v[34:35], v[40:41], v[34:35]
	v_pk_add_f32 v[38:39], v[64:65], v[38:39]
	s_max_i32 s7, s19, 8
	v_div_scale_f32 v18, s[16:17], v16, v16, 1.0
	v_rcp_f32_e32 v20, v18
	s_min_i32 s16, s77, s23
	s_sub_i32 s7, s16, s7
	v_and_b32_e32 v43, 0xffff0000, v160
	v_fma_f32 v40, -v18, v20, 1.0
	v_fmac_f32_e32 v20, v40, v20
	v_div_scale_f32 v40, vcc, 1.0, v16, 1.0
	v_mul_f32_e32 v41, v40, v20
	v_fma_f32 v42, -v18, v41, v40
	v_fmac_f32_e32 v41, v42, v20
	v_fma_f32 v18, -v18, v41, v40
	v_div_fmas_f32 v18, v18, v20, v41
	v_div_fixup_f32 v16, v18, v16, 1.0
	v_pk_fma_f32 v[40:41], v[16:17], v[34:35], v[52:53] op_sel_hi:[0,1,1] neg_lo:[0,0,1] neg_hi:[0,0,1]
	v_pk_fma_f32 v[36:37], v[16:17], v[38:39], v[36:37] op_sel_hi:[0,1,1] neg_lo:[0,0,1] neg_hi:[0,0,1]
	v_pk_mul_f32 v[36:37], v[2:3], v[36:37]
	v_pk_mul_f32 v[40:41], v[0:1], v[40:41]
	v_lshlrev_b32_e32 v42, 16, v160
	v_cvt_pk_bf16_f32 v40, v40, v41
	v_cvt_pk_bf16_f32 v41, v36, v37
	v_add_co_u32_e32 v36, vcc, s59, v22
	s_add_i32 s7, s7, 8
	s_nop 0
	v_addc_co_u32_e32 v37, vcc, 0, v23, vcc
	global_store_dwordx2 v[36:37], v[40:41], off offset:1536
	v_lshlrev_b32_e32 v40, 16, v161
	v_and_b32_e32 v41, 0xffff0000, v161
	v_pk_fma_f32 v[40:41], v[14:15], v[40:41], v[98:99] op_sel_hi:[0,1,1] neg_lo:[0,0,1] neg_hi:[0,0,1]
	v_pk_fma_f32 v[42:43], v[14:15], v[42:43], v[62:63] op_sel_hi:[0,1,1] neg_lo:[0,0,1] neg_hi:[0,0,1]
	v_cvt_f32_i32_e32 v14, s7
	v_pk_add_f32 v[34:35], v[34:35], v[40:41]
	s_max_i32 s7, s20, 8
	v_pk_add_f32 v[38:39], v[38:39], v[42:43]
	v_div_scale_f32 v16, s[16:17], v14, v14, 1.0
	v_rcp_f32_e32 v18, v16
	s_min_i32 s16, s75, s23
	s_sub_i32 s7, s16, s7
	s_add_i32 s7, s7, 8
	v_fma_f32 v20, -v16, v18, 1.0
	v_fmac_f32_e32 v18, v20, v18
	v_div_scale_f32 v20, vcc, 1.0, v14, 1.0
	v_mul_f32_e32 v40, v20, v18
	v_fma_f32 v41, -v16, v40, v20
	v_fmac_f32_e32 v40, v41, v18
	v_fma_f32 v16, -v16, v40, v20
	v_div_fmas_f32 v16, v16, v18, v40
	v_lshlrev_b32_e32 v20, 16, v21
	v_and_b32_e32 v21, 0xffff0000, v21
	v_lshlrev_b32_e32 v18, 16, v19
	v_and_b32_e32 v19, 0xffff0000, v19
	v_pk_fma_f32 v[20:21], v[12:13], v[20:21], v[100:101] op_sel_hi:[0,1,1] neg_lo:[0,0,1] neg_hi:[0,0,1]
	v_pk_fma_f32 v[18:19], v[12:13], v[18:19], v[58:59] op_sel_hi:[0,1,1] neg_lo:[0,0,1] neg_hi:[0,0,1]
	v_cvt_f32_i32_e32 v12, s7
	v_div_fixup_f32 v14, v16, v14, 1.0
	v_pk_fma_f32 v[40:41], v[14:15], v[34:35], v[48:49] op_sel_hi:[0,1,1] neg_lo:[0,0,1] neg_hi:[0,0,1]
	v_pk_fma_f32 v[30:31], v[14:15], v[38:39], v[30:31] op_sel_hi:[0,1,1] neg_lo:[0,0,1] neg_hi:[0,0,1]
	v_div_scale_f32 v14, s[16:17], v12, v12, 1.0
	v_rcp_f32_e32 v16, v14
	v_pk_mul_f32 v[30:31], v[2:3], v[30:31]
	v_pk_mul_f32 v[40:41], v[0:1], v[40:41]
	v_pk_add_f32 v[20:21], v[34:35], v[20:21]
	v_cvt_pk_bf16_f32 v40, v40, v41
	v_cvt_pk_bf16_f32 v41, v30, v31
	v_fma_f32 v30, -v14, v16, 1.0
	v_fmac_f32_e32 v16, v30, v16
	v_div_scale_f32 v30, vcc, 1.0, v12, 1.0
	v_mul_f32_e32 v31, v30, v16
	v_fma_f32 v34, -v14, v31, v30
	v_fmac_f32_e32 v31, v34, v16
	v_fma_f32 v14, -v14, v31, v30
	s_max_i32 s7, s18, 8
	s_min_i32 s16, s72, s23
	v_div_fmas_f32 v14, v14, v16, v31
	s_sub_i32 s7, s16, s7
	v_div_fixup_f32 v12, v14, v12, 1.0
	v_lshlrev_b32_e32 v16, 16, v17
	v_and_b32_e32 v17, 0xffff0000, v17
	v_lshlrev_b32_e32 v14, 16, v15
	v_and_b32_e32 v15, 0xffff0000, v15
	s_add_i32 s7, s7, 8
	v_pk_fma_f32 v[16:17], v[10:11], v[16:17], v[102:103] op_sel_hi:[0,1,1] neg_lo:[0,0,1] neg_hi:[0,0,1]
	v_pk_fma_f32 v[14:15], v[10:11], v[14:15], v[54:55] op_sel_hi:[0,1,1] neg_lo:[0,0,1] neg_hi:[0,0,1]
	v_cvt_f32_i32_e32 v10, s7
	v_pk_add_f32 v[18:19], v[38:39], v[18:19]
	v_pk_fma_f32 v[30:31], v[12:13], v[20:21], v[60:61] op_sel_hi:[0,1,1] neg_lo:[0,0,1] neg_hi:[0,0,1]
	v_pk_fma_f32 v[32:33], v[12:13], v[18:19], v[32:33] op_sel_hi:[0,1,1] neg_lo:[0,0,1] neg_hi:[0,0,1]
	v_div_scale_f32 v12, s[16:17], v10, v10, 1.0
	v_pk_add_f32 v[14:15], v[18:19], v[14:15]
	v_rcp_f32_e32 v18, v12
	v_pk_mul_f32 v[32:33], v[2:3], v[32:33]
	v_pk_mul_f32 v[30:31], v[0:1], v[30:31]
	global_store_dwordx2 v[36:37], v[40:41], off offset:3584
	v_cvt_pk_bf16_f32 v30, v30, v31
	v_cvt_pk_bf16_f32 v31, v32, v33
	v_add_co_u32_e32 v32, vcc, s60, v22
	v_fma_f32 v19, -v12, v18, 1.0
	s_nop 0
	v_addc_co_u32_e32 v33, vcc, 0, v23, vcc
	v_fmac_f32_e32 v18, v19, v18
	v_div_scale_f32 v19, vcc, 1.0, v10, 1.0
	v_pk_add_f32 v[16:17], v[20:21], v[16:17]
	v_mul_f32_e32 v20, v19, v18
	v_fma_f32 v21, -v12, v20, v19
	v_fmac_f32_e32 v20, v21, v18
	v_fma_f32 v12, -v12, v20, v19
	v_div_fmas_f32 v12, v12, v18, v20
	s_max_i32 s7, s15, 8
	s_min_i32 s15, s70, s23
	v_div_fixup_f32 v10, v12, v10, 1.0
	s_sub_i32 s7, s15, s7
	v_pk_fma_f32 v[18:19], v[10:11], v[16:17], v[56:57] op_sel_hi:[0,1,1] neg_lo:[0,0,1] neg_hi:[0,0,1]
	s_add_i32 s7, s7, 8
	v_pk_fma_f32 v[20:21], v[10:11], v[14:15], v[28:29] op_sel_hi:[0,1,1] neg_lo:[0,0,1] neg_hi:[0,0,1]
	v_pk_mul_f32 v[18:19], v[0:1], v[18:19]
	v_cvt_f32_i32_e32 v12, s7
	global_store_dwordx2 v[32:33], v[30:31], off offset:1536
	v_pk_mul_f32 v[20:21], v[2:3], v[20:21]
	v_cvt_pk_bf16_f32 v18, v18, v19
	v_lshlrev_b32_e32 v10, 16, v11
	v_cvt_pk_bf16_f32 v19, v20, v21
	global_store_dwordx2 v[32:33], v[18:19], off offset:3584
	v_and_b32_e32 v11, 0xffff0000, v11
	v_lshlrev_b32_e32 v18, 16, v7
	v_and_b32_e32 v19, 0xffff0000, v7
	v_pk_fma_f32 v[10:11], v[6:7], v[10:11], v[104:105] op_sel_hi:[0,1,1] neg_lo:[0,0,1] neg_hi:[0,0,1]
	v_pk_fma_f32 v[6:7], v[6:7], v[18:19], v[50:51] op_sel_hi:[0,1,1] neg_lo:[0,0,1] neg_hi:[0,0,1]
	v_pk_add_f32 v[6:7], v[14:15], v[6:7]
	v_div_scale_f32 v14, s[16:17], v12, v12, 1.0
	v_rcp_f32_e32 v15, v14
	v_pk_add_f32 v[10:11], v[16:17], v[10:11]
	s_add_i32 s7, s4, 39
	s_min_i32 s7, s7, s23
	v_fma_f32 v16, -v14, v15, 1.0
	v_fmac_f32_e32 v15, v16, v15
	v_div_scale_f32 v16, vcc, 1.0, v12, 1.0
	v_mul_f32_e32 v17, v16, v15
	v_fma_f32 v18, -v14, v17, v16
	v_fmac_f32_e32 v17, v18, v15
	v_fma_f32 v14, -v14, v17, v16
	v_div_fmas_f32 v14, v14, v15, v17
	v_div_fixup_f32 v12, v14, v12, 1.0
	v_pk_fma_f32 v[14:15], v[12:13], v[10:11], v[72:73] op_sel_hi:[0,1,1] neg_lo:[0,0,1] neg_hi:[0,0,1]
	v_pk_fma_f32 v[16:17], v[12:13], v[6:7], v[66:67] op_sel_hi:[0,1,1] neg_lo:[0,0,1] neg_hi:[0,0,1]
	v_pk_mul_f32 v[16:17], v[2:3], v[16:17]
	v_pk_mul_f32 v[14:15], v[0:1], v[14:15]
	v_lshlrev_b32_e32 v12, 16, v13
	v_cvt_pk_bf16_f32 v14, v14, v15
	v_cvt_pk_bf16_f32 v15, v16, v17
	v_add_co_u32_e32 v16, vcc, s50, v22
	v_and_b32_e32 v13, 0xffff0000, v13
	s_nop 0
	v_addc_co_u32_e32 v17, vcc, 0, v23, vcc
	global_store_dwordx2 v[16:17], v[14:15], off offset:1536
	v_lshlrev_b32_e32 v14, 16, v9
	v_and_b32_e32 v15, 0xffff0000, v9
	s_sub_i32 s5, s7, s5
	s_waitcnt vmcnt(31)
	v_pk_fma_f32 v[12:13], v[8:9], v[12:13], v[106:107] op_sel_hi:[0,1,1] neg_lo:[0,0,1] neg_hi:[0,0,1]
	v_pk_fma_f32 v[8:9], v[8:9], v[14:15], v[44:45] op_sel_hi:[0,1,1] neg_lo:[0,0,1] neg_hi:[0,0,1]
	s_add_i32 s5, s5, 8
	v_pk_add_f32 v[6:7], v[6:7], v[8:9]
	v_pk_add_f32 v[8:9], v[10:11], v[12:13]
	v_cvt_f32_i32_e32 v10, s5
	v_div_scale_f32 v11, s[16:17], v10, v10, 1.0
	v_rcp_f32_e32 v12, v11
	s_nop 0
	v_fma_f32 v13, -v11, v12, 1.0
	v_fmac_f32_e32 v12, v13, v12
	v_div_scale_f32 v13, vcc, 1.0, v10, 1.0
	v_mul_f32_e32 v14, v13, v12
	v_fma_f32 v15, -v11, v14, v13
	v_fmac_f32_e32 v14, v15, v12
	v_fma_f32 v11, -v11, v14, v13
	v_div_fmas_f32 v11, v11, v12, v14
	v_div_fixup_f32 v10, v11, v10, 1.0
	v_pk_fma_f32 v[8:9], v[10:11], v[8:9], v[26:27] op_sel_hi:[0,1,1] neg_lo:[0,0,1] neg_hi:[0,0,1]
	v_pk_fma_f32 v[6:7], v[10:11], v[6:7], v[24:25] op_sel_hi:[0,1,1] neg_lo:[0,0,1] neg_hi:[0,0,1]
	v_pk_mul_f32 v[10:11], v[2:3], v[6:7]
	v_pk_mul_f32 v[6:7], v[0:1], v[8:9]
	s_nop 0
	v_cvt_pk_bf16_f32 v6, v6, v7
	v_cvt_pk_bf16_f32 v7, v10, v11
	s_cbranch_execz .LBB0_294
	s_branch .LBB0_295

.LBB0_490:
	v_mov_b32_e32 v52, v214
	s_movk_i32 s13, 0xffe0
	v_ashrrev_i32_e32 v16, 4, v52
	v_lshlrev_b32_e32 v22, 3, v52
	v_add_u32_e32 v18, 32, v16
	v_and_b32_e32 v0, 0x78, v22
	v_ashrrev_i32_e32 v17, 31, v16
	v_ashrrev_i32_e32 v19, 31, v18
	v_lshlrev_b32_e32 v23, 1, v0
	v_lshlrev_b64 v[48:49], 9, v[16:17]
	v_lshlrev_b64 v[8:9], 9, v[18:19]
	v_or_b32_e32 v50, v48, v23
	v_mov_b32_e32 v51, v49
	v_or_b32_e32 v8, v8, v23
	v_lshl_add_u64 v[0:1], s[68:69], 0, v[50:51]
	v_lshl_add_u64 v[4:5], s[68:69], 0, v[8:9]
	v_lshl_add_u64 v[10:11], s[4:5], 0, v[50:51]
	v_lshl_add_u64 v[12:13], s[4:5], 0, v[8:9]
	v_ashrrev_i32_e32 v53, 1, v52
	global_load_dwordx4 v[0:3], v[0:1], off
	s_nop 0
	global_load_dwordx4 v[4:7], v[4:5], off
	s_nop 0
	global_load_dwordx4 v[8:11], v[10:11], off
	s_nop 0
	global_load_dwordx4 v[12:15], v[12:13], off
	v_bfi_b32 v20, s13, v53, v52
	v_ashrrev_i32_e32 v21, 31, v20
	v_bfe_u32 v190, v52, 5, 1
	v_lshlrev_b64 v[20:21], 11, v[20:21]
	v_lshl_add_u64 v[20:21], s[2:3], 0, v[20:21]
	v_lshlrev_b32_e32 v178, 4, v190
	v_mov_b32_e32 v179, v97
	v_lshl_add_u64 v[20:21], v[20:21], 0, v[178:179]
	global_load_dwordx4 v[114:117], v[20:21], off nt
	global_load_dwordx4 v[110:113], v[20:21], off offset:32 nt
	global_load_dwordx4 v[122:125], v[20:21], off offset:64 nt
	global_load_dwordx4 v[126:129], v[20:21], off offset:96 nt
	global_load_dwordx4 v[118:121], v[20:21], off offset:128 nt
	global_load_dwordx4 v[106:109], v[20:21], off offset:160 nt
	global_load_dwordx4 v[102:105], v[20:21], off offset:192 nt
	global_load_dwordx4 v[98:101], v[20:21], off offset:224 nt
	v_and_b32_e32 v19, 0xfffff0, v16
	v_lshlrev_b32_e32 v24, 1, v16
	v_lshrrev_b32_e32 v25, 1, v16
	v_and_b32_e32 v26, 3, v16
	v_and_or_b32 v19, v24, 8, v19
	v_and_or_b32 v24, v25, 4, v26
	v_and_b32_e32 v25, 0xfffff0, v18
	v_lshlrev_b32_e32 v26, 1, v18
	v_and_b32_e32 v17, 0x70, v52
	v_bfe_u32 v22, v22, 5, 2
	v_lshlrev_b32_e32 v16, 8, v16
	v_lshlrev_b32_e32 v18, 8, v18
	v_lshrrev_b32_e32 v19, 1, v19
	v_and_or_b32 v25, v26, 8, v25
	v_and_b32_e32 v179, 31, v52
	v_lshlrev_b32_e32 v54, 4, v52
	v_bitop3_b32 v16, v23, v16, v17 bitop3:0xde
	v_bitop3_b32 v17, v23, v18, v17 bitop3:0xde
	v_or_b32_e32 v18, v19, v22
	v_lshrrev_b32_e32 v19, 1, v25
	v_lshlrev_b32_e32 v70, 8, v179
	v_and_b32_e32 v71, 0x70, v54
	v_lshlrev_b32_e32 v24, 6, v24
	v_and_b32_e32 v28, 48, v23
	v_add_u32_e32 v196, 0, v16
	v_add_u32_e32 v197, 0, v17
	v_lshlrev_b32_e32 v16, 9, v18
	v_or_b32_e32 v17, v19, v22
	v_bitop3_b32 v27, v178, v70, v71 bitop3:0xde
	v_or3_b32 v16, v16, v24, v28
	v_lshlrev_b32_e32 v17, 9, v17
	v_add_u32_e32 v195, 0, v27
	v_or3_b32 v17, v17, v24, v28
	v_add_u32_e32 v198, 0, v16
	s_waitcnt vmcnt(0)
	v_add_u32_e32 v199, 0, v17
	s_add_i32 s2, 0, 0x10000
	v_and_b32_e32 v72, 0xc0, v54
	v_and_b32_e32 v76, 63, v52
	v_and_b32_e32 v180, 0xffffffe0, v53
	v_lshlrev_b32_e32 v53, 3, v76
	s_cmp_lg_u32 0, -1
	s_cselect_b32 s30, 0, 0
	s_mov_b32 s13, s12
	s_mov_b32 s14, s12
	s_mov_b32 s15, s12
	s_mov_b32 s16, s12
	s_mov_b32 s17, s12
	s_mov_b32 s18, s12
	s_mov_b32 s19, s12
	s_mov_b32 s20, s12
	s_mov_b32 s21, s12
	s_mov_b32 s22, s12
	s_mov_b32 s23, s12
	s_waitcnt vmcnt(11)
	ds_write_b128 v198, v[0:3]
	s_waitcnt vmcnt(10)
	ds_write_b128 v199, v[4:7]
	s_waitcnt vmcnt(9)
	ds_write_b128 v196, v[8:11] offset:32768
	s_waitcnt vmcnt(8)
	ds_write_b128 v197, v[12:15] offset:32768
	s_waitcnt lgkmcnt(0)
	s_barrier
	ds_read_b128 v[0:3], v195 offset:32768
	ds_read_b128 v[4:7], v195 offset:40960
	s_waitcnt vmcnt(7) lgkmcnt(1)
	v_mfma_f32_32x32x16_bf16 v[16:31], v[0:3], v[114:117], 0
	v_or_b32_e32 v0, 32, v178
	v_bitop3_b32 v0, v0, v70, v71 bitop3:0xde
	v_add_u32_e32 v203, 0, v0
	s_mov_b32 s24, s12
	s_mov_b32 s25, s12
	s_mov_b32 s26, s12
	s_mov_b32 s27, s12
	s_waitcnt lgkmcnt(0)
	v_mfma_f32_32x32x16_bf16 v[32:47], v[4:7], v[114:117], 0
	ds_read_b128 v[0:3], v203 offset:32768
	ds_read_b128 v[4:7], v203 offset:40960
	v_lshl_add_u64 v[182:183], s[4:5], 0, v[48:49]
	v_lshl_add_u64 v[184:185], s[68:69], 0, v[48:49]
	v_mov_b32_e32 v192, 0
	s_waitcnt vmcnt(6) lgkmcnt(1)
	v_mfma_f32_32x32x16_bf16 v[16:31], v[0:3], v[110:113], v[16:31]
	v_or_b32_e32 v0, 64, v178
	v_bitop3_b32 v0, v0, v70, v71 bitop3:0xde
	v_add_u32_e32 v202, 0, v0
	s_waitcnt lgkmcnt(0)
	v_mfma_f32_32x32x16_bf16 v[32:47], v[4:7], v[110:113], v[32:47]
	ds_read_b128 v[0:3], v202 offset:32768
	ds_read_b128 v[4:7], v202 offset:40960
	s_waitcnt vmcnt(5) lgkmcnt(1)
	v_mfma_f32_32x32x16_bf16 v[16:31], v[0:3], v[122:125], v[16:31]
	v_or_b32_e32 v0, 0x60, v178
	v_bitop3_b32 v0, v0, v70, v71 bitop3:0xde
	v_add_u32_e32 v201, 0, v0
	s_waitcnt lgkmcnt(0)
	v_mfma_f32_32x32x16_bf16 v[32:47], v[4:7], v[122:125], v[32:47]
	ds_read_b128 v[0:3], v201 offset:32768
	ds_read_b128 v[4:7], v201 offset:40960
	s_waitcnt vmcnt(4) lgkmcnt(1)
	v_mfma_f32_32x32x16_bf16 v[16:31], v[0:3], v[126:129], v[16:31]
	v_or_b32_e32 v0, 0x80, v178
	v_bitop3_b32 v0, v0, v70, v71 bitop3:0xde
	v_add_u32_e32 v200, 0, v0
	ds_read_b128 v[0:3], v200 offset:32768
	s_waitcnt lgkmcnt(1)
	v_mfma_f32_32x32x16_bf16 v[32:47], v[4:7], v[126:129], v[32:47]
	v_and_b32_e32 v4, 0x3fffffc0, v52
	v_lshl_add_u32 v181, v4, 2, s2
	ds_read_b128 v[4:7], v200 offset:40960
	s_mov_b64 s[2:3], 0x8000
	v_lshl_add_u64 v[8:9], v[50:51], 0, s[2:3]
	s_mov_b64 s[2:3], 0xc000
	v_lshl_add_u64 v[10:11], v[50:51], 0, s[2:3]
	s_waitcnt vmcnt(3) lgkmcnt(1)
	v_mfma_f32_32x32x16_bf16 v[16:31], v[0:3], v[118:121], v[16:31]
	v_or_b32_e32 v0, 0xa0, v178
	v_bitop3_b32 v0, v0, v70, v71 bitop3:0xde
	v_add_u32_e32 v204, 0, v0
	ds_read_b128 v[0:3], v204 offset:32768
	v_lshl_add_u64 v[12:13], s[68:69], 0, v[8:9]
	v_lshl_add_u64 v[8:9], s[4:5], 0, v[8:9]
	v_lshl_add_u64 v[14:15], s[68:69], 0, v[10:11]
	s_waitcnt lgkmcnt(1)
	v_mfma_f32_32x32x16_bf16 v[32:47], v[4:7], v[118:121], v[32:47]
	ds_read_b128 v[4:7], v204 offset:40960
	v_lshl_add_u64 v[10:11], s[4:5], 0, v[10:11]
	global_load_dwordx4 v[54:57], v[12:13], off
	global_load_dwordx4 v[58:61], v[14:15], off
	global_load_dwordx4 v[62:65], v[8:9], off
	global_load_dwordx4 v[66:69], v[10:11], off
	v_lshlrev_b32_e32 v9, 1, v52
	v_and_or_b32 v8, v53, 24, v72
	s_mov_b64 s[2:3], 0x14000
	s_waitcnt vmcnt(6) lgkmcnt(1)
	v_mfma_f32_32x32x16_bf16 v[16:31], v[0:3], v[106:109], v[16:31]
	v_or_b32_e32 v0, 0xc0, v178
	v_bitop3_b32 v0, v0, v70, v71 bitop3:0xde
	v_add_u32_e32 v206, 0, v0
	ds_read_b128 v[0:3], v206 offset:32768
	v_lshl_add_u32 v191, v179, 2, v181
	s_waitcnt lgkmcnt(1)
	v_mfma_f32_32x32x16_bf16 v[32:47], v[4:7], v[106:109], v[32:47]
	v_and_b32_e32 v4, 32, v9
	v_and_b32_e32 v5, 0x100, v53
	v_or3_b32 v53, v8, v4, v5
	ds_read_b128 v[4:7], v206 offset:40960
	v_add_u32_e32 v194, s30, v53
	s_waitcnt vmcnt(5) lgkmcnt(1)
	v_mfma_f32_32x32x16_bf16 v[16:31], v[0:3], v[102:105], v[16:31]
	v_or_b32_e32 v0, 0xe0, v178
	v_bitop3_b32 v0, v0, v70, v71 bitop3:0xde
	v_add_u32_e32 v205, 0, v0
	ds_read_b128 v[0:3], v205 offset:32768
	ds_read_b128 v[70:73], v205 offset:40960
	s_waitcnt lgkmcnt(2)
	v_mfma_f32_32x32x16_bf16 v[32:47], v[4:7], v[102:105], v[32:47]
	s_waitcnt vmcnt(4) lgkmcnt(1)
	v_mfma_f32_32x32x16_bf16 v[16:31], v[0:3], v[98:101], v[16:31]
	v_mov_b64_e32 v[0:1], s[12:13]
	v_mov_b64_e32 v[14:15], s[26:27]
	v_mov_b64_e32 v[2:3], s[14:15]
	v_mov_b64_e32 v[4:5], s[16:17]
	v_mov_b64_e32 v[6:7], s[18:19]
	v_mov_b64_e32 v[8:9], s[20:21]
	v_mov_b64_e32 v[10:11], s[22:23]
	s_waitcnt lgkmcnt(0)
	v_mfma_f32_32x32x16_bf16 v[32:47], v[70:73], v[98:101], v[32:47]
	s_nop 2
	v_max_f32_e32 v70, v17, v17
	v_max_f32_e32 v71, v16, v16
	v_max_f32_e32 v70, v71, v70
	v_max3_f32 v70, v70, v18, v19
	v_max3_f32 v70, v70, v20, v21
	v_max3_f32 v70, v70, v22, v23
	v_max3_f32 v70, v70, v24, v25
	v_max3_f32 v70, v70, v26, v27
	v_max3_f32 v70, v70, v28, v29
	v_max3_f32 v70, v70, v30, v31
	v_max3_f32 v70, v70, v32, v33
	v_max3_f32 v70, v70, v34, v35
	v_max3_f32 v70, v70, v36, v37
	v_max3_f32 v70, v70, v38, v39
	v_max3_f32 v70, v70, v40, v41
	v_max3_f32 v77, v70, v42, v43
	v_lshl_add_u64 v[70:71], v[50:51], 0, s[2:3]
	v_lshl_add_u64 v[72:73], s[4:5], 0, v[70:71]
	v_lshl_add_u64 v[50:51], v[50:51], 0, s[54:55]
	v_lshl_add_u64 v[70:71], s[68:69], 0, v[70:71]
	v_lshl_add_u64 v[74:75], s[4:5], 0, v[50:51]
	global_load_dwordx4 v[142:145], v[72:73], off
	global_load_dwordx4 v[138:141], v[74:75], off
	v_lshl_add_u64 v[50:51], s[68:69], 0, v[50:51]
	global_load_dwordx4 v[134:137], v[70:71], off
	global_load_dwordx4 v[130:133], v[50:51], off
	v_max3_f32 v50, v77, v44, v45
	v_max3_f32 v50, v50, v46, v47
	v_mov_b32_e32 v51, v50
	s_nop 1
	v_permlane32_swap_b32_e32 v50, v51
	v_max_f32_e32 v51, v51, v51
	v_max_f32_e32 v50, v50, v50
	v_max_f32_e32 v50, v50, v51
	v_add_f32_e32 v51, 0x7149f2ca, v50
	v_max_f32_e32 v50, 0xf149f2ca, v50
	v_cmp_ge_f32_e32 vcc, s28, v51
	v_sub_f32_e32 v51, 0xf149f2ca, v50
	v_mul_f32_e32 v51, 0x3e0293ee, v51
	v_exp_f32_e32 v51, v51
	s_cmp_eq_u64 vcc, exec
	s_cselect_b64 vcc, -1, 0
	s_waitcnt vmcnt(4)
	v_cndmask_b32_e64 v207, v51, 1.0, vcc
	v_mov_b32_e32 v51, 0xf149f2ca
	v_cndmask_b32_e32 v166, v50, v51, vcc
	v_mul_f32_e32 v50, 0xbe0293ee, v166
	v_fmamk_f32 v16, v16, 0x3e0293ee, v50
	v_exp_f32_e32 v163, v16
	v_fmamk_f32 v16, v17, 0x3e0293ee, v50
	v_exp_f32_e32 v177, v16
	v_fmamk_f32 v16, v18, 0x3e0293ee, v50
	v_exp_f32_e32 v164, v16
	v_fmamk_f32 v16, v19, 0x3e0293ee, v50
	v_exp_f32_e32 v186, v16
	v_fmamk_f32 v16, v20, 0x3e0293ee, v50
	v_exp_f32_e32 v176, v16
	v_fmamk_f32 v16, v21, 0x3e0293ee, v50
	v_exp_f32_e32 v187, v16
	v_fmamk_f32 v16, v22, 0x3e0293ee, v50
	v_exp_f32_e32 v165, v16
	v_fmamk_f32 v16, v23, 0x3e0293ee, v50
	v_exp_f32_e32 v175, v16
	v_fmamk_f32 v16, v24, 0x3e0293ee, v50
	v_exp_f32_e32 v171, v16
	v_fmamk_f32 v16, v25, 0x3e0293ee, v50
	v_exp_f32_e32 v173, v16
	v_fmamk_f32 v16, v26, 0x3e0293ee, v50
	v_exp_f32_e32 v172, v16
	v_fmamk_f32 v16, v27, 0x3e0293ee, v50
	v_exp_f32_e32 v174, v16
	v_fmamk_f32 v16, v28, 0x3e0293ee, v50
	v_exp_f32_e32 v167, v16
	v_fmamk_f32 v16, v29, 0x3e0293ee, v50
	v_pk_fma_f32 v[146:147], v[46:47], s[56:57], v[50:51] op_sel_hi:[1,0,0]
	v_pk_fma_f32 v[152:153], v[44:45], s[56:57], v[50:51] op_sel_hi:[1,0,0]
	v_pk_fma_f32 v[156:157], v[42:43], s[56:57], v[50:51] op_sel_hi:[1,0,0]
	v_pk_fma_f32 v[148:149], v[40:41], s[56:57], v[50:51] op_sel_hi:[1,0,0]
	v_pk_fma_f32 v[150:151], v[38:39], s[56:57], v[50:51] op_sel_hi:[1,0,0]
	v_pk_fma_f32 v[154:155], v[36:37], s[56:57], v[50:51] op_sel_hi:[1,0,0]
	v_pk_fma_f32 v[158:159], v[34:35], s[56:57], v[50:51] op_sel_hi:[1,0,0]
	v_pk_fma_f32 v[160:161], v[32:33], s[56:57], v[50:51] op_sel_hi:[1,0,0]
	v_exp_f32_e32 v169, v16
	v_fmamk_f32 v16, v30, 0x3e0293ee, v50
	v_fmac_f32_e32 v50, 0x3e0293ee, v31
	v_exp_f32_e32 v168, v16
	v_exp_f32_e32 v170, v50
	s_addk_i32 s30, 0x4000
	v_and_b32_e32 v16, 15, v52
	v_mov_b64_e32 v[12:13], s[24:25]
	s_waitcnt vmcnt(7)
	ds_write_b128 v198, v[54:57] offset:16384
	s_waitcnt vmcnt(6)
	ds_write_b128 v199, v[58:61] offset:16384
	s_waitcnt vmcnt(5)
	ds_write_b128 v196, v[62:65] offset:49152
	s_waitcnt vmcnt(4)
	ds_write_b128 v197, v[66:69] offset:49152
	v_add_u32_e32 v193, s30, v53
	v_lshlrev_b32_e32 v96, 4, v16
	v_mov_b64_e32 v[62:63], v[14:15]
	v_mov_b64_e32 v[46:47], v[14:15]
	v_mov_b64_e32 v[30:31], v[14:15]
	v_cmp_gt_u32_e64 s[2:3], 32, v76
	v_mov_b64_e32 v[60:61], v[12:13]
	v_mov_b64_e32 v[58:59], v[10:11]
	v_mov_b64_e32 v[56:57], v[8:9]
	v_mov_b64_e32 v[54:55], v[6:7]
	v_mov_b64_e32 v[52:53], v[4:5]
	v_mov_b64_e32 v[50:51], v[2:3]
	v_mov_b64_e32 v[48:49], v[0:1]
	v_mov_b64_e32 v[44:45], v[12:13]
	v_mov_b64_e32 v[42:43], v[10:11]
	v_mov_b64_e32 v[40:41], v[8:9]
	v_mov_b64_e32 v[38:39], v[6:7]
	v_mov_b64_e32 v[36:37], v[4:5]
	v_mov_b64_e32 v[34:35], v[2:3]
	v_mov_b64_e32 v[32:33], v[0:1]
	v_mov_b64_e32 v[28:29], v[12:13]
	v_mov_b64_e32 v[26:27], v[10:11]
	v_mov_b64_e32 v[24:25], v[8:9]
	v_mov_b64_e32 v[22:23], v[6:7]
	v_mov_b64_e32 v[20:21], v[4:5]
	v_mov_b64_e32 v[18:19], v[2:3]
	v_mov_b64_e32 v[16:17], v[0:1]
	s_waitcnt lgkmcnt(0)
	s_barrier
